# v50 + K-loop load/compute rebalance: last LDS-DMA issue of phases 2 and 4 moved from the LOAD segment into the following MMA segment (after its 8th MFMA), even-phase waits vmcnt(7); all 12 loops + 9 p
# baseline (speedup 1.0000x reference)
.LBB0_297:
	s_add_u32 s47, s38, s46
	s_addc_u32 s66, s39, 0
	s_add_u32 s64, s47, 0x100
	s_addc_u32 s65, s66, 0
	s_and_b64 s[48:49], s[44:45], exec
	s_cselect_b32 s49, s70, s65
	s_cselect_b32 s48, s71, s64
	s_add_u32 s46, s36, s46
	s_addc_u32 s64, s37, 0
	s_add_u32 s46, s46, 0x100
	s_addc_u32 s64, s64, 0
	s_and_b64 s[44:45], s[44:45], exec
	s_cselect_b32 s65, s72, s64
	s_cselect_b32 s64, s73, s46
	s_add_u32 s68, s47, 0x10080
	ds_read_b128 v[150:153], v146
	ds_read_b128 v[154:157], v146 offset:1024
	ds_read_b128 v[158:161], v146 offset:2048
	ds_read_b128 v[162:165], v146 offset:3072
	ds_read_b128 v[166:169], v147
	ds_read_b128 v[170:173], v147 offset:1024
	ds_read_b128 v[174:177], v147 offset:2048
	ds_read_b128 v[178:181], v147 offset:3072
	s_addc_u32 s69, s66, 0
	s_add_i32 s83, s30, s2
	s_add_i32 m0, s16, 0xc000
	s_add_i32 s84, s16, 0xe000
	s_add_i32 s80, s83, 0x2000
	s_add_u32 s66, s64, 0x40000
	s_addc_u32 s67, s65, 0
	s_add_i32 s82, s31, s2
	s_add_i32 s81, s82, 0x2000
	s_add_i32 s79, 0, 0x18000
	s_add_i32 s78, 0, 0x1c000
	s_add_u32 s46, s48, 0x10000
	s_addc_u32 s47, s49, 0
	s_add_i32 s77, s79, s2
	s_add_i32 s75, s77, 0x2000
	s_add_u32 s44, s64, 0x40080
	s_addc_u32 s45, s65, 0
	s_add_i32 s76, s78, s2
	s_add_i32 s74, s76, 0x2000
	v_lshl_add_u64 v[202:203], s[68:69], 0, v[130:131]
	ds_read_b128 v[182:185], v148
	ds_read_b128 v[186:189], v148 offset:1024
	ds_read_b128 v[190:193], v148 offset:2048
	ds_read_b128 v[194:197], v148 offset:3072
	ds_read_b128 v[198:201], v148 offset:4096
	ds_read_b128 v[206:209], v148 offset:5120
	ds_read_b128 v[210:213], v148 offset:6144
	ds_read_b128 v[214:217], v148 offset:7168
	global_load_lds_dwordx4 v[202:203], off
	v_lshl_add_u64 v[202:203], s[68:69], 0, v[132:133]
	s_mov_b32 m0, s84
	s_nop 0
	global_load_lds_dwordx4 v[202:203], off
	s_waitcnt vmcnt(8)
	s_waitcnt lgkmcnt(0)
	s_barrier
	s_setprio 1
	s_waitcnt lgkmcnt(0)
	v_mfma_f32_16x16x32_bf16 v[126:129], v[150:153], v[182:185], v[126:129]
	v_mfma_f32_16x16x32_bf16 v[122:125], v[158:161], v[182:185], v[122:125]
	v_mfma_f32_16x16x32_bf16 v[118:121], v[150:153], v[190:193], v[118:121]
	v_mfma_f32_16x16x32_bf16 v[114:117], v[158:161], v[190:193], v[114:117]
	v_mfma_f32_16x16x32_bf16 v[102:105], v[150:153], v[198:201], v[102:105]
	v_mfma_f32_16x16x32_bf16 v[98:101], v[158:161], v[198:201], v[98:101]
	v_mfma_f32_16x16x32_bf16 v[86:89], v[150:153], v[210:213], v[86:89]
	v_mfma_f32_16x16x32_bf16 v[82:85], v[158:161], v[210:213], v[82:85]
	v_mfma_f32_16x16x32_bf16 v[126:129], v[154:157], v[186:189], v[126:129]
	v_mfma_f32_16x16x32_bf16 v[122:125], v[162:165], v[186:189], v[122:125]
	v_mfma_f32_16x16x32_bf16 v[118:121], v[154:157], v[194:197], v[118:121]
	v_mfma_f32_16x16x32_bf16 v[114:117], v[162:165], v[194:197], v[114:117]
	v_mfma_f32_16x16x32_bf16 v[102:105], v[154:157], v[206:209], v[102:105]
	v_mfma_f32_16x16x32_bf16 v[98:101], v[162:165], v[206:209], v[98:101]
	v_mfma_f32_16x16x32_bf16 v[86:89], v[154:157], v[214:217], v[86:89]
	v_mfma_f32_16x16x32_bf16 v[82:85], v[162:165], v[214:217], v[82:85]
	s_setprio 0
	s_setprio 1
	v_mfma_f32_16x16x32_bf16 v[110:113], v[166:169], v[182:185], v[110:113]
	v_mfma_f32_16x16x32_bf16 v[106:109], v[174:177], v[182:185], v[106:109]
	v_mfma_f32_16x16x32_bf16 v[94:97], v[166:169], v[190:193], v[94:97]
	v_mfma_f32_16x16x32_bf16 v[90:93], v[174:177], v[190:193], v[90:93]
	v_mfma_f32_16x16x32_bf16 v[78:81], v[166:169], v[198:201], v[78:81]
	v_mfma_f32_16x16x32_bf16 v[74:77], v[174:177], v[198:201], v[74:77]
	v_mfma_f32_16x16x32_bf16 v[70:73], v[166:169], v[210:213], v[70:73]
	v_mfma_f32_16x16x32_bf16 v[66:69], v[174:177], v[210:213], v[66:69]
	v_mfma_f32_16x16x32_bf16 v[110:113], v[170:173], v[186:189], v[110:113]
	v_mfma_f32_16x16x32_bf16 v[106:109], v[178:181], v[186:189], v[106:109]
	v_mfma_f32_16x16x32_bf16 v[94:97], v[170:173], v[194:197], v[94:97]
	v_mfma_f32_16x16x32_bf16 v[90:93], v[178:181], v[194:197], v[90:93]
	v_mfma_f32_16x16x32_bf16 v[78:81], v[170:173], v[206:209], v[78:81]
	v_mfma_f32_16x16x32_bf16 v[74:77], v[178:181], v[206:209], v[74:77]
	v_mfma_f32_16x16x32_bf16 v[70:73], v[170:173], v[214:217], v[70:73]
	v_mfma_f32_16x16x32_bf16 v[66:69], v[178:181], v[214:217], v[66:69]
	s_setprio 0
	s_barrier
	s_mov_b32 m0, s83
	v_lshl_add_u64 v[202:203], s[64:65], 0, v[136:137]
	ds_read_b128 v[182:185], v148 offset:16384
	ds_read_b128 v[186:189], v148 offset:17408
	ds_read_b128 v[190:193], v148 offset:18432
	ds_read_b128 v[194:197], v148 offset:19456
	ds_read_b128 v[198:201], v148 offset:20480
	ds_read_b128 v[206:209], v148 offset:21504
	ds_read_b128 v[210:213], v148 offset:22528
	ds_read_b128 v[214:217], v148 offset:23552
	global_load_lds_dwordx4 v[202:203], off
	v_lshl_add_u64 v[218:219], s[64:65], 0, v[134:135]
	s_mov_b32 m0, s80
	v_lshl_add_u64 v[220:221], s[66:67], 0, v[136:137]
	global_load_lds_dwordx4 v[218:219], off
	s_mov_b32 m0, s82
	v_lshl_add_u64 v[222:223], s[48:49], 0, v[132:133]
	global_load_lds_dwordx4 v[220:221], off
	v_lshl_add_u64 v[220:221], s[66:67], 0, v[134:135]
	s_mov_b32 m0, s81
	s_nop 0
	global_load_lds_dwordx4 v[220:221], off
	v_lshl_add_u64 v[220:221], s[48:49], 0, v[130:131]
	s_mov_b32 m0, s16
	s_nop 0
	global_load_lds_dwordx4 v[220:221], off
	s_waitcnt vmcnt(7)
	s_waitcnt lgkmcnt(0)
	s_barrier
	s_setprio 1
	s_waitcnt lgkmcnt(0)
	v_mfma_f32_16x16x32_bf16 v[62:65], v[150:153], v[182:185], v[62:65]
	v_mfma_f32_16x16x32_bf16 v[58:61], v[158:161], v[182:185], v[58:61]
	v_mfma_f32_16x16x32_bf16 v[54:57], v[150:153], v[190:193], v[54:57]
	v_mfma_f32_16x16x32_bf16 v[50:53], v[158:161], v[190:193], v[50:53]
	v_mfma_f32_16x16x32_bf16 v[38:41], v[150:153], v[198:201], v[38:41]
	v_mfma_f32_16x16x32_bf16 v[34:37], v[158:161], v[198:201], v[34:37]
	v_mfma_f32_16x16x32_bf16 v[22:25], v[150:153], v[210:213], v[22:25]
	v_mfma_f32_16x16x32_bf16 v[18:21], v[158:161], v[210:213], v[18:21]
	s_mov_b32 m0, s17
	s_nop 0
	global_load_lds_dwordx4 v[222:223], off
	v_mfma_f32_16x16x32_bf16 v[62:65], v[154:157], v[186:189], v[62:65]
	v_mfma_f32_16x16x32_bf16 v[58:61], v[162:165], v[186:189], v[58:61]
	v_mfma_f32_16x16x32_bf16 v[54:57], v[154:157], v[194:197], v[54:57]
	v_mfma_f32_16x16x32_bf16 v[50:53], v[162:165], v[194:197], v[50:53]
	v_mfma_f32_16x16x32_bf16 v[38:41], v[154:157], v[206:209], v[38:41]
	v_mfma_f32_16x16x32_bf16 v[34:37], v[162:165], v[206:209], v[34:37]
	v_mfma_f32_16x16x32_bf16 v[22:25], v[154:157], v[214:217], v[22:25]
	v_mfma_f32_16x16x32_bf16 v[18:21], v[162:165], v[214:217], v[18:21]
	s_setprio 0
	s_setprio 1
	v_mfma_f32_16x16x32_bf16 v[46:49], v[166:169], v[182:185], v[46:49]
	v_mfma_f32_16x16x32_bf16 v[42:45], v[174:177], v[182:185], v[42:45]
	v_mfma_f32_16x16x32_bf16 v[30:33], v[166:169], v[190:193], v[30:33]
	v_mfma_f32_16x16x32_bf16 v[26:29], v[174:177], v[190:193], v[26:29]
	v_mfma_f32_16x16x32_bf16 v[14:17], v[166:169], v[198:201], v[14:17]
	v_mfma_f32_16x16x32_bf16 v[10:13], v[174:177], v[198:201], v[10:13]
	v_mfma_f32_16x16x32_bf16 v[6:9], v[166:169], v[210:213], v[6:9]
	v_mfma_f32_16x16x32_bf16 v[2:5], v[174:177], v[210:213], v[2:5]
	v_mfma_f32_16x16x32_bf16 v[46:49], v[170:173], v[186:189], v[46:49]
	v_mfma_f32_16x16x32_bf16 v[42:45], v[178:181], v[186:189], v[42:45]
	v_mfma_f32_16x16x32_bf16 v[30:33], v[170:173], v[194:197], v[30:33]
	v_mfma_f32_16x16x32_bf16 v[26:29], v[178:181], v[194:197], v[26:29]
	v_mfma_f32_16x16x32_bf16 v[14:17], v[170:173], v[206:209], v[14:17]
	v_mfma_f32_16x16x32_bf16 v[10:13], v[178:181], v[206:209], v[10:13]
	v_mfma_f32_16x16x32_bf16 v[6:9], v[170:173], v[214:217], v[6:9]
	v_mfma_f32_16x16x32_bf16 v[2:5], v[178:181], v[214:217], v[2:5]
	s_setprio 0
	s_barrier
	v_add_u32_e32 v149, s79, v145
	ds_read_b128 v[150:153], v149
	ds_read_b128 v[154:157], v149 offset:1024
	ds_read_b128 v[158:161], v149 offset:2048
	ds_read_b128 v[162:165], v149 offset:3072
	v_add_u32_e32 v149, s78, v145
	ds_read_b128 v[166:169], v149
	ds_read_b128 v[170:173], v149 offset:1024
	ds_read_b128 v[174:177], v149 offset:2048
	ds_read_b128 v[178:181], v149 offset:3072
	s_mov_b32 m0, s18
	v_lshl_add_u64 v[224:225], s[46:47], 0, v[130:131]
	ds_read_b128 v[182:185], v148 offset:32768
	ds_read_b128 v[186:189], v148 offset:33792
	ds_read_b128 v[190:193], v148 offset:34816
	ds_read_b128 v[194:197], v148 offset:35840
	ds_read_b128 v[198:201], v148 offset:36864
	ds_read_b128 v[206:209], v148 offset:37888
	ds_read_b128 v[210:213], v148 offset:38912
	ds_read_b128 v[214:217], v148 offset:39936
	global_load_lds_dwordx4 v[224:225], off
	v_lshl_add_u64 v[224:225], s[46:47], 0, v[132:133]
	s_mov_b32 m0, s19
	s_nop 0
	global_load_lds_dwordx4 v[224:225], off
	s_waitcnt vmcnt(8)
	s_waitcnt lgkmcnt(0)
	s_barrier
	s_setprio 1
	s_waitcnt lgkmcnt(0)
	v_mfma_f32_16x16x32_bf16 v[126:129], v[150:153], v[182:185], v[126:129]
	v_mfma_f32_16x16x32_bf16 v[122:125], v[158:161], v[182:185], v[122:125]
	v_mfma_f32_16x16x32_bf16 v[118:121], v[150:153], v[190:193], v[118:121]
	v_mfma_f32_16x16x32_bf16 v[114:117], v[158:161], v[190:193], v[114:117]
	v_mfma_f32_16x16x32_bf16 v[102:105], v[150:153], v[198:201], v[102:105]
	v_mfma_f32_16x16x32_bf16 v[98:101], v[158:161], v[198:201], v[98:101]
	v_mfma_f32_16x16x32_bf16 v[86:89], v[150:153], v[210:213], v[86:89]
	v_mfma_f32_16x16x32_bf16 v[82:85], v[158:161], v[210:213], v[82:85]
	v_mfma_f32_16x16x32_bf16 v[126:129], v[154:157], v[186:189], v[126:129]
	v_mfma_f32_16x16x32_bf16 v[122:125], v[162:165], v[186:189], v[122:125]
	v_mfma_f32_16x16x32_bf16 v[118:121], v[154:157], v[194:197], v[118:121]
	v_mfma_f32_16x16x32_bf16 v[114:117], v[162:165], v[194:197], v[114:117]
	v_mfma_f32_16x16x32_bf16 v[102:105], v[154:157], v[206:209], v[102:105]
	v_mfma_f32_16x16x32_bf16 v[98:101], v[162:165], v[206:209], v[98:101]
	v_mfma_f32_16x16x32_bf16 v[86:89], v[154:157], v[214:217], v[86:89]
	v_mfma_f32_16x16x32_bf16 v[82:85], v[162:165], v[214:217], v[82:85]
	s_setprio 0
	s_setprio 1
	v_mfma_f32_16x16x32_bf16 v[110:113], v[166:169], v[182:185], v[110:113]
	v_mfma_f32_16x16x32_bf16 v[106:109], v[174:177], v[182:185], v[106:109]
	v_mfma_f32_16x16x32_bf16 v[94:97], v[166:169], v[190:193], v[94:97]
	v_mfma_f32_16x16x32_bf16 v[90:93], v[174:177], v[190:193], v[90:93]
	v_mfma_f32_16x16x32_bf16 v[78:81], v[166:169], v[198:201], v[78:81]
	v_mfma_f32_16x16x32_bf16 v[74:77], v[174:177], v[198:201], v[74:77]
	v_mfma_f32_16x16x32_bf16 v[70:73], v[166:169], v[210:213], v[70:73]
	v_mfma_f32_16x16x32_bf16 v[66:69], v[174:177], v[210:213], v[66:69]
	v_mfma_f32_16x16x32_bf16 v[110:113], v[170:173], v[186:189], v[110:113]
	v_mfma_f32_16x16x32_bf16 v[106:109], v[178:181], v[186:189], v[106:109]
	v_mfma_f32_16x16x32_bf16 v[94:97], v[170:173], v[194:197], v[94:97]
	v_mfma_f32_16x16x32_bf16 v[90:93], v[178:181], v[194:197], v[90:93]
	v_mfma_f32_16x16x32_bf16 v[78:81], v[170:173], v[206:209], v[78:81]
	v_mfma_f32_16x16x32_bf16 v[74:77], v[178:181], v[206:209], v[74:77]
	v_mfma_f32_16x16x32_bf16 v[70:73], v[170:173], v[214:217], v[70:73]
	v_mfma_f32_16x16x32_bf16 v[66:69], v[178:181], v[214:217], v[66:69]
	s_setprio 0
	s_barrier
	s_mov_b32 m0, s77
	v_lshl_add_u64 v[202:203], v[202:203], 0, s[8:9]
	ds_read_b128 v[182:185], v148 offset:49152
	ds_read_b128 v[186:189], v148 offset:50176
	ds_read_b128 v[190:193], v148 offset:51200
	ds_read_b128 v[194:197], v148 offset:52224
	ds_read_b128 v[198:201], v148 offset:53248
	ds_read_b128 v[206:209], v148 offset:54272
	ds_read_b128 v[210:213], v148 offset:55296
	ds_read_b128 v[214:217], v148 offset:56320
	global_load_lds_dwordx4 v[202:203], off
	v_lshl_add_u64 v[202:203], v[218:219], 0, s[8:9]
	s_mov_b32 m0, s75
	s_nop 0
	global_load_lds_dwordx4 v[202:203], off
	v_lshl_add_u64 v[202:203], s[44:45], 0, v[136:137]
	s_mov_b32 m0, s76
	s_nop 0
	global_load_lds_dwordx4 v[202:203], off
	v_lshl_add_u64 v[202:203], s[44:45], 0, v[134:135]
	s_mov_b32 m0, s74
	s_nop 0
	global_load_lds_dwordx4 v[202:203], off
	v_lshl_add_u64 v[202:203], v[220:221], 0, s[8:9]
	s_mov_b32 m0, s28
	s_nop 0
	global_load_lds_dwordx4 v[202:203], off
	v_lshl_add_u64 v[202:203], v[222:223], 0, s[8:9]
	s_waitcnt vmcnt(7)
	s_waitcnt lgkmcnt(0)
	s_barrier
	s_setprio 1
	s_waitcnt lgkmcnt(0)
	v_mfma_f32_16x16x32_bf16 v[62:65], v[150:153], v[182:185], v[62:65]
	v_mfma_f32_16x16x32_bf16 v[58:61], v[158:161], v[182:185], v[58:61]
	v_mfma_f32_16x16x32_bf16 v[54:57], v[150:153], v[190:193], v[54:57]
	v_mfma_f32_16x16x32_bf16 v[50:53], v[158:161], v[190:193], v[50:53]
	v_mfma_f32_16x16x32_bf16 v[38:41], v[150:153], v[198:201], v[38:41]
	v_mfma_f32_16x16x32_bf16 v[34:37], v[158:161], v[198:201], v[34:37]
	v_mfma_f32_16x16x32_bf16 v[22:25], v[150:153], v[210:213], v[22:25]
	v_mfma_f32_16x16x32_bf16 v[18:21], v[158:161], v[210:213], v[18:21]
	s_mov_b32 m0, s29
	s_nop 0
	global_load_lds_dwordx4 v[202:203], off
	v_mfma_f32_16x16x32_bf16 v[62:65], v[154:157], v[186:189], v[62:65]
	v_mfma_f32_16x16x32_bf16 v[58:61], v[162:165], v[186:189], v[58:61]
	v_mfma_f32_16x16x32_bf16 v[54:57], v[154:157], v[194:197], v[54:57]
	v_mfma_f32_16x16x32_bf16 v[50:53], v[162:165], v[194:197], v[50:53]
	v_mfma_f32_16x16x32_bf16 v[38:41], v[154:157], v[206:209], v[38:41]
	v_mfma_f32_16x16x32_bf16 v[34:37], v[162:165], v[206:209], v[34:37]
	v_mfma_f32_16x16x32_bf16 v[22:25], v[154:157], v[214:217], v[22:25]
	v_mfma_f32_16x16x32_bf16 v[18:21], v[162:165], v[214:217], v[18:21]
	s_setprio 0
	s_setprio 1
	v_mfma_f32_16x16x32_bf16 v[46:49], v[166:169], v[182:185], v[46:49]
	v_mfma_f32_16x16x32_bf16 v[42:45], v[174:177], v[182:185], v[42:45]
	v_mfma_f32_16x16x32_bf16 v[30:33], v[166:169], v[190:193], v[30:33]
	v_mfma_f32_16x16x32_bf16 v[26:29], v[174:177], v[190:193], v[26:29]
	v_mfma_f32_16x16x32_bf16 v[14:17], v[166:169], v[198:201], v[14:17]
	v_mfma_f32_16x16x32_bf16 v[10:13], v[174:177], v[198:201], v[10:13]
	v_mfma_f32_16x16x32_bf16 v[6:9], v[166:169], v[210:213], v[6:9]
	v_mfma_f32_16x16x32_bf16 v[2:5], v[174:177], v[210:213], v[2:5]
	v_mfma_f32_16x16x32_bf16 v[46:49], v[170:173], v[186:189], v[46:49]
	v_mfma_f32_16x16x32_bf16 v[42:45], v[178:181], v[186:189], v[42:45]
	v_mfma_f32_16x16x32_bf16 v[30:33], v[170:173], v[194:197], v[30:33]
	v_mfma_f32_16x16x32_bf16 v[26:29], v[178:181], v[194:197], v[26:29]
	v_mfma_f32_16x16x32_bf16 v[14:17], v[170:173], v[206:209], v[14:17]
	v_mfma_f32_16x16x32_bf16 v[10:13], v[178:181], v[206:209], v[10:13]
	v_mfma_f32_16x16x32_bf16 v[6:9], v[170:173], v[214:217], v[6:9]
	v_mfma_f32_16x16x32_bf16 v[2:5], v[178:181], v[214:217], v[2:5]
	s_setprio 0
	s_barrier
	s_movk_i32 s46, 0x100
	s_andn2_b64 vcc, exec, s[42:43]
	s_mov_b64 s[44:45], -1
	s_mov_b64 s[42:43], 0
	s_cbranch_vccz .LBB0_297
	s_and_b64 vcc, exec, s[10:11]
	s_cbranch_vccz .LBB0_300
	s_barrier

.LBB0_313:
	s_add_u32 s49, s38, s48
	s_addc_u32 s68, s39, 0
	s_add_u32 s66, s49, 0x100
	s_addc_u32 s67, s68, 0
	s_and_b64 s[64:65], s[46:47], exec
	s_cselect_b32 s65, s43, s67
	s_cselect_b32 s64, s75, s66
	s_add_u32 s48, s36, s48
	s_addc_u32 s66, s37, 0
	s_add_u32 s48, s48, 0x100
	s_addc_u32 s66, s66, 0
	s_and_b64 s[46:47], s[46:47], exec
	s_cselect_b32 s67, s76, s66
	s_cselect_b32 s66, s77, s48
	s_add_u32 s70, s49, 0x10080
	ds_read_b128 v[144:147], v140
	ds_read_b128 v[148:151], v140 offset:1024
	ds_read_b128 v[152:155], v140 offset:2048
	ds_read_b128 v[156:159], v140 offset:3072
	ds_read_b128 v[160:163], v141
	ds_read_b128 v[164:167], v141 offset:1024
	ds_read_b128 v[168:171], v141 offset:2048
	ds_read_b128 v[172:175], v141 offset:3072
	s_addc_u32 s71, s68, 0
	s_add_i32 s87, s33, s2
	s_add_i32 m0, s16, 0xc000
	s_add_i32 s88, s16, 0xe000
	s_add_i32 s84, s87, 0x2000
	s_add_u32 s68, s66, 0x1000
	s_addc_u32 s69, s67, 0
	s_add_i32 s86, s34, s2
	s_add_i32 s85, s86, 0x2000
	s_add_i32 s83, 0, 0x18000
	s_add_i32 s82, 0, 0x1c000
	s_add_u32 s48, s64, 0x10000
	s_addc_u32 s49, s65, 0
	s_add_i32 s81, s83, s2
	s_add_i32 s79, s81, 0x2000
	s_add_u32 s46, s66, 0x1080
	s_addc_u32 s47, s67, 0
	s_add_i32 s80, s82, s2
	s_add_i32 s78, s80, 0x2000
	v_lshl_add_u64 v[210:211], s[70:71], 0, v[130:131]
	ds_read_b128 v[176:179], v142
	ds_read_b128 v[180:183], v142 offset:1024
	ds_read_b128 v[184:187], v142 offset:2048
	ds_read_b128 v[188:191], v142 offset:3072
	ds_read_b128 v[192:195], v142 offset:4096
	ds_read_b128 v[196:199], v142 offset:5120
	ds_read_b128 v[200:203], v142 offset:6144
	ds_read_b128 v[206:209], v142 offset:7168
	global_load_lds_dwordx4 v[210:211], off
	v_lshl_add_u64 v[210:211], s[70:71], 0, v[132:133]
	s_mov_b32 m0, s88
	s_nop 0
	global_load_lds_dwordx4 v[210:211], off
	s_waitcnt vmcnt(8)
	s_waitcnt lgkmcnt(0)
	s_barrier
	s_setprio 1
	s_waitcnt lgkmcnt(0)
	v_mfma_f32_16x16x32_bf16 v[126:129], v[144:147], v[176:179], v[126:129]
	v_mfma_f32_16x16x32_bf16 v[122:125], v[152:155], v[176:179], v[122:125]
	v_mfma_f32_16x16x32_bf16 v[118:121], v[144:147], v[184:187], v[118:121]
	v_mfma_f32_16x16x32_bf16 v[114:117], v[152:155], v[184:187], v[114:117]
	v_mfma_f32_16x16x32_bf16 v[102:105], v[144:147], v[192:195], v[102:105]
	v_mfma_f32_16x16x32_bf16 v[98:101], v[152:155], v[192:195], v[98:101]
	v_mfma_f32_16x16x32_bf16 v[86:89], v[144:147], v[200:203], v[86:89]
	v_mfma_f32_16x16x32_bf16 v[82:85], v[152:155], v[200:203], v[82:85]
	v_mfma_f32_16x16x32_bf16 v[126:129], v[148:151], v[180:183], v[126:129]
	v_mfma_f32_16x16x32_bf16 v[122:125], v[156:159], v[180:183], v[122:125]
	v_mfma_f32_16x16x32_bf16 v[118:121], v[148:151], v[188:191], v[118:121]
	v_mfma_f32_16x16x32_bf16 v[114:117], v[156:159], v[188:191], v[114:117]
	v_mfma_f32_16x16x32_bf16 v[102:105], v[148:151], v[196:199], v[102:105]
	v_mfma_f32_16x16x32_bf16 v[98:101], v[156:159], v[196:199], v[98:101]
	v_mfma_f32_16x16x32_bf16 v[86:89], v[148:151], v[206:209], v[86:89]
	v_mfma_f32_16x16x32_bf16 v[82:85], v[156:159], v[206:209], v[82:85]
	s_setprio 0
	s_setprio 1
	v_mfma_f32_16x16x32_bf16 v[110:113], v[160:163], v[176:179], v[110:113]
	v_mfma_f32_16x16x32_bf16 v[106:109], v[168:171], v[176:179], v[106:109]
	v_mfma_f32_16x16x32_bf16 v[94:97], v[160:163], v[184:187], v[94:97]
	v_mfma_f32_16x16x32_bf16 v[90:93], v[168:171], v[184:187], v[90:93]
	v_mfma_f32_16x16x32_bf16 v[78:81], v[160:163], v[192:195], v[78:81]
	v_mfma_f32_16x16x32_bf16 v[74:77], v[168:171], v[192:195], v[74:77]
	v_mfma_f32_16x16x32_bf16 v[70:73], v[160:163], v[200:203], v[70:73]
	v_mfma_f32_16x16x32_bf16 v[66:69], v[168:171], v[200:203], v[66:69]
	v_mfma_f32_16x16x32_bf16 v[110:113], v[164:167], v[180:183], v[110:113]
	v_mfma_f32_16x16x32_bf16 v[106:109], v[172:175], v[180:183], v[106:109]
	v_mfma_f32_16x16x32_bf16 v[94:97], v[164:167], v[188:191], v[94:97]
	v_mfma_f32_16x16x32_bf16 v[90:93], v[172:175], v[188:191], v[90:93]
	v_mfma_f32_16x16x32_bf16 v[78:81], v[164:167], v[196:199], v[78:81]
	v_mfma_f32_16x16x32_bf16 v[74:77], v[172:175], v[196:199], v[74:77]
	v_mfma_f32_16x16x32_bf16 v[70:73], v[164:167], v[206:209], v[70:73]
	v_mfma_f32_16x16x32_bf16 v[66:69], v[172:175], v[206:209], v[66:69]
	s_setprio 0
	s_barrier
	s_mov_b32 m0, s87
	v_lshl_add_u64 v[210:211], s[66:67], 0, v[136:137]
	ds_read_b128 v[176:179], v142 offset:16384
	ds_read_b128 v[180:183], v142 offset:17408
	ds_read_b128 v[184:187], v142 offset:18432
	ds_read_b128 v[188:191], v142 offset:19456
	ds_read_b128 v[192:195], v142 offset:20480
	ds_read_b128 v[196:199], v142 offset:21504
	ds_read_b128 v[200:203], v142 offset:22528
	ds_read_b128 v[206:209], v142 offset:23552
	global_load_lds_dwordx4 v[210:211], off
	v_lshl_add_u64 v[212:213], s[66:67], 0, v[134:135]
	s_mov_b32 m0, s84
	v_lshl_add_u64 v[214:215], s[68:69], 0, v[136:137]
	global_load_lds_dwordx4 v[212:213], off
	s_mov_b32 m0, s86
	v_lshl_add_u64 v[216:217], s[64:65], 0, v[132:133]
	global_load_lds_dwordx4 v[214:215], off
	v_lshl_add_u64 v[214:215], s[68:69], 0, v[134:135]
	s_mov_b32 m0, s85
	s_nop 0
	global_load_lds_dwordx4 v[214:215], off
	v_lshl_add_u64 v[214:215], s[64:65], 0, v[130:131]
	s_mov_b32 m0, s16
	s_nop 0
	global_load_lds_dwordx4 v[214:215], off
	s_waitcnt vmcnt(7)
	s_waitcnt lgkmcnt(0)
	s_barrier
	s_setprio 1
	s_waitcnt lgkmcnt(0)
	v_mfma_f32_16x16x32_bf16 v[62:65], v[144:147], v[176:179], v[62:65]
	v_mfma_f32_16x16x32_bf16 v[58:61], v[152:155], v[176:179], v[58:61]
	v_mfma_f32_16x16x32_bf16 v[54:57], v[144:147], v[184:187], v[54:57]
	v_mfma_f32_16x16x32_bf16 v[50:53], v[152:155], v[184:187], v[50:53]
	v_mfma_f32_16x16x32_bf16 v[38:41], v[144:147], v[192:195], v[38:41]
	v_mfma_f32_16x16x32_bf16 v[34:37], v[152:155], v[192:195], v[34:37]
	v_mfma_f32_16x16x32_bf16 v[22:25], v[144:147], v[200:203], v[22:25]
	v_mfma_f32_16x16x32_bf16 v[18:21], v[152:155], v[200:203], v[18:21]
	s_mov_b32 m0, s17
	s_nop 0
	global_load_lds_dwordx4 v[216:217], off
	v_mfma_f32_16x16x32_bf16 v[62:65], v[148:151], v[180:183], v[62:65]
	v_mfma_f32_16x16x32_bf16 v[58:61], v[156:159], v[180:183], v[58:61]
	v_mfma_f32_16x16x32_bf16 v[54:57], v[148:151], v[188:191], v[54:57]
	v_mfma_f32_16x16x32_bf16 v[50:53], v[156:159], v[188:191], v[50:53]
	v_mfma_f32_16x16x32_bf16 v[38:41], v[148:151], v[196:199], v[38:41]
	v_mfma_f32_16x16x32_bf16 v[34:37], v[156:159], v[196:199], v[34:37]
	v_mfma_f32_16x16x32_bf16 v[22:25], v[148:151], v[206:209], v[22:25]
	v_mfma_f32_16x16x32_bf16 v[18:21], v[156:159], v[206:209], v[18:21]
	s_setprio 0
	s_setprio 1
	v_mfma_f32_16x16x32_bf16 v[46:49], v[160:163], v[176:179], v[46:49]
	v_mfma_f32_16x16x32_bf16 v[42:45], v[168:171], v[176:179], v[42:45]
	v_mfma_f32_16x16x32_bf16 v[30:33], v[160:163], v[184:187], v[30:33]
	v_mfma_f32_16x16x32_bf16 v[26:29], v[168:171], v[184:187], v[26:29]
	v_mfma_f32_16x16x32_bf16 v[14:17], v[160:163], v[192:195], v[14:17]
	v_mfma_f32_16x16x32_bf16 v[10:13], v[168:171], v[192:195], v[10:13]
	v_mfma_f32_16x16x32_bf16 v[6:9], v[160:163], v[200:203], v[6:9]
	v_mfma_f32_16x16x32_bf16 v[2:5], v[168:171], v[200:203], v[2:5]
	v_mfma_f32_16x16x32_bf16 v[46:49], v[164:167], v[180:183], v[46:49]
	v_mfma_f32_16x16x32_bf16 v[42:45], v[172:175], v[180:183], v[42:45]
	v_mfma_f32_16x16x32_bf16 v[30:33], v[164:167], v[188:191], v[30:33]
	v_mfma_f32_16x16x32_bf16 v[26:29], v[172:175], v[188:191], v[26:29]
	v_mfma_f32_16x16x32_bf16 v[14:17], v[164:167], v[196:199], v[14:17]
	v_mfma_f32_16x16x32_bf16 v[10:13], v[172:175], v[196:199], v[10:13]
	v_mfma_f32_16x16x32_bf16 v[6:9], v[164:167], v[206:209], v[6:9]
	v_mfma_f32_16x16x32_bf16 v[2:5], v[172:175], v[206:209], v[2:5]
	s_setprio 0
	s_barrier
	v_add_u32_e32 v143, s83, v139
	ds_read_b128 v[144:147], v143
	ds_read_b128 v[148:151], v143 offset:1024
	ds_read_b128 v[152:155], v143 offset:2048
	ds_read_b128 v[156:159], v143 offset:3072
	v_add_u32_e32 v143, s82, v139
	ds_read_b128 v[160:163], v143
	ds_read_b128 v[164:167], v143 offset:1024
	ds_read_b128 v[168:171], v143 offset:2048
	ds_read_b128 v[172:175], v143 offset:3072
	s_mov_b32 m0, s18
	v_lshl_add_u64 v[218:219], s[48:49], 0, v[130:131]
	ds_read_b128 v[176:179], v142 offset:32768
	ds_read_b128 v[180:183], v142 offset:33792
	ds_read_b128 v[184:187], v142 offset:34816
	ds_read_b128 v[188:191], v142 offset:35840
	ds_read_b128 v[192:195], v142 offset:36864
	ds_read_b128 v[196:199], v142 offset:37888
	ds_read_b128 v[200:203], v142 offset:38912
	ds_read_b128 v[206:209], v142 offset:39936
	global_load_lds_dwordx4 v[218:219], off
	v_lshl_add_u64 v[218:219], s[48:49], 0, v[132:133]
	s_mov_b32 m0, s19
	s_nop 0
	global_load_lds_dwordx4 v[218:219], off
	s_waitcnt vmcnt(8)
	s_waitcnt lgkmcnt(0)
	s_barrier
	s_setprio 1
	s_waitcnt lgkmcnt(0)
	v_mfma_f32_16x16x32_bf16 v[126:129], v[144:147], v[176:179], v[126:129]
	v_mfma_f32_16x16x32_bf16 v[122:125], v[152:155], v[176:179], v[122:125]
	v_mfma_f32_16x16x32_bf16 v[118:121], v[144:147], v[184:187], v[118:121]
	v_mfma_f32_16x16x32_bf16 v[114:117], v[152:155], v[184:187], v[114:117]
	v_mfma_f32_16x16x32_bf16 v[102:105], v[144:147], v[192:195], v[102:105]
	v_mfma_f32_16x16x32_bf16 v[98:101], v[152:155], v[192:195], v[98:101]
	v_mfma_f32_16x16x32_bf16 v[86:89], v[144:147], v[200:203], v[86:89]
	v_mfma_f32_16x16x32_bf16 v[82:85], v[152:155], v[200:203], v[82:85]
	v_mfma_f32_16x16x32_bf16 v[126:129], v[148:151], v[180:183], v[126:129]
	v_mfma_f32_16x16x32_bf16 v[122:125], v[156:159], v[180:183], v[122:125]
	v_mfma_f32_16x16x32_bf16 v[118:121], v[148:151], v[188:191], v[118:121]
	v_mfma_f32_16x16x32_bf16 v[114:117], v[156:159], v[188:191], v[114:117]
	v_mfma_f32_16x16x32_bf16 v[102:105], v[148:151], v[196:199], v[102:105]
	v_mfma_f32_16x16x32_bf16 v[98:101], v[156:159], v[196:199], v[98:101]
	v_mfma_f32_16x16x32_bf16 v[86:89], v[148:151], v[206:209], v[86:89]
	v_mfma_f32_16x16x32_bf16 v[82:85], v[156:159], v[206:209], v[82:85]
	s_setprio 0
	s_setprio 1
	v_mfma_f32_16x16x32_bf16 v[110:113], v[160:163], v[176:179], v[110:113]
	v_mfma_f32_16x16x32_bf16 v[106:109], v[168:171], v[176:179], v[106:109]
	v_mfma_f32_16x16x32_bf16 v[94:97], v[160:163], v[184:187], v[94:97]
	v_mfma_f32_16x16x32_bf16 v[90:93], v[168:171], v[184:187], v[90:93]
	v_mfma_f32_16x16x32_bf16 v[78:81], v[160:163], v[192:195], v[78:81]
	v_mfma_f32_16x16x32_bf16 v[74:77], v[168:171], v[192:195], v[74:77]
	v_mfma_f32_16x16x32_bf16 v[70:73], v[160:163], v[200:203], v[70:73]
	v_mfma_f32_16x16x32_bf16 v[66:69], v[168:171], v[200:203], v[66:69]
	v_mfma_f32_16x16x32_bf16 v[110:113], v[164:167], v[180:183], v[110:113]
	v_mfma_f32_16x16x32_bf16 v[106:109], v[172:175], v[180:183], v[106:109]
	v_mfma_f32_16x16x32_bf16 v[94:97], v[164:167], v[188:191], v[94:97]
	v_mfma_f32_16x16x32_bf16 v[90:93], v[172:175], v[188:191], v[90:93]
	v_mfma_f32_16x16x32_bf16 v[78:81], v[164:167], v[196:199], v[78:81]
	v_mfma_f32_16x16x32_bf16 v[74:77], v[172:175], v[196:199], v[74:77]
	v_mfma_f32_16x16x32_bf16 v[70:73], v[164:167], v[206:209], v[70:73]
	v_mfma_f32_16x16x32_bf16 v[66:69], v[172:175], v[206:209], v[66:69]
	s_setprio 0
	s_barrier
	s_mov_b32 m0, s81
	v_lshl_add_u64 v[210:211], v[210:211], 0, s[8:9]
	ds_read_b128 v[176:179], v142 offset:49152
	ds_read_b128 v[180:183], v142 offset:50176
	ds_read_b128 v[184:187], v142 offset:51200
	ds_read_b128 v[188:191], v142 offset:52224
	ds_read_b128 v[192:195], v142 offset:53248
	ds_read_b128 v[196:199], v142 offset:54272
	ds_read_b128 v[200:203], v142 offset:55296
	ds_read_b128 v[206:209], v142 offset:56320
	global_load_lds_dwordx4 v[210:211], off
	v_lshl_add_u64 v[210:211], v[212:213], 0, s[8:9]
	s_mov_b32 m0, s79
	s_nop 0
	global_load_lds_dwordx4 v[210:211], off
	v_lshl_add_u64 v[210:211], s[46:47], 0, v[136:137]
	s_mov_b32 m0, s80
	s_nop 0
	global_load_lds_dwordx4 v[210:211], off
	v_lshl_add_u64 v[210:211], s[46:47], 0, v[134:135]
	s_mov_b32 m0, s78
	s_nop 0
	global_load_lds_dwordx4 v[210:211], off
	v_lshl_add_u64 v[210:211], v[214:215], 0, s[8:9]
	s_mov_b32 m0, s30
	s_nop 0
	global_load_lds_dwordx4 v[210:211], off
	v_lshl_add_u64 v[210:211], v[216:217], 0, s[8:9]
	s_waitcnt vmcnt(7)
	s_waitcnt lgkmcnt(0)
	s_barrier
	s_setprio 1
	s_waitcnt lgkmcnt(0)
	v_mfma_f32_16x16x32_bf16 v[62:65], v[144:147], v[176:179], v[62:65]
	v_mfma_f32_16x16x32_bf16 v[58:61], v[152:155], v[176:179], v[58:61]
	v_mfma_f32_16x16x32_bf16 v[54:57], v[144:147], v[184:187], v[54:57]
	v_mfma_f32_16x16x32_bf16 v[50:53], v[152:155], v[184:187], v[50:53]
	v_mfma_f32_16x16x32_bf16 v[38:41], v[144:147], v[192:195], v[38:41]
	v_mfma_f32_16x16x32_bf16 v[34:37], v[152:155], v[192:195], v[34:37]
	v_mfma_f32_16x16x32_bf16 v[22:25], v[144:147], v[200:203], v[22:25]
	v_mfma_f32_16x16x32_bf16 v[18:21], v[152:155], v[200:203], v[18:21]
	s_mov_b32 m0, s31
	s_nop 0
	global_load_lds_dwordx4 v[210:211], off
	v_mfma_f32_16x16x32_bf16 v[62:65], v[148:151], v[180:183], v[62:65]
	v_mfma_f32_16x16x32_bf16 v[58:61], v[156:159], v[180:183], v[58:61]
	v_mfma_f32_16x16x32_bf16 v[54:57], v[148:151], v[188:191], v[54:57]
	v_mfma_f32_16x16x32_bf16 v[50:53], v[156:159], v[188:191], v[50:53]
	v_mfma_f32_16x16x32_bf16 v[38:41], v[148:151], v[196:199], v[38:41]
	v_mfma_f32_16x16x32_bf16 v[34:37], v[156:159], v[196:199], v[34:37]
	v_mfma_f32_16x16x32_bf16 v[22:25], v[148:151], v[206:209], v[22:25]
	v_mfma_f32_16x16x32_bf16 v[18:21], v[156:159], v[206:209], v[18:21]
	s_setprio 0
	s_setprio 1
	v_mfma_f32_16x16x32_bf16 v[46:49], v[160:163], v[176:179], v[46:49]
	v_mfma_f32_16x16x32_bf16 v[42:45], v[168:171], v[176:179], v[42:45]
	v_mfma_f32_16x16x32_bf16 v[30:33], v[160:163], v[184:187], v[30:33]
	v_mfma_f32_16x16x32_bf16 v[26:29], v[168:171], v[184:187], v[26:29]
	v_mfma_f32_16x16x32_bf16 v[14:17], v[160:163], v[192:195], v[14:17]
	v_mfma_f32_16x16x32_bf16 v[10:13], v[168:171], v[192:195], v[10:13]
	v_mfma_f32_16x16x32_bf16 v[6:9], v[160:163], v[200:203], v[6:9]
	v_mfma_f32_16x16x32_bf16 v[2:5], v[168:171], v[200:203], v[2:5]
	v_mfma_f32_16x16x32_bf16 v[46:49], v[164:167], v[180:183], v[46:49]
	v_mfma_f32_16x16x32_bf16 v[42:45], v[172:175], v[180:183], v[42:45]
	v_mfma_f32_16x16x32_bf16 v[30:33], v[164:167], v[188:191], v[30:33]
	v_mfma_f32_16x16x32_bf16 v[26:29], v[172:175], v[188:191], v[26:29]
	v_mfma_f32_16x16x32_bf16 v[14:17], v[164:167], v[196:199], v[14:17]
	v_mfma_f32_16x16x32_bf16 v[10:13], v[172:175], v[196:199], v[10:13]
	v_mfma_f32_16x16x32_bf16 v[6:9], v[164:167], v[206:209], v[6:9]
	v_mfma_f32_16x16x32_bf16 v[2:5], v[172:175], v[206:209], v[2:5]
	s_setprio 0
	s_barrier
	s_movk_i32 s48, 0x100
	s_andn2_b64 vcc, exec, s[44:45]
	s_mov_b64 s[46:47], -1
	s_mov_b64 s[44:45], 0
	s_cbranch_vccz .LBB0_313
	s_and_b64 vcc, exec, s[10:11]
	s_cbranch_vccz .LBB0_316
	s_barrier

.LBB0_383:
	s_add_u32 s26, s0, s22
	s_addc_u32 s27, s1, s23
	s_and_b64 s[44:45], s[36:37], exec
	s_cselect_b32 s15, s27, s43
	s_cselect_b32 s39, s26, s42
	s_add_u32 s66, s42, 0x100
	s_addc_u32 s67, s43, 0
	s_mov_b32 s68, -2
	s_mov_b64 s[42:43], 0
	ds_read_b128 v[152:155], v146
	ds_read_b128 v[156:159], v146 offset:1024
	ds_read_b128 v[160:163], v146 offset:2048
	ds_read_b128 v[164:167], v146 offset:3072
	ds_read_b128 v[168:171], v147
	ds_read_b128 v[172:175], v147 offset:1024
	ds_read_b128 v[176:179], v147 offset:2048
	ds_read_b128 v[180:183], v147 offset:3072
	s_add_u32 s44, s42, 0x100
	s_addc_u32 s45, s43, 0
	s_add_u32 s46, s66, s42
	s_addc_u32 s47, s67, s43
	s_cmp_eq_u32 s68, 4
	s_cselect_b32 s48, 0, s44
	s_cselect_b32 s49, 0, s45
	s_cselect_b32 s46, s39, s46
	s_cselect_b32 s47, s15, s47
	s_add_u32 s48, s6, s48
	s_addc_u32 s49, s7, s49
	s_mov_b32 m0, s29
	v_lshl_add_u64 v[218:219], v[138:139], 0, s[42:43]
	ds_read_b128 v[184:187], v148
	ds_read_b128 v[188:191], v148 offset:1024
	ds_read_b128 v[192:195], v148 offset:2048
	ds_read_b128 v[196:199], v148 offset:3072
	ds_read_b128 v[200:203], v148 offset:4096
	ds_read_b128 v[206:209], v148 offset:5120
	ds_read_b128 v[210:213], v148 offset:6144
	ds_read_b128 v[214:217], v148 offset:7168
	global_load_lds_dwordx4 v[218:219], off
	v_lshl_add_u64 v[218:219], v[140:141], 0, s[42:43]
	s_mov_b32 m0, s30
	s_nop 0
	global_load_lds_dwordx4 v[218:219], off
	s_waitcnt vmcnt(8)
	s_waitcnt lgkmcnt(0)
	s_barrier
	s_setprio 1
	s_waitcnt lgkmcnt(0)
	v_mfma_f32_16x16x32_bf16 v[126:129], v[152:155], v[184:187], 0
	v_mfma_f32_16x16x32_bf16 v[122:125], v[160:163], v[184:187], 0
	v_mfma_f32_16x16x32_bf16 v[118:121], v[152:155], v[192:195], 0
	v_mfma_f32_16x16x32_bf16 v[114:117], v[160:163], v[192:195], 0
	v_mfma_f32_16x16x32_bf16 v[102:105], v[152:155], v[200:203], 0
	v_mfma_f32_16x16x32_bf16 v[98:101], v[160:163], v[200:203], 0
	v_mfma_f32_16x16x32_bf16 v[86:89], v[152:155], v[210:213], 0
	v_mfma_f32_16x16x32_bf16 v[82:85], v[160:163], v[210:213], 0
	v_mfma_f32_16x16x32_bf16 v[126:129], v[156:159], v[188:191], v[126:129]
	v_mfma_f32_16x16x32_bf16 v[122:125], v[164:167], v[188:191], v[122:125]
	v_mfma_f32_16x16x32_bf16 v[118:121], v[156:159], v[196:199], v[118:121]
	v_mfma_f32_16x16x32_bf16 v[114:117], v[164:167], v[196:199], v[114:117]
	v_mfma_f32_16x16x32_bf16 v[102:105], v[156:159], v[206:209], v[102:105]
	v_mfma_f32_16x16x32_bf16 v[98:101], v[164:167], v[206:209], v[98:101]
	v_mfma_f32_16x16x32_bf16 v[86:89], v[156:159], v[214:217], v[86:89]
	v_mfma_f32_16x16x32_bf16 v[82:85], v[164:167], v[214:217], v[82:85]
	s_setprio 0
	s_setprio 1
	v_mfma_f32_16x16x32_bf16 v[110:113], v[168:171], v[184:187], 0
	v_mfma_f32_16x16x32_bf16 v[106:109], v[176:179], v[184:187], 0
	v_mfma_f32_16x16x32_bf16 v[94:97], v[168:171], v[192:195], 0
	v_mfma_f32_16x16x32_bf16 v[90:93], v[176:179], v[192:195], 0
	v_mfma_f32_16x16x32_bf16 v[78:81], v[168:171], v[200:203], 0
	v_mfma_f32_16x16x32_bf16 v[74:77], v[176:179], v[200:203], 0
	v_mfma_f32_16x16x32_bf16 v[70:73], v[168:171], v[210:213], 0
	v_mfma_f32_16x16x32_bf16 v[66:69], v[176:179], v[210:213], 0
	v_mfma_f32_16x16x32_bf16 v[110:113], v[172:175], v[188:191], v[110:113]
	v_mfma_f32_16x16x32_bf16 v[106:109], v[180:183], v[188:191], v[106:109]
	v_mfma_f32_16x16x32_bf16 v[94:97], v[172:175], v[196:199], v[94:97]
	v_mfma_f32_16x16x32_bf16 v[90:93], v[180:183], v[196:199], v[90:93]
	v_mfma_f32_16x16x32_bf16 v[78:81], v[172:175], v[206:209], v[78:81]
	v_mfma_f32_16x16x32_bf16 v[74:77], v[180:183], v[206:209], v[74:77]
	v_mfma_f32_16x16x32_bf16 v[70:73], v[172:175], v[214:217], v[70:73]
	v_mfma_f32_16x16x32_bf16 v[66:69], v[180:183], v[214:217], v[66:69]
	s_setprio 0
	s_barrier
	s_mov_b32 m0, s31
	v_lshl_add_u64 v[218:219], s[46:47], 0, v[134:135]
	s_add_u32 s42, s46, 0x20000
	ds_read_b128 v[184:187], v148 offset:16384
	ds_read_b128 v[188:191], v148 offset:17408
	ds_read_b128 v[192:195], v148 offset:18432
	ds_read_b128 v[196:199], v148 offset:19456
	ds_read_b128 v[200:203], v148 offset:20480
	ds_read_b128 v[206:209], v148 offset:21504
	ds_read_b128 v[210:213], v148 offset:22528
	ds_read_b128 v[214:217], v148 offset:23552
	global_load_lds_dwordx4 v[218:219], off
	v_lshl_add_u64 v[220:221], s[46:47], 0, v[130:131]
	s_mov_b32 m0, s33
	s_addc_u32 s43, s47, 0
	global_load_lds_dwordx4 v[220:221], off
	v_lshl_add_u64 v[222:223], s[42:43], 0, v[134:135]
	s_mov_b32 m0, s34
	v_lshl_add_u64 v[224:225], s[48:49], 0, v[132:133]
	global_load_lds_dwordx4 v[222:223], off
	v_lshl_add_u64 v[222:223], s[42:43], 0, v[130:131]
	s_mov_b32 m0, s35
	s_nop 0
	global_load_lds_dwordx4 v[222:223], off
	v_lshl_add_u64 v[222:223], s[48:49], 0, v[136:137]
	s_mov_b32 m0, s2
	s_nop 0
	global_load_lds_dwordx4 v[222:223], off
	s_waitcnt vmcnt(7)
	s_waitcnt lgkmcnt(0)
	s_barrier
	s_setprio 1
	s_waitcnt lgkmcnt(0)
	v_mfma_f32_16x16x32_bf16 v[62:65], v[152:155], v[184:187], 0
	v_mfma_f32_16x16x32_bf16 v[58:61], v[160:163], v[184:187], 0
	v_mfma_f32_16x16x32_bf16 v[54:57], v[152:155], v[192:195], 0
	v_mfma_f32_16x16x32_bf16 v[50:53], v[160:163], v[192:195], 0
	v_mfma_f32_16x16x32_bf16 v[38:41], v[152:155], v[200:203], 0
	v_mfma_f32_16x16x32_bf16 v[34:37], v[160:163], v[200:203], 0
	v_mfma_f32_16x16x32_bf16 v[22:25], v[152:155], v[210:213], 0
	v_mfma_f32_16x16x32_bf16 v[18:21], v[160:163], v[210:213], 0
	s_mov_b32 m0, s3
	s_nop 0
	global_load_lds_dwordx4 v[224:225], off
	v_mfma_f32_16x16x32_bf16 v[62:65], v[156:159], v[188:191], v[62:65]
	v_mfma_f32_16x16x32_bf16 v[58:61], v[164:167], v[188:191], v[58:61]
	v_mfma_f32_16x16x32_bf16 v[54:57], v[156:159], v[196:199], v[54:57]
	v_mfma_f32_16x16x32_bf16 v[50:53], v[164:167], v[196:199], v[50:53]
	v_mfma_f32_16x16x32_bf16 v[38:41], v[156:159], v[206:209], v[38:41]
	v_mfma_f32_16x16x32_bf16 v[34:37], v[164:167], v[206:209], v[34:37]
	v_mfma_f32_16x16x32_bf16 v[22:25], v[156:159], v[214:217], v[22:25]
	v_mfma_f32_16x16x32_bf16 v[18:21], v[164:167], v[214:217], v[18:21]
	s_setprio 0
	s_setprio 1
	v_mfma_f32_16x16x32_bf16 v[46:49], v[168:171], v[184:187], 0
	v_mfma_f32_16x16x32_bf16 v[42:45], v[176:179], v[184:187], 0
	v_mfma_f32_16x16x32_bf16 v[30:33], v[168:171], v[192:195], 0
	v_mfma_f32_16x16x32_bf16 v[26:29], v[176:179], v[192:195], 0
	v_mfma_f32_16x16x32_bf16 v[14:17], v[168:171], v[200:203], 0
	v_mfma_f32_16x16x32_bf16 v[10:13], v[176:179], v[200:203], 0
	v_mfma_f32_16x16x32_bf16 v[6:9], v[168:171], v[210:213], 0
	v_mfma_f32_16x16x32_bf16 v[2:5], v[176:179], v[210:213], 0
	v_mfma_f32_16x16x32_bf16 v[46:49], v[172:175], v[188:191], v[46:49]
	v_mfma_f32_16x16x32_bf16 v[42:45], v[180:183], v[188:191], v[42:45]
	v_mfma_f32_16x16x32_bf16 v[30:33], v[172:175], v[196:199], v[30:33]
	v_mfma_f32_16x16x32_bf16 v[26:29], v[180:183], v[196:199], v[26:29]
	v_mfma_f32_16x16x32_bf16 v[14:17], v[172:175], v[206:209], v[14:17]
	v_mfma_f32_16x16x32_bf16 v[10:13], v[180:183], v[206:209], v[10:13]
	v_mfma_f32_16x16x32_bf16 v[6:9], v[172:175], v[214:217], v[6:9]
	v_mfma_f32_16x16x32_bf16 v[2:5], v[180:183], v[214:217], v[2:5]
	s_setprio 0
	s_barrier
	ds_read_b128 v[152:155], v149
	ds_read_b128 v[156:159], v149 offset:1024
	ds_read_b128 v[160:163], v149 offset:2048
	ds_read_b128 v[164:167], v149 offset:3072
	ds_read_b128 v[168:171], v150
	ds_read_b128 v[172:175], v150 offset:1024
	ds_read_b128 v[176:179], v150 offset:2048
	ds_read_b128 v[180:183], v150 offset:3072
	s_add_u32 s42, s48, 0x20000
	s_addc_u32 s43, s49, 0
	s_mov_b32 m0, s16
	v_lshl_add_u64 v[226:227], s[42:43], 0, v[136:137]
	ds_read_b128 v[184:187], v148 offset:32768
	ds_read_b128 v[188:191], v148 offset:33792
	ds_read_b128 v[192:195], v148 offset:34816
	ds_read_b128 v[196:199], v148 offset:35840
	ds_read_b128 v[200:203], v148 offset:36864
	ds_read_b128 v[206:209], v148 offset:37888
	ds_read_b128 v[210:213], v148 offset:38912
	ds_read_b128 v[214:217], v148 offset:39936
	global_load_lds_dwordx4 v[226:227], off
	v_lshl_add_u64 v[226:227], s[42:43], 0, v[132:133]
	s_mov_b32 m0, s17
	s_nop 0
	global_load_lds_dwordx4 v[226:227], off
	s_waitcnt vmcnt(8)
	s_waitcnt lgkmcnt(0)
	s_barrier
	s_setprio 1
	s_waitcnt lgkmcnt(0)
	v_mfma_f32_16x16x32_bf16 v[126:129], v[152:155], v[184:187], v[126:129]
	v_mfma_f32_16x16x32_bf16 v[122:125], v[160:163], v[184:187], v[122:125]
	v_mfma_f32_16x16x32_bf16 v[118:121], v[152:155], v[192:195], v[118:121]
	v_mfma_f32_16x16x32_bf16 v[114:117], v[160:163], v[192:195], v[114:117]
	v_mfma_f32_16x16x32_bf16 v[102:105], v[152:155], v[200:203], v[102:105]
	v_mfma_f32_16x16x32_bf16 v[98:101], v[160:163], v[200:203], v[98:101]
	v_mfma_f32_16x16x32_bf16 v[86:89], v[152:155], v[210:213], v[86:89]
	v_mfma_f32_16x16x32_bf16 v[82:85], v[160:163], v[210:213], v[82:85]
	v_mfma_f32_16x16x32_bf16 v[126:129], v[156:159], v[188:191], v[126:129]
	v_mfma_f32_16x16x32_bf16 v[122:125], v[164:167], v[188:191], v[122:125]
	v_mfma_f32_16x16x32_bf16 v[118:121], v[156:159], v[196:199], v[118:121]
	v_mfma_f32_16x16x32_bf16 v[114:117], v[164:167], v[196:199], v[114:117]
	v_mfma_f32_16x16x32_bf16 v[102:105], v[156:159], v[206:209], v[102:105]
	v_mfma_f32_16x16x32_bf16 v[98:101], v[164:167], v[206:209], v[98:101]
	v_mfma_f32_16x16x32_bf16 v[86:89], v[156:159], v[214:217], v[86:89]
	v_mfma_f32_16x16x32_bf16 v[82:85], v[164:167], v[214:217], v[82:85]
	s_setprio 0
	s_setprio 1
	v_mfma_f32_16x16x32_bf16 v[110:113], v[168:171], v[184:187], v[110:113]
	v_mfma_f32_16x16x32_bf16 v[106:109], v[176:179], v[184:187], v[106:109]
	v_mfma_f32_16x16x32_bf16 v[94:97], v[168:171], v[192:195], v[94:97]
	v_mfma_f32_16x16x32_bf16 v[90:93], v[176:179], v[192:195], v[90:93]
	v_mfma_f32_16x16x32_bf16 v[78:81], v[168:171], v[200:203], v[78:81]
	v_mfma_f32_16x16x32_bf16 v[74:77], v[176:179], v[200:203], v[74:77]
	v_mfma_f32_16x16x32_bf16 v[70:73], v[168:171], v[210:213], v[70:73]
	v_mfma_f32_16x16x32_bf16 v[66:69], v[176:179], v[210:213], v[66:69]
	v_mfma_f32_16x16x32_bf16 v[110:113], v[172:175], v[188:191], v[110:113]
	v_mfma_f32_16x16x32_bf16 v[106:109], v[180:183], v[188:191], v[106:109]
	v_mfma_f32_16x16x32_bf16 v[94:97], v[172:175], v[196:199], v[94:97]
	v_mfma_f32_16x16x32_bf16 v[90:93], v[180:183], v[196:199], v[90:93]
	v_mfma_f32_16x16x32_bf16 v[78:81], v[172:175], v[206:209], v[78:81]
	v_mfma_f32_16x16x32_bf16 v[74:77], v[180:183], v[206:209], v[74:77]
	v_mfma_f32_16x16x32_bf16 v[70:73], v[172:175], v[214:217], v[70:73]
	v_mfma_f32_16x16x32_bf16 v[66:69], v[180:183], v[214:217], v[66:69]
	s_setprio 0
	s_barrier
	s_mov_b32 m0, s62
	v_lshl_add_u64 v[218:219], v[218:219], 0, s[10:11]
	s_add_u32 s42, s46, 0x20080
	ds_read_b128 v[184:187], v148 offset:49152
	ds_read_b128 v[188:191], v148 offset:50176
	ds_read_b128 v[192:195], v148 offset:51200
	ds_read_b128 v[196:199], v148 offset:52224
	ds_read_b128 v[200:203], v148 offset:53248
	ds_read_b128 v[206:209], v148 offset:54272
	ds_read_b128 v[210:213], v148 offset:55296
	ds_read_b128 v[214:217], v148 offset:56320
	global_load_lds_dwordx4 v[218:219], off
	v_lshl_add_u64 v[218:219], v[220:221], 0, s[10:11]
	s_mov_b32 m0, s63
	s_addc_u32 s43, s47, 0
	global_load_lds_dwordx4 v[218:219], off
	v_lshl_add_u64 v[218:219], s[42:43], 0, v[134:135]
	s_mov_b32 m0, s64
	s_nop 0
	global_load_lds_dwordx4 v[218:219], off
	v_lshl_add_u64 v[218:219], s[42:43], 0, v[130:131]
	s_mov_b32 m0, s65
	s_nop 0
	global_load_lds_dwordx4 v[218:219], off
	v_lshl_add_u64 v[218:219], v[222:223], 0, s[10:11]
	s_mov_b32 m0, s25
	s_nop 0
	global_load_lds_dwordx4 v[218:219], off
	v_lshl_add_u64 v[218:219], v[224:225], 0, s[10:11]
	s_waitcnt vmcnt(7)
	s_waitcnt lgkmcnt(0)
	s_barrier
	s_setprio 1
	s_waitcnt lgkmcnt(0)
	v_mfma_f32_16x16x32_bf16 v[62:65], v[152:155], v[184:187], v[62:65]
	v_mfma_f32_16x16x32_bf16 v[58:61], v[160:163], v[184:187], v[58:61]
	v_mfma_f32_16x16x32_bf16 v[54:57], v[152:155], v[192:195], v[54:57]
	v_mfma_f32_16x16x32_bf16 v[50:53], v[160:163], v[192:195], v[50:53]
	v_mfma_f32_16x16x32_bf16 v[38:41], v[152:155], v[200:203], v[38:41]
	v_mfma_f32_16x16x32_bf16 v[34:37], v[160:163], v[200:203], v[34:37]
	v_mfma_f32_16x16x32_bf16 v[22:25], v[152:155], v[210:213], v[22:25]
	v_mfma_f32_16x16x32_bf16 v[18:21], v[160:163], v[210:213], v[18:21]
	s_mov_b32 m0, s28
	s_nop 0
	global_load_lds_dwordx4 v[218:219], off
	v_mfma_f32_16x16x32_bf16 v[62:65], v[156:159], v[188:191], v[62:65]
	v_mfma_f32_16x16x32_bf16 v[58:61], v[164:167], v[188:191], v[58:61]
	v_mfma_f32_16x16x32_bf16 v[54:57], v[156:159], v[196:199], v[54:57]
	v_mfma_f32_16x16x32_bf16 v[50:53], v[164:167], v[196:199], v[50:53]
	v_mfma_f32_16x16x32_bf16 v[38:41], v[156:159], v[206:209], v[38:41]
	v_mfma_f32_16x16x32_bf16 v[34:37], v[164:167], v[206:209], v[34:37]
	v_mfma_f32_16x16x32_bf16 v[22:25], v[156:159], v[214:217], v[22:25]
	v_mfma_f32_16x16x32_bf16 v[18:21], v[164:167], v[214:217], v[18:21]
	s_setprio 0
	s_setprio 1
	v_mfma_f32_16x16x32_bf16 v[46:49], v[168:171], v[184:187], v[46:49]
	v_mfma_f32_16x16x32_bf16 v[42:45], v[176:179], v[184:187], v[42:45]
	v_mfma_f32_16x16x32_bf16 v[30:33], v[168:171], v[192:195], v[30:33]
	v_mfma_f32_16x16x32_bf16 v[26:29], v[176:179], v[192:195], v[26:29]
	v_mfma_f32_16x16x32_bf16 v[14:17], v[168:171], v[200:203], v[14:17]
	v_mfma_f32_16x16x32_bf16 v[10:13], v[176:179], v[200:203], v[10:13]
	v_mfma_f32_16x16x32_bf16 v[6:9], v[168:171], v[210:213], v[6:9]
	v_mfma_f32_16x16x32_bf16 v[2:5], v[176:179], v[210:213], v[2:5]
	v_mfma_f32_16x16x32_bf16 v[46:49], v[172:175], v[188:191], v[46:49]
	v_mfma_f32_16x16x32_bf16 v[42:45], v[180:183], v[188:191], v[42:45]
	v_mfma_f32_16x16x32_bf16 v[30:33], v[172:175], v[196:199], v[30:33]
	v_mfma_f32_16x16x32_bf16 v[26:29], v[180:183], v[196:199], v[26:29]
	v_mfma_f32_16x16x32_bf16 v[14:17], v[172:175], v[206:209], v[14:17]
	v_mfma_f32_16x16x32_bf16 v[10:13], v[180:183], v[206:209], v[10:13]
	v_mfma_f32_16x16x32_bf16 v[6:9], v[172:175], v[214:217], v[6:9]
	v_mfma_f32_16x16x32_bf16 v[2:5], v[180:183], v[214:217], v[2:5]
	s_setprio 0
	s_barrier
	s_add_i32 s68, s68, 2
	s_cmp_gt_u32 s68, 5
	s_mov_b64 s[42:43], s[44:45]
.LBB0_384:
	ds_read_b128 v[152:155], v146
	ds_read_b128 v[156:159], v146 offset:1024
	ds_read_b128 v[160:163], v146 offset:2048
	ds_read_b128 v[164:167], v146 offset:3072
	ds_read_b128 v[168:171], v147
	ds_read_b128 v[172:175], v147 offset:1024
	ds_read_b128 v[176:179], v147 offset:2048
	ds_read_b128 v[180:183], v147 offset:3072
	s_add_u32 s44, s42, 0x100
	s_addc_u32 s45, s43, 0
	s_add_u32 s46, s66, s42
	s_addc_u32 s47, s67, s43
	s_cmp_eq_u32 s68, 4
	s_cselect_b32 s48, 0, s44
	s_cselect_b32 s49, 0, s45
	s_cselect_b32 s46, s39, s46
	s_cselect_b32 s47, s15, s47
	s_add_u32 s48, s6, s48
	s_addc_u32 s49, s7, s49
	s_mov_b32 m0, s29
	v_lshl_add_u64 v[218:219], v[138:139], 0, s[42:43]
	ds_read_b128 v[184:187], v148
	ds_read_b128 v[188:191], v148 offset:1024
	ds_read_b128 v[192:195], v148 offset:2048
	ds_read_b128 v[196:199], v148 offset:3072
	ds_read_b128 v[200:203], v148 offset:4096
	ds_read_b128 v[206:209], v148 offset:5120
	ds_read_b128 v[210:213], v148 offset:6144
	ds_read_b128 v[214:217], v148 offset:7168
	global_load_lds_dwordx4 v[218:219], off
	v_lshl_add_u64 v[218:219], v[140:141], 0, s[42:43]
	s_mov_b32 m0, s30
	s_nop 0
	global_load_lds_dwordx4 v[218:219], off
	s_waitcnt vmcnt(8)
	s_waitcnt lgkmcnt(0)
	s_barrier
	s_setprio 1
	s_waitcnt lgkmcnt(0)
	v_mfma_f32_16x16x32_bf16 v[126:129], v[152:155], v[184:187], v[126:129]
	v_mfma_f32_16x16x32_bf16 v[122:125], v[160:163], v[184:187], v[122:125]
	v_mfma_f32_16x16x32_bf16 v[118:121], v[152:155], v[192:195], v[118:121]
	v_mfma_f32_16x16x32_bf16 v[114:117], v[160:163], v[192:195], v[114:117]
	v_mfma_f32_16x16x32_bf16 v[102:105], v[152:155], v[200:203], v[102:105]
	v_mfma_f32_16x16x32_bf16 v[98:101], v[160:163], v[200:203], v[98:101]
	v_mfma_f32_16x16x32_bf16 v[86:89], v[152:155], v[210:213], v[86:89]
	v_mfma_f32_16x16x32_bf16 v[82:85], v[160:163], v[210:213], v[82:85]
	v_mfma_f32_16x16x32_bf16 v[126:129], v[156:159], v[188:191], v[126:129]
	v_mfma_f32_16x16x32_bf16 v[122:125], v[164:167], v[188:191], v[122:125]
	v_mfma_f32_16x16x32_bf16 v[118:121], v[156:159], v[196:199], v[118:121]
	v_mfma_f32_16x16x32_bf16 v[114:117], v[164:167], v[196:199], v[114:117]
	v_mfma_f32_16x16x32_bf16 v[102:105], v[156:159], v[206:209], v[102:105]
	v_mfma_f32_16x16x32_bf16 v[98:101], v[164:167], v[206:209], v[98:101]
	v_mfma_f32_16x16x32_bf16 v[86:89], v[156:159], v[214:217], v[86:89]
	v_mfma_f32_16x16x32_bf16 v[82:85], v[164:167], v[214:217], v[82:85]
	s_setprio 0
	s_setprio 1
	v_mfma_f32_16x16x32_bf16 v[110:113], v[168:171], v[184:187], v[110:113]
	v_mfma_f32_16x16x32_bf16 v[106:109], v[176:179], v[184:187], v[106:109]
	v_mfma_f32_16x16x32_bf16 v[94:97], v[168:171], v[192:195], v[94:97]
	v_mfma_f32_16x16x32_bf16 v[90:93], v[176:179], v[192:195], v[90:93]
	v_mfma_f32_16x16x32_bf16 v[78:81], v[168:171], v[200:203], v[78:81]
	v_mfma_f32_16x16x32_bf16 v[74:77], v[176:179], v[200:203], v[74:77]
	v_mfma_f32_16x16x32_bf16 v[70:73], v[168:171], v[210:213], v[70:73]
	v_mfma_f32_16x16x32_bf16 v[66:69], v[176:179], v[210:213], v[66:69]
	v_mfma_f32_16x16x32_bf16 v[110:113], v[172:175], v[188:191], v[110:113]
	v_mfma_f32_16x16x32_bf16 v[106:109], v[180:183], v[188:191], v[106:109]
	v_mfma_f32_16x16x32_bf16 v[94:97], v[172:175], v[196:199], v[94:97]
	v_mfma_f32_16x16x32_bf16 v[90:93], v[180:183], v[196:199], v[90:93]
	v_mfma_f32_16x16x32_bf16 v[78:81], v[172:175], v[206:209], v[78:81]
	v_mfma_f32_16x16x32_bf16 v[74:77], v[180:183], v[206:209], v[74:77]
	v_mfma_f32_16x16x32_bf16 v[70:73], v[172:175], v[214:217], v[70:73]
	v_mfma_f32_16x16x32_bf16 v[66:69], v[180:183], v[214:217], v[66:69]
	s_setprio 0
	s_barrier
	s_mov_b32 m0, s31
	v_lshl_add_u64 v[218:219], s[46:47], 0, v[134:135]
	s_add_u32 s42, s46, 0x20000
	ds_read_b128 v[184:187], v148 offset:16384
	ds_read_b128 v[188:191], v148 offset:17408
	ds_read_b128 v[192:195], v148 offset:18432
	ds_read_b128 v[196:199], v148 offset:19456
	ds_read_b128 v[200:203], v148 offset:20480
	ds_read_b128 v[206:209], v148 offset:21504
	ds_read_b128 v[210:213], v148 offset:22528
	ds_read_b128 v[214:217], v148 offset:23552
	global_load_lds_dwordx4 v[218:219], off
	v_lshl_add_u64 v[220:221], s[46:47], 0, v[130:131]
	s_mov_b32 m0, s33
	s_addc_u32 s43, s47, 0
	global_load_lds_dwordx4 v[220:221], off
	v_lshl_add_u64 v[222:223], s[42:43], 0, v[134:135]
	s_mov_b32 m0, s34
	v_lshl_add_u64 v[224:225], s[48:49], 0, v[132:133]
	global_load_lds_dwordx4 v[222:223], off
	v_lshl_add_u64 v[222:223], s[42:43], 0, v[130:131]
	s_mov_b32 m0, s35
	s_nop 0
	global_load_lds_dwordx4 v[222:223], off
	v_lshl_add_u64 v[222:223], s[48:49], 0, v[136:137]
	s_mov_b32 m0, s2
	s_nop 0
	global_load_lds_dwordx4 v[222:223], off
	s_waitcnt vmcnt(7)
	s_waitcnt lgkmcnt(0)
	s_barrier
	s_setprio 1
	s_waitcnt lgkmcnt(0)
	v_mfma_f32_16x16x32_bf16 v[62:65], v[152:155], v[184:187], v[62:65]
	v_mfma_f32_16x16x32_bf16 v[58:61], v[160:163], v[184:187], v[58:61]
	v_mfma_f32_16x16x32_bf16 v[54:57], v[152:155], v[192:195], v[54:57]
	v_mfma_f32_16x16x32_bf16 v[50:53], v[160:163], v[192:195], v[50:53]
	v_mfma_f32_16x16x32_bf16 v[38:41], v[152:155], v[200:203], v[38:41]
	v_mfma_f32_16x16x32_bf16 v[34:37], v[160:163], v[200:203], v[34:37]
	v_mfma_f32_16x16x32_bf16 v[22:25], v[152:155], v[210:213], v[22:25]
	v_mfma_f32_16x16x32_bf16 v[18:21], v[160:163], v[210:213], v[18:21]
	s_mov_b32 m0, s3
	s_nop 0
	global_load_lds_dwordx4 v[224:225], off
	v_mfma_f32_16x16x32_bf16 v[62:65], v[156:159], v[188:191], v[62:65]
	v_mfma_f32_16x16x32_bf16 v[58:61], v[164:167], v[188:191], v[58:61]
	v_mfma_f32_16x16x32_bf16 v[54:57], v[156:159], v[196:199], v[54:57]
	v_mfma_f32_16x16x32_bf16 v[50:53], v[164:167], v[196:199], v[50:53]
	v_mfma_f32_16x16x32_bf16 v[38:41], v[156:159], v[206:209], v[38:41]
	v_mfma_f32_16x16x32_bf16 v[34:37], v[164:167], v[206:209], v[34:37]
	v_mfma_f32_16x16x32_bf16 v[22:25], v[156:159], v[214:217], v[22:25]
	v_mfma_f32_16x16x32_bf16 v[18:21], v[164:167], v[214:217], v[18:21]
	s_setprio 0
	s_setprio 1
	v_mfma_f32_16x16x32_bf16 v[46:49], v[168:171], v[184:187], v[46:49]
	v_mfma_f32_16x16x32_bf16 v[42:45], v[176:179], v[184:187], v[42:45]
	v_mfma_f32_16x16x32_bf16 v[30:33], v[168:171], v[192:195], v[30:33]
	v_mfma_f32_16x16x32_bf16 v[26:29], v[176:179], v[192:195], v[26:29]
	v_mfma_f32_16x16x32_bf16 v[14:17], v[168:171], v[200:203], v[14:17]
	v_mfma_f32_16x16x32_bf16 v[10:13], v[176:179], v[200:203], v[10:13]
	v_mfma_f32_16x16x32_bf16 v[6:9], v[168:171], v[210:213], v[6:9]
	v_mfma_f32_16x16x32_bf16 v[2:5], v[176:179], v[210:213], v[2:5]
	v_mfma_f32_16x16x32_bf16 v[46:49], v[172:175], v[188:191], v[46:49]
	v_mfma_f32_16x16x32_bf16 v[42:45], v[180:183], v[188:191], v[42:45]
	v_mfma_f32_16x16x32_bf16 v[30:33], v[172:175], v[196:199], v[30:33]
	v_mfma_f32_16x16x32_bf16 v[26:29], v[180:183], v[196:199], v[26:29]
	v_mfma_f32_16x16x32_bf16 v[14:17], v[172:175], v[206:209], v[14:17]
	v_mfma_f32_16x16x32_bf16 v[10:13], v[180:183], v[206:209], v[10:13]
	v_mfma_f32_16x16x32_bf16 v[6:9], v[172:175], v[214:217], v[6:9]
	v_mfma_f32_16x16x32_bf16 v[2:5], v[180:183], v[214:217], v[2:5]
	s_setprio 0
	s_barrier
	ds_read_b128 v[152:155], v149
	ds_read_b128 v[156:159], v149 offset:1024
	ds_read_b128 v[160:163], v149 offset:2048
	ds_read_b128 v[164:167], v149 offset:3072
	ds_read_b128 v[168:171], v150
	ds_read_b128 v[172:175], v150 offset:1024
	ds_read_b128 v[176:179], v150 offset:2048
	ds_read_b128 v[180:183], v150 offset:3072
	s_add_u32 s42, s48, 0x20000
	s_addc_u32 s43, s49, 0
	s_mov_b32 m0, s16
	v_lshl_add_u64 v[226:227], s[42:43], 0, v[136:137]
	ds_read_b128 v[184:187], v148 offset:32768
	ds_read_b128 v[188:191], v148 offset:33792
	ds_read_b128 v[192:195], v148 offset:34816
	ds_read_b128 v[196:199], v148 offset:35840
	ds_read_b128 v[200:203], v148 offset:36864
	ds_read_b128 v[206:209], v148 offset:37888
	ds_read_b128 v[210:213], v148 offset:38912
	ds_read_b128 v[214:217], v148 offset:39936
	global_load_lds_dwordx4 v[226:227], off
	v_lshl_add_u64 v[226:227], s[42:43], 0, v[132:133]
	s_mov_b32 m0, s17
	s_nop 0
	global_load_lds_dwordx4 v[226:227], off
	s_waitcnt vmcnt(8)
	s_waitcnt lgkmcnt(0)
	s_barrier
	s_setprio 1
	s_waitcnt lgkmcnt(0)
	v_mfma_f32_16x16x32_bf16 v[126:129], v[152:155], v[184:187], v[126:129]
	v_mfma_f32_16x16x32_bf16 v[122:125], v[160:163], v[184:187], v[122:125]
	v_mfma_f32_16x16x32_bf16 v[118:121], v[152:155], v[192:195], v[118:121]
	v_mfma_f32_16x16x32_bf16 v[114:117], v[160:163], v[192:195], v[114:117]
	v_mfma_f32_16x16x32_bf16 v[102:105], v[152:155], v[200:203], v[102:105]
	v_mfma_f32_16x16x32_bf16 v[98:101], v[160:163], v[200:203], v[98:101]
	v_mfma_f32_16x16x32_bf16 v[86:89], v[152:155], v[210:213], v[86:89]
	v_mfma_f32_16x16x32_bf16 v[82:85], v[160:163], v[210:213], v[82:85]
	v_mfma_f32_16x16x32_bf16 v[126:129], v[156:159], v[188:191], v[126:129]
	v_mfma_f32_16x16x32_bf16 v[122:125], v[164:167], v[188:191], v[122:125]
	v_mfma_f32_16x16x32_bf16 v[118:121], v[156:159], v[196:199], v[118:121]
	v_mfma_f32_16x16x32_bf16 v[114:117], v[164:167], v[196:199], v[114:117]
	v_mfma_f32_16x16x32_bf16 v[102:105], v[156:159], v[206:209], v[102:105]
	v_mfma_f32_16x16x32_bf16 v[98:101], v[164:167], v[206:209], v[98:101]
	v_mfma_f32_16x16x32_bf16 v[86:89], v[156:159], v[214:217], v[86:89]
	v_mfma_f32_16x16x32_bf16 v[82:85], v[164:167], v[214:217], v[82:85]
	s_setprio 0
	s_setprio 1
	v_mfma_f32_16x16x32_bf16 v[110:113], v[168:171], v[184:187], v[110:113]
	v_mfma_f32_16x16x32_bf16 v[106:109], v[176:179], v[184:187], v[106:109]
	v_mfma_f32_16x16x32_bf16 v[94:97], v[168:171], v[192:195], v[94:97]
	v_mfma_f32_16x16x32_bf16 v[90:93], v[176:179], v[192:195], v[90:93]
	v_mfma_f32_16x16x32_bf16 v[78:81], v[168:171], v[200:203], v[78:81]
	v_mfma_f32_16x16x32_bf16 v[74:77], v[176:179], v[200:203], v[74:77]
	v_mfma_f32_16x16x32_bf16 v[70:73], v[168:171], v[210:213], v[70:73]
	v_mfma_f32_16x16x32_bf16 v[66:69], v[176:179], v[210:213], v[66:69]
	v_mfma_f32_16x16x32_bf16 v[110:113], v[172:175], v[188:191], v[110:113]
	v_mfma_f32_16x16x32_bf16 v[106:109], v[180:183], v[188:191], v[106:109]
	v_mfma_f32_16x16x32_bf16 v[94:97], v[172:175], v[196:199], v[94:97]
	v_mfma_f32_16x16x32_bf16 v[90:93], v[180:183], v[196:199], v[90:93]
	v_mfma_f32_16x16x32_bf16 v[78:81], v[172:175], v[206:209], v[78:81]
	v_mfma_f32_16x16x32_bf16 v[74:77], v[180:183], v[206:209], v[74:77]
	v_mfma_f32_16x16x32_bf16 v[70:73], v[172:175], v[214:217], v[70:73]
	v_mfma_f32_16x16x32_bf16 v[66:69], v[180:183], v[214:217], v[66:69]
	s_setprio 0
	s_barrier
	s_mov_b32 m0, s62
	v_lshl_add_u64 v[218:219], v[218:219], 0, s[10:11]
	s_add_u32 s42, s46, 0x20080
	ds_read_b128 v[184:187], v148 offset:49152
	ds_read_b128 v[188:191], v148 offset:50176
	ds_read_b128 v[192:195], v148 offset:51200
	ds_read_b128 v[196:199], v148 offset:52224
	ds_read_b128 v[200:203], v148 offset:53248
	ds_read_b128 v[206:209], v148 offset:54272
	ds_read_b128 v[210:213], v148 offset:55296
	ds_read_b128 v[214:217], v148 offset:56320
	global_load_lds_dwordx4 v[218:219], off
	v_lshl_add_u64 v[218:219], v[220:221], 0, s[10:11]
	s_mov_b32 m0, s63
	s_addc_u32 s43, s47, 0
	global_load_lds_dwordx4 v[218:219], off
	v_lshl_add_u64 v[218:219], s[42:43], 0, v[134:135]
	s_mov_b32 m0, s64
	s_nop 0
	global_load_lds_dwordx4 v[218:219], off
	v_lshl_add_u64 v[218:219], s[42:43], 0, v[130:131]
	s_mov_b32 m0, s65
	s_nop 0
	global_load_lds_dwordx4 v[218:219], off
	v_lshl_add_u64 v[218:219], v[222:223], 0, s[10:11]
	s_mov_b32 m0, s25
	s_nop 0
	global_load_lds_dwordx4 v[218:219], off
	v_lshl_add_u64 v[218:219], v[224:225], 0, s[10:11]
	s_waitcnt vmcnt(7)
	s_waitcnt lgkmcnt(0)
	s_barrier
	s_setprio 1
	s_waitcnt lgkmcnt(0)
	v_mfma_f32_16x16x32_bf16 v[62:65], v[152:155], v[184:187], v[62:65]
	v_mfma_f32_16x16x32_bf16 v[58:61], v[160:163], v[184:187], v[58:61]
	v_mfma_f32_16x16x32_bf16 v[54:57], v[152:155], v[192:195], v[54:57]
	v_mfma_f32_16x16x32_bf16 v[50:53], v[160:163], v[192:195], v[50:53]
	v_mfma_f32_16x16x32_bf16 v[38:41], v[152:155], v[200:203], v[38:41]
	v_mfma_f32_16x16x32_bf16 v[34:37], v[160:163], v[200:203], v[34:37]
	v_mfma_f32_16x16x32_bf16 v[22:25], v[152:155], v[210:213], v[22:25]
	v_mfma_f32_16x16x32_bf16 v[18:21], v[160:163], v[210:213], v[18:21]
	s_mov_b32 m0, s28
	s_nop 0
	global_load_lds_dwordx4 v[218:219], off
	v_mfma_f32_16x16x32_bf16 v[62:65], v[156:159], v[188:191], v[62:65]
	v_mfma_f32_16x16x32_bf16 v[58:61], v[164:167], v[188:191], v[58:61]
	v_mfma_f32_16x16x32_bf16 v[54:57], v[156:159], v[196:199], v[54:57]
	v_mfma_f32_16x16x32_bf16 v[50:53], v[164:167], v[196:199], v[50:53]
	v_mfma_f32_16x16x32_bf16 v[38:41], v[156:159], v[206:209], v[38:41]
	v_mfma_f32_16x16x32_bf16 v[34:37], v[164:167], v[206:209], v[34:37]
	v_mfma_f32_16x16x32_bf16 v[22:25], v[156:159], v[214:217], v[22:25]
	v_mfma_f32_16x16x32_bf16 v[18:21], v[164:167], v[214:217], v[18:21]
	s_setprio 0
	s_setprio 1
	v_mfma_f32_16x16x32_bf16 v[46:49], v[168:171], v[184:187], v[46:49]
	v_mfma_f32_16x16x32_bf16 v[42:45], v[176:179], v[184:187], v[42:45]
	v_mfma_f32_16x16x32_bf16 v[30:33], v[168:171], v[192:195], v[30:33]
	v_mfma_f32_16x16x32_bf16 v[26:29], v[176:179], v[192:195], v[26:29]
	v_mfma_f32_16x16x32_bf16 v[14:17], v[168:171], v[200:203], v[14:17]
	v_mfma_f32_16x16x32_bf16 v[10:13], v[176:179], v[200:203], v[10:13]
	v_mfma_f32_16x16x32_bf16 v[6:9], v[168:171], v[210:213], v[6:9]
	v_mfma_f32_16x16x32_bf16 v[2:5], v[176:179], v[210:213], v[2:5]
	v_mfma_f32_16x16x32_bf16 v[46:49], v[172:175], v[188:191], v[46:49]
	v_mfma_f32_16x16x32_bf16 v[42:45], v[180:183], v[188:191], v[42:45]
	v_mfma_f32_16x16x32_bf16 v[30:33], v[172:175], v[196:199], v[30:33]
	v_mfma_f32_16x16x32_bf16 v[26:29], v[180:183], v[196:199], v[26:29]
	v_mfma_f32_16x16x32_bf16 v[14:17], v[172:175], v[206:209], v[14:17]
	v_mfma_f32_16x16x32_bf16 v[10:13], v[180:183], v[206:209], v[10:13]
	v_mfma_f32_16x16x32_bf16 v[6:9], v[172:175], v[214:217], v[6:9]
	v_mfma_f32_16x16x32_bf16 v[2:5], v[180:183], v[214:217], v[2:5]
	s_setprio 0
	s_barrier
	s_add_i32 s68, s68, 2
	s_cmp_gt_u32 s68, 5
	s_mov_b64 s[42:43], s[44:45]
	s_cbranch_scc0 .LBB0_384
	s_and_b64 vcc, exec, s[12:13]
	s_cbranch_vccz .LBB0_387
	s_barrier

.LBB0_406:
	s_lshl_b32 s74, s12, 7
	s_add_i32 s12, s12, 2
	v_cndmask_b32_e64 v138, 0, 1, s[66:67]
	s_lshl_b64 s[66:67], s[12:13], 7
	s_and_b64 s[68:69], s[64:65], exec
	s_cselect_b32 s66, 0, s66
	s_cselect_b32 s67, 0, s67
	s_add_u32 s70, s8, s66
	s_addc_u32 s71, s9, s67
	s_lshl_b64 s[66:67], s[12:13], 12
	s_add_u32 s12, s48, s66
	s_addc_u32 s66, s49, s67
	s_and_b64 s[64:65], s[64:65], exec
	s_cselect_b32 s73, s14, s66
	s_cselect_b32 s72, s15, s12
	s_add_u32 s76, s10, s74
	s_addc_u32 s77, s11, 0
	s_add_i32 s91, s62, s16
	s_add_i32 m0, s17, 0xc000
	s_add_i32 s92, s17, 0xe000
	s_add_i32 s88, s91, 0x2000
	s_add_u32 s74, s72, 0x10000
	ds_read_b128 v[146:149], v141
	ds_read_b128 v[150:153], v141 offset:1024
	ds_read_b128 v[154:157], v141 offset:2048
	ds_read_b128 v[158:161], v141 offset:3072
	ds_read_b128 v[162:165], v143
	ds_read_b128 v[166:169], v143 offset:1024
	ds_read_b128 v[170:173], v143 offset:2048
	ds_read_b128 v[174:177], v143 offset:3072
	s_addc_u32 s75, s73, 0
	s_add_i32 s90, s63, s16
	s_add_i32 s89, s90, 0x2000
	s_add_i32 s87, 0, 0x18000
	s_add_i32 s86, 0, 0x1c000
	s_add_u32 s68, s70, 0x10000
	s_addc_u32 s69, s71, 0
	s_add_u32 s64, s72, 0x1000
	s_addc_u32 s65, s73, 0
	s_add_i32 s85, s87, s16
	s_add_i32 s83, s85, 0x2000
	s_add_u32 s66, s72, 0x11000
	s_addc_u32 s67, s73, 0
	s_add_i32 s84, s86, s16
	s_add_i32 s12, s84, 0x2000
	v_cmp_ne_u32_e32 vcc, 1, v138
	v_lshl_add_u64 v[202:203], s[76:77], 0, v[136:137]
	v_lshl_add_u64 v[202:203], v[202:203], 0, s[36:37]
	ds_read_b128 v[178:181], v144
	ds_read_b128 v[182:185], v144 offset:1024
	ds_read_b128 v[186:189], v144 offset:2048
	ds_read_b128 v[190:193], v144 offset:3072
	ds_read_b128 v[194:197], v144 offset:4096
	ds_read_b128 v[198:201], v144 offset:5120
	ds_read_b128 v[206:209], v144 offset:6144
	ds_read_b128 v[210:213], v144 offset:7168
	global_load_lds_dwordx4 v[202:203], off
	v_lshl_add_u64 v[202:203], s[76:77], 0, v[132:133]
	v_lshl_add_u64 v[202:203], v[202:203], 0, s[36:37]
	s_mov_b32 m0, s92
	s_nop 0
	global_load_lds_dwordx4 v[202:203], off
	s_waitcnt vmcnt(8)
	s_waitcnt lgkmcnt(0)
	s_barrier
	s_setprio 1
	s_waitcnt lgkmcnt(0)
	v_mfma_f32_16x16x32_bf16 v[126:129], v[146:149], v[178:181], v[126:129]
	v_mfma_f32_16x16x32_bf16 v[122:125], v[154:157], v[178:181], v[122:125]
	v_mfma_f32_16x16x32_bf16 v[118:121], v[146:149], v[186:189], v[118:121]
	v_mfma_f32_16x16x32_bf16 v[110:113], v[154:157], v[186:189], v[110:113]
	v_mfma_f32_16x16x32_bf16 v[102:105], v[146:149], v[194:197], v[102:105]
	v_mfma_f32_16x16x32_bf16 v[98:101], v[154:157], v[194:197], v[98:101]
	v_mfma_f32_16x16x32_bf16 v[86:89], v[146:149], v[206:209], v[86:89]
	v_mfma_f32_16x16x32_bf16 v[82:85], v[154:157], v[206:209], v[82:85]
	v_mfma_f32_16x16x32_bf16 v[126:129], v[150:153], v[182:185], v[126:129]
	v_mfma_f32_16x16x32_bf16 v[122:125], v[158:161], v[182:185], v[122:125]
	v_mfma_f32_16x16x32_bf16 v[118:121], v[150:153], v[190:193], v[118:121]
	v_mfma_f32_16x16x32_bf16 v[110:113], v[158:161], v[190:193], v[110:113]
	v_mfma_f32_16x16x32_bf16 v[102:105], v[150:153], v[198:201], v[102:105]
	v_mfma_f32_16x16x32_bf16 v[98:101], v[158:161], v[198:201], v[98:101]
	v_mfma_f32_16x16x32_bf16 v[86:89], v[150:153], v[210:213], v[86:89]
	v_mfma_f32_16x16x32_bf16 v[82:85], v[158:161], v[210:213], v[82:85]
	s_setprio 0
	s_setprio 1
	v_mfma_f32_16x16x32_bf16 v[114:117], v[162:165], v[178:181], v[114:117]
	v_mfma_f32_16x16x32_bf16 v[106:109], v[170:173], v[178:181], v[106:109]
	v_mfma_f32_16x16x32_bf16 v[94:97], v[162:165], v[186:189], v[94:97]
	v_mfma_f32_16x16x32_bf16 v[90:93], v[170:173], v[186:189], v[90:93]
	v_mfma_f32_16x16x32_bf16 v[78:81], v[162:165], v[194:197], v[78:81]
	v_mfma_f32_16x16x32_bf16 v[74:77], v[170:173], v[194:197], v[74:77]
	v_mfma_f32_16x16x32_bf16 v[70:73], v[162:165], v[206:209], v[70:73]
	v_mfma_f32_16x16x32_bf16 v[66:69], v[170:173], v[206:209], v[66:69]
	v_mfma_f32_16x16x32_bf16 v[114:117], v[166:169], v[182:185], v[114:117]
	v_mfma_f32_16x16x32_bf16 v[106:109], v[174:177], v[182:185], v[106:109]
	v_mfma_f32_16x16x32_bf16 v[94:97], v[166:169], v[190:193], v[94:97]
	v_mfma_f32_16x16x32_bf16 v[90:93], v[174:177], v[190:193], v[90:93]
	v_mfma_f32_16x16x32_bf16 v[78:81], v[166:169], v[198:201], v[78:81]
	v_mfma_f32_16x16x32_bf16 v[74:77], v[174:177], v[198:201], v[74:77]
	v_mfma_f32_16x16x32_bf16 v[70:73], v[166:169], v[210:213], v[70:73]
	v_mfma_f32_16x16x32_bf16 v[66:69], v[174:177], v[210:213], v[66:69]
	s_setprio 0
	s_barrier
	s_mov_b32 m0, s91
	v_lshl_add_u64 v[202:203], s[72:73], 0, v[134:135]
	ds_read_b128 v[178:181], v144 offset:16384
	ds_read_b128 v[182:185], v144 offset:17408
	ds_read_b128 v[186:189], v144 offset:18432
	ds_read_b128 v[190:193], v144 offset:19456
	ds_read_b128 v[194:197], v144 offset:20480
	ds_read_b128 v[198:201], v144 offset:21504
	ds_read_b128 v[206:209], v144 offset:22528
	ds_read_b128 v[210:213], v144 offset:23552
	global_load_lds_dwordx4 v[202:203], off
	v_lshl_add_u64 v[202:203], s[72:73], 0, v[130:131]
	s_mov_b32 m0, s88
	v_lshl_add_u64 v[214:215], s[70:71], 0, v[132:133]
	global_load_lds_dwordx4 v[202:203], off
	v_lshl_add_u64 v[202:203], s[74:75], 0, v[134:135]
	s_mov_b32 m0, s90
	s_nop 0
	global_load_lds_dwordx4 v[202:203], off
	v_lshl_add_u64 v[202:203], s[74:75], 0, v[130:131]
	s_mov_b32 m0, s89
	s_nop 0
	global_load_lds_dwordx4 v[202:203], off
	v_lshl_add_u64 v[202:203], s[70:71], 0, v[136:137]
	s_mov_b32 m0, s17
	s_nop 0
	global_load_lds_dwordx4 v[202:203], off
	s_waitcnt vmcnt(7)
	s_waitcnt lgkmcnt(0)
	s_barrier
	s_setprio 1
	s_waitcnt lgkmcnt(0)
	v_mfma_f32_16x16x32_bf16 v[62:65], v[146:149], v[178:181], v[62:65]
	v_mfma_f32_16x16x32_bf16 v[58:61], v[154:157], v[178:181], v[58:61]
	v_mfma_f32_16x16x32_bf16 v[54:57], v[146:149], v[186:189], v[54:57]
	v_mfma_f32_16x16x32_bf16 v[50:53], v[154:157], v[186:189], v[50:53]
	v_mfma_f32_16x16x32_bf16 v[38:41], v[146:149], v[194:197], v[38:41]
	v_mfma_f32_16x16x32_bf16 v[34:37], v[154:157], v[194:197], v[34:37]
	v_mfma_f32_16x16x32_bf16 v[22:25], v[146:149], v[206:209], v[22:25]
	v_mfma_f32_16x16x32_bf16 v[18:21], v[154:157], v[206:209], v[18:21]
	s_mov_b32 m0, s18
	s_nop 0
	global_load_lds_dwordx4 v[214:215], off
	v_mfma_f32_16x16x32_bf16 v[62:65], v[150:153], v[182:185], v[62:65]
	v_mfma_f32_16x16x32_bf16 v[58:61], v[158:161], v[182:185], v[58:61]
	v_mfma_f32_16x16x32_bf16 v[54:57], v[150:153], v[190:193], v[54:57]
	v_mfma_f32_16x16x32_bf16 v[50:53], v[158:161], v[190:193], v[50:53]
	v_mfma_f32_16x16x32_bf16 v[38:41], v[150:153], v[198:201], v[38:41]
	v_mfma_f32_16x16x32_bf16 v[34:37], v[158:161], v[198:201], v[34:37]
	v_mfma_f32_16x16x32_bf16 v[22:25], v[150:153], v[210:213], v[22:25]
	v_mfma_f32_16x16x32_bf16 v[18:21], v[158:161], v[210:213], v[18:21]
	s_setprio 0
	s_setprio 1
	v_mfma_f32_16x16x32_bf16 v[46:49], v[162:165], v[178:181], v[46:49]
	v_mfma_f32_16x16x32_bf16 v[42:45], v[170:173], v[178:181], v[42:45]
	v_mfma_f32_16x16x32_bf16 v[30:33], v[162:165], v[186:189], v[30:33]
	v_mfma_f32_16x16x32_bf16 v[26:29], v[170:173], v[186:189], v[26:29]
	v_mfma_f32_16x16x32_bf16 v[14:17], v[162:165], v[194:197], v[14:17]
	v_mfma_f32_16x16x32_bf16 v[10:13], v[170:173], v[194:197], v[10:13]
	v_mfma_f32_16x16x32_bf16 v[6:9], v[162:165], v[206:209], v[6:9]
	v_mfma_f32_16x16x32_bf16 v[2:5], v[170:173], v[206:209], v[2:5]
	v_mfma_f32_16x16x32_bf16 v[46:49], v[166:169], v[182:185], v[46:49]
	v_mfma_f32_16x16x32_bf16 v[42:45], v[174:177], v[182:185], v[42:45]
	v_mfma_f32_16x16x32_bf16 v[30:33], v[166:169], v[190:193], v[30:33]
	v_mfma_f32_16x16x32_bf16 v[26:29], v[174:177], v[190:193], v[26:29]
	v_mfma_f32_16x16x32_bf16 v[14:17], v[166:169], v[198:201], v[14:17]
	v_mfma_f32_16x16x32_bf16 v[10:13], v[174:177], v[198:201], v[10:13]
	v_mfma_f32_16x16x32_bf16 v[6:9], v[166:169], v[210:213], v[6:9]
	v_mfma_f32_16x16x32_bf16 v[2:5], v[174:177], v[210:213], v[2:5]
	s_setprio 0
	s_barrier
	v_add_u32_e32 v138, s87, v140
	ds_read_b128 v[146:149], v138
	ds_read_b128 v[150:153], v138 offset:1024
	ds_read_b128 v[154:157], v138 offset:2048
	ds_read_b128 v[158:161], v138 offset:3072
	v_add_u32_e32 v138, s86, v140
	ds_read_b128 v[162:165], v138
	ds_read_b128 v[166:169], v138 offset:1024
	ds_read_b128 v[170:173], v138 offset:2048
	ds_read_b128 v[174:177], v138 offset:3072
	s_mov_b32 m0, s19
	v_lshl_add_u64 v[216:217], s[68:69], 0, v[136:137]
	ds_read_b128 v[178:181], v144 offset:32768
	ds_read_b128 v[182:185], v144 offset:33792
	ds_read_b128 v[186:189], v144 offset:34816
	ds_read_b128 v[190:193], v144 offset:35840
	ds_read_b128 v[194:197], v144 offset:36864
	ds_read_b128 v[198:201], v144 offset:37888
	ds_read_b128 v[206:209], v144 offset:38912
	ds_read_b128 v[210:213], v144 offset:39936
	global_load_lds_dwordx4 v[216:217], off
	v_lshl_add_u64 v[216:217], s[68:69], 0, v[132:133]
	s_mov_b32 m0, s24
	s_nop 0
	global_load_lds_dwordx4 v[216:217], off
	s_waitcnt vmcnt(8)
	s_waitcnt lgkmcnt(0)
	s_barrier
	s_setprio 1
	s_waitcnt lgkmcnt(0)
	v_mfma_f32_16x16x32_bf16 v[126:129], v[146:149], v[178:181], v[126:129]
	v_mfma_f32_16x16x32_bf16 v[122:125], v[154:157], v[178:181], v[122:125]
	v_mfma_f32_16x16x32_bf16 v[118:121], v[146:149], v[186:189], v[118:121]
	v_mfma_f32_16x16x32_bf16 v[110:113], v[154:157], v[186:189], v[110:113]
	v_mfma_f32_16x16x32_bf16 v[102:105], v[146:149], v[194:197], v[102:105]
	v_mfma_f32_16x16x32_bf16 v[98:101], v[154:157], v[194:197], v[98:101]
	v_mfma_f32_16x16x32_bf16 v[86:89], v[146:149], v[206:209], v[86:89]
	v_mfma_f32_16x16x32_bf16 v[82:85], v[154:157], v[206:209], v[82:85]
	v_mfma_f32_16x16x32_bf16 v[126:129], v[150:153], v[182:185], v[126:129]
	v_mfma_f32_16x16x32_bf16 v[122:125], v[158:161], v[182:185], v[122:125]
	v_mfma_f32_16x16x32_bf16 v[118:121], v[150:153], v[190:193], v[118:121]
	v_mfma_f32_16x16x32_bf16 v[110:113], v[158:161], v[190:193], v[110:113]
	v_mfma_f32_16x16x32_bf16 v[102:105], v[150:153], v[198:201], v[102:105]
	v_mfma_f32_16x16x32_bf16 v[98:101], v[158:161], v[198:201], v[98:101]
	v_mfma_f32_16x16x32_bf16 v[86:89], v[150:153], v[210:213], v[86:89]
	v_mfma_f32_16x16x32_bf16 v[82:85], v[158:161], v[210:213], v[82:85]
	s_setprio 0
	s_setprio 1
	v_mfma_f32_16x16x32_bf16 v[114:117], v[162:165], v[178:181], v[114:117]
	v_mfma_f32_16x16x32_bf16 v[106:109], v[170:173], v[178:181], v[106:109]
	v_mfma_f32_16x16x32_bf16 v[94:97], v[162:165], v[186:189], v[94:97]
	v_mfma_f32_16x16x32_bf16 v[90:93], v[170:173], v[186:189], v[90:93]
	v_mfma_f32_16x16x32_bf16 v[78:81], v[162:165], v[194:197], v[78:81]
	v_mfma_f32_16x16x32_bf16 v[74:77], v[170:173], v[194:197], v[74:77]
	v_mfma_f32_16x16x32_bf16 v[70:73], v[162:165], v[206:209], v[70:73]
	v_mfma_f32_16x16x32_bf16 v[66:69], v[170:173], v[206:209], v[66:69]
	v_mfma_f32_16x16x32_bf16 v[114:117], v[166:169], v[182:185], v[114:117]
	v_mfma_f32_16x16x32_bf16 v[106:109], v[174:177], v[182:185], v[106:109]
	v_mfma_f32_16x16x32_bf16 v[94:97], v[166:169], v[190:193], v[94:97]
	v_mfma_f32_16x16x32_bf16 v[90:93], v[174:177], v[190:193], v[90:93]
	v_mfma_f32_16x16x32_bf16 v[78:81], v[166:169], v[198:201], v[78:81]
	v_mfma_f32_16x16x32_bf16 v[74:77], v[174:177], v[198:201], v[74:77]
	v_mfma_f32_16x16x32_bf16 v[70:73], v[166:169], v[210:213], v[70:73]
	v_mfma_f32_16x16x32_bf16 v[66:69], v[174:177], v[210:213], v[66:69]
	s_setprio 0
	s_barrier
	s_mov_b32 m0, s85
	v_lshl_add_u64 v[216:217], s[64:65], 0, v[134:135]
	ds_read_b128 v[178:181], v144 offset:49152
	ds_read_b128 v[182:185], v144 offset:50176
	ds_read_b128 v[186:189], v144 offset:51200
	ds_read_b128 v[190:193], v144 offset:52224
	ds_read_b128 v[194:197], v144 offset:53248
	ds_read_b128 v[198:201], v144 offset:54272
	ds_read_b128 v[206:209], v144 offset:55296
	ds_read_b128 v[210:213], v144 offset:56320
	global_load_lds_dwordx4 v[216:217], off
	v_lshl_add_u64 v[216:217], s[64:65], 0, v[130:131]
	s_mov_b32 m0, s83
	v_lshl_add_u64 v[202:203], v[202:203], 0, s[36:37]
	global_load_lds_dwordx4 v[216:217], off
	v_lshl_add_u64 v[216:217], s[66:67], 0, v[134:135]
	s_mov_b32 m0, s84
	s_nop 0
	global_load_lds_dwordx4 v[216:217], off
	v_lshl_add_u64 v[216:217], s[66:67], 0, v[130:131]
	s_mov_b32 m0, s12
	s_nop 0
	global_load_lds_dwordx4 v[216:217], off
	s_mov_b32 m0, s31
	s_nop 0
	global_load_lds_dwordx4 v[202:203], off
	v_lshl_add_u64 v[202:203], v[214:215], 0, s[36:37]
	s_waitcnt vmcnt(7)
	s_waitcnt lgkmcnt(0)
	s_barrier
	s_setprio 1
	s_waitcnt lgkmcnt(0)
	v_mfma_f32_16x16x32_bf16 v[62:65], v[146:149], v[178:181], v[62:65]
	v_mfma_f32_16x16x32_bf16 v[58:61], v[154:157], v[178:181], v[58:61]
	v_mfma_f32_16x16x32_bf16 v[54:57], v[146:149], v[186:189], v[54:57]
	v_mfma_f32_16x16x32_bf16 v[50:53], v[154:157], v[186:189], v[50:53]
	v_mfma_f32_16x16x32_bf16 v[38:41], v[146:149], v[194:197], v[38:41]
	v_mfma_f32_16x16x32_bf16 v[34:37], v[154:157], v[194:197], v[34:37]
	v_mfma_f32_16x16x32_bf16 v[22:25], v[146:149], v[206:209], v[22:25]
	v_mfma_f32_16x16x32_bf16 v[18:21], v[154:157], v[206:209], v[18:21]
	s_mov_b32 m0, s33
	s_nop 0
	global_load_lds_dwordx4 v[202:203], off
	v_mfma_f32_16x16x32_bf16 v[62:65], v[150:153], v[182:185], v[62:65]
	v_mfma_f32_16x16x32_bf16 v[58:61], v[158:161], v[182:185], v[58:61]
	v_mfma_f32_16x16x32_bf16 v[54:57], v[150:153], v[190:193], v[54:57]
	v_mfma_f32_16x16x32_bf16 v[50:53], v[158:161], v[190:193], v[50:53]
	v_mfma_f32_16x16x32_bf16 v[38:41], v[150:153], v[198:201], v[38:41]
	v_mfma_f32_16x16x32_bf16 v[34:37], v[158:161], v[198:201], v[34:37]
	v_mfma_f32_16x16x32_bf16 v[22:25], v[150:153], v[210:213], v[22:25]
	v_mfma_f32_16x16x32_bf16 v[18:21], v[158:161], v[210:213], v[18:21]
	s_setprio 0
	s_setprio 1
	v_mfma_f32_16x16x32_bf16 v[46:49], v[162:165], v[178:181], v[46:49]
	v_mfma_f32_16x16x32_bf16 v[42:45], v[170:173], v[178:181], v[42:45]
	v_mfma_f32_16x16x32_bf16 v[30:33], v[162:165], v[186:189], v[30:33]
	v_mfma_f32_16x16x32_bf16 v[26:29], v[170:173], v[186:189], v[26:29]
	v_mfma_f32_16x16x32_bf16 v[14:17], v[162:165], v[194:197], v[14:17]
	v_mfma_f32_16x16x32_bf16 v[10:13], v[170:173], v[194:197], v[10:13]
	v_mfma_f32_16x16x32_bf16 v[6:9], v[162:165], v[206:209], v[6:9]
	v_mfma_f32_16x16x32_bf16 v[2:5], v[170:173], v[206:209], v[2:5]
	v_mfma_f32_16x16x32_bf16 v[46:49], v[166:169], v[182:185], v[46:49]
	v_mfma_f32_16x16x32_bf16 v[42:45], v[174:177], v[182:185], v[42:45]
	v_mfma_f32_16x16x32_bf16 v[30:33], v[166:169], v[190:193], v[30:33]
	v_mfma_f32_16x16x32_bf16 v[26:29], v[174:177], v[190:193], v[26:29]
	v_mfma_f32_16x16x32_bf16 v[14:17], v[166:169], v[198:201], v[14:17]
	v_mfma_f32_16x16x32_bf16 v[10:13], v[174:177], v[198:201], v[10:13]
	v_mfma_f32_16x16x32_bf16 v[6:9], v[166:169], v[210:213], v[6:9]
	v_mfma_f32_16x16x32_bf16 v[2:5], v[174:177], v[210:213], v[2:5]
	s_setprio 0
	s_barrier
	s_mov_b64 s[66:67], 0
	s_mov_b64 s[64:65], -1
	s_mov_b32 s12, 2
	s_cbranch_vccz .LBB0_406
	s_and_b64 vcc, exec, s[22:23]
	s_cbranch_vccz .LBB0_409
	s_barrier

.LBB0_476:
	s_add_u32 s22, s2, s49
	s_addc_u32 s23, s3, s29
	s_and_b64 s[26:27], s[20:21], exec
	s_cselect_b32 s63, s23, s37
	s_cselect_b32 s64, s22, s36
	s_add_u32 s26, s16, s12
	s_addc_u32 s27, s17, s13
	s_and_b64 s[42:43], s[20:21], exec
	s_cselect_b32 s65, s27, s39
	s_cselect_b32 s66, s26, s38
	s_add_u32 s36, s36, 0x20080
	s_addc_u32 s37, s37, 0
	s_add_u32 s67, s38, 0x100
	s_addc_u32 s68, s39, 0
	s_mov_b32 s69, -2
	ds_read_b128 v[148:151], v144
	ds_read_b128 v[152:155], v144 offset:1024
	ds_read_b128 v[156:159], v144 offset:2048
	ds_read_b128 v[160:163], v144 offset:3072
	ds_read_b128 v[164:167], v145
	ds_read_b128 v[168:171], v145 offset:1024
	ds_read_b128 v[172:175], v145 offset:2048
	ds_read_b128 v[176:179], v145 offset:3072
	s_add_u32 s38, s36, 0xfffe0080
	s_addc_u32 s39, s37, -1
	s_cmp_eq_u32 s69, 4
	s_cselect_b32 s43, s63, s39
	s_cselect_b32 s42, s64, s38
	s_cselect_b32 s39, s65, s68
	s_cselect_b32 s38, s66, s67
	v_lshl_add_u64 v[214:215], s[36:37], 0, v[138:139]
	s_add_i32 m0, s19, 0xc000
	ds_read_b128 v[180:183], v146
	ds_read_b128 v[184:187], v146 offset:1024
	ds_read_b128 v[188:191], v146 offset:2048
	ds_read_b128 v[192:195], v146 offset:3072
	ds_read_b128 v[196:199], v146 offset:4096
	ds_read_b128 v[200:203], v146 offset:5120
	ds_read_b128 v[206:209], v146 offset:6144
	ds_read_b128 v[210:213], v146 offset:7168
	global_load_lds_dwordx4 v[214:215], off
	v_lshl_add_u64 v[214:215], s[36:37], 0, v[140:141]
	s_add_i32 m0, s19, 0xe000
	s_nop 0
	global_load_lds_dwordx4 v[214:215], off
	s_waitcnt vmcnt(8)
	s_waitcnt lgkmcnt(0)
	s_barrier
	s_setprio 1
	s_waitcnt lgkmcnt(0)
	v_mfma_f32_16x16x32_bf16 v[126:129], v[148:151], v[180:183], 0
	v_mfma_f32_16x16x32_bf16 v[122:125], v[156:159], v[180:183], 0
	v_mfma_f32_16x16x32_bf16 v[118:121], v[148:151], v[188:191], 0
	v_mfma_f32_16x16x32_bf16 v[114:117], v[156:159], v[188:191], 0
	v_mfma_f32_16x16x32_bf16 v[102:105], v[148:151], v[196:199], 0
	v_mfma_f32_16x16x32_bf16 v[98:101], v[156:159], v[196:199], 0
	v_mfma_f32_16x16x32_bf16 v[86:89], v[148:151], v[206:209], 0
	v_mfma_f32_16x16x32_bf16 v[82:85], v[156:159], v[206:209], 0
	v_mfma_f32_16x16x32_bf16 v[126:129], v[152:155], v[184:187], v[126:129]
	v_mfma_f32_16x16x32_bf16 v[122:125], v[160:163], v[184:187], v[122:125]
	v_mfma_f32_16x16x32_bf16 v[118:121], v[152:155], v[192:195], v[118:121]
	v_mfma_f32_16x16x32_bf16 v[114:117], v[160:163], v[192:195], v[114:117]
	v_mfma_f32_16x16x32_bf16 v[102:105], v[152:155], v[200:203], v[102:105]
	v_mfma_f32_16x16x32_bf16 v[98:101], v[160:163], v[200:203], v[98:101]
	v_mfma_f32_16x16x32_bf16 v[86:89], v[152:155], v[210:213], v[86:89]
	v_mfma_f32_16x16x32_bf16 v[82:85], v[160:163], v[210:213], v[82:85]
	s_setprio 0
	s_setprio 1
	v_mfma_f32_16x16x32_bf16 v[110:113], v[164:167], v[180:183], 0
	v_mfma_f32_16x16x32_bf16 v[106:109], v[172:175], v[180:183], 0
	v_mfma_f32_16x16x32_bf16 v[94:97], v[164:167], v[188:191], 0
	v_mfma_f32_16x16x32_bf16 v[90:93], v[172:175], v[188:191], 0
	v_mfma_f32_16x16x32_bf16 v[78:81], v[164:167], v[196:199], 0
	v_mfma_f32_16x16x32_bf16 v[74:77], v[172:175], v[196:199], 0
	v_mfma_f32_16x16x32_bf16 v[70:73], v[164:167], v[206:209], 0
	v_mfma_f32_16x16x32_bf16 v[66:69], v[172:175], v[206:209], 0
	v_mfma_f32_16x16x32_bf16 v[110:113], v[168:171], v[184:187], v[110:113]
	v_mfma_f32_16x16x32_bf16 v[106:109], v[176:179], v[184:187], v[106:109]
	v_mfma_f32_16x16x32_bf16 v[94:97], v[168:171], v[192:195], v[94:97]
	v_mfma_f32_16x16x32_bf16 v[90:93], v[176:179], v[192:195], v[90:93]
	v_mfma_f32_16x16x32_bf16 v[78:81], v[168:171], v[200:203], v[78:81]
	v_mfma_f32_16x16x32_bf16 v[74:77], v[176:179], v[200:203], v[74:77]
	v_mfma_f32_16x16x32_bf16 v[70:73], v[168:171], v[210:213], v[70:73]
	v_mfma_f32_16x16x32_bf16 v[66:69], v[176:179], v[210:213], v[66:69]
	s_setprio 0
	s_barrier
	s_add_i32 s70, s35, s18
	v_lshl_add_u64 v[214:215], s[38:39], 0, v[134:135]
	s_mov_b32 m0, s70
	ds_read_b128 v[180:183], v146 offset:16384
	ds_read_b128 v[184:187], v146 offset:17408
	ds_read_b128 v[188:191], v146 offset:18432
	ds_read_b128 v[192:195], v146 offset:19456
	ds_read_b128 v[196:199], v146 offset:20480
	ds_read_b128 v[200:203], v146 offset:21504
	ds_read_b128 v[206:209], v146 offset:22528
	ds_read_b128 v[210:213], v146 offset:23552
	global_load_lds_dwordx4 v[214:215], off
	s_add_i32 m0, s70, 0x2000
	s_add_u32 s70, s38, 0x200000
	v_lshl_add_u64 v[216:217], s[38:39], 0, v[130:131]
	s_addc_u32 s71, s39, 0
	s_add_i32 s72, s44, s18
	global_load_lds_dwordx4 v[216:217], off
	v_lshl_add_u64 v[218:219], s[70:71], 0, v[134:135]
	s_mov_b32 m0, s72
	v_lshl_add_u64 v[220:221], s[42:43], 0, v[132:133]
	global_load_lds_dwordx4 v[218:219], off
	v_lshl_add_u64 v[218:219], s[70:71], 0, v[130:131]
	s_add_i32 m0, s72, 0x2000
	s_nop 0
	global_load_lds_dwordx4 v[218:219], off
	v_lshl_add_u64 v[218:219], s[42:43], 0, v[136:137]
	s_mov_b32 m0, s19
	s_nop 0
	global_load_lds_dwordx4 v[218:219], off
	s_waitcnt vmcnt(7)
	s_waitcnt lgkmcnt(0)
	s_barrier
	s_setprio 1
	s_waitcnt lgkmcnt(0)
	v_mfma_f32_16x16x32_bf16 v[62:65], v[148:151], v[180:183], 0
	v_mfma_f32_16x16x32_bf16 v[58:61], v[156:159], v[180:183], 0
	v_mfma_f32_16x16x32_bf16 v[54:57], v[148:151], v[188:191], 0
	v_mfma_f32_16x16x32_bf16 v[50:53], v[156:159], v[188:191], 0
	v_mfma_f32_16x16x32_bf16 v[38:41], v[148:151], v[196:199], 0
	v_mfma_f32_16x16x32_bf16 v[34:37], v[156:159], v[196:199], 0
	v_mfma_f32_16x16x32_bf16 v[22:25], v[148:151], v[206:209], 0
	v_mfma_f32_16x16x32_bf16 v[18:21], v[156:159], v[206:209], 0
	s_mov_b32 m0, s24
	s_nop 0
	global_load_lds_dwordx4 v[220:221], off
	v_mfma_f32_16x16x32_bf16 v[62:65], v[152:155], v[184:187], v[62:65]
	v_mfma_f32_16x16x32_bf16 v[58:61], v[160:163], v[184:187], v[58:61]
	v_mfma_f32_16x16x32_bf16 v[54:57], v[152:155], v[192:195], v[54:57]
	v_mfma_f32_16x16x32_bf16 v[50:53], v[160:163], v[192:195], v[50:53]
	v_mfma_f32_16x16x32_bf16 v[38:41], v[152:155], v[200:203], v[38:41]
	v_mfma_f32_16x16x32_bf16 v[34:37], v[160:163], v[200:203], v[34:37]
	v_mfma_f32_16x16x32_bf16 v[22:25], v[152:155], v[210:213], v[22:25]
	v_mfma_f32_16x16x32_bf16 v[18:21], v[160:163], v[210:213], v[18:21]
	s_setprio 0
	s_setprio 1
	v_mfma_f32_16x16x32_bf16 v[46:49], v[164:167], v[180:183], 0
	v_mfma_f32_16x16x32_bf16 v[42:45], v[172:175], v[180:183], 0
	v_mfma_f32_16x16x32_bf16 v[30:33], v[164:167], v[188:191], 0
	v_mfma_f32_16x16x32_bf16 v[26:29], v[172:175], v[188:191], 0
	v_mfma_f32_16x16x32_bf16 v[14:17], v[164:167], v[196:199], 0
	v_mfma_f32_16x16x32_bf16 v[10:13], v[172:175], v[196:199], 0
	v_mfma_f32_16x16x32_bf16 v[6:9], v[164:167], v[206:209], 0
	v_mfma_f32_16x16x32_bf16 v[2:5], v[172:175], v[206:209], 0
	v_mfma_f32_16x16x32_bf16 v[46:49], v[168:171], v[184:187], v[46:49]
	v_mfma_f32_16x16x32_bf16 v[42:45], v[176:179], v[184:187], v[42:45]
	v_mfma_f32_16x16x32_bf16 v[30:33], v[168:171], v[192:195], v[30:33]
	v_mfma_f32_16x16x32_bf16 v[26:29], v[176:179], v[192:195], v[26:29]
	v_mfma_f32_16x16x32_bf16 v[14:17], v[168:171], v[200:203], v[14:17]
	v_mfma_f32_16x16x32_bf16 v[10:13], v[176:179], v[200:203], v[10:13]
	v_mfma_f32_16x16x32_bf16 v[6:9], v[168:171], v[210:213], v[6:9]
	v_mfma_f32_16x16x32_bf16 v[2:5], v[176:179], v[210:213], v[2:5]
	s_setprio 0
	s_barrier
	s_add_i32 s70, 0, 0x18000
	v_add_u32_e32 v147, s70, v143
	s_add_i32 s71, 0, 0x1c000
	ds_read_b128 v[148:151], v147
	ds_read_b128 v[152:155], v147 offset:1024
	ds_read_b128 v[156:159], v147 offset:2048
	ds_read_b128 v[160:163], v147 offset:3072
	v_add_u32_e32 v147, s71, v143
	ds_read_b128 v[164:167], v147
	ds_read_b128 v[168:171], v147 offset:1024
	ds_read_b128 v[172:175], v147 offset:2048
	ds_read_b128 v[176:179], v147 offset:3072
	s_add_u32 s42, s42, 0x20000
	s_addc_u32 s43, s43, 0
	s_mov_b32 m0, s25
	v_lshl_add_u64 v[222:223], s[42:43], 0, v[136:137]
	ds_read_b128 v[180:183], v146 offset:32768
	ds_read_b128 v[184:187], v146 offset:33792
	ds_read_b128 v[188:191], v146 offset:34816
	ds_read_b128 v[192:195], v146 offset:35840
	ds_read_b128 v[196:199], v146 offset:36864
	ds_read_b128 v[200:203], v146 offset:37888
	ds_read_b128 v[206:209], v146 offset:38912
	ds_read_b128 v[210:213], v146 offset:39936
	global_load_lds_dwordx4 v[222:223], off
	v_lshl_add_u64 v[222:223], s[42:43], 0, v[132:133]
	s_mov_b32 m0, s28
	s_nop 0
	global_load_lds_dwordx4 v[222:223], off
	s_waitcnt vmcnt(8)
	s_waitcnt lgkmcnt(0)
	s_barrier
	s_setprio 1
	s_waitcnt lgkmcnt(0)
	v_mfma_f32_16x16x32_bf16 v[126:129], v[148:151], v[180:183], v[126:129]
	v_mfma_f32_16x16x32_bf16 v[122:125], v[156:159], v[180:183], v[122:125]
	v_mfma_f32_16x16x32_bf16 v[118:121], v[148:151], v[188:191], v[118:121]
	v_mfma_f32_16x16x32_bf16 v[114:117], v[156:159], v[188:191], v[114:117]
	v_mfma_f32_16x16x32_bf16 v[102:105], v[148:151], v[196:199], v[102:105]
	v_mfma_f32_16x16x32_bf16 v[98:101], v[156:159], v[196:199], v[98:101]
	v_mfma_f32_16x16x32_bf16 v[86:89], v[148:151], v[206:209], v[86:89]
	v_mfma_f32_16x16x32_bf16 v[82:85], v[156:159], v[206:209], v[82:85]
	v_mfma_f32_16x16x32_bf16 v[126:129], v[152:155], v[184:187], v[126:129]
	v_mfma_f32_16x16x32_bf16 v[122:125], v[160:163], v[184:187], v[122:125]
	v_mfma_f32_16x16x32_bf16 v[118:121], v[152:155], v[192:195], v[118:121]
	v_mfma_f32_16x16x32_bf16 v[114:117], v[160:163], v[192:195], v[114:117]
	v_mfma_f32_16x16x32_bf16 v[102:105], v[152:155], v[200:203], v[102:105]
	v_mfma_f32_16x16x32_bf16 v[98:101], v[160:163], v[200:203], v[98:101]
	v_mfma_f32_16x16x32_bf16 v[86:89], v[152:155], v[210:213], v[86:89]
	v_mfma_f32_16x16x32_bf16 v[82:85], v[160:163], v[210:213], v[82:85]
	s_setprio 0
	s_setprio 1
	v_mfma_f32_16x16x32_bf16 v[110:113], v[164:167], v[180:183], v[110:113]
	v_mfma_f32_16x16x32_bf16 v[106:109], v[172:175], v[180:183], v[106:109]
	v_mfma_f32_16x16x32_bf16 v[94:97], v[164:167], v[188:191], v[94:97]
	v_mfma_f32_16x16x32_bf16 v[90:93], v[172:175], v[188:191], v[90:93]
	v_mfma_f32_16x16x32_bf16 v[78:81], v[164:167], v[196:199], v[78:81]
	v_mfma_f32_16x16x32_bf16 v[74:77], v[172:175], v[196:199], v[74:77]
	v_mfma_f32_16x16x32_bf16 v[70:73], v[164:167], v[206:209], v[70:73]
	v_mfma_f32_16x16x32_bf16 v[66:69], v[172:175], v[206:209], v[66:69]
	v_mfma_f32_16x16x32_bf16 v[110:113], v[168:171], v[184:187], v[110:113]
	v_mfma_f32_16x16x32_bf16 v[106:109], v[176:179], v[184:187], v[106:109]
	v_mfma_f32_16x16x32_bf16 v[94:97], v[168:171], v[192:195], v[94:97]
	v_mfma_f32_16x16x32_bf16 v[90:93], v[176:179], v[192:195], v[90:93]
	v_mfma_f32_16x16x32_bf16 v[78:81], v[168:171], v[200:203], v[78:81]
	v_mfma_f32_16x16x32_bf16 v[74:77], v[176:179], v[200:203], v[74:77]
	v_mfma_f32_16x16x32_bf16 v[70:73], v[168:171], v[210:213], v[70:73]
	v_mfma_f32_16x16x32_bf16 v[66:69], v[176:179], v[210:213], v[66:69]
	s_setprio 0
	s_barrier
	s_add_i32 s42, s70, s18
	v_lshl_add_u64 v[214:215], v[214:215], 0, s[8:9]
	s_mov_b32 m0, s42
	ds_read_b128 v[180:183], v146 offset:49152
	ds_read_b128 v[184:187], v146 offset:50176
	ds_read_b128 v[188:191], v146 offset:51200
	ds_read_b128 v[192:195], v146 offset:52224
	ds_read_b128 v[196:199], v146 offset:53248
	ds_read_b128 v[200:203], v146 offset:54272
	ds_read_b128 v[206:209], v146 offset:55296
	ds_read_b128 v[210:213], v146 offset:56320
	global_load_lds_dwordx4 v[214:215], off
	s_add_i32 m0, s42, 0x2000
	s_add_u32 s38, s38, 0x200080
	v_lshl_add_u64 v[214:215], v[216:217], 0, s[8:9]
	s_addc_u32 s39, s39, 0
	s_add_i32 s42, s71, s18
	global_load_lds_dwordx4 v[214:215], off
	v_lshl_add_u64 v[214:215], s[38:39], 0, v[134:135]
	s_mov_b32 m0, s42
	s_nop 0
	global_load_lds_dwordx4 v[214:215], off
	v_lshl_add_u64 v[214:215], s[38:39], 0, v[130:131]
	s_add_i32 m0, s42, 0x2000
	s_nop 0
	global_load_lds_dwordx4 v[214:215], off
	v_lshl_add_u64 v[214:215], v[218:219], 0, s[8:9]
	s_mov_b32 m0, s33
	s_nop 0
	global_load_lds_dwordx4 v[214:215], off
	v_lshl_add_u64 v[214:215], v[220:221], 0, s[8:9]
	s_waitcnt vmcnt(7)
	s_waitcnt lgkmcnt(0)
	s_barrier
	s_setprio 1
	s_waitcnt lgkmcnt(0)
	v_mfma_f32_16x16x32_bf16 v[62:65], v[148:151], v[180:183], v[62:65]
	v_mfma_f32_16x16x32_bf16 v[58:61], v[156:159], v[180:183], v[58:61]
	v_mfma_f32_16x16x32_bf16 v[54:57], v[148:151], v[188:191], v[54:57]
	v_mfma_f32_16x16x32_bf16 v[50:53], v[156:159], v[188:191], v[50:53]
	v_mfma_f32_16x16x32_bf16 v[38:41], v[148:151], v[196:199], v[38:41]
	v_mfma_f32_16x16x32_bf16 v[34:37], v[156:159], v[196:199], v[34:37]
	v_mfma_f32_16x16x32_bf16 v[22:25], v[148:151], v[206:209], v[22:25]
	v_mfma_f32_16x16x32_bf16 v[18:21], v[156:159], v[206:209], v[18:21]
	s_mov_b32 m0, s34
	s_nop 0
	global_load_lds_dwordx4 v[214:215], off
	v_mfma_f32_16x16x32_bf16 v[62:65], v[152:155], v[184:187], v[62:65]
	v_mfma_f32_16x16x32_bf16 v[58:61], v[160:163], v[184:187], v[58:61]
	v_mfma_f32_16x16x32_bf16 v[54:57], v[152:155], v[192:195], v[54:57]
	v_mfma_f32_16x16x32_bf16 v[50:53], v[160:163], v[192:195], v[50:53]
	v_mfma_f32_16x16x32_bf16 v[38:41], v[152:155], v[200:203], v[38:41]
	v_mfma_f32_16x16x32_bf16 v[34:37], v[160:163], v[200:203], v[34:37]
	v_mfma_f32_16x16x32_bf16 v[22:25], v[152:155], v[210:213], v[22:25]
	v_mfma_f32_16x16x32_bf16 v[18:21], v[160:163], v[210:213], v[18:21]
	s_setprio 0
	s_setprio 1
	v_mfma_f32_16x16x32_bf16 v[46:49], v[164:167], v[180:183], v[46:49]
	v_mfma_f32_16x16x32_bf16 v[42:45], v[172:175], v[180:183], v[42:45]
	v_mfma_f32_16x16x32_bf16 v[30:33], v[164:167], v[188:191], v[30:33]
	v_mfma_f32_16x16x32_bf16 v[26:29], v[172:175], v[188:191], v[26:29]
	v_mfma_f32_16x16x32_bf16 v[14:17], v[164:167], v[196:199], v[14:17]
	v_mfma_f32_16x16x32_bf16 v[10:13], v[172:175], v[196:199], v[10:13]
	v_mfma_f32_16x16x32_bf16 v[6:9], v[164:167], v[206:209], v[6:9]
	v_mfma_f32_16x16x32_bf16 v[2:5], v[172:175], v[206:209], v[2:5]
	v_mfma_f32_16x16x32_bf16 v[46:49], v[168:171], v[184:187], v[46:49]
	v_mfma_f32_16x16x32_bf16 v[42:45], v[176:179], v[184:187], v[42:45]
	v_mfma_f32_16x16x32_bf16 v[30:33], v[168:171], v[192:195], v[30:33]
	v_mfma_f32_16x16x32_bf16 v[26:29], v[176:179], v[192:195], v[26:29]
	v_mfma_f32_16x16x32_bf16 v[14:17], v[168:171], v[200:203], v[14:17]
	v_mfma_f32_16x16x32_bf16 v[10:13], v[176:179], v[200:203], v[10:13]
	v_mfma_f32_16x16x32_bf16 v[6:9], v[168:171], v[210:213], v[6:9]
	v_mfma_f32_16x16x32_bf16 v[2:5], v[176:179], v[210:213], v[2:5]
	s_setprio 0
	s_barrier
	s_add_i32 s69, s69, 2
	s_add_u32 s36, s36, 0x100
	s_addc_u32 s37, s37, 0
	s_add_u32 s67, s67, 0x100
	s_addc_u32 s68, s68, 0
	s_cmp_gt_u32 s69, 5
.LBB0_477:
	ds_read_b128 v[148:151], v144
	ds_read_b128 v[152:155], v144 offset:1024
	ds_read_b128 v[156:159], v144 offset:2048
	ds_read_b128 v[160:163], v144 offset:3072
	ds_read_b128 v[164:167], v145
	ds_read_b128 v[168:171], v145 offset:1024
	ds_read_b128 v[172:175], v145 offset:2048
	ds_read_b128 v[176:179], v145 offset:3072
	s_add_u32 s38, s36, 0xfffe0080
	s_addc_u32 s39, s37, -1
	s_cmp_eq_u32 s69, 4
	s_cselect_b32 s43, s63, s39
	s_cselect_b32 s42, s64, s38
	s_cselect_b32 s39, s65, s68
	s_cselect_b32 s38, s66, s67
	v_lshl_add_u64 v[214:215], s[36:37], 0, v[138:139]
	s_add_i32 m0, s19, 0xc000
	ds_read_b128 v[180:183], v146
	ds_read_b128 v[184:187], v146 offset:1024
	ds_read_b128 v[188:191], v146 offset:2048
	ds_read_b128 v[192:195], v146 offset:3072
	ds_read_b128 v[196:199], v146 offset:4096
	ds_read_b128 v[200:203], v146 offset:5120
	ds_read_b128 v[206:209], v146 offset:6144
	ds_read_b128 v[210:213], v146 offset:7168
	global_load_lds_dwordx4 v[214:215], off
	v_lshl_add_u64 v[214:215], s[36:37], 0, v[140:141]
	s_add_i32 m0, s19, 0xe000
	s_nop 0
	global_load_lds_dwordx4 v[214:215], off
	s_waitcnt vmcnt(8)
	s_waitcnt lgkmcnt(0)
	s_barrier
	s_setprio 1
	s_waitcnt lgkmcnt(0)
	v_mfma_f32_16x16x32_bf16 v[126:129], v[148:151], v[180:183], v[126:129]
	v_mfma_f32_16x16x32_bf16 v[122:125], v[156:159], v[180:183], v[122:125]
	v_mfma_f32_16x16x32_bf16 v[118:121], v[148:151], v[188:191], v[118:121]
	v_mfma_f32_16x16x32_bf16 v[114:117], v[156:159], v[188:191], v[114:117]
	v_mfma_f32_16x16x32_bf16 v[102:105], v[148:151], v[196:199], v[102:105]
	v_mfma_f32_16x16x32_bf16 v[98:101], v[156:159], v[196:199], v[98:101]
	v_mfma_f32_16x16x32_bf16 v[86:89], v[148:151], v[206:209], v[86:89]
	v_mfma_f32_16x16x32_bf16 v[82:85], v[156:159], v[206:209], v[82:85]
	v_mfma_f32_16x16x32_bf16 v[126:129], v[152:155], v[184:187], v[126:129]
	v_mfma_f32_16x16x32_bf16 v[122:125], v[160:163], v[184:187], v[122:125]
	v_mfma_f32_16x16x32_bf16 v[118:121], v[152:155], v[192:195], v[118:121]
	v_mfma_f32_16x16x32_bf16 v[114:117], v[160:163], v[192:195], v[114:117]
	v_mfma_f32_16x16x32_bf16 v[102:105], v[152:155], v[200:203], v[102:105]
	v_mfma_f32_16x16x32_bf16 v[98:101], v[160:163], v[200:203], v[98:101]
	v_mfma_f32_16x16x32_bf16 v[86:89], v[152:155], v[210:213], v[86:89]
	v_mfma_f32_16x16x32_bf16 v[82:85], v[160:163], v[210:213], v[82:85]
	s_setprio 0
	s_setprio 1
	v_mfma_f32_16x16x32_bf16 v[110:113], v[164:167], v[180:183], v[110:113]
	v_mfma_f32_16x16x32_bf16 v[106:109], v[172:175], v[180:183], v[106:109]
	v_mfma_f32_16x16x32_bf16 v[94:97], v[164:167], v[188:191], v[94:97]
	v_mfma_f32_16x16x32_bf16 v[90:93], v[172:175], v[188:191], v[90:93]
	v_mfma_f32_16x16x32_bf16 v[78:81], v[164:167], v[196:199], v[78:81]
	v_mfma_f32_16x16x32_bf16 v[74:77], v[172:175], v[196:199], v[74:77]
	v_mfma_f32_16x16x32_bf16 v[70:73], v[164:167], v[206:209], v[70:73]
	v_mfma_f32_16x16x32_bf16 v[66:69], v[172:175], v[206:209], v[66:69]
	v_mfma_f32_16x16x32_bf16 v[110:113], v[168:171], v[184:187], v[110:113]
	v_mfma_f32_16x16x32_bf16 v[106:109], v[176:179], v[184:187], v[106:109]
	v_mfma_f32_16x16x32_bf16 v[94:97], v[168:171], v[192:195], v[94:97]
	v_mfma_f32_16x16x32_bf16 v[90:93], v[176:179], v[192:195], v[90:93]
	v_mfma_f32_16x16x32_bf16 v[78:81], v[168:171], v[200:203], v[78:81]
	v_mfma_f32_16x16x32_bf16 v[74:77], v[176:179], v[200:203], v[74:77]
	v_mfma_f32_16x16x32_bf16 v[70:73], v[168:171], v[210:213], v[70:73]
	v_mfma_f32_16x16x32_bf16 v[66:69], v[176:179], v[210:213], v[66:69]
	s_setprio 0
	s_barrier
	s_add_i32 s70, s35, s18
	v_lshl_add_u64 v[214:215], s[38:39], 0, v[134:135]
	s_mov_b32 m0, s70
	ds_read_b128 v[180:183], v146 offset:16384
	ds_read_b128 v[184:187], v146 offset:17408
	ds_read_b128 v[188:191], v146 offset:18432
	ds_read_b128 v[192:195], v146 offset:19456
	ds_read_b128 v[196:199], v146 offset:20480
	ds_read_b128 v[200:203], v146 offset:21504
	ds_read_b128 v[206:209], v146 offset:22528
	ds_read_b128 v[210:213], v146 offset:23552
	global_load_lds_dwordx4 v[214:215], off
	s_add_i32 m0, s70, 0x2000
	s_add_u32 s70, s38, 0x200000
	v_lshl_add_u64 v[216:217], s[38:39], 0, v[130:131]
	s_addc_u32 s71, s39, 0
	s_add_i32 s72, s44, s18
	global_load_lds_dwordx4 v[216:217], off
	v_lshl_add_u64 v[218:219], s[70:71], 0, v[134:135]
	s_mov_b32 m0, s72
	v_lshl_add_u64 v[220:221], s[42:43], 0, v[132:133]
	global_load_lds_dwordx4 v[218:219], off
	v_lshl_add_u64 v[218:219], s[70:71], 0, v[130:131]
	s_add_i32 m0, s72, 0x2000
	s_nop 0
	global_load_lds_dwordx4 v[218:219], off
	v_lshl_add_u64 v[218:219], s[42:43], 0, v[136:137]
	s_mov_b32 m0, s19
	s_nop 0
	global_load_lds_dwordx4 v[218:219], off
	s_waitcnt vmcnt(7)
	s_waitcnt lgkmcnt(0)
	s_barrier
	s_setprio 1
	s_waitcnt lgkmcnt(0)
	v_mfma_f32_16x16x32_bf16 v[62:65], v[148:151], v[180:183], v[62:65]
	v_mfma_f32_16x16x32_bf16 v[58:61], v[156:159], v[180:183], v[58:61]
	v_mfma_f32_16x16x32_bf16 v[54:57], v[148:151], v[188:191], v[54:57]
	v_mfma_f32_16x16x32_bf16 v[50:53], v[156:159], v[188:191], v[50:53]
	v_mfma_f32_16x16x32_bf16 v[38:41], v[148:151], v[196:199], v[38:41]
	v_mfma_f32_16x16x32_bf16 v[34:37], v[156:159], v[196:199], v[34:37]
	v_mfma_f32_16x16x32_bf16 v[22:25], v[148:151], v[206:209], v[22:25]
	v_mfma_f32_16x16x32_bf16 v[18:21], v[156:159], v[206:209], v[18:21]
	s_mov_b32 m0, s24
	s_nop 0
	global_load_lds_dwordx4 v[220:221], off
	v_mfma_f32_16x16x32_bf16 v[62:65], v[152:155], v[184:187], v[62:65]
	v_mfma_f32_16x16x32_bf16 v[58:61], v[160:163], v[184:187], v[58:61]
	v_mfma_f32_16x16x32_bf16 v[54:57], v[152:155], v[192:195], v[54:57]
	v_mfma_f32_16x16x32_bf16 v[50:53], v[160:163], v[192:195], v[50:53]
	v_mfma_f32_16x16x32_bf16 v[38:41], v[152:155], v[200:203], v[38:41]
	v_mfma_f32_16x16x32_bf16 v[34:37], v[160:163], v[200:203], v[34:37]
	v_mfma_f32_16x16x32_bf16 v[22:25], v[152:155], v[210:213], v[22:25]
	v_mfma_f32_16x16x32_bf16 v[18:21], v[160:163], v[210:213], v[18:21]
	s_setprio 0
	s_setprio 1
	v_mfma_f32_16x16x32_bf16 v[46:49], v[164:167], v[180:183], v[46:49]
	v_mfma_f32_16x16x32_bf16 v[42:45], v[172:175], v[180:183], v[42:45]
	v_mfma_f32_16x16x32_bf16 v[30:33], v[164:167], v[188:191], v[30:33]
	v_mfma_f32_16x16x32_bf16 v[26:29], v[172:175], v[188:191], v[26:29]
	v_mfma_f32_16x16x32_bf16 v[14:17], v[164:167], v[196:199], v[14:17]
	v_mfma_f32_16x16x32_bf16 v[10:13], v[172:175], v[196:199], v[10:13]
	v_mfma_f32_16x16x32_bf16 v[6:9], v[164:167], v[206:209], v[6:9]
	v_mfma_f32_16x16x32_bf16 v[2:5], v[172:175], v[206:209], v[2:5]
	v_mfma_f32_16x16x32_bf16 v[46:49], v[168:171], v[184:187], v[46:49]
	v_mfma_f32_16x16x32_bf16 v[42:45], v[176:179], v[184:187], v[42:45]
	v_mfma_f32_16x16x32_bf16 v[30:33], v[168:171], v[192:195], v[30:33]
	v_mfma_f32_16x16x32_bf16 v[26:29], v[176:179], v[192:195], v[26:29]
	v_mfma_f32_16x16x32_bf16 v[14:17], v[168:171], v[200:203], v[14:17]
	v_mfma_f32_16x16x32_bf16 v[10:13], v[176:179], v[200:203], v[10:13]
	v_mfma_f32_16x16x32_bf16 v[6:9], v[168:171], v[210:213], v[6:9]
	v_mfma_f32_16x16x32_bf16 v[2:5], v[176:179], v[210:213], v[2:5]
	s_setprio 0
	s_barrier
	s_add_i32 s70, 0, 0x18000
	v_add_u32_e32 v147, s70, v143
	s_add_i32 s71, 0, 0x1c000
	ds_read_b128 v[148:151], v147
	ds_read_b128 v[152:155], v147 offset:1024
	ds_read_b128 v[156:159], v147 offset:2048
	ds_read_b128 v[160:163], v147 offset:3072
	v_add_u32_e32 v147, s71, v143
	ds_read_b128 v[164:167], v147
	ds_read_b128 v[168:171], v147 offset:1024
	ds_read_b128 v[172:175], v147 offset:2048
	ds_read_b128 v[176:179], v147 offset:3072
	s_add_u32 s42, s42, 0x20000
	s_addc_u32 s43, s43, 0
	s_mov_b32 m0, s25
	v_lshl_add_u64 v[222:223], s[42:43], 0, v[136:137]
	ds_read_b128 v[180:183], v146 offset:32768
	ds_read_b128 v[184:187], v146 offset:33792
	ds_read_b128 v[188:191], v146 offset:34816
	ds_read_b128 v[192:195], v146 offset:35840
	ds_read_b128 v[196:199], v146 offset:36864
	ds_read_b128 v[200:203], v146 offset:37888
	ds_read_b128 v[206:209], v146 offset:38912
	ds_read_b128 v[210:213], v146 offset:39936
	global_load_lds_dwordx4 v[222:223], off
	v_lshl_add_u64 v[222:223], s[42:43], 0, v[132:133]
	s_mov_b32 m0, s28
	s_nop 0
	global_load_lds_dwordx4 v[222:223], off
	s_waitcnt vmcnt(8)
	s_waitcnt lgkmcnt(0)
	s_barrier
	s_setprio 1
	s_waitcnt lgkmcnt(0)
	v_mfma_f32_16x16x32_bf16 v[126:129], v[148:151], v[180:183], v[126:129]
	v_mfma_f32_16x16x32_bf16 v[122:125], v[156:159], v[180:183], v[122:125]
	v_mfma_f32_16x16x32_bf16 v[118:121], v[148:151], v[188:191], v[118:121]
	v_mfma_f32_16x16x32_bf16 v[114:117], v[156:159], v[188:191], v[114:117]
	v_mfma_f32_16x16x32_bf16 v[102:105], v[148:151], v[196:199], v[102:105]
	v_mfma_f32_16x16x32_bf16 v[98:101], v[156:159], v[196:199], v[98:101]
	v_mfma_f32_16x16x32_bf16 v[86:89], v[148:151], v[206:209], v[86:89]
	v_mfma_f32_16x16x32_bf16 v[82:85], v[156:159], v[206:209], v[82:85]
	v_mfma_f32_16x16x32_bf16 v[126:129], v[152:155], v[184:187], v[126:129]
	v_mfma_f32_16x16x32_bf16 v[122:125], v[160:163], v[184:187], v[122:125]
	v_mfma_f32_16x16x32_bf16 v[118:121], v[152:155], v[192:195], v[118:121]
	v_mfma_f32_16x16x32_bf16 v[114:117], v[160:163], v[192:195], v[114:117]
	v_mfma_f32_16x16x32_bf16 v[102:105], v[152:155], v[200:203], v[102:105]
	v_mfma_f32_16x16x32_bf16 v[98:101], v[160:163], v[200:203], v[98:101]
	v_mfma_f32_16x16x32_bf16 v[86:89], v[152:155], v[210:213], v[86:89]
	v_mfma_f32_16x16x32_bf16 v[82:85], v[160:163], v[210:213], v[82:85]
	s_setprio 0
	s_setprio 1
	v_mfma_f32_16x16x32_bf16 v[110:113], v[164:167], v[180:183], v[110:113]
	v_mfma_f32_16x16x32_bf16 v[106:109], v[172:175], v[180:183], v[106:109]
	v_mfma_f32_16x16x32_bf16 v[94:97], v[164:167], v[188:191], v[94:97]
	v_mfma_f32_16x16x32_bf16 v[90:93], v[172:175], v[188:191], v[90:93]
	v_mfma_f32_16x16x32_bf16 v[78:81], v[164:167], v[196:199], v[78:81]
	v_mfma_f32_16x16x32_bf16 v[74:77], v[172:175], v[196:199], v[74:77]
	v_mfma_f32_16x16x32_bf16 v[70:73], v[164:167], v[206:209], v[70:73]
	v_mfma_f32_16x16x32_bf16 v[66:69], v[172:175], v[206:209], v[66:69]
	v_mfma_f32_16x16x32_bf16 v[110:113], v[168:171], v[184:187], v[110:113]
	v_mfma_f32_16x16x32_bf16 v[106:109], v[176:179], v[184:187], v[106:109]
	v_mfma_f32_16x16x32_bf16 v[94:97], v[168:171], v[192:195], v[94:97]
	v_mfma_f32_16x16x32_bf16 v[90:93], v[176:179], v[192:195], v[90:93]
	v_mfma_f32_16x16x32_bf16 v[78:81], v[168:171], v[200:203], v[78:81]
	v_mfma_f32_16x16x32_bf16 v[74:77], v[176:179], v[200:203], v[74:77]
	v_mfma_f32_16x16x32_bf16 v[70:73], v[168:171], v[210:213], v[70:73]
	v_mfma_f32_16x16x32_bf16 v[66:69], v[176:179], v[210:213], v[66:69]
	s_setprio 0
	s_barrier
	s_add_i32 s42, s70, s18
	v_lshl_add_u64 v[214:215], v[214:215], 0, s[8:9]
	s_mov_b32 m0, s42
	ds_read_b128 v[180:183], v146 offset:49152
	ds_read_b128 v[184:187], v146 offset:50176
	ds_read_b128 v[188:191], v146 offset:51200
	ds_read_b128 v[192:195], v146 offset:52224
	ds_read_b128 v[196:199], v146 offset:53248
	ds_read_b128 v[200:203], v146 offset:54272
	ds_read_b128 v[206:209], v146 offset:55296
	ds_read_b128 v[210:213], v146 offset:56320
	global_load_lds_dwordx4 v[214:215], off
	s_add_i32 m0, s42, 0x2000
	s_add_u32 s38, s38, 0x200080
	v_lshl_add_u64 v[214:215], v[216:217], 0, s[8:9]
	s_addc_u32 s39, s39, 0
	s_add_i32 s42, s71, s18
	global_load_lds_dwordx4 v[214:215], off
	v_lshl_add_u64 v[214:215], s[38:39], 0, v[134:135]
	s_mov_b32 m0, s42
	s_nop 0
	global_load_lds_dwordx4 v[214:215], off
	v_lshl_add_u64 v[214:215], s[38:39], 0, v[130:131]
	s_add_i32 m0, s42, 0x2000
	s_nop 0
	global_load_lds_dwordx4 v[214:215], off
	v_lshl_add_u64 v[214:215], v[218:219], 0, s[8:9]
	s_mov_b32 m0, s33
	s_nop 0
	global_load_lds_dwordx4 v[214:215], off
	v_lshl_add_u64 v[214:215], v[220:221], 0, s[8:9]
	s_waitcnt vmcnt(7)
	s_waitcnt lgkmcnt(0)
	s_barrier
	s_setprio 1
	s_waitcnt lgkmcnt(0)
	v_mfma_f32_16x16x32_bf16 v[62:65], v[148:151], v[180:183], v[62:65]
	v_mfma_f32_16x16x32_bf16 v[58:61], v[156:159], v[180:183], v[58:61]
	v_mfma_f32_16x16x32_bf16 v[54:57], v[148:151], v[188:191], v[54:57]
	v_mfma_f32_16x16x32_bf16 v[50:53], v[156:159], v[188:191], v[50:53]
	v_mfma_f32_16x16x32_bf16 v[38:41], v[148:151], v[196:199], v[38:41]
	v_mfma_f32_16x16x32_bf16 v[34:37], v[156:159], v[196:199], v[34:37]
	v_mfma_f32_16x16x32_bf16 v[22:25], v[148:151], v[206:209], v[22:25]
	v_mfma_f32_16x16x32_bf16 v[18:21], v[156:159], v[206:209], v[18:21]
	s_mov_b32 m0, s34
	s_nop 0
	global_load_lds_dwordx4 v[214:215], off
	v_mfma_f32_16x16x32_bf16 v[62:65], v[152:155], v[184:187], v[62:65]
	v_mfma_f32_16x16x32_bf16 v[58:61], v[160:163], v[184:187], v[58:61]
	v_mfma_f32_16x16x32_bf16 v[54:57], v[152:155], v[192:195], v[54:57]
	v_mfma_f32_16x16x32_bf16 v[50:53], v[160:163], v[192:195], v[50:53]
	v_mfma_f32_16x16x32_bf16 v[38:41], v[152:155], v[200:203], v[38:41]
	v_mfma_f32_16x16x32_bf16 v[34:37], v[160:163], v[200:203], v[34:37]
	v_mfma_f32_16x16x32_bf16 v[22:25], v[152:155], v[210:213], v[22:25]
	v_mfma_f32_16x16x32_bf16 v[18:21], v[160:163], v[210:213], v[18:21]
	s_setprio 0
	s_setprio 1
	v_mfma_f32_16x16x32_bf16 v[46:49], v[164:167], v[180:183], v[46:49]
	v_mfma_f32_16x16x32_bf16 v[42:45], v[172:175], v[180:183], v[42:45]
	v_mfma_f32_16x16x32_bf16 v[30:33], v[164:167], v[188:191], v[30:33]
	v_mfma_f32_16x16x32_bf16 v[26:29], v[172:175], v[188:191], v[26:29]
	v_mfma_f32_16x16x32_bf16 v[14:17], v[164:167], v[196:199], v[14:17]
	v_mfma_f32_16x16x32_bf16 v[10:13], v[172:175], v[196:199], v[10:13]
	v_mfma_f32_16x16x32_bf16 v[6:9], v[164:167], v[206:209], v[6:9]
	v_mfma_f32_16x16x32_bf16 v[2:5], v[172:175], v[206:209], v[2:5]
	v_mfma_f32_16x16x32_bf16 v[46:49], v[168:171], v[184:187], v[46:49]
	v_mfma_f32_16x16x32_bf16 v[42:45], v[176:179], v[184:187], v[42:45]
	v_mfma_f32_16x16x32_bf16 v[30:33], v[168:171], v[192:195], v[30:33]
	v_mfma_f32_16x16x32_bf16 v[26:29], v[176:179], v[192:195], v[26:29]
	v_mfma_f32_16x16x32_bf16 v[14:17], v[168:171], v[200:203], v[14:17]
	v_mfma_f32_16x16x32_bf16 v[10:13], v[176:179], v[200:203], v[10:13]
	v_mfma_f32_16x16x32_bf16 v[6:9], v[168:171], v[210:213], v[6:9]
	v_mfma_f32_16x16x32_bf16 v[2:5], v[176:179], v[210:213], v[2:5]
	s_setprio 0
	s_barrier
	s_add_i32 s69, s69, 2
	s_add_u32 s36, s36, 0x100
	s_addc_u32 s37, s37, 0
	s_add_u32 s67, s67, 0x100
	s_addc_u32 s68, s68, 0
	s_cmp_gt_u32 s69, 5
	s_cbranch_scc0 .LBB0_477
	s_and_b64 vcc, exec, s[10:11]
	s_cbranch_vccz .LBB0_480
	s_barrier

.LBB0_565:
	v_readlane_b32 s62, v249, 27
	v_readlane_b32 s63, v249, 28
	s_add_u32 s72, s62, s68
	s_addc_u32 s73, s63, s69
	s_and_b64 s[62:63], s[70:71], exec
	s_cselect_b32 s31, s73, s77
	s_cselect_b32 s33, s72, s76
	s_add_u32 s74, s35, s66
	s_addc_u32 s75, s85, s67
	s_and_b64 s[62:63], s[70:71], exec
	s_cselect_b32 s34, s75, s79
	s_cselect_b32 s39, s74, s78
	s_add_i32 s45, s7, -2
	s_add_u32 s76, s76, 0x40080
	s_addc_u32 s77, s77, 0
	s_add_u32 s47, s78, 0x100
	s_addc_u32 s62, s79, 0
	s_mov_b32 s63, 0
	s_waitcnt vmcnt(0)
	ds_read_b128 v[114:117], v190
	ds_read_b128 v[118:121], v190 offset:1024
	ds_read_b128 v[122:125], v190 offset:2048
	ds_read_b128 v[126:129], v190 offset:3072
	ds_read_b128 v[146:149], v191
	ds_read_b128 v[150:153], v191 offset:1024
	ds_read_b128 v[154:157], v191 offset:2048
	ds_read_b128 v[158:161], v191 offset:3072
	s_add_i32 s82, s63, 2
	s_add_u32 s78, s76, 0xfffc0080
	s_addc_u32 s79, s77, -1
	s_cmp_eq_u32 s45, s63
	s_cselect_b32 s81, s31, s79
	s_cselect_b32 s80, s33, s78
	s_cselect_b32 s79, s34, s62
	s_cselect_b32 s78, s39, s47
	v_lshl_add_u64 v[186:187], s[76:77], 0, v[180:181]
	s_add_i32 m0, s87, 0xc000
	ds_read_b128 v[162:165], v192
	ds_read_b128 v[166:169], v192 offset:1024
	ds_read_b128 v[194:197], v192 offset:2048
	ds_read_b128 v[198:201], v192 offset:3072
	ds_read_b128 v[206:209], v192 offset:4096
	ds_read_b128 v[210:213], v192 offset:5120
	ds_read_b128 v[214:217], v192 offset:6144
	ds_read_b128 v[218:221], v192 offset:7168
	global_load_lds_dwordx4 v[186:187], off
	v_lshl_add_u64 v[186:187], s[76:77], 0, v[182:183]
	s_add_i32 m0, s87, 0xe000
	s_nop 0
	global_load_lds_dwordx4 v[186:187], off
	s_waitcnt vmcnt(8)
	s_waitcnt lgkmcnt(0)
	s_barrier
	s_setprio 1
	s_waitcnt lgkmcnt(0)
	v_mfma_f32_16x16x32_bf16 v[142:145], v[114:117], v[162:165], 0
	v_mfma_f32_16x16x32_bf16 v[138:141], v[122:125], v[162:165], 0
	v_mfma_f32_16x16x32_bf16 v[110:113], v[114:117], v[194:197], 0
	v_mfma_f32_16x16x32_bf16 v[106:109], v[122:125], v[194:197], 0
	v_mfma_f32_16x16x32_bf16 v[98:101], v[114:117], v[206:209], 0
	v_mfma_f32_16x16x32_bf16 v[90:93], v[122:125], v[206:209], 0
	v_mfma_f32_16x16x32_bf16 v[82:85], v[114:117], v[214:217], 0
	v_mfma_f32_16x16x32_bf16 v[74:77], v[122:125], v[214:217], 0
	v_mfma_f32_16x16x32_bf16 v[142:145], v[118:121], v[166:169], v[142:145]
	v_mfma_f32_16x16x32_bf16 v[138:141], v[126:129], v[166:169], v[138:141]
	v_mfma_f32_16x16x32_bf16 v[110:113], v[118:121], v[198:201], v[110:113]
	v_mfma_f32_16x16x32_bf16 v[106:109], v[126:129], v[198:201], v[106:109]
	v_mfma_f32_16x16x32_bf16 v[98:101], v[118:121], v[210:213], v[98:101]
	v_mfma_f32_16x16x32_bf16 v[90:93], v[126:129], v[210:213], v[90:93]
	v_mfma_f32_16x16x32_bf16 v[82:85], v[118:121], v[218:221], v[82:85]
	v_mfma_f32_16x16x32_bf16 v[74:77], v[126:129], v[218:221], v[74:77]
	s_setprio 0
	s_setprio 1
	v_mfma_f32_16x16x32_bf16 v[134:137], v[146:149], v[162:165], 0
	v_mfma_f32_16x16x32_bf16 v[130:133], v[154:157], v[162:165], 0
	v_mfma_f32_16x16x32_bf16 v[102:105], v[146:149], v[194:197], 0
	v_mfma_f32_16x16x32_bf16 v[94:97], v[154:157], v[194:197], 0
	v_mfma_f32_16x16x32_bf16 v[86:89], v[146:149], v[206:209], 0
	v_mfma_f32_16x16x32_bf16 v[78:81], v[154:157], v[206:209], 0
	v_mfma_f32_16x16x32_bf16 v[70:73], v[146:149], v[214:217], 0
	v_mfma_f32_16x16x32_bf16 v[66:69], v[154:157], v[214:217], 0
	v_mfma_f32_16x16x32_bf16 v[134:137], v[150:153], v[166:169], v[134:137]
	v_mfma_f32_16x16x32_bf16 v[130:133], v[158:161], v[166:169], v[130:133]
	v_mfma_f32_16x16x32_bf16 v[102:105], v[150:153], v[198:201], v[102:105]
	v_mfma_f32_16x16x32_bf16 v[94:97], v[158:161], v[198:201], v[94:97]
	v_mfma_f32_16x16x32_bf16 v[86:89], v[150:153], v[210:213], v[86:89]
	v_mfma_f32_16x16x32_bf16 v[78:81], v[158:161], v[210:213], v[78:81]
	v_mfma_f32_16x16x32_bf16 v[70:73], v[150:153], v[218:221], v[70:73]
	v_mfma_f32_16x16x32_bf16 v[66:69], v[158:161], v[218:221], v[66:69]
	s_setprio 0
	s_barrier
	s_add_i32 s63, s24, s86
	v_lshl_add_u64 v[186:187], s[78:79], 0, v[172:173]
	s_mov_b32 m0, s63
	ds_read_b128 v[162:165], v192 offset:16384
	ds_read_b128 v[166:169], v192 offset:17408
	ds_read_b128 v[194:197], v192 offset:18432
	ds_read_b128 v[198:201], v192 offset:19456
	ds_read_b128 v[206:209], v192 offset:20480
	ds_read_b128 v[210:213], v192 offset:21504
	ds_read_b128 v[214:217], v192 offset:22528
	ds_read_b128 v[218:221], v192 offset:23552
	global_load_lds_dwordx4 v[186:187], off
	s_add_i32 m0, s63, 0x2000
	s_add_u32 vcc_lo, s78, 0x40000
	v_lshl_add_u64 v[202:203], s[78:79], 0, v[176:177]
	s_addc_u32 vcc_hi, s79, 0
	s_add_i32 s63, s25, s86
	global_load_lds_dwordx4 v[202:203], off
	v_lshl_add_u64 v[222:223], vcc, 0, v[172:173]
	s_mov_b32 m0, s63
	v_lshl_add_u64 v[224:225], s[80:81], 0, v[174:175]
	global_load_lds_dwordx4 v[222:223], off
	v_lshl_add_u64 v[222:223], vcc, 0, v[176:177]
	s_add_i32 m0, s63, 0x2000
	s_nop 0
	global_load_lds_dwordx4 v[222:223], off
	v_lshl_add_u64 v[222:223], s[80:81], 0, v[170:171]
	s_mov_b32 m0, s87
	s_nop 0
	global_load_lds_dwordx4 v[222:223], off
	s_waitcnt vmcnt(7)
	s_waitcnt lgkmcnt(0)
	s_barrier
	s_setprio 1
	s_waitcnt lgkmcnt(0)
	v_mfma_f32_16x16x32_bf16 v[62:65], v[114:117], v[162:165], 0
	v_mfma_f32_16x16x32_bf16 v[58:61], v[122:125], v[162:165], 0
	v_mfma_f32_16x16x32_bf16 v[50:53], v[114:117], v[194:197], 0
	v_mfma_f32_16x16x32_bf16 v[42:45], v[122:125], v[194:197], 0
	v_mfma_f32_16x16x32_bf16 v[34:37], v[114:117], v[206:209], 0
	v_mfma_f32_16x16x32_bf16 v[26:29], v[122:125], v[206:209], 0
	v_mfma_f32_16x16x32_bf16 v[18:21], v[114:117], v[214:217], 0
	v_mfma_f32_16x16x32_bf16 v[10:13], v[122:125], v[214:217], 0
	s_mov_b32 m0, s88
	s_nop 0
	global_load_lds_dwordx4 v[224:225], off
	v_mfma_f32_16x16x32_bf16 v[62:65], v[118:121], v[166:169], v[62:65]
	v_mfma_f32_16x16x32_bf16 v[58:61], v[126:129], v[166:169], v[58:61]
	v_mfma_f32_16x16x32_bf16 v[50:53], v[118:121], v[198:201], v[50:53]
	v_mfma_f32_16x16x32_bf16 v[42:45], v[126:129], v[198:201], v[42:45]
	v_mfma_f32_16x16x32_bf16 v[34:37], v[118:121], v[210:213], v[34:37]
	v_mfma_f32_16x16x32_bf16 v[26:29], v[126:129], v[210:213], v[26:29]
	v_mfma_f32_16x16x32_bf16 v[18:21], v[118:121], v[218:221], v[18:21]
	v_mfma_f32_16x16x32_bf16 v[10:13], v[126:129], v[218:221], v[10:13]
	s_setprio 0
	s_setprio 1
	v_mfma_f32_16x16x32_bf16 v[54:57], v[146:149], v[162:165], 0
	v_mfma_f32_16x16x32_bf16 v[46:49], v[154:157], v[162:165], 0
	v_mfma_f32_16x16x32_bf16 v[38:41], v[146:149], v[194:197], 0
	v_mfma_f32_16x16x32_bf16 v[30:33], v[154:157], v[194:197], 0
	v_mfma_f32_16x16x32_bf16 v[22:25], v[146:149], v[206:209], 0
	v_mfma_f32_16x16x32_bf16 v[14:17], v[154:157], v[206:209], 0
	v_mfma_f32_16x16x32_bf16 v[6:9], v[146:149], v[214:217], 0
	v_mfma_f32_16x16x32_bf16 v[2:5], v[154:157], v[214:217], 0
	v_mfma_f32_16x16x32_bf16 v[54:57], v[150:153], v[166:169], v[54:57]
	v_mfma_f32_16x16x32_bf16 v[46:49], v[158:161], v[166:169], v[46:49]
	v_mfma_f32_16x16x32_bf16 v[38:41], v[150:153], v[198:201], v[38:41]
	v_mfma_f32_16x16x32_bf16 v[30:33], v[158:161], v[198:201], v[30:33]
	v_mfma_f32_16x16x32_bf16 v[22:25], v[150:153], v[210:213], v[22:25]
	v_mfma_f32_16x16x32_bf16 v[14:17], v[158:161], v[210:213], v[14:17]
	v_mfma_f32_16x16x32_bf16 v[6:9], v[150:153], v[218:221], v[6:9]
	v_mfma_f32_16x16x32_bf16 v[2:5], v[158:161], v[218:221], v[2:5]
	s_setprio 0
	s_barrier
	s_add_i32 s63, 0, 0x18000
	s_add_i32 s83, 0, 0x1c000
	v_add_u32_e32 v126, s63, v189
	v_add_u32_e32 v158, s83, v189
	ds_read_b128 v[114:117], v126
	ds_read_b128 v[118:121], v126 offset:1024
	ds_read_b128 v[122:125], v126 offset:2048
	ds_read_b128 v[126:129], v126 offset:3072
	ds_read_b128 v[146:149], v158
	ds_read_b128 v[150:153], v158 offset:1024
	ds_read_b128 v[154:157], v158 offset:2048
	ds_read_b128 v[158:161], v158 offset:3072
	s_add_u32 s80, s80, 0x40000
	s_addc_u32 s81, s81, 0
	s_mov_b32 m0, s89
	v_lshl_add_u64 v[226:227], s[80:81], 0, v[170:171]
	ds_read_b128 v[162:165], v192 offset:32768
	ds_read_b128 v[166:169], v192 offset:33792
	ds_read_b128 v[194:197], v192 offset:34816
	ds_read_b128 v[198:201], v192 offset:35840
	ds_read_b128 v[206:209], v192 offset:36864
	ds_read_b128 v[210:213], v192 offset:37888
	ds_read_b128 v[214:217], v192 offset:38912
	ds_read_b128 v[218:221], v192 offset:39936
	global_load_lds_dwordx4 v[226:227], off
	v_lshl_add_u64 v[226:227], s[80:81], 0, v[174:175]
	s_mov_b32 m0, s90
	s_nop 0
	global_load_lds_dwordx4 v[226:227], off
	s_waitcnt vmcnt(8)
	s_waitcnt lgkmcnt(0)
	s_barrier
	s_setprio 1
	s_waitcnt lgkmcnt(0)
	v_mfma_f32_16x16x32_bf16 v[142:145], v[114:117], v[162:165], v[142:145]
	v_mfma_f32_16x16x32_bf16 v[138:141], v[122:125], v[162:165], v[138:141]
	v_mfma_f32_16x16x32_bf16 v[110:113], v[114:117], v[194:197], v[110:113]
	v_mfma_f32_16x16x32_bf16 v[106:109], v[122:125], v[194:197], v[106:109]
	v_mfma_f32_16x16x32_bf16 v[98:101], v[114:117], v[206:209], v[98:101]
	v_mfma_f32_16x16x32_bf16 v[90:93], v[122:125], v[206:209], v[90:93]
	v_mfma_f32_16x16x32_bf16 v[82:85], v[114:117], v[214:217], v[82:85]
	v_mfma_f32_16x16x32_bf16 v[74:77], v[122:125], v[214:217], v[74:77]
	v_mfma_f32_16x16x32_bf16 v[142:145], v[118:121], v[166:169], v[142:145]
	v_mfma_f32_16x16x32_bf16 v[138:141], v[126:129], v[166:169], v[138:141]
	v_mfma_f32_16x16x32_bf16 v[110:113], v[118:121], v[198:201], v[110:113]
	v_mfma_f32_16x16x32_bf16 v[106:109], v[126:129], v[198:201], v[106:109]
	v_mfma_f32_16x16x32_bf16 v[98:101], v[118:121], v[210:213], v[98:101]
	v_mfma_f32_16x16x32_bf16 v[90:93], v[126:129], v[210:213], v[90:93]
	v_mfma_f32_16x16x32_bf16 v[82:85], v[118:121], v[218:221], v[82:85]
	v_mfma_f32_16x16x32_bf16 v[74:77], v[126:129], v[218:221], v[74:77]
	s_setprio 0
	s_setprio 1
	v_mfma_f32_16x16x32_bf16 v[134:137], v[146:149], v[162:165], v[134:137]
	v_mfma_f32_16x16x32_bf16 v[130:133], v[154:157], v[162:165], v[130:133]
	v_mfma_f32_16x16x32_bf16 v[102:105], v[146:149], v[194:197], v[102:105]
	v_mfma_f32_16x16x32_bf16 v[94:97], v[154:157], v[194:197], v[94:97]
	v_mfma_f32_16x16x32_bf16 v[86:89], v[146:149], v[206:209], v[86:89]
	v_mfma_f32_16x16x32_bf16 v[78:81], v[154:157], v[206:209], v[78:81]
	v_mfma_f32_16x16x32_bf16 v[70:73], v[146:149], v[214:217], v[70:73]
	v_mfma_f32_16x16x32_bf16 v[66:69], v[154:157], v[214:217], v[66:69]
	v_mfma_f32_16x16x32_bf16 v[134:137], v[150:153], v[166:169], v[134:137]
	v_mfma_f32_16x16x32_bf16 v[130:133], v[158:161], v[166:169], v[130:133]
	v_mfma_f32_16x16x32_bf16 v[102:105], v[150:153], v[198:201], v[102:105]
	v_mfma_f32_16x16x32_bf16 v[94:97], v[158:161], v[198:201], v[94:97]
	v_mfma_f32_16x16x32_bf16 v[86:89], v[150:153], v[210:213], v[86:89]
	v_mfma_f32_16x16x32_bf16 v[78:81], v[158:161], v[210:213], v[78:81]
	v_mfma_f32_16x16x32_bf16 v[70:73], v[150:153], v[218:221], v[70:73]
	v_mfma_f32_16x16x32_bf16 v[66:69], v[158:161], v[218:221], v[66:69]
	s_setprio 0
	s_barrier
	s_add_i32 s63, s63, s86
	v_lshl_add_u64 v[186:187], v[186:187], 0, s[22:23]
	s_mov_b32 m0, s63
	ds_read_b128 v[162:165], v192 offset:49152
	ds_read_b128 v[166:169], v192 offset:50176
	ds_read_b128 v[194:197], v192 offset:51200
	ds_read_b128 v[198:201], v192 offset:52224
	ds_read_b128 v[206:209], v192 offset:53248
	ds_read_b128 v[210:213], v192 offset:54272
	ds_read_b128 v[214:217], v192 offset:55296
	ds_read_b128 v[218:221], v192 offset:56320
	global_load_lds_dwordx4 v[186:187], off
	s_add_i32 m0, s63, 0x2000
	s_add_u32 s78, s78, 0x40080
	v_lshl_add_u64 v[186:187], v[202:203], 0, s[22:23]
	s_addc_u32 s79, s79, 0
	s_add_i32 s63, s83, s86
	global_load_lds_dwordx4 v[186:187], off
	v_lshl_add_u64 v[186:187], s[78:79], 0, v[172:173]
	s_mov_b32 m0, s63
	s_nop 0
	global_load_lds_dwordx4 v[186:187], off
	v_lshl_add_u64 v[186:187], s[78:79], 0, v[176:177]
	s_add_i32 m0, s63, 0x2000
	s_nop 0
	global_load_lds_dwordx4 v[186:187], off
	v_lshl_add_u64 v[186:187], v[222:223], 0, s[22:23]
	s_mov_b32 m0, s95
	s_nop 0
	global_load_lds_dwordx4 v[186:187], off
	v_lshl_add_u64 v[186:187], v[224:225], 0, s[22:23]
	s_waitcnt vmcnt(7)
	s_waitcnt lgkmcnt(0)
	s_barrier
	s_setprio 1
	s_waitcnt lgkmcnt(0)
	v_mfma_f32_16x16x32_bf16 v[62:65], v[114:117], v[162:165], v[62:65]
	v_mfma_f32_16x16x32_bf16 v[58:61], v[122:125], v[162:165], v[58:61]
	v_mfma_f32_16x16x32_bf16 v[50:53], v[114:117], v[194:197], v[50:53]
	v_mfma_f32_16x16x32_bf16 v[42:45], v[122:125], v[194:197], v[42:45]
	v_mfma_f32_16x16x32_bf16 v[34:37], v[114:117], v[206:209], v[34:37]
	v_mfma_f32_16x16x32_bf16 v[26:29], v[122:125], v[206:209], v[26:29]
	v_mfma_f32_16x16x32_bf16 v[18:21], v[114:117], v[214:217], v[18:21]
	v_mfma_f32_16x16x32_bf16 v[10:13], v[122:125], v[214:217], v[10:13]
	s_mov_b32 m0, s96
	s_nop 0
	global_load_lds_dwordx4 v[186:187], off
	v_mfma_f32_16x16x32_bf16 v[62:65], v[118:121], v[166:169], v[62:65]
	v_mfma_f32_16x16x32_bf16 v[58:61], v[126:129], v[166:169], v[58:61]
	v_mfma_f32_16x16x32_bf16 v[50:53], v[118:121], v[198:201], v[50:53]
	v_mfma_f32_16x16x32_bf16 v[42:45], v[126:129], v[198:201], v[42:45]
	v_mfma_f32_16x16x32_bf16 v[34:37], v[118:121], v[210:213], v[34:37]
	v_mfma_f32_16x16x32_bf16 v[26:29], v[126:129], v[210:213], v[26:29]
	v_mfma_f32_16x16x32_bf16 v[18:21], v[118:121], v[218:221], v[18:21]
	v_mfma_f32_16x16x32_bf16 v[10:13], v[126:129], v[218:221], v[10:13]
	s_setprio 0
	s_setprio 1
	v_mfma_f32_16x16x32_bf16 v[54:57], v[146:149], v[162:165], v[54:57]
	v_mfma_f32_16x16x32_bf16 v[46:49], v[154:157], v[162:165], v[46:49]
	v_mfma_f32_16x16x32_bf16 v[38:41], v[146:149], v[194:197], v[38:41]
	v_mfma_f32_16x16x32_bf16 v[30:33], v[154:157], v[194:197], v[30:33]
	v_mfma_f32_16x16x32_bf16 v[22:25], v[146:149], v[206:209], v[22:25]
	v_mfma_f32_16x16x32_bf16 v[14:17], v[154:157], v[206:209], v[14:17]
	v_mfma_f32_16x16x32_bf16 v[6:9], v[146:149], v[214:217], v[6:9]
	v_mfma_f32_16x16x32_bf16 v[2:5], v[154:157], v[214:217], v[2:5]
	v_mfma_f32_16x16x32_bf16 v[54:57], v[150:153], v[166:169], v[54:57]
	v_mfma_f32_16x16x32_bf16 v[46:49], v[158:161], v[166:169], v[46:49]
	v_mfma_f32_16x16x32_bf16 v[38:41], v[150:153], v[198:201], v[38:41]
	v_mfma_f32_16x16x32_bf16 v[30:33], v[158:161], v[198:201], v[30:33]
	v_mfma_f32_16x16x32_bf16 v[22:25], v[150:153], v[210:213], v[22:25]
	v_mfma_f32_16x16x32_bf16 v[14:17], v[158:161], v[210:213], v[14:17]
	v_mfma_f32_16x16x32_bf16 v[6:9], v[150:153], v[218:221], v[6:9]
	v_mfma_f32_16x16x32_bf16 v[2:5], v[158:161], v[218:221], v[2:5]
	s_setprio 0
	s_barrier
	s_add_u32 s76, s76, 0x100
	s_addc_u32 s77, s77, 0
	s_add_u32 s47, s47, 0x100
	s_addc_u32 s62, s62, 0
	s_cmp_ge_i32 s82, s7
	s_mov_b32 s63, s82
.LBB0_566:
	s_waitcnt vmcnt(0)
	ds_read_b128 v[114:117], v190
	ds_read_b128 v[118:121], v190 offset:1024
	ds_read_b128 v[122:125], v190 offset:2048
	ds_read_b128 v[126:129], v190 offset:3072
	ds_read_b128 v[146:149], v191
	ds_read_b128 v[150:153], v191 offset:1024
	ds_read_b128 v[154:157], v191 offset:2048
	ds_read_b128 v[158:161], v191 offset:3072
	s_add_i32 s82, s63, 2
	s_add_u32 s78, s76, 0xfffc0080
	s_addc_u32 s79, s77, -1
	s_cmp_eq_u32 s45, s63
	s_cselect_b32 s81, s31, s79
	s_cselect_b32 s80, s33, s78
	s_cselect_b32 s79, s34, s62
	s_cselect_b32 s78, s39, s47
	v_lshl_add_u64 v[186:187], s[76:77], 0, v[180:181]
	s_add_i32 m0, s87, 0xc000
	ds_read_b128 v[162:165], v192
	ds_read_b128 v[166:169], v192 offset:1024
	ds_read_b128 v[194:197], v192 offset:2048
	ds_read_b128 v[198:201], v192 offset:3072
	ds_read_b128 v[206:209], v192 offset:4096
	ds_read_b128 v[210:213], v192 offset:5120
	ds_read_b128 v[214:217], v192 offset:6144
	ds_read_b128 v[218:221], v192 offset:7168
	global_load_lds_dwordx4 v[186:187], off
	v_lshl_add_u64 v[186:187], s[76:77], 0, v[182:183]
	s_add_i32 m0, s87, 0xe000
	s_nop 0
	global_load_lds_dwordx4 v[186:187], off
	s_waitcnt vmcnt(8)
	s_waitcnt lgkmcnt(0)
	s_barrier
	s_setprio 1
	s_waitcnt lgkmcnt(0)
	v_mfma_f32_16x16x32_bf16 v[142:145], v[114:117], v[162:165], v[142:145]
	v_mfma_f32_16x16x32_bf16 v[138:141], v[122:125], v[162:165], v[138:141]
	v_mfma_f32_16x16x32_bf16 v[110:113], v[114:117], v[194:197], v[110:113]
	v_mfma_f32_16x16x32_bf16 v[106:109], v[122:125], v[194:197], v[106:109]
	v_mfma_f32_16x16x32_bf16 v[98:101], v[114:117], v[206:209], v[98:101]
	v_mfma_f32_16x16x32_bf16 v[90:93], v[122:125], v[206:209], v[90:93]
	v_mfma_f32_16x16x32_bf16 v[82:85], v[114:117], v[214:217], v[82:85]
	v_mfma_f32_16x16x32_bf16 v[74:77], v[122:125], v[214:217], v[74:77]
	v_mfma_f32_16x16x32_bf16 v[142:145], v[118:121], v[166:169], v[142:145]
	v_mfma_f32_16x16x32_bf16 v[138:141], v[126:129], v[166:169], v[138:141]
	v_mfma_f32_16x16x32_bf16 v[110:113], v[118:121], v[198:201], v[110:113]
	v_mfma_f32_16x16x32_bf16 v[106:109], v[126:129], v[198:201], v[106:109]
	v_mfma_f32_16x16x32_bf16 v[98:101], v[118:121], v[210:213], v[98:101]
	v_mfma_f32_16x16x32_bf16 v[90:93], v[126:129], v[210:213], v[90:93]
	v_mfma_f32_16x16x32_bf16 v[82:85], v[118:121], v[218:221], v[82:85]
	v_mfma_f32_16x16x32_bf16 v[74:77], v[126:129], v[218:221], v[74:77]
	s_setprio 0
	s_setprio 1
	v_mfma_f32_16x16x32_bf16 v[134:137], v[146:149], v[162:165], v[134:137]
	v_mfma_f32_16x16x32_bf16 v[130:133], v[154:157], v[162:165], v[130:133]
	v_mfma_f32_16x16x32_bf16 v[102:105], v[146:149], v[194:197], v[102:105]
	v_mfma_f32_16x16x32_bf16 v[94:97], v[154:157], v[194:197], v[94:97]
	v_mfma_f32_16x16x32_bf16 v[86:89], v[146:149], v[206:209], v[86:89]
	v_mfma_f32_16x16x32_bf16 v[78:81], v[154:157], v[206:209], v[78:81]
	v_mfma_f32_16x16x32_bf16 v[70:73], v[146:149], v[214:217], v[70:73]
	v_mfma_f32_16x16x32_bf16 v[66:69], v[154:157], v[214:217], v[66:69]
	v_mfma_f32_16x16x32_bf16 v[134:137], v[150:153], v[166:169], v[134:137]
	v_mfma_f32_16x16x32_bf16 v[130:133], v[158:161], v[166:169], v[130:133]
	v_mfma_f32_16x16x32_bf16 v[102:105], v[150:153], v[198:201], v[102:105]
	v_mfma_f32_16x16x32_bf16 v[94:97], v[158:161], v[198:201], v[94:97]
	v_mfma_f32_16x16x32_bf16 v[86:89], v[150:153], v[210:213], v[86:89]
	v_mfma_f32_16x16x32_bf16 v[78:81], v[158:161], v[210:213], v[78:81]
	v_mfma_f32_16x16x32_bf16 v[70:73], v[150:153], v[218:221], v[70:73]
	v_mfma_f32_16x16x32_bf16 v[66:69], v[158:161], v[218:221], v[66:69]
	s_setprio 0
	s_barrier
	s_add_i32 s63, s24, s86
	v_lshl_add_u64 v[186:187], s[78:79], 0, v[172:173]
	s_mov_b32 m0, s63
	ds_read_b128 v[162:165], v192 offset:16384
	ds_read_b128 v[166:169], v192 offset:17408
	ds_read_b128 v[194:197], v192 offset:18432
	ds_read_b128 v[198:201], v192 offset:19456
	ds_read_b128 v[206:209], v192 offset:20480
	ds_read_b128 v[210:213], v192 offset:21504
	ds_read_b128 v[214:217], v192 offset:22528
	ds_read_b128 v[218:221], v192 offset:23552
	global_load_lds_dwordx4 v[186:187], off
	s_add_i32 m0, s63, 0x2000
	s_add_u32 vcc_lo, s78, 0x40000
	v_lshl_add_u64 v[202:203], s[78:79], 0, v[176:177]
	s_addc_u32 vcc_hi, s79, 0
	s_add_i32 s63, s25, s86
	global_load_lds_dwordx4 v[202:203], off
	v_lshl_add_u64 v[222:223], vcc, 0, v[172:173]
	s_mov_b32 m0, s63
	v_lshl_add_u64 v[224:225], s[80:81], 0, v[174:175]
	global_load_lds_dwordx4 v[222:223], off
	v_lshl_add_u64 v[222:223], vcc, 0, v[176:177]
	s_add_i32 m0, s63, 0x2000
	s_nop 0
	global_load_lds_dwordx4 v[222:223], off
	v_lshl_add_u64 v[222:223], s[80:81], 0, v[170:171]
	s_mov_b32 m0, s87
	s_nop 0
	global_load_lds_dwordx4 v[222:223], off
	s_waitcnt vmcnt(7)
	s_waitcnt lgkmcnt(0)
	s_barrier
	s_setprio 1
	s_waitcnt lgkmcnt(0)
	v_mfma_f32_16x16x32_bf16 v[62:65], v[114:117], v[162:165], v[62:65]
	v_mfma_f32_16x16x32_bf16 v[58:61], v[122:125], v[162:165], v[58:61]
	v_mfma_f32_16x16x32_bf16 v[50:53], v[114:117], v[194:197], v[50:53]
	v_mfma_f32_16x16x32_bf16 v[42:45], v[122:125], v[194:197], v[42:45]
	v_mfma_f32_16x16x32_bf16 v[34:37], v[114:117], v[206:209], v[34:37]
	v_mfma_f32_16x16x32_bf16 v[26:29], v[122:125], v[206:209], v[26:29]
	v_mfma_f32_16x16x32_bf16 v[18:21], v[114:117], v[214:217], v[18:21]
	v_mfma_f32_16x16x32_bf16 v[10:13], v[122:125], v[214:217], v[10:13]
	s_mov_b32 m0, s88
	s_nop 0
	global_load_lds_dwordx4 v[224:225], off
	v_mfma_f32_16x16x32_bf16 v[62:65], v[118:121], v[166:169], v[62:65]
	v_mfma_f32_16x16x32_bf16 v[58:61], v[126:129], v[166:169], v[58:61]
	v_mfma_f32_16x16x32_bf16 v[50:53], v[118:121], v[198:201], v[50:53]
	v_mfma_f32_16x16x32_bf16 v[42:45], v[126:129], v[198:201], v[42:45]
	v_mfma_f32_16x16x32_bf16 v[34:37], v[118:121], v[210:213], v[34:37]
	v_mfma_f32_16x16x32_bf16 v[26:29], v[126:129], v[210:213], v[26:29]
	v_mfma_f32_16x16x32_bf16 v[18:21], v[118:121], v[218:221], v[18:21]
	v_mfma_f32_16x16x32_bf16 v[10:13], v[126:129], v[218:221], v[10:13]
	s_setprio 0
	s_setprio 1
	v_mfma_f32_16x16x32_bf16 v[54:57], v[146:149], v[162:165], v[54:57]
	v_mfma_f32_16x16x32_bf16 v[46:49], v[154:157], v[162:165], v[46:49]
	v_mfma_f32_16x16x32_bf16 v[38:41], v[146:149], v[194:197], v[38:41]
	v_mfma_f32_16x16x32_bf16 v[30:33], v[154:157], v[194:197], v[30:33]
	v_mfma_f32_16x16x32_bf16 v[22:25], v[146:149], v[206:209], v[22:25]
	v_mfma_f32_16x16x32_bf16 v[14:17], v[154:157], v[206:209], v[14:17]
	v_mfma_f32_16x16x32_bf16 v[6:9], v[146:149], v[214:217], v[6:9]
	v_mfma_f32_16x16x32_bf16 v[2:5], v[154:157], v[214:217], v[2:5]
	v_mfma_f32_16x16x32_bf16 v[54:57], v[150:153], v[166:169], v[54:57]
	v_mfma_f32_16x16x32_bf16 v[46:49], v[158:161], v[166:169], v[46:49]
	v_mfma_f32_16x16x32_bf16 v[38:41], v[150:153], v[198:201], v[38:41]
	v_mfma_f32_16x16x32_bf16 v[30:33], v[158:161], v[198:201], v[30:33]
	v_mfma_f32_16x16x32_bf16 v[22:25], v[150:153], v[210:213], v[22:25]
	v_mfma_f32_16x16x32_bf16 v[14:17], v[158:161], v[210:213], v[14:17]
	v_mfma_f32_16x16x32_bf16 v[6:9], v[150:153], v[218:221], v[6:9]
	v_mfma_f32_16x16x32_bf16 v[2:5], v[158:161], v[218:221], v[2:5]
	s_setprio 0
	s_barrier
	s_add_i32 s63, 0, 0x18000
	s_add_i32 s83, 0, 0x1c000
	v_add_u32_e32 v126, s63, v189
	v_add_u32_e32 v158, s83, v189
	ds_read_b128 v[114:117], v126
	ds_read_b128 v[118:121], v126 offset:1024
	ds_read_b128 v[122:125], v126 offset:2048
	ds_read_b128 v[126:129], v126 offset:3072
	ds_read_b128 v[146:149], v158
	ds_read_b128 v[150:153], v158 offset:1024
	ds_read_b128 v[154:157], v158 offset:2048
	ds_read_b128 v[158:161], v158 offset:3072
	s_add_u32 s80, s80, 0x40000
	s_addc_u32 s81, s81, 0
	s_mov_b32 m0, s89
	v_lshl_add_u64 v[226:227], s[80:81], 0, v[170:171]
	ds_read_b128 v[162:165], v192 offset:32768
	ds_read_b128 v[166:169], v192 offset:33792
	ds_read_b128 v[194:197], v192 offset:34816
	ds_read_b128 v[198:201], v192 offset:35840
	ds_read_b128 v[206:209], v192 offset:36864
	ds_read_b128 v[210:213], v192 offset:37888
	ds_read_b128 v[214:217], v192 offset:38912
	ds_read_b128 v[218:221], v192 offset:39936
	global_load_lds_dwordx4 v[226:227], off
	v_lshl_add_u64 v[226:227], s[80:81], 0, v[174:175]
	s_mov_b32 m0, s90
	s_nop 0
	global_load_lds_dwordx4 v[226:227], off
	s_waitcnt vmcnt(8)
	s_waitcnt lgkmcnt(0)
	s_barrier
	s_setprio 1
	s_waitcnt lgkmcnt(0)
	v_mfma_f32_16x16x32_bf16 v[142:145], v[114:117], v[162:165], v[142:145]
	v_mfma_f32_16x16x32_bf16 v[138:141], v[122:125], v[162:165], v[138:141]
	v_mfma_f32_16x16x32_bf16 v[110:113], v[114:117], v[194:197], v[110:113]
	v_mfma_f32_16x16x32_bf16 v[106:109], v[122:125], v[194:197], v[106:109]
	v_mfma_f32_16x16x32_bf16 v[98:101], v[114:117], v[206:209], v[98:101]
	v_mfma_f32_16x16x32_bf16 v[90:93], v[122:125], v[206:209], v[90:93]
	v_mfma_f32_16x16x32_bf16 v[82:85], v[114:117], v[214:217], v[82:85]
	v_mfma_f32_16x16x32_bf16 v[74:77], v[122:125], v[214:217], v[74:77]
	v_mfma_f32_16x16x32_bf16 v[142:145], v[118:121], v[166:169], v[142:145]
	v_mfma_f32_16x16x32_bf16 v[138:141], v[126:129], v[166:169], v[138:141]
	v_mfma_f32_16x16x32_bf16 v[110:113], v[118:121], v[198:201], v[110:113]
	v_mfma_f32_16x16x32_bf16 v[106:109], v[126:129], v[198:201], v[106:109]
	v_mfma_f32_16x16x32_bf16 v[98:101], v[118:121], v[210:213], v[98:101]
	v_mfma_f32_16x16x32_bf16 v[90:93], v[126:129], v[210:213], v[90:93]
	v_mfma_f32_16x16x32_bf16 v[82:85], v[118:121], v[218:221], v[82:85]
	v_mfma_f32_16x16x32_bf16 v[74:77], v[126:129], v[218:221], v[74:77]
	s_setprio 0
	s_setprio 1
	v_mfma_f32_16x16x32_bf16 v[134:137], v[146:149], v[162:165], v[134:137]
	v_mfma_f32_16x16x32_bf16 v[130:133], v[154:157], v[162:165], v[130:133]
	v_mfma_f32_16x16x32_bf16 v[102:105], v[146:149], v[194:197], v[102:105]
	v_mfma_f32_16x16x32_bf16 v[94:97], v[154:157], v[194:197], v[94:97]
	v_mfma_f32_16x16x32_bf16 v[86:89], v[146:149], v[206:209], v[86:89]
	v_mfma_f32_16x16x32_bf16 v[78:81], v[154:157], v[206:209], v[78:81]
	v_mfma_f32_16x16x32_bf16 v[70:73], v[146:149], v[214:217], v[70:73]
	v_mfma_f32_16x16x32_bf16 v[66:69], v[154:157], v[214:217], v[66:69]
	v_mfma_f32_16x16x32_bf16 v[134:137], v[150:153], v[166:169], v[134:137]
	v_mfma_f32_16x16x32_bf16 v[130:133], v[158:161], v[166:169], v[130:133]
	v_mfma_f32_16x16x32_bf16 v[102:105], v[150:153], v[198:201], v[102:105]
	v_mfma_f32_16x16x32_bf16 v[94:97], v[158:161], v[198:201], v[94:97]
	v_mfma_f32_16x16x32_bf16 v[86:89], v[150:153], v[210:213], v[86:89]
	v_mfma_f32_16x16x32_bf16 v[78:81], v[158:161], v[210:213], v[78:81]
	v_mfma_f32_16x16x32_bf16 v[70:73], v[150:153], v[218:221], v[70:73]
	v_mfma_f32_16x16x32_bf16 v[66:69], v[158:161], v[218:221], v[66:69]
	s_setprio 0
	s_barrier
	s_add_i32 s63, s63, s86
	v_lshl_add_u64 v[186:187], v[186:187], 0, s[22:23]
	s_mov_b32 m0, s63
	ds_read_b128 v[162:165], v192 offset:49152
	ds_read_b128 v[166:169], v192 offset:50176
	ds_read_b128 v[194:197], v192 offset:51200
	ds_read_b128 v[198:201], v192 offset:52224
	ds_read_b128 v[206:209], v192 offset:53248
	ds_read_b128 v[210:213], v192 offset:54272
	ds_read_b128 v[214:217], v192 offset:55296
	ds_read_b128 v[218:221], v192 offset:56320
	global_load_lds_dwordx4 v[186:187], off
	s_add_i32 m0, s63, 0x2000
	s_add_u32 s78, s78, 0x40080
	v_lshl_add_u64 v[186:187], v[202:203], 0, s[22:23]
	s_addc_u32 s79, s79, 0
	s_add_i32 s63, s83, s86
	global_load_lds_dwordx4 v[186:187], off
	v_lshl_add_u64 v[186:187], s[78:79], 0, v[172:173]
	s_mov_b32 m0, s63
	s_nop 0
	global_load_lds_dwordx4 v[186:187], off
	v_lshl_add_u64 v[186:187], s[78:79], 0, v[176:177]
	s_add_i32 m0, s63, 0x2000
	s_nop 0
	global_load_lds_dwordx4 v[186:187], off
	v_lshl_add_u64 v[186:187], v[222:223], 0, s[22:23]
	s_mov_b32 m0, s95
	s_nop 0
	global_load_lds_dwordx4 v[186:187], off
	v_lshl_add_u64 v[186:187], v[224:225], 0, s[22:23]
	s_waitcnt vmcnt(7)
	s_waitcnt lgkmcnt(0)
	s_barrier
	s_setprio 1
	s_waitcnt lgkmcnt(0)
	v_mfma_f32_16x16x32_bf16 v[62:65], v[114:117], v[162:165], v[62:65]
	v_mfma_f32_16x16x32_bf16 v[58:61], v[122:125], v[162:165], v[58:61]
	v_mfma_f32_16x16x32_bf16 v[50:53], v[114:117], v[194:197], v[50:53]
	v_mfma_f32_16x16x32_bf16 v[42:45], v[122:125], v[194:197], v[42:45]
	v_mfma_f32_16x16x32_bf16 v[34:37], v[114:117], v[206:209], v[34:37]
	v_mfma_f32_16x16x32_bf16 v[26:29], v[122:125], v[206:209], v[26:29]
	v_mfma_f32_16x16x32_bf16 v[18:21], v[114:117], v[214:217], v[18:21]
	v_mfma_f32_16x16x32_bf16 v[10:13], v[122:125], v[214:217], v[10:13]
	s_mov_b32 m0, s96
	s_nop 0
	global_load_lds_dwordx4 v[186:187], off
	v_mfma_f32_16x16x32_bf16 v[62:65], v[118:121], v[166:169], v[62:65]
	v_mfma_f32_16x16x32_bf16 v[58:61], v[126:129], v[166:169], v[58:61]
	v_mfma_f32_16x16x32_bf16 v[50:53], v[118:121], v[198:201], v[50:53]
	v_mfma_f32_16x16x32_bf16 v[42:45], v[126:129], v[198:201], v[42:45]
	v_mfma_f32_16x16x32_bf16 v[34:37], v[118:121], v[210:213], v[34:37]
	v_mfma_f32_16x16x32_bf16 v[26:29], v[126:129], v[210:213], v[26:29]
	v_mfma_f32_16x16x32_bf16 v[18:21], v[118:121], v[218:221], v[18:21]
	v_mfma_f32_16x16x32_bf16 v[10:13], v[126:129], v[218:221], v[10:13]
	s_setprio 0
	s_setprio 1
	v_mfma_f32_16x16x32_bf16 v[54:57], v[146:149], v[162:165], v[54:57]
	v_mfma_f32_16x16x32_bf16 v[46:49], v[154:157], v[162:165], v[46:49]
	v_mfma_f32_16x16x32_bf16 v[38:41], v[146:149], v[194:197], v[38:41]
	v_mfma_f32_16x16x32_bf16 v[30:33], v[154:157], v[194:197], v[30:33]
	v_mfma_f32_16x16x32_bf16 v[22:25], v[146:149], v[206:209], v[22:25]
	v_mfma_f32_16x16x32_bf16 v[14:17], v[154:157], v[206:209], v[14:17]
	v_mfma_f32_16x16x32_bf16 v[6:9], v[146:149], v[214:217], v[6:9]
	v_mfma_f32_16x16x32_bf16 v[2:5], v[154:157], v[214:217], v[2:5]
	v_mfma_f32_16x16x32_bf16 v[54:57], v[150:153], v[166:169], v[54:57]
	v_mfma_f32_16x16x32_bf16 v[46:49], v[158:161], v[166:169], v[46:49]
	v_mfma_f32_16x16x32_bf16 v[38:41], v[150:153], v[198:201], v[38:41]
	v_mfma_f32_16x16x32_bf16 v[30:33], v[158:161], v[198:201], v[30:33]
	v_mfma_f32_16x16x32_bf16 v[22:25], v[150:153], v[210:213], v[22:25]
	v_mfma_f32_16x16x32_bf16 v[14:17], v[158:161], v[210:213], v[14:17]
	v_mfma_f32_16x16x32_bf16 v[6:9], v[150:153], v[218:221], v[6:9]
	v_mfma_f32_16x16x32_bf16 v[2:5], v[158:161], v[218:221], v[2:5]
	s_setprio 0
	s_barrier
	s_add_u32 s76, s76, 0x100
	s_addc_u32 s77, s77, 0
	s_add_u32 s47, s47, 0x100
	s_addc_u32 s62, s62, 0
	s_cmp_ge_i32 s82, s7
	s_mov_b32 s63, s82
	s_cbranch_scc0 .LBB0_566
	s_and_b64 vcc, exec, s[26:27]
	s_cbranch_vccz .LBB0_569
	s_barrier

.LBB0_744:
	s_add_u32 s36, s96, s22
	s_addc_u32 s37, s97, s23
	s_and_b64 s[14:15], s[4:5], exec
	s_cselect_b32 s14, s37, s43
	s_cselect_b32 s15, s36, s42
	s_add_u32 s38, s2, s26
	s_addc_u32 s39, s3, s27
	s_and_b64 s[46:47], s[4:5], exec
	s_cselect_b32 s21, s39, s45
	s_cselect_b32 s65, s38, s44
	s_add_u32 s42, s42, 0x40080
	s_addc_u32 s43, s43, 0
	s_add_u32 s66, s44, 0x100
	s_addc_u32 s67, s45, 0
	s_mov_b32 s68, -2
	ds_read_b128 v[154:157], v150
	ds_read_b128 v[158:161], v150 offset:1024
	ds_read_b128 v[162:165], v150 offset:2048
	ds_read_b128 v[166:169], v150 offset:3072
	ds_read_b128 v[170:173], v151
	ds_read_b128 v[174:177], v151 offset:1024
	ds_read_b128 v[178:181], v151 offset:2048
	ds_read_b128 v[182:185], v151 offset:3072
	s_add_u32 s44, s42, 0xfffc0080
	s_addc_u32 s45, s43, -1
	s_cmp_eq_u32 s68, 12
	s_cselect_b32 s47, s14, s45
	s_cselect_b32 s46, s15, s44
	s_cselect_b32 s45, s21, s67
	s_cselect_b32 s44, s65, s66
	v_lshl_add_u64 v[146:147], s[42:43], 0, v[138:139]
	s_add_i32 m0, s19, 0xc000
	ds_read_b128 v[186:189], v152
	ds_read_b128 v[190:193], v152 offset:1024
	ds_read_b128 v[194:197], v152 offset:2048
	ds_read_b128 v[198:201], v152 offset:3072
	ds_read_b128 v[206:209], v152 offset:4096
	ds_read_b128 v[210:213], v152 offset:5120
	ds_read_b128 v[214:217], v152 offset:6144
	ds_read_b128 v[218:221], v152 offset:7168
	global_load_lds_dwordx4 v[146:147], off
	v_lshl_add_u64 v[146:147], s[42:43], 0, v[140:141]
	s_add_i32 m0, s19, 0xe000
	s_nop 0
	global_load_lds_dwordx4 v[146:147], off
	s_waitcnt vmcnt(8)
	s_waitcnt lgkmcnt(0)
	s_barrier
	s_setprio 1
	s_waitcnt lgkmcnt(0)
	v_mfma_f32_16x16x32_bf16 v[126:129], v[154:157], v[186:189], 0
	v_mfma_f32_16x16x32_bf16 v[122:125], v[162:165], v[186:189], 0
	v_mfma_f32_16x16x32_bf16 v[110:113], v[154:157], v[194:197], 0
	v_mfma_f32_16x16x32_bf16 v[106:109], v[162:165], v[194:197], 0
	v_mfma_f32_16x16x32_bf16 v[94:97], v[154:157], v[206:209], 0
	v_mfma_f32_16x16x32_bf16 v[90:93], v[162:165], v[206:209], 0
	v_mfma_f32_16x16x32_bf16 v[78:81], v[154:157], v[214:217], 0
	v_mfma_f32_16x16x32_bf16 v[74:77], v[162:165], v[214:217], 0
	v_mfma_f32_16x16x32_bf16 v[126:129], v[158:161], v[190:193], v[126:129]
	v_mfma_f32_16x16x32_bf16 v[122:125], v[166:169], v[190:193], v[122:125]
	v_mfma_f32_16x16x32_bf16 v[110:113], v[158:161], v[198:201], v[110:113]
	v_mfma_f32_16x16x32_bf16 v[106:109], v[166:169], v[198:201], v[106:109]
	v_mfma_f32_16x16x32_bf16 v[94:97], v[158:161], v[210:213], v[94:97]
	v_mfma_f32_16x16x32_bf16 v[90:93], v[166:169], v[210:213], v[90:93]
	v_mfma_f32_16x16x32_bf16 v[78:81], v[158:161], v[218:221], v[78:81]
	v_mfma_f32_16x16x32_bf16 v[74:77], v[166:169], v[218:221], v[74:77]
	s_setprio 0
	s_setprio 1
	v_mfma_f32_16x16x32_bf16 v[118:121], v[170:173], v[186:189], 0
	v_mfma_f32_16x16x32_bf16 v[114:117], v[178:181], v[186:189], 0
	v_mfma_f32_16x16x32_bf16 v[102:105], v[170:173], v[194:197], 0
	v_mfma_f32_16x16x32_bf16 v[98:101], v[178:181], v[194:197], 0
	v_mfma_f32_16x16x32_bf16 v[86:89], v[170:173], v[206:209], 0
	v_mfma_f32_16x16x32_bf16 v[82:85], v[178:181], v[206:209], 0
	v_mfma_f32_16x16x32_bf16 v[70:73], v[170:173], v[214:217], 0
	v_mfma_f32_16x16x32_bf16 v[66:69], v[178:181], v[214:217], 0
	v_mfma_f32_16x16x32_bf16 v[118:121], v[174:177], v[190:193], v[118:121]
	v_mfma_f32_16x16x32_bf16 v[114:117], v[182:185], v[190:193], v[114:117]
	v_mfma_f32_16x16x32_bf16 v[102:105], v[174:177], v[198:201], v[102:105]
	v_mfma_f32_16x16x32_bf16 v[98:101], v[182:185], v[198:201], v[98:101]
	v_mfma_f32_16x16x32_bf16 v[86:89], v[174:177], v[210:213], v[86:89]
	v_mfma_f32_16x16x32_bf16 v[82:85], v[182:185], v[210:213], v[82:85]
	v_mfma_f32_16x16x32_bf16 v[70:73], v[174:177], v[218:221], v[70:73]
	v_mfma_f32_16x16x32_bf16 v[66:69], v[182:185], v[218:221], v[66:69]
	s_setprio 0
	s_barrier
	s_add_i32 s69, s49, s16
	v_lshl_add_u64 v[146:147], s[44:45], 0, v[134:135]
	s_mov_b32 m0, s69
	ds_read_b128 v[186:189], v152 offset:16384
	ds_read_b128 v[190:193], v152 offset:17408
	ds_read_b128 v[194:197], v152 offset:18432
	ds_read_b128 v[198:201], v152 offset:19456
	ds_read_b128 v[206:209], v152 offset:20480
	ds_read_b128 v[210:213], v152 offset:21504
	ds_read_b128 v[214:217], v152 offset:22528
	ds_read_b128 v[218:221], v152 offset:23552
	global_load_lds_dwordx4 v[146:147], off
	s_add_i32 m0, s69, 0x2000
	s_add_u32 s70, s44, 0x40000
	v_lshl_add_u64 v[202:203], s[44:45], 0, v[130:131]
	s_addc_u32 s71, s45, 0
	s_add_i32 s69, s62, s16
	global_load_lds_dwordx4 v[202:203], off
	v_lshl_add_u64 v[222:223], s[70:71], 0, v[134:135]
	s_mov_b32 m0, s69
	v_lshl_add_u64 v[224:225], s[46:47], 0, v[132:133]
	global_load_lds_dwordx4 v[222:223], off
	v_lshl_add_u64 v[222:223], s[70:71], 0, v[130:131]
	s_add_i32 m0, s69, 0x2000
	s_nop 0
	global_load_lds_dwordx4 v[222:223], off
	v_lshl_add_u64 v[222:223], s[46:47], 0, v[136:137]
	s_mov_b32 m0, s19
	s_nop 0
	global_load_lds_dwordx4 v[222:223], off
	s_waitcnt vmcnt(7)
	s_waitcnt lgkmcnt(0)
	s_barrier
	s_setprio 1
	s_waitcnt lgkmcnt(0)
	v_mfma_f32_16x16x32_bf16 v[62:65], v[154:157], v[186:189], 0
	v_mfma_f32_16x16x32_bf16 v[58:61], v[162:165], v[186:189], 0
	v_mfma_f32_16x16x32_bf16 v[46:49], v[154:157], v[194:197], 0
	v_mfma_f32_16x16x32_bf16 v[42:45], v[162:165], v[194:197], 0
	v_mfma_f32_16x16x32_bf16 v[30:33], v[154:157], v[206:209], 0
	v_mfma_f32_16x16x32_bf16 v[26:29], v[162:165], v[206:209], 0
	v_mfma_f32_16x16x32_bf16 v[14:17], v[154:157], v[214:217], 0
	v_mfma_f32_16x16x32_bf16 v[10:13], v[162:165], v[214:217], 0
	s_mov_b32 m0, s24
	s_nop 0
	global_load_lds_dwordx4 v[224:225], off
	v_mfma_f32_16x16x32_bf16 v[62:65], v[158:161], v[190:193], v[62:65]
	v_mfma_f32_16x16x32_bf16 v[58:61], v[166:169], v[190:193], v[58:61]
	v_mfma_f32_16x16x32_bf16 v[46:49], v[158:161], v[198:201], v[46:49]
	v_mfma_f32_16x16x32_bf16 v[42:45], v[166:169], v[198:201], v[42:45]
	v_mfma_f32_16x16x32_bf16 v[30:33], v[158:161], v[210:213], v[30:33]
	v_mfma_f32_16x16x32_bf16 v[26:29], v[166:169], v[210:213], v[26:29]
	v_mfma_f32_16x16x32_bf16 v[14:17], v[158:161], v[218:221], v[14:17]
	v_mfma_f32_16x16x32_bf16 v[10:13], v[166:169], v[218:221], v[10:13]
	s_setprio 0
	s_setprio 1
	v_mfma_f32_16x16x32_bf16 v[54:57], v[170:173], v[186:189], 0
	v_mfma_f32_16x16x32_bf16 v[50:53], v[178:181], v[186:189], 0
	v_mfma_f32_16x16x32_bf16 v[38:41], v[170:173], v[194:197], 0
	v_mfma_f32_16x16x32_bf16 v[34:37], v[178:181], v[194:197], 0
	v_mfma_f32_16x16x32_bf16 v[22:25], v[170:173], v[206:209], 0
	v_mfma_f32_16x16x32_bf16 v[18:21], v[178:181], v[206:209], 0
	v_mfma_f32_16x16x32_bf16 v[6:9], v[170:173], v[214:217], 0
	v_mfma_f32_16x16x32_bf16 v[2:5], v[178:181], v[214:217], 0
	v_mfma_f32_16x16x32_bf16 v[54:57], v[174:177], v[190:193], v[54:57]
	v_mfma_f32_16x16x32_bf16 v[50:53], v[182:185], v[190:193], v[50:53]
	v_mfma_f32_16x16x32_bf16 v[38:41], v[174:177], v[198:201], v[38:41]
	v_mfma_f32_16x16x32_bf16 v[34:37], v[182:185], v[198:201], v[34:37]
	v_mfma_f32_16x16x32_bf16 v[22:25], v[174:177], v[210:213], v[22:25]
	v_mfma_f32_16x16x32_bf16 v[18:21], v[182:185], v[210:213], v[18:21]
	v_mfma_f32_16x16x32_bf16 v[6:9], v[174:177], v[218:221], v[6:9]
	v_mfma_f32_16x16x32_bf16 v[2:5], v[182:185], v[218:221], v[2:5]
	s_setprio 0
	s_barrier
	s_add_i32 s69, 0, 0x18000
	v_add_u32_e32 v153, s69, v149
	s_add_i32 s70, 0, 0x1c000
	ds_read_b128 v[154:157], v153
	ds_read_b128 v[158:161], v153 offset:1024
	ds_read_b128 v[162:165], v153 offset:2048
	ds_read_b128 v[166:169], v153 offset:3072
	v_add_u32_e32 v153, s70, v149
	ds_read_b128 v[170:173], v153
	ds_read_b128 v[174:177], v153 offset:1024
	ds_read_b128 v[178:181], v153 offset:2048
	ds_read_b128 v[182:185], v153 offset:3072
	s_add_u32 s46, s46, 0x40000
	s_addc_u32 s47, s47, 0
	s_mov_b32 m0, s25
	v_lshl_add_u64 v[226:227], s[46:47], 0, v[136:137]
	ds_read_b128 v[186:189], v152 offset:32768
	ds_read_b128 v[190:193], v152 offset:33792
	ds_read_b128 v[194:197], v152 offset:34816
	ds_read_b128 v[198:201], v152 offset:35840
	ds_read_b128 v[206:209], v152 offset:36864
	ds_read_b128 v[210:213], v152 offset:37888
	ds_read_b128 v[214:217], v152 offset:38912
	ds_read_b128 v[218:221], v152 offset:39936
	global_load_lds_dwordx4 v[226:227], off
	v_lshl_add_u64 v[226:227], s[46:47], 0, v[132:133]
	s_mov_b32 m0, s28
	s_nop 0
	global_load_lds_dwordx4 v[226:227], off
	s_waitcnt vmcnt(8)
	s_waitcnt lgkmcnt(0)
	s_barrier
	s_setprio 1
	s_waitcnt lgkmcnt(0)
	v_mfma_f32_16x16x32_bf16 v[126:129], v[154:157], v[186:189], v[126:129]
	v_mfma_f32_16x16x32_bf16 v[122:125], v[162:165], v[186:189], v[122:125]
	v_mfma_f32_16x16x32_bf16 v[110:113], v[154:157], v[194:197], v[110:113]
	v_mfma_f32_16x16x32_bf16 v[106:109], v[162:165], v[194:197], v[106:109]
	v_mfma_f32_16x16x32_bf16 v[94:97], v[154:157], v[206:209], v[94:97]
	v_mfma_f32_16x16x32_bf16 v[90:93], v[162:165], v[206:209], v[90:93]
	v_mfma_f32_16x16x32_bf16 v[78:81], v[154:157], v[214:217], v[78:81]
	v_mfma_f32_16x16x32_bf16 v[74:77], v[162:165], v[214:217], v[74:77]
	v_mfma_f32_16x16x32_bf16 v[126:129], v[158:161], v[190:193], v[126:129]
	v_mfma_f32_16x16x32_bf16 v[122:125], v[166:169], v[190:193], v[122:125]
	v_mfma_f32_16x16x32_bf16 v[110:113], v[158:161], v[198:201], v[110:113]
	v_mfma_f32_16x16x32_bf16 v[106:109], v[166:169], v[198:201], v[106:109]
	v_mfma_f32_16x16x32_bf16 v[94:97], v[158:161], v[210:213], v[94:97]
	v_mfma_f32_16x16x32_bf16 v[90:93], v[166:169], v[210:213], v[90:93]
	v_mfma_f32_16x16x32_bf16 v[78:81], v[158:161], v[218:221], v[78:81]
	v_mfma_f32_16x16x32_bf16 v[74:77], v[166:169], v[218:221], v[74:77]
	s_setprio 0
	s_setprio 1
	v_mfma_f32_16x16x32_bf16 v[118:121], v[170:173], v[186:189], v[118:121]
	v_mfma_f32_16x16x32_bf16 v[114:117], v[178:181], v[186:189], v[114:117]
	v_mfma_f32_16x16x32_bf16 v[102:105], v[170:173], v[194:197], v[102:105]
	v_mfma_f32_16x16x32_bf16 v[98:101], v[178:181], v[194:197], v[98:101]
	v_mfma_f32_16x16x32_bf16 v[86:89], v[170:173], v[206:209], v[86:89]
	v_mfma_f32_16x16x32_bf16 v[82:85], v[178:181], v[206:209], v[82:85]
	v_mfma_f32_16x16x32_bf16 v[70:73], v[170:173], v[214:217], v[70:73]
	v_mfma_f32_16x16x32_bf16 v[66:69], v[178:181], v[214:217], v[66:69]
	v_mfma_f32_16x16x32_bf16 v[118:121], v[174:177], v[190:193], v[118:121]
	v_mfma_f32_16x16x32_bf16 v[114:117], v[182:185], v[190:193], v[114:117]
	v_mfma_f32_16x16x32_bf16 v[102:105], v[174:177], v[198:201], v[102:105]
	v_mfma_f32_16x16x32_bf16 v[98:101], v[182:185], v[198:201], v[98:101]
	v_mfma_f32_16x16x32_bf16 v[86:89], v[174:177], v[210:213], v[86:89]
	v_mfma_f32_16x16x32_bf16 v[82:85], v[182:185], v[210:213], v[82:85]
	v_mfma_f32_16x16x32_bf16 v[70:73], v[174:177], v[218:221], v[70:73]
	v_mfma_f32_16x16x32_bf16 v[66:69], v[182:185], v[218:221], v[66:69]
	s_setprio 0
	s_barrier
	s_add_i32 s46, s69, s16
	v_lshl_add_u64 v[146:147], v[146:147], 0, s[10:11]
	s_mov_b32 m0, s46
	ds_read_b128 v[186:189], v152 offset:49152
	ds_read_b128 v[190:193], v152 offset:50176
	ds_read_b128 v[194:197], v152 offset:51200
	ds_read_b128 v[198:201], v152 offset:52224
	ds_read_b128 v[206:209], v152 offset:53248
	ds_read_b128 v[210:213], v152 offset:54272
	ds_read_b128 v[214:217], v152 offset:55296
	ds_read_b128 v[218:221], v152 offset:56320
	global_load_lds_dwordx4 v[146:147], off
	s_add_i32 m0, s46, 0x2000
	s_add_u32 s44, s44, 0x40080
	v_lshl_add_u64 v[146:147], v[202:203], 0, s[10:11]
	s_addc_u32 s45, s45, 0
	s_add_i32 s46, s70, s16
	global_load_lds_dwordx4 v[146:147], off
	v_lshl_add_u64 v[146:147], s[44:45], 0, v[134:135]
	s_mov_b32 m0, s46
	s_nop 0
	global_load_lds_dwordx4 v[146:147], off
	v_lshl_add_u64 v[146:147], s[44:45], 0, v[130:131]
	s_add_i32 m0, s46, 0x2000
	s_nop 0
	global_load_lds_dwordx4 v[146:147], off
	v_lshl_add_u64 v[146:147], v[222:223], 0, s[10:11]
	s_mov_b32 m0, s33
	s_nop 0
	global_load_lds_dwordx4 v[146:147], off
	v_lshl_add_u64 v[146:147], v[224:225], 0, s[10:11]
	s_waitcnt vmcnt(7)
	s_waitcnt lgkmcnt(0)
	s_barrier
	s_setprio 1
	s_waitcnt lgkmcnt(0)
	v_mfma_f32_16x16x32_bf16 v[62:65], v[154:157], v[186:189], v[62:65]
	v_mfma_f32_16x16x32_bf16 v[58:61], v[162:165], v[186:189], v[58:61]
	v_mfma_f32_16x16x32_bf16 v[46:49], v[154:157], v[194:197], v[46:49]
	v_mfma_f32_16x16x32_bf16 v[42:45], v[162:165], v[194:197], v[42:45]
	v_mfma_f32_16x16x32_bf16 v[30:33], v[154:157], v[206:209], v[30:33]
	v_mfma_f32_16x16x32_bf16 v[26:29], v[162:165], v[206:209], v[26:29]
	v_mfma_f32_16x16x32_bf16 v[14:17], v[154:157], v[214:217], v[14:17]
	v_mfma_f32_16x16x32_bf16 v[10:13], v[162:165], v[214:217], v[10:13]
	s_mov_b32 m0, s35
	s_nop 0
	global_load_lds_dwordx4 v[146:147], off
	v_mfma_f32_16x16x32_bf16 v[62:65], v[158:161], v[190:193], v[62:65]
	v_mfma_f32_16x16x32_bf16 v[58:61], v[166:169], v[190:193], v[58:61]
	v_mfma_f32_16x16x32_bf16 v[46:49], v[158:161], v[198:201], v[46:49]
	v_mfma_f32_16x16x32_bf16 v[42:45], v[166:169], v[198:201], v[42:45]
	v_mfma_f32_16x16x32_bf16 v[30:33], v[158:161], v[210:213], v[30:33]
	v_mfma_f32_16x16x32_bf16 v[26:29], v[166:169], v[210:213], v[26:29]
	v_mfma_f32_16x16x32_bf16 v[14:17], v[158:161], v[218:221], v[14:17]
	v_mfma_f32_16x16x32_bf16 v[10:13], v[166:169], v[218:221], v[10:13]
	s_setprio 0
	s_setprio 1
	v_mfma_f32_16x16x32_bf16 v[54:57], v[170:173], v[186:189], v[54:57]
	v_mfma_f32_16x16x32_bf16 v[50:53], v[178:181], v[186:189], v[50:53]
	v_mfma_f32_16x16x32_bf16 v[38:41], v[170:173], v[194:197], v[38:41]
	v_mfma_f32_16x16x32_bf16 v[34:37], v[178:181], v[194:197], v[34:37]
	v_mfma_f32_16x16x32_bf16 v[22:25], v[170:173], v[206:209], v[22:25]
	v_mfma_f32_16x16x32_bf16 v[18:21], v[178:181], v[206:209], v[18:21]
	v_mfma_f32_16x16x32_bf16 v[6:9], v[170:173], v[214:217], v[6:9]
	v_mfma_f32_16x16x32_bf16 v[2:5], v[178:181], v[214:217], v[2:5]
	v_mfma_f32_16x16x32_bf16 v[54:57], v[174:177], v[190:193], v[54:57]
	v_mfma_f32_16x16x32_bf16 v[50:53], v[182:185], v[190:193], v[50:53]
	v_mfma_f32_16x16x32_bf16 v[38:41], v[174:177], v[198:201], v[38:41]
	v_mfma_f32_16x16x32_bf16 v[34:37], v[182:185], v[198:201], v[34:37]
	v_mfma_f32_16x16x32_bf16 v[22:25], v[174:177], v[210:213], v[22:25]
	v_mfma_f32_16x16x32_bf16 v[18:21], v[182:185], v[210:213], v[18:21]
	v_mfma_f32_16x16x32_bf16 v[6:9], v[174:177], v[218:221], v[6:9]
	v_mfma_f32_16x16x32_bf16 v[2:5], v[182:185], v[218:221], v[2:5]
	s_setprio 0
	s_barrier
	s_add_i32 s68, s68, 2
	s_add_u32 s42, s42, 0x100
	s_addc_u32 s43, s43, 0
	s_add_u32 s66, s66, 0x100
	s_addc_u32 s67, s67, 0
	s_cmp_gt_u32 s68, 13
.LBB0_745:
	ds_read_b128 v[154:157], v150
	ds_read_b128 v[158:161], v150 offset:1024
	ds_read_b128 v[162:165], v150 offset:2048
	ds_read_b128 v[166:169], v150 offset:3072
	ds_read_b128 v[170:173], v151
	ds_read_b128 v[174:177], v151 offset:1024
	ds_read_b128 v[178:181], v151 offset:2048
	ds_read_b128 v[182:185], v151 offset:3072
	s_add_u32 s44, s42, 0xfffc0080
	s_addc_u32 s45, s43, -1
	s_cmp_eq_u32 s68, 12
	s_cselect_b32 s47, s14, s45
	s_cselect_b32 s46, s15, s44
	s_cselect_b32 s45, s21, s67
	s_cselect_b32 s44, s65, s66
	v_lshl_add_u64 v[146:147], s[42:43], 0, v[138:139]
	s_add_i32 m0, s19, 0xc000
	ds_read_b128 v[186:189], v152
	ds_read_b128 v[190:193], v152 offset:1024
	ds_read_b128 v[194:197], v152 offset:2048
	ds_read_b128 v[198:201], v152 offset:3072
	ds_read_b128 v[206:209], v152 offset:4096
	ds_read_b128 v[210:213], v152 offset:5120
	ds_read_b128 v[214:217], v152 offset:6144
	ds_read_b128 v[218:221], v152 offset:7168
	global_load_lds_dwordx4 v[146:147], off
	v_lshl_add_u64 v[146:147], s[42:43], 0, v[140:141]
	s_add_i32 m0, s19, 0xe000
	s_nop 0
	global_load_lds_dwordx4 v[146:147], off
	s_waitcnt vmcnt(8)
	s_waitcnt lgkmcnt(0)
	s_barrier
	s_setprio 1
	s_waitcnt lgkmcnt(0)
	v_mfma_f32_16x16x32_bf16 v[126:129], v[154:157], v[186:189], v[126:129]
	v_mfma_f32_16x16x32_bf16 v[122:125], v[162:165], v[186:189], v[122:125]
	v_mfma_f32_16x16x32_bf16 v[110:113], v[154:157], v[194:197], v[110:113]
	v_mfma_f32_16x16x32_bf16 v[106:109], v[162:165], v[194:197], v[106:109]
	v_mfma_f32_16x16x32_bf16 v[94:97], v[154:157], v[206:209], v[94:97]
	v_mfma_f32_16x16x32_bf16 v[90:93], v[162:165], v[206:209], v[90:93]
	v_mfma_f32_16x16x32_bf16 v[78:81], v[154:157], v[214:217], v[78:81]
	v_mfma_f32_16x16x32_bf16 v[74:77], v[162:165], v[214:217], v[74:77]
	v_mfma_f32_16x16x32_bf16 v[126:129], v[158:161], v[190:193], v[126:129]
	v_mfma_f32_16x16x32_bf16 v[122:125], v[166:169], v[190:193], v[122:125]
	v_mfma_f32_16x16x32_bf16 v[110:113], v[158:161], v[198:201], v[110:113]
	v_mfma_f32_16x16x32_bf16 v[106:109], v[166:169], v[198:201], v[106:109]
	v_mfma_f32_16x16x32_bf16 v[94:97], v[158:161], v[210:213], v[94:97]
	v_mfma_f32_16x16x32_bf16 v[90:93], v[166:169], v[210:213], v[90:93]
	v_mfma_f32_16x16x32_bf16 v[78:81], v[158:161], v[218:221], v[78:81]
	v_mfma_f32_16x16x32_bf16 v[74:77], v[166:169], v[218:221], v[74:77]
	s_setprio 0
	s_setprio 1
	v_mfma_f32_16x16x32_bf16 v[118:121], v[170:173], v[186:189], v[118:121]
	v_mfma_f32_16x16x32_bf16 v[114:117], v[178:181], v[186:189], v[114:117]
	v_mfma_f32_16x16x32_bf16 v[102:105], v[170:173], v[194:197], v[102:105]
	v_mfma_f32_16x16x32_bf16 v[98:101], v[178:181], v[194:197], v[98:101]
	v_mfma_f32_16x16x32_bf16 v[86:89], v[170:173], v[206:209], v[86:89]
	v_mfma_f32_16x16x32_bf16 v[82:85], v[178:181], v[206:209], v[82:85]
	v_mfma_f32_16x16x32_bf16 v[70:73], v[170:173], v[214:217], v[70:73]
	v_mfma_f32_16x16x32_bf16 v[66:69], v[178:181], v[214:217], v[66:69]
	v_mfma_f32_16x16x32_bf16 v[118:121], v[174:177], v[190:193], v[118:121]
	v_mfma_f32_16x16x32_bf16 v[114:117], v[182:185], v[190:193], v[114:117]
	v_mfma_f32_16x16x32_bf16 v[102:105], v[174:177], v[198:201], v[102:105]
	v_mfma_f32_16x16x32_bf16 v[98:101], v[182:185], v[198:201], v[98:101]
	v_mfma_f32_16x16x32_bf16 v[86:89], v[174:177], v[210:213], v[86:89]
	v_mfma_f32_16x16x32_bf16 v[82:85], v[182:185], v[210:213], v[82:85]
	v_mfma_f32_16x16x32_bf16 v[70:73], v[174:177], v[218:221], v[70:73]
	v_mfma_f32_16x16x32_bf16 v[66:69], v[182:185], v[218:221], v[66:69]
	s_setprio 0
	s_barrier
	s_add_i32 s69, s49, s16
	v_lshl_add_u64 v[146:147], s[44:45], 0, v[134:135]
	s_mov_b32 m0, s69
	ds_read_b128 v[186:189], v152 offset:16384
	ds_read_b128 v[190:193], v152 offset:17408
	ds_read_b128 v[194:197], v152 offset:18432
	ds_read_b128 v[198:201], v152 offset:19456
	ds_read_b128 v[206:209], v152 offset:20480
	ds_read_b128 v[210:213], v152 offset:21504
	ds_read_b128 v[214:217], v152 offset:22528
	ds_read_b128 v[218:221], v152 offset:23552
	global_load_lds_dwordx4 v[146:147], off
	s_add_i32 m0, s69, 0x2000
	s_add_u32 s70, s44, 0x40000
	v_lshl_add_u64 v[202:203], s[44:45], 0, v[130:131]
	s_addc_u32 s71, s45, 0
	s_add_i32 s69, s62, s16
	global_load_lds_dwordx4 v[202:203], off
	v_lshl_add_u64 v[222:223], s[70:71], 0, v[134:135]
	s_mov_b32 m0, s69
	v_lshl_add_u64 v[224:225], s[46:47], 0, v[132:133]
	global_load_lds_dwordx4 v[222:223], off
	v_lshl_add_u64 v[222:223], s[70:71], 0, v[130:131]
	s_add_i32 m0, s69, 0x2000
	s_nop 0
	global_load_lds_dwordx4 v[222:223], off
	v_lshl_add_u64 v[222:223], s[46:47], 0, v[136:137]
	s_mov_b32 m0, s19
	s_nop 0
	global_load_lds_dwordx4 v[222:223], off
	s_waitcnt vmcnt(7)
	s_waitcnt lgkmcnt(0)
	s_barrier
	s_setprio 1
	s_waitcnt lgkmcnt(0)
	v_mfma_f32_16x16x32_bf16 v[62:65], v[154:157], v[186:189], v[62:65]
	v_mfma_f32_16x16x32_bf16 v[58:61], v[162:165], v[186:189], v[58:61]
	v_mfma_f32_16x16x32_bf16 v[46:49], v[154:157], v[194:197], v[46:49]
	v_mfma_f32_16x16x32_bf16 v[42:45], v[162:165], v[194:197], v[42:45]
	v_mfma_f32_16x16x32_bf16 v[30:33], v[154:157], v[206:209], v[30:33]
	v_mfma_f32_16x16x32_bf16 v[26:29], v[162:165], v[206:209], v[26:29]
	v_mfma_f32_16x16x32_bf16 v[14:17], v[154:157], v[214:217], v[14:17]
	v_mfma_f32_16x16x32_bf16 v[10:13], v[162:165], v[214:217], v[10:13]
	s_mov_b32 m0, s24
	s_nop 0
	global_load_lds_dwordx4 v[224:225], off
	v_mfma_f32_16x16x32_bf16 v[62:65], v[158:161], v[190:193], v[62:65]
	v_mfma_f32_16x16x32_bf16 v[58:61], v[166:169], v[190:193], v[58:61]
	v_mfma_f32_16x16x32_bf16 v[46:49], v[158:161], v[198:201], v[46:49]
	v_mfma_f32_16x16x32_bf16 v[42:45], v[166:169], v[198:201], v[42:45]
	v_mfma_f32_16x16x32_bf16 v[30:33], v[158:161], v[210:213], v[30:33]
	v_mfma_f32_16x16x32_bf16 v[26:29], v[166:169], v[210:213], v[26:29]
	v_mfma_f32_16x16x32_bf16 v[14:17], v[158:161], v[218:221], v[14:17]
	v_mfma_f32_16x16x32_bf16 v[10:13], v[166:169], v[218:221], v[10:13]
	s_setprio 0
	s_setprio 1
	v_mfma_f32_16x16x32_bf16 v[54:57], v[170:173], v[186:189], v[54:57]
	v_mfma_f32_16x16x32_bf16 v[50:53], v[178:181], v[186:189], v[50:53]
	v_mfma_f32_16x16x32_bf16 v[38:41], v[170:173], v[194:197], v[38:41]
	v_mfma_f32_16x16x32_bf16 v[34:37], v[178:181], v[194:197], v[34:37]
	v_mfma_f32_16x16x32_bf16 v[22:25], v[170:173], v[206:209], v[22:25]
	v_mfma_f32_16x16x32_bf16 v[18:21], v[178:181], v[206:209], v[18:21]
	v_mfma_f32_16x16x32_bf16 v[6:9], v[170:173], v[214:217], v[6:9]
	v_mfma_f32_16x16x32_bf16 v[2:5], v[178:181], v[214:217], v[2:5]
	v_mfma_f32_16x16x32_bf16 v[54:57], v[174:177], v[190:193], v[54:57]
	v_mfma_f32_16x16x32_bf16 v[50:53], v[182:185], v[190:193], v[50:53]
	v_mfma_f32_16x16x32_bf16 v[38:41], v[174:177], v[198:201], v[38:41]
	v_mfma_f32_16x16x32_bf16 v[34:37], v[182:185], v[198:201], v[34:37]
	v_mfma_f32_16x16x32_bf16 v[22:25], v[174:177], v[210:213], v[22:25]
	v_mfma_f32_16x16x32_bf16 v[18:21], v[182:185], v[210:213], v[18:21]
	v_mfma_f32_16x16x32_bf16 v[6:9], v[174:177], v[218:221], v[6:9]
	v_mfma_f32_16x16x32_bf16 v[2:5], v[182:185], v[218:221], v[2:5]
	s_setprio 0
	s_barrier
	s_add_i32 s69, 0, 0x18000
	v_add_u32_e32 v153, s69, v149
	s_add_i32 s70, 0, 0x1c000
	ds_read_b128 v[154:157], v153
	ds_read_b128 v[158:161], v153 offset:1024
	ds_read_b128 v[162:165], v153 offset:2048
	ds_read_b128 v[166:169], v153 offset:3072
	v_add_u32_e32 v153, s70, v149
	ds_read_b128 v[170:173], v153
	ds_read_b128 v[174:177], v153 offset:1024
	ds_read_b128 v[178:181], v153 offset:2048
	ds_read_b128 v[182:185], v153 offset:3072
	s_add_u32 s46, s46, 0x40000
	s_addc_u32 s47, s47, 0
	s_mov_b32 m0, s25
	v_lshl_add_u64 v[226:227], s[46:47], 0, v[136:137]
	ds_read_b128 v[186:189], v152 offset:32768
	ds_read_b128 v[190:193], v152 offset:33792
	ds_read_b128 v[194:197], v152 offset:34816
	ds_read_b128 v[198:201], v152 offset:35840
	ds_read_b128 v[206:209], v152 offset:36864
	ds_read_b128 v[210:213], v152 offset:37888
	ds_read_b128 v[214:217], v152 offset:38912
	ds_read_b128 v[218:221], v152 offset:39936
	global_load_lds_dwordx4 v[226:227], off
	v_lshl_add_u64 v[226:227], s[46:47], 0, v[132:133]
	s_mov_b32 m0, s28
	s_nop 0
	global_load_lds_dwordx4 v[226:227], off
	s_waitcnt vmcnt(8)
	s_waitcnt lgkmcnt(0)
	s_barrier
	s_setprio 1
	s_waitcnt lgkmcnt(0)
	v_mfma_f32_16x16x32_bf16 v[126:129], v[154:157], v[186:189], v[126:129]
	v_mfma_f32_16x16x32_bf16 v[122:125], v[162:165], v[186:189], v[122:125]
	v_mfma_f32_16x16x32_bf16 v[110:113], v[154:157], v[194:197], v[110:113]
	v_mfma_f32_16x16x32_bf16 v[106:109], v[162:165], v[194:197], v[106:109]
	v_mfma_f32_16x16x32_bf16 v[94:97], v[154:157], v[206:209], v[94:97]
	v_mfma_f32_16x16x32_bf16 v[90:93], v[162:165], v[206:209], v[90:93]
	v_mfma_f32_16x16x32_bf16 v[78:81], v[154:157], v[214:217], v[78:81]
	v_mfma_f32_16x16x32_bf16 v[74:77], v[162:165], v[214:217], v[74:77]
	v_mfma_f32_16x16x32_bf16 v[126:129], v[158:161], v[190:193], v[126:129]
	v_mfma_f32_16x16x32_bf16 v[122:125], v[166:169], v[190:193], v[122:125]
	v_mfma_f32_16x16x32_bf16 v[110:113], v[158:161], v[198:201], v[110:113]
	v_mfma_f32_16x16x32_bf16 v[106:109], v[166:169], v[198:201], v[106:109]
	v_mfma_f32_16x16x32_bf16 v[94:97], v[158:161], v[210:213], v[94:97]
	v_mfma_f32_16x16x32_bf16 v[90:93], v[166:169], v[210:213], v[90:93]
	v_mfma_f32_16x16x32_bf16 v[78:81], v[158:161], v[218:221], v[78:81]
	v_mfma_f32_16x16x32_bf16 v[74:77], v[166:169], v[218:221], v[74:77]
	s_setprio 0
	s_setprio 1
	v_mfma_f32_16x16x32_bf16 v[118:121], v[170:173], v[186:189], v[118:121]
	v_mfma_f32_16x16x32_bf16 v[114:117], v[178:181], v[186:189], v[114:117]
	v_mfma_f32_16x16x32_bf16 v[102:105], v[170:173], v[194:197], v[102:105]
	v_mfma_f32_16x16x32_bf16 v[98:101], v[178:181], v[194:197], v[98:101]
	v_mfma_f32_16x16x32_bf16 v[86:89], v[170:173], v[206:209], v[86:89]
	v_mfma_f32_16x16x32_bf16 v[82:85], v[178:181], v[206:209], v[82:85]
	v_mfma_f32_16x16x32_bf16 v[70:73], v[170:173], v[214:217], v[70:73]
	v_mfma_f32_16x16x32_bf16 v[66:69], v[178:181], v[214:217], v[66:69]
	v_mfma_f32_16x16x32_bf16 v[118:121], v[174:177], v[190:193], v[118:121]
	v_mfma_f32_16x16x32_bf16 v[114:117], v[182:185], v[190:193], v[114:117]
	v_mfma_f32_16x16x32_bf16 v[102:105], v[174:177], v[198:201], v[102:105]
	v_mfma_f32_16x16x32_bf16 v[98:101], v[182:185], v[198:201], v[98:101]
	v_mfma_f32_16x16x32_bf16 v[86:89], v[174:177], v[210:213], v[86:89]
	v_mfma_f32_16x16x32_bf16 v[82:85], v[182:185], v[210:213], v[82:85]
	v_mfma_f32_16x16x32_bf16 v[70:73], v[174:177], v[218:221], v[70:73]
	v_mfma_f32_16x16x32_bf16 v[66:69], v[182:185], v[218:221], v[66:69]
	s_setprio 0
	s_barrier
	s_add_i32 s46, s69, s16
	v_lshl_add_u64 v[146:147], v[146:147], 0, s[10:11]
	s_mov_b32 m0, s46
	ds_read_b128 v[186:189], v152 offset:49152
	ds_read_b128 v[190:193], v152 offset:50176
	ds_read_b128 v[194:197], v152 offset:51200
	ds_read_b128 v[198:201], v152 offset:52224
	ds_read_b128 v[206:209], v152 offset:53248
	ds_read_b128 v[210:213], v152 offset:54272
	ds_read_b128 v[214:217], v152 offset:55296
	ds_read_b128 v[218:221], v152 offset:56320
	global_load_lds_dwordx4 v[146:147], off
	s_add_i32 m0, s46, 0x2000
	s_add_u32 s44, s44, 0x40080
	v_lshl_add_u64 v[146:147], v[202:203], 0, s[10:11]
	s_addc_u32 s45, s45, 0
	s_add_i32 s46, s70, s16
	global_load_lds_dwordx4 v[146:147], off
	v_lshl_add_u64 v[146:147], s[44:45], 0, v[134:135]
	s_mov_b32 m0, s46
	s_nop 0
	global_load_lds_dwordx4 v[146:147], off
	v_lshl_add_u64 v[146:147], s[44:45], 0, v[130:131]
	s_add_i32 m0, s46, 0x2000
	s_nop 0
	global_load_lds_dwordx4 v[146:147], off
	v_lshl_add_u64 v[146:147], v[222:223], 0, s[10:11]
	s_mov_b32 m0, s33
	s_nop 0
	global_load_lds_dwordx4 v[146:147], off
	v_lshl_add_u64 v[146:147], v[224:225], 0, s[10:11]
	s_waitcnt vmcnt(7)
	s_waitcnt lgkmcnt(0)
	s_barrier
	s_setprio 1
	s_waitcnt lgkmcnt(0)
	v_mfma_f32_16x16x32_bf16 v[62:65], v[154:157], v[186:189], v[62:65]
	v_mfma_f32_16x16x32_bf16 v[58:61], v[162:165], v[186:189], v[58:61]
	v_mfma_f32_16x16x32_bf16 v[46:49], v[154:157], v[194:197], v[46:49]
	v_mfma_f32_16x16x32_bf16 v[42:45], v[162:165], v[194:197], v[42:45]
	v_mfma_f32_16x16x32_bf16 v[30:33], v[154:157], v[206:209], v[30:33]
	v_mfma_f32_16x16x32_bf16 v[26:29], v[162:165], v[206:209], v[26:29]
	v_mfma_f32_16x16x32_bf16 v[14:17], v[154:157], v[214:217], v[14:17]
	v_mfma_f32_16x16x32_bf16 v[10:13], v[162:165], v[214:217], v[10:13]
	s_mov_b32 m0, s35
	s_nop 0
	global_load_lds_dwordx4 v[146:147], off
	v_mfma_f32_16x16x32_bf16 v[62:65], v[158:161], v[190:193], v[62:65]
	v_mfma_f32_16x16x32_bf16 v[58:61], v[166:169], v[190:193], v[58:61]
	v_mfma_f32_16x16x32_bf16 v[46:49], v[158:161], v[198:201], v[46:49]
	v_mfma_f32_16x16x32_bf16 v[42:45], v[166:169], v[198:201], v[42:45]
	v_mfma_f32_16x16x32_bf16 v[30:33], v[158:161], v[210:213], v[30:33]
	v_mfma_f32_16x16x32_bf16 v[26:29], v[166:169], v[210:213], v[26:29]
	v_mfma_f32_16x16x32_bf16 v[14:17], v[158:161], v[218:221], v[14:17]
	v_mfma_f32_16x16x32_bf16 v[10:13], v[166:169], v[218:221], v[10:13]
	s_setprio 0
	s_setprio 1
	v_mfma_f32_16x16x32_bf16 v[54:57], v[170:173], v[186:189], v[54:57]
	v_mfma_f32_16x16x32_bf16 v[50:53], v[178:181], v[186:189], v[50:53]
	v_mfma_f32_16x16x32_bf16 v[38:41], v[170:173], v[194:197], v[38:41]
	v_mfma_f32_16x16x32_bf16 v[34:37], v[178:181], v[194:197], v[34:37]
	v_mfma_f32_16x16x32_bf16 v[22:25], v[170:173], v[206:209], v[22:25]
	v_mfma_f32_16x16x32_bf16 v[18:21], v[178:181], v[206:209], v[18:21]
	v_mfma_f32_16x16x32_bf16 v[6:9], v[170:173], v[214:217], v[6:9]
	v_mfma_f32_16x16x32_bf16 v[2:5], v[178:181], v[214:217], v[2:5]
	v_mfma_f32_16x16x32_bf16 v[54:57], v[174:177], v[190:193], v[54:57]
	v_mfma_f32_16x16x32_bf16 v[50:53], v[182:185], v[190:193], v[50:53]
	v_mfma_f32_16x16x32_bf16 v[38:41], v[174:177], v[198:201], v[38:41]
	v_mfma_f32_16x16x32_bf16 v[34:37], v[182:185], v[198:201], v[34:37]
	v_mfma_f32_16x16x32_bf16 v[22:25], v[174:177], v[210:213], v[22:25]
	v_mfma_f32_16x16x32_bf16 v[18:21], v[182:185], v[210:213], v[18:21]
	v_mfma_f32_16x16x32_bf16 v[6:9], v[174:177], v[218:221], v[6:9]
	v_mfma_f32_16x16x32_bf16 v[2:5], v[182:185], v[218:221], v[2:5]
	s_setprio 0
	s_barrier
	s_add_i32 s68, s68, 2
	s_add_u32 s42, s42, 0x100
	s_addc_u32 s43, s43, 0
	s_add_u32 s66, s66, 0x100
	s_addc_u32 s67, s67, 0
	s_cmp_gt_u32 s68, 13
	s_cbranch_scc0 .LBB0_745
	s_and_b64 vcc, exec, s[12:13]
	s_cbranch_vccz .LBB0_748
	s_barrier

.LBB0_833:
	s_add_u32 s72, s0, s68
	s_addc_u32 s73, s1, s69
	s_and_b64 s[62:63], s[70:71], exec
	s_cselect_b32 s15, s73, s77
	s_cselect_b32 s33, s72, s76
	s_add_u32 s74, s35, s66
	s_addc_u32 s75, s85, s67
	s_and_b64 s[62:63], s[70:71], exec
	s_cselect_b32 s34, s75, s79
	s_cselect_b32 s39, s74, s78
	s_add_i32 s45, s7, -2
	s_add_u32 s76, s76, 0x100080
	s_addc_u32 s77, s77, 0
	s_add_u32 s47, s78, 0x100
	s_addc_u32 s62, s79, 0
	s_mov_b32 s63, 0
	s_waitcnt vmcnt(0)
	ds_read_b128 v[114:117], v190
	ds_read_b128 v[118:121], v190 offset:1024
	ds_read_b128 v[122:125], v190 offset:2048
	ds_read_b128 v[126:129], v190 offset:3072
	ds_read_b128 v[146:149], v191
	ds_read_b128 v[150:153], v191 offset:1024
	ds_read_b128 v[154:157], v191 offset:2048
	ds_read_b128 v[158:161], v191 offset:3072
	s_add_i32 s82, s63, 2
	s_add_u32 s78, s76, 0xfff00080
	s_addc_u32 s79, s77, -1
	s_cmp_eq_u32 s45, s63
	s_cselect_b32 s81, s15, s79
	s_cselect_b32 s80, s33, s78
	s_cselect_b32 s79, s34, s62
	s_cselect_b32 s78, s39, s47
	v_lshl_add_u64 v[186:187], s[76:77], 0, v[180:181]
	s_add_i32 m0, s87, 0xc000
	ds_read_b128 v[162:165], v192
	ds_read_b128 v[166:169], v192 offset:1024
	ds_read_b128 v[194:197], v192 offset:2048
	ds_read_b128 v[198:201], v192 offset:3072
	ds_read_b128 v[206:209], v192 offset:4096
	ds_read_b128 v[210:213], v192 offset:5120
	ds_read_b128 v[214:217], v192 offset:6144
	ds_read_b128 v[218:221], v192 offset:7168
	global_load_lds_dwordx4 v[186:187], off
	v_lshl_add_u64 v[186:187], s[76:77], 0, v[182:183]
	s_add_i32 m0, s87, 0xe000
	s_nop 0
	global_load_lds_dwordx4 v[186:187], off
	s_waitcnt vmcnt(8)
	s_waitcnt lgkmcnt(0)
	s_barrier
	s_setprio 1
	s_waitcnt lgkmcnt(0)
	v_mfma_f32_16x16x32_bf16 v[142:145], v[114:117], v[162:165], 0
	v_mfma_f32_16x16x32_bf16 v[138:141], v[122:125], v[162:165], 0
	v_mfma_f32_16x16x32_bf16 v[110:113], v[114:117], v[194:197], 0
	v_mfma_f32_16x16x32_bf16 v[106:109], v[122:125], v[194:197], 0
	v_mfma_f32_16x16x32_bf16 v[98:101], v[114:117], v[206:209], 0
	v_mfma_f32_16x16x32_bf16 v[90:93], v[122:125], v[206:209], 0
	v_mfma_f32_16x16x32_bf16 v[82:85], v[114:117], v[214:217], 0
	v_mfma_f32_16x16x32_bf16 v[74:77], v[122:125], v[214:217], 0
	v_mfma_f32_16x16x32_bf16 v[142:145], v[118:121], v[166:169], v[142:145]
	v_mfma_f32_16x16x32_bf16 v[138:141], v[126:129], v[166:169], v[138:141]
	v_mfma_f32_16x16x32_bf16 v[110:113], v[118:121], v[198:201], v[110:113]
	v_mfma_f32_16x16x32_bf16 v[106:109], v[126:129], v[198:201], v[106:109]
	v_mfma_f32_16x16x32_bf16 v[98:101], v[118:121], v[210:213], v[98:101]
	v_mfma_f32_16x16x32_bf16 v[90:93], v[126:129], v[210:213], v[90:93]
	v_mfma_f32_16x16x32_bf16 v[82:85], v[118:121], v[218:221], v[82:85]
	v_mfma_f32_16x16x32_bf16 v[74:77], v[126:129], v[218:221], v[74:77]
	s_setprio 0
	s_setprio 1
	v_mfma_f32_16x16x32_bf16 v[134:137], v[146:149], v[162:165], 0
	v_mfma_f32_16x16x32_bf16 v[130:133], v[154:157], v[162:165], 0
	v_mfma_f32_16x16x32_bf16 v[102:105], v[146:149], v[194:197], 0
	v_mfma_f32_16x16x32_bf16 v[94:97], v[154:157], v[194:197], 0
	v_mfma_f32_16x16x32_bf16 v[86:89], v[146:149], v[206:209], 0
	v_mfma_f32_16x16x32_bf16 v[78:81], v[154:157], v[206:209], 0
	v_mfma_f32_16x16x32_bf16 v[70:73], v[146:149], v[214:217], 0
	v_mfma_f32_16x16x32_bf16 v[66:69], v[154:157], v[214:217], 0
	v_mfma_f32_16x16x32_bf16 v[134:137], v[150:153], v[166:169], v[134:137]
	v_mfma_f32_16x16x32_bf16 v[130:133], v[158:161], v[166:169], v[130:133]
	v_mfma_f32_16x16x32_bf16 v[102:105], v[150:153], v[198:201], v[102:105]
	v_mfma_f32_16x16x32_bf16 v[94:97], v[158:161], v[198:201], v[94:97]
	v_mfma_f32_16x16x32_bf16 v[86:89], v[150:153], v[210:213], v[86:89]
	v_mfma_f32_16x16x32_bf16 v[78:81], v[158:161], v[210:213], v[78:81]
	v_mfma_f32_16x16x32_bf16 v[70:73], v[150:153], v[218:221], v[70:73]
	v_mfma_f32_16x16x32_bf16 v[66:69], v[158:161], v[218:221], v[66:69]
	s_setprio 0
	s_barrier
	s_add_i32 s63, s24, s86
	v_lshl_add_u64 v[186:187], s[78:79], 0, v[172:173]
	s_mov_b32 m0, s63
	ds_read_b128 v[162:165], v192 offset:16384
	ds_read_b128 v[166:169], v192 offset:17408
	ds_read_b128 v[194:197], v192 offset:18432
	ds_read_b128 v[198:201], v192 offset:19456
	ds_read_b128 v[206:209], v192 offset:20480
	ds_read_b128 v[210:213], v192 offset:21504
	ds_read_b128 v[214:217], v192 offset:22528
	ds_read_b128 v[218:221], v192 offset:23552
	global_load_lds_dwordx4 v[186:187], off
	s_add_i32 m0, s63, 0x2000
	s_add_u32 vcc_lo, s78, 0x100000
	v_lshl_add_u64 v[202:203], s[78:79], 0, v[176:177]
	s_addc_u32 vcc_hi, s79, 0
	s_add_i32 s63, s25, s86
	global_load_lds_dwordx4 v[202:203], off
	v_lshl_add_u64 v[222:223], vcc, 0, v[172:173]
	s_mov_b32 m0, s63
	v_lshl_add_u64 v[224:225], s[80:81], 0, v[174:175]
	global_load_lds_dwordx4 v[222:223], off
	v_lshl_add_u64 v[222:223], vcc, 0, v[176:177]
	s_add_i32 m0, s63, 0x2000
	s_nop 0
	global_load_lds_dwordx4 v[222:223], off
	v_lshl_add_u64 v[222:223], s[80:81], 0, v[170:171]
	s_mov_b32 m0, s87
	s_nop 0
	global_load_lds_dwordx4 v[222:223], off
	s_waitcnt vmcnt(7)
	s_waitcnt lgkmcnt(0)
	s_barrier
	s_setprio 1
	s_waitcnt lgkmcnt(0)
	v_mfma_f32_16x16x32_bf16 v[62:65], v[114:117], v[162:165], 0
	v_mfma_f32_16x16x32_bf16 v[58:61], v[122:125], v[162:165], 0
	v_mfma_f32_16x16x32_bf16 v[50:53], v[114:117], v[194:197], 0
	v_mfma_f32_16x16x32_bf16 v[42:45], v[122:125], v[194:197], 0
	v_mfma_f32_16x16x32_bf16 v[34:37], v[114:117], v[206:209], 0
	v_mfma_f32_16x16x32_bf16 v[26:29], v[122:125], v[206:209], 0
	v_mfma_f32_16x16x32_bf16 v[18:21], v[114:117], v[214:217], 0
	v_mfma_f32_16x16x32_bf16 v[10:13], v[122:125], v[214:217], 0
	s_mov_b32 m0, s88
	s_nop 0
	global_load_lds_dwordx4 v[224:225], off
	v_mfma_f32_16x16x32_bf16 v[62:65], v[118:121], v[166:169], v[62:65]
	v_mfma_f32_16x16x32_bf16 v[58:61], v[126:129], v[166:169], v[58:61]
	v_mfma_f32_16x16x32_bf16 v[50:53], v[118:121], v[198:201], v[50:53]
	v_mfma_f32_16x16x32_bf16 v[42:45], v[126:129], v[198:201], v[42:45]
	v_mfma_f32_16x16x32_bf16 v[34:37], v[118:121], v[210:213], v[34:37]
	v_mfma_f32_16x16x32_bf16 v[26:29], v[126:129], v[210:213], v[26:29]
	v_mfma_f32_16x16x32_bf16 v[18:21], v[118:121], v[218:221], v[18:21]
	v_mfma_f32_16x16x32_bf16 v[10:13], v[126:129], v[218:221], v[10:13]
	s_setprio 0
	s_setprio 1
	v_mfma_f32_16x16x32_bf16 v[54:57], v[146:149], v[162:165], 0
	v_mfma_f32_16x16x32_bf16 v[46:49], v[154:157], v[162:165], 0
	v_mfma_f32_16x16x32_bf16 v[38:41], v[146:149], v[194:197], 0
	v_mfma_f32_16x16x32_bf16 v[30:33], v[154:157], v[194:197], 0
	v_mfma_f32_16x16x32_bf16 v[22:25], v[146:149], v[206:209], 0
	v_mfma_f32_16x16x32_bf16 v[14:17], v[154:157], v[206:209], 0
	v_mfma_f32_16x16x32_bf16 v[6:9], v[146:149], v[214:217], 0
	v_mfma_f32_16x16x32_bf16 v[2:5], v[154:157], v[214:217], 0
	v_mfma_f32_16x16x32_bf16 v[54:57], v[150:153], v[166:169], v[54:57]
	v_mfma_f32_16x16x32_bf16 v[46:49], v[158:161], v[166:169], v[46:49]
	v_mfma_f32_16x16x32_bf16 v[38:41], v[150:153], v[198:201], v[38:41]
	v_mfma_f32_16x16x32_bf16 v[30:33], v[158:161], v[198:201], v[30:33]
	v_mfma_f32_16x16x32_bf16 v[22:25], v[150:153], v[210:213], v[22:25]
	v_mfma_f32_16x16x32_bf16 v[14:17], v[158:161], v[210:213], v[14:17]
	v_mfma_f32_16x16x32_bf16 v[6:9], v[150:153], v[218:221], v[6:9]
	v_mfma_f32_16x16x32_bf16 v[2:5], v[158:161], v[218:221], v[2:5]
	s_setprio 0
	s_barrier
	s_add_i32 s63, 0, 0x18000
	s_add_i32 s83, 0, 0x1c000
	v_add_u32_e32 v126, s63, v189
	v_add_u32_e32 v158, s83, v189
	ds_read_b128 v[114:117], v126
	ds_read_b128 v[118:121], v126 offset:1024
	ds_read_b128 v[122:125], v126 offset:2048
	ds_read_b128 v[126:129], v126 offset:3072
	ds_read_b128 v[146:149], v158
	ds_read_b128 v[150:153], v158 offset:1024
	ds_read_b128 v[154:157], v158 offset:2048
	ds_read_b128 v[158:161], v158 offset:3072
	s_add_u32 s80, s80, 0x100000
	s_addc_u32 s81, s81, 0
	s_mov_b32 m0, s89
	v_lshl_add_u64 v[226:227], s[80:81], 0, v[170:171]
	ds_read_b128 v[162:165], v192 offset:32768
	ds_read_b128 v[166:169], v192 offset:33792
	ds_read_b128 v[194:197], v192 offset:34816
	ds_read_b128 v[198:201], v192 offset:35840
	ds_read_b128 v[206:209], v192 offset:36864
	ds_read_b128 v[210:213], v192 offset:37888
	ds_read_b128 v[214:217], v192 offset:38912
	ds_read_b128 v[218:221], v192 offset:39936
	global_load_lds_dwordx4 v[226:227], off
	v_lshl_add_u64 v[226:227], s[80:81], 0, v[174:175]
	s_mov_b32 m0, s90
	s_nop 0
	global_load_lds_dwordx4 v[226:227], off
	s_waitcnt vmcnt(8)
	s_waitcnt lgkmcnt(0)
	s_barrier
	s_setprio 1
	s_waitcnt lgkmcnt(0)
	v_mfma_f32_16x16x32_bf16 v[142:145], v[114:117], v[162:165], v[142:145]
	v_mfma_f32_16x16x32_bf16 v[138:141], v[122:125], v[162:165], v[138:141]
	v_mfma_f32_16x16x32_bf16 v[110:113], v[114:117], v[194:197], v[110:113]
	v_mfma_f32_16x16x32_bf16 v[106:109], v[122:125], v[194:197], v[106:109]
	v_mfma_f32_16x16x32_bf16 v[98:101], v[114:117], v[206:209], v[98:101]
	v_mfma_f32_16x16x32_bf16 v[90:93], v[122:125], v[206:209], v[90:93]
	v_mfma_f32_16x16x32_bf16 v[82:85], v[114:117], v[214:217], v[82:85]
	v_mfma_f32_16x16x32_bf16 v[74:77], v[122:125], v[214:217], v[74:77]
	v_mfma_f32_16x16x32_bf16 v[142:145], v[118:121], v[166:169], v[142:145]
	v_mfma_f32_16x16x32_bf16 v[138:141], v[126:129], v[166:169], v[138:141]
	v_mfma_f32_16x16x32_bf16 v[110:113], v[118:121], v[198:201], v[110:113]
	v_mfma_f32_16x16x32_bf16 v[106:109], v[126:129], v[198:201], v[106:109]
	v_mfma_f32_16x16x32_bf16 v[98:101], v[118:121], v[210:213], v[98:101]
	v_mfma_f32_16x16x32_bf16 v[90:93], v[126:129], v[210:213], v[90:93]
	v_mfma_f32_16x16x32_bf16 v[82:85], v[118:121], v[218:221], v[82:85]
	v_mfma_f32_16x16x32_bf16 v[74:77], v[126:129], v[218:221], v[74:77]
	s_setprio 0
	s_setprio 1
	v_mfma_f32_16x16x32_bf16 v[134:137], v[146:149], v[162:165], v[134:137]
	v_mfma_f32_16x16x32_bf16 v[130:133], v[154:157], v[162:165], v[130:133]
	v_mfma_f32_16x16x32_bf16 v[102:105], v[146:149], v[194:197], v[102:105]
	v_mfma_f32_16x16x32_bf16 v[94:97], v[154:157], v[194:197], v[94:97]
	v_mfma_f32_16x16x32_bf16 v[86:89], v[146:149], v[206:209], v[86:89]
	v_mfma_f32_16x16x32_bf16 v[78:81], v[154:157], v[206:209], v[78:81]
	v_mfma_f32_16x16x32_bf16 v[70:73], v[146:149], v[214:217], v[70:73]
	v_mfma_f32_16x16x32_bf16 v[66:69], v[154:157], v[214:217], v[66:69]
	v_mfma_f32_16x16x32_bf16 v[134:137], v[150:153], v[166:169], v[134:137]
	v_mfma_f32_16x16x32_bf16 v[130:133], v[158:161], v[166:169], v[130:133]
	v_mfma_f32_16x16x32_bf16 v[102:105], v[150:153], v[198:201], v[102:105]
	v_mfma_f32_16x16x32_bf16 v[94:97], v[158:161], v[198:201], v[94:97]
	v_mfma_f32_16x16x32_bf16 v[86:89], v[150:153], v[210:213], v[86:89]
	v_mfma_f32_16x16x32_bf16 v[78:81], v[158:161], v[210:213], v[78:81]
	v_mfma_f32_16x16x32_bf16 v[70:73], v[150:153], v[218:221], v[70:73]
	v_mfma_f32_16x16x32_bf16 v[66:69], v[158:161], v[218:221], v[66:69]
	s_setprio 0
	s_barrier
	s_add_i32 s63, s63, s86
	v_lshl_add_u64 v[186:187], v[186:187], 0, s[22:23]
	s_mov_b32 m0, s63
	ds_read_b128 v[162:165], v192 offset:49152
	ds_read_b128 v[166:169], v192 offset:50176
	ds_read_b128 v[194:197], v192 offset:51200
	ds_read_b128 v[198:201], v192 offset:52224
	ds_read_b128 v[206:209], v192 offset:53248
	ds_read_b128 v[210:213], v192 offset:54272
	ds_read_b128 v[214:217], v192 offset:55296
	ds_read_b128 v[218:221], v192 offset:56320
	global_load_lds_dwordx4 v[186:187], off
	s_add_i32 m0, s63, 0x2000
	s_add_u32 s78, s78, 0x100080
	v_lshl_add_u64 v[186:187], v[202:203], 0, s[22:23]
	s_addc_u32 s79, s79, 0
	s_add_i32 s63, s83, s86
	global_load_lds_dwordx4 v[186:187], off
	v_lshl_add_u64 v[186:187], s[78:79], 0, v[172:173]
	s_mov_b32 m0, s63
	s_nop 0
	global_load_lds_dwordx4 v[186:187], off
	v_lshl_add_u64 v[186:187], s[78:79], 0, v[176:177]
	s_add_i32 m0, s63, 0x2000
	s_nop 0
	global_load_lds_dwordx4 v[186:187], off
	v_lshl_add_u64 v[186:187], v[222:223], 0, s[22:23]
	s_mov_b32 m0, s95
	s_nop 0
	global_load_lds_dwordx4 v[186:187], off
	v_lshl_add_u64 v[186:187], v[224:225], 0, s[22:23]
	s_waitcnt vmcnt(7)
	s_waitcnt lgkmcnt(0)
	s_barrier
	s_setprio 1
	s_waitcnt lgkmcnt(0)
	v_mfma_f32_16x16x32_bf16 v[62:65], v[114:117], v[162:165], v[62:65]
	v_mfma_f32_16x16x32_bf16 v[58:61], v[122:125], v[162:165], v[58:61]
	v_mfma_f32_16x16x32_bf16 v[50:53], v[114:117], v[194:197], v[50:53]
	v_mfma_f32_16x16x32_bf16 v[42:45], v[122:125], v[194:197], v[42:45]
	v_mfma_f32_16x16x32_bf16 v[34:37], v[114:117], v[206:209], v[34:37]
	v_mfma_f32_16x16x32_bf16 v[26:29], v[122:125], v[206:209], v[26:29]
	v_mfma_f32_16x16x32_bf16 v[18:21], v[114:117], v[214:217], v[18:21]
	v_mfma_f32_16x16x32_bf16 v[10:13], v[122:125], v[214:217], v[10:13]
	s_mov_b32 m0, s96
	s_nop 0
	global_load_lds_dwordx4 v[186:187], off
	v_mfma_f32_16x16x32_bf16 v[62:65], v[118:121], v[166:169], v[62:65]
	v_mfma_f32_16x16x32_bf16 v[58:61], v[126:129], v[166:169], v[58:61]
	v_mfma_f32_16x16x32_bf16 v[50:53], v[118:121], v[198:201], v[50:53]
	v_mfma_f32_16x16x32_bf16 v[42:45], v[126:129], v[198:201], v[42:45]
	v_mfma_f32_16x16x32_bf16 v[34:37], v[118:121], v[210:213], v[34:37]
	v_mfma_f32_16x16x32_bf16 v[26:29], v[126:129], v[210:213], v[26:29]
	v_mfma_f32_16x16x32_bf16 v[18:21], v[118:121], v[218:221], v[18:21]
	v_mfma_f32_16x16x32_bf16 v[10:13], v[126:129], v[218:221], v[10:13]
	s_setprio 0
	s_setprio 1
	v_mfma_f32_16x16x32_bf16 v[54:57], v[146:149], v[162:165], v[54:57]
	v_mfma_f32_16x16x32_bf16 v[46:49], v[154:157], v[162:165], v[46:49]
	v_mfma_f32_16x16x32_bf16 v[38:41], v[146:149], v[194:197], v[38:41]
	v_mfma_f32_16x16x32_bf16 v[30:33], v[154:157], v[194:197], v[30:33]
	v_mfma_f32_16x16x32_bf16 v[22:25], v[146:149], v[206:209], v[22:25]
	v_mfma_f32_16x16x32_bf16 v[14:17], v[154:157], v[206:209], v[14:17]
	v_mfma_f32_16x16x32_bf16 v[6:9], v[146:149], v[214:217], v[6:9]
	v_mfma_f32_16x16x32_bf16 v[2:5], v[154:157], v[214:217], v[2:5]
	v_mfma_f32_16x16x32_bf16 v[54:57], v[150:153], v[166:169], v[54:57]
	v_mfma_f32_16x16x32_bf16 v[46:49], v[158:161], v[166:169], v[46:49]
	v_mfma_f32_16x16x32_bf16 v[38:41], v[150:153], v[198:201], v[38:41]
	v_mfma_f32_16x16x32_bf16 v[30:33], v[158:161], v[198:201], v[30:33]
	v_mfma_f32_16x16x32_bf16 v[22:25], v[150:153], v[210:213], v[22:25]
	v_mfma_f32_16x16x32_bf16 v[14:17], v[158:161], v[210:213], v[14:17]
	v_mfma_f32_16x16x32_bf16 v[6:9], v[150:153], v[218:221], v[6:9]
	v_mfma_f32_16x16x32_bf16 v[2:5], v[158:161], v[218:221], v[2:5]
	s_setprio 0
	s_barrier
	s_add_u32 s76, s76, 0x100
	s_addc_u32 s77, s77, 0
	s_add_u32 s47, s47, 0x100
	s_addc_u32 s62, s62, 0
	s_cmp_ge_i32 s82, s7
	s_mov_b32 s63, s82
.LBB0_834:
	ds_read_b128 v[114:117], v190
	ds_read_b128 v[118:121], v190 offset:1024
	ds_read_b128 v[122:125], v190 offset:2048
	ds_read_b128 v[126:129], v190 offset:3072
	ds_read_b128 v[146:149], v191
	ds_read_b128 v[150:153], v191 offset:1024
	ds_read_b128 v[154:157], v191 offset:2048
	ds_read_b128 v[158:161], v191 offset:3072
	s_add_i32 s82, s63, 2
	s_add_u32 s78, s76, 0xfff00080
	s_addc_u32 s79, s77, -1
	s_cmp_eq_u32 s45, s63
	s_cselect_b32 s81, s15, s79
	s_cselect_b32 s80, s33, s78
	s_cselect_b32 s79, s34, s62
	s_cselect_b32 s78, s39, s47
	v_lshl_add_u64 v[186:187], s[76:77], 0, v[180:181]
	s_add_i32 m0, s87, 0xc000
	ds_read_b128 v[162:165], v192
	ds_read_b128 v[166:169], v192 offset:1024
	ds_read_b128 v[194:197], v192 offset:2048
	ds_read_b128 v[198:201], v192 offset:3072
	ds_read_b128 v[206:209], v192 offset:4096
	ds_read_b128 v[210:213], v192 offset:5120
	ds_read_b128 v[214:217], v192 offset:6144
	ds_read_b128 v[218:221], v192 offset:7168
	global_load_lds_dwordx4 v[186:187], off
	v_lshl_add_u64 v[186:187], s[76:77], 0, v[182:183]
	s_add_i32 m0, s87, 0xe000
	s_nop 0
	global_load_lds_dwordx4 v[186:187], off
	s_waitcnt vmcnt(8)
	s_waitcnt lgkmcnt(0)
	s_barrier
	s_setprio 1
	s_waitcnt lgkmcnt(0)
	v_mfma_f32_16x16x32_bf16 v[142:145], v[114:117], v[162:165], v[142:145]
	v_mfma_f32_16x16x32_bf16 v[138:141], v[122:125], v[162:165], v[138:141]
	v_mfma_f32_16x16x32_bf16 v[110:113], v[114:117], v[194:197], v[110:113]
	v_mfma_f32_16x16x32_bf16 v[106:109], v[122:125], v[194:197], v[106:109]
	v_mfma_f32_16x16x32_bf16 v[98:101], v[114:117], v[206:209], v[98:101]
	v_mfma_f32_16x16x32_bf16 v[90:93], v[122:125], v[206:209], v[90:93]
	v_mfma_f32_16x16x32_bf16 v[82:85], v[114:117], v[214:217], v[82:85]
	v_mfma_f32_16x16x32_bf16 v[74:77], v[122:125], v[214:217], v[74:77]
	v_mfma_f32_16x16x32_bf16 v[142:145], v[118:121], v[166:169], v[142:145]
	v_mfma_f32_16x16x32_bf16 v[138:141], v[126:129], v[166:169], v[138:141]
	v_mfma_f32_16x16x32_bf16 v[110:113], v[118:121], v[198:201], v[110:113]
	v_mfma_f32_16x16x32_bf16 v[106:109], v[126:129], v[198:201], v[106:109]
	v_mfma_f32_16x16x32_bf16 v[98:101], v[118:121], v[210:213], v[98:101]
	v_mfma_f32_16x16x32_bf16 v[90:93], v[126:129], v[210:213], v[90:93]
	v_mfma_f32_16x16x32_bf16 v[82:85], v[118:121], v[218:221], v[82:85]
	v_mfma_f32_16x16x32_bf16 v[74:77], v[126:129], v[218:221], v[74:77]
	s_setprio 0
	s_setprio 1
	v_mfma_f32_16x16x32_bf16 v[134:137], v[146:149], v[162:165], v[134:137]
	v_mfma_f32_16x16x32_bf16 v[130:133], v[154:157], v[162:165], v[130:133]
	v_mfma_f32_16x16x32_bf16 v[102:105], v[146:149], v[194:197], v[102:105]
	v_mfma_f32_16x16x32_bf16 v[94:97], v[154:157], v[194:197], v[94:97]
	v_mfma_f32_16x16x32_bf16 v[86:89], v[146:149], v[206:209], v[86:89]
	v_mfma_f32_16x16x32_bf16 v[78:81], v[154:157], v[206:209], v[78:81]
	v_mfma_f32_16x16x32_bf16 v[70:73], v[146:149], v[214:217], v[70:73]
	v_mfma_f32_16x16x32_bf16 v[66:69], v[154:157], v[214:217], v[66:69]
	v_mfma_f32_16x16x32_bf16 v[134:137], v[150:153], v[166:169], v[134:137]
	v_mfma_f32_16x16x32_bf16 v[130:133], v[158:161], v[166:169], v[130:133]
	v_mfma_f32_16x16x32_bf16 v[102:105], v[150:153], v[198:201], v[102:105]
	v_mfma_f32_16x16x32_bf16 v[94:97], v[158:161], v[198:201], v[94:97]
	v_mfma_f32_16x16x32_bf16 v[86:89], v[150:153], v[210:213], v[86:89]
	v_mfma_f32_16x16x32_bf16 v[78:81], v[158:161], v[210:213], v[78:81]
	v_mfma_f32_16x16x32_bf16 v[70:73], v[150:153], v[218:221], v[70:73]
	v_mfma_f32_16x16x32_bf16 v[66:69], v[158:161], v[218:221], v[66:69]
	s_setprio 0
	s_barrier
	s_add_i32 s63, s24, s86
	v_lshl_add_u64 v[186:187], s[78:79], 0, v[172:173]
	s_mov_b32 m0, s63
	ds_read_b128 v[162:165], v192 offset:16384
	ds_read_b128 v[166:169], v192 offset:17408
	ds_read_b128 v[194:197], v192 offset:18432
	ds_read_b128 v[198:201], v192 offset:19456
	ds_read_b128 v[206:209], v192 offset:20480
	ds_read_b128 v[210:213], v192 offset:21504
	ds_read_b128 v[214:217], v192 offset:22528
	ds_read_b128 v[218:221], v192 offset:23552
	global_load_lds_dwordx4 v[186:187], off
	s_add_i32 m0, s63, 0x2000
	s_add_u32 vcc_lo, s78, 0x100000
	v_lshl_add_u64 v[202:203], s[78:79], 0, v[176:177]
	s_addc_u32 vcc_hi, s79, 0
	s_add_i32 s63, s25, s86
	global_load_lds_dwordx4 v[202:203], off
	v_lshl_add_u64 v[222:223], vcc, 0, v[172:173]
	s_mov_b32 m0, s63
	v_lshl_add_u64 v[224:225], s[80:81], 0, v[174:175]
	global_load_lds_dwordx4 v[222:223], off
	v_lshl_add_u64 v[222:223], vcc, 0, v[176:177]
	s_add_i32 m0, s63, 0x2000
	s_nop 0
	global_load_lds_dwordx4 v[222:223], off
	v_lshl_add_u64 v[222:223], s[80:81], 0, v[170:171]
	s_mov_b32 m0, s87
	s_nop 0
	global_load_lds_dwordx4 v[222:223], off
	s_waitcnt vmcnt(7)
	s_waitcnt lgkmcnt(0)
	s_barrier
	s_setprio 1
	s_waitcnt lgkmcnt(0)
	v_mfma_f32_16x16x32_bf16 v[62:65], v[114:117], v[162:165], v[62:65]
	v_mfma_f32_16x16x32_bf16 v[58:61], v[122:125], v[162:165], v[58:61]
	v_mfma_f32_16x16x32_bf16 v[50:53], v[114:117], v[194:197], v[50:53]
	v_mfma_f32_16x16x32_bf16 v[42:45], v[122:125], v[194:197], v[42:45]
	v_mfma_f32_16x16x32_bf16 v[34:37], v[114:117], v[206:209], v[34:37]
	v_mfma_f32_16x16x32_bf16 v[26:29], v[122:125], v[206:209], v[26:29]
	v_mfma_f32_16x16x32_bf16 v[18:21], v[114:117], v[214:217], v[18:21]
	v_mfma_f32_16x16x32_bf16 v[10:13], v[122:125], v[214:217], v[10:13]
	s_mov_b32 m0, s88
	s_nop 0
	global_load_lds_dwordx4 v[224:225], off
	v_mfma_f32_16x16x32_bf16 v[62:65], v[118:121], v[166:169], v[62:65]
	v_mfma_f32_16x16x32_bf16 v[58:61], v[126:129], v[166:169], v[58:61]
	v_mfma_f32_16x16x32_bf16 v[50:53], v[118:121], v[198:201], v[50:53]
	v_mfma_f32_16x16x32_bf16 v[42:45], v[126:129], v[198:201], v[42:45]
	v_mfma_f32_16x16x32_bf16 v[34:37], v[118:121], v[210:213], v[34:37]
	v_mfma_f32_16x16x32_bf16 v[26:29], v[126:129], v[210:213], v[26:29]
	v_mfma_f32_16x16x32_bf16 v[18:21], v[118:121], v[218:221], v[18:21]
	v_mfma_f32_16x16x32_bf16 v[10:13], v[126:129], v[218:221], v[10:13]
	s_setprio 0
	s_setprio 1
	v_mfma_f32_16x16x32_bf16 v[54:57], v[146:149], v[162:165], v[54:57]
	v_mfma_f32_16x16x32_bf16 v[46:49], v[154:157], v[162:165], v[46:49]
	v_mfma_f32_16x16x32_bf16 v[38:41], v[146:149], v[194:197], v[38:41]
	v_mfma_f32_16x16x32_bf16 v[30:33], v[154:157], v[194:197], v[30:33]
	v_mfma_f32_16x16x32_bf16 v[22:25], v[146:149], v[206:209], v[22:25]
	v_mfma_f32_16x16x32_bf16 v[14:17], v[154:157], v[206:209], v[14:17]
	v_mfma_f32_16x16x32_bf16 v[6:9], v[146:149], v[214:217], v[6:9]
	v_mfma_f32_16x16x32_bf16 v[2:5], v[154:157], v[214:217], v[2:5]
	v_mfma_f32_16x16x32_bf16 v[54:57], v[150:153], v[166:169], v[54:57]
	v_mfma_f32_16x16x32_bf16 v[46:49], v[158:161], v[166:169], v[46:49]
	v_mfma_f32_16x16x32_bf16 v[38:41], v[150:153], v[198:201], v[38:41]
	v_mfma_f32_16x16x32_bf16 v[30:33], v[158:161], v[198:201], v[30:33]
	v_mfma_f32_16x16x32_bf16 v[22:25], v[150:153], v[210:213], v[22:25]
	v_mfma_f32_16x16x32_bf16 v[14:17], v[158:161], v[210:213], v[14:17]
	v_mfma_f32_16x16x32_bf16 v[6:9], v[150:153], v[218:221], v[6:9]
	v_mfma_f32_16x16x32_bf16 v[2:5], v[158:161], v[218:221], v[2:5]
	s_setprio 0
	s_barrier
	s_add_i32 s63, 0, 0x18000
	s_add_i32 s83, 0, 0x1c000
	v_add_u32_e32 v126, s63, v189
	v_add_u32_e32 v158, s83, v189
	ds_read_b128 v[114:117], v126
	ds_read_b128 v[118:121], v126 offset:1024
	ds_read_b128 v[122:125], v126 offset:2048
	ds_read_b128 v[126:129], v126 offset:3072
	ds_read_b128 v[146:149], v158
	ds_read_b128 v[150:153], v158 offset:1024
	ds_read_b128 v[154:157], v158 offset:2048
	ds_read_b128 v[158:161], v158 offset:3072
	s_add_u32 s80, s80, 0x100000
	s_addc_u32 s81, s81, 0
	s_mov_b32 m0, s89
	v_lshl_add_u64 v[226:227], s[80:81], 0, v[170:171]
	ds_read_b128 v[162:165], v192 offset:32768
	ds_read_b128 v[166:169], v192 offset:33792
	ds_read_b128 v[194:197], v192 offset:34816
	ds_read_b128 v[198:201], v192 offset:35840
	ds_read_b128 v[206:209], v192 offset:36864
	ds_read_b128 v[210:213], v192 offset:37888
	ds_read_b128 v[214:217], v192 offset:38912
	ds_read_b128 v[218:221], v192 offset:39936
	global_load_lds_dwordx4 v[226:227], off
	v_lshl_add_u64 v[226:227], s[80:81], 0, v[174:175]
	s_mov_b32 m0, s90
	s_nop 0
	global_load_lds_dwordx4 v[226:227], off
	s_waitcnt vmcnt(8)
	s_waitcnt lgkmcnt(0)
	s_barrier
	s_setprio 1
	s_waitcnt lgkmcnt(0)
	v_mfma_f32_16x16x32_bf16 v[142:145], v[114:117], v[162:165], v[142:145]
	v_mfma_f32_16x16x32_bf16 v[138:141], v[122:125], v[162:165], v[138:141]
	v_mfma_f32_16x16x32_bf16 v[110:113], v[114:117], v[194:197], v[110:113]
	v_mfma_f32_16x16x32_bf16 v[106:109], v[122:125], v[194:197], v[106:109]
	v_mfma_f32_16x16x32_bf16 v[98:101], v[114:117], v[206:209], v[98:101]
	v_mfma_f32_16x16x32_bf16 v[90:93], v[122:125], v[206:209], v[90:93]
	v_mfma_f32_16x16x32_bf16 v[82:85], v[114:117], v[214:217], v[82:85]
	v_mfma_f32_16x16x32_bf16 v[74:77], v[122:125], v[214:217], v[74:77]
	v_mfma_f32_16x16x32_bf16 v[142:145], v[118:121], v[166:169], v[142:145]
	v_mfma_f32_16x16x32_bf16 v[138:141], v[126:129], v[166:169], v[138:141]
	v_mfma_f32_16x16x32_bf16 v[110:113], v[118:121], v[198:201], v[110:113]
	v_mfma_f32_16x16x32_bf16 v[106:109], v[126:129], v[198:201], v[106:109]
	v_mfma_f32_16x16x32_bf16 v[98:101], v[118:121], v[210:213], v[98:101]
	v_mfma_f32_16x16x32_bf16 v[90:93], v[126:129], v[210:213], v[90:93]
	v_mfma_f32_16x16x32_bf16 v[82:85], v[118:121], v[218:221], v[82:85]
	v_mfma_f32_16x16x32_bf16 v[74:77], v[126:129], v[218:221], v[74:77]
	s_setprio 0
	s_setprio 1
	v_mfma_f32_16x16x32_bf16 v[134:137], v[146:149], v[162:165], v[134:137]
	v_mfma_f32_16x16x32_bf16 v[130:133], v[154:157], v[162:165], v[130:133]
	v_mfma_f32_16x16x32_bf16 v[102:105], v[146:149], v[194:197], v[102:105]
	v_mfma_f32_16x16x32_bf16 v[94:97], v[154:157], v[194:197], v[94:97]
	v_mfma_f32_16x16x32_bf16 v[86:89], v[146:149], v[206:209], v[86:89]
	v_mfma_f32_16x16x32_bf16 v[78:81], v[154:157], v[206:209], v[78:81]
	v_mfma_f32_16x16x32_bf16 v[70:73], v[146:149], v[214:217], v[70:73]
	v_mfma_f32_16x16x32_bf16 v[66:69], v[154:157], v[214:217], v[66:69]
	v_mfma_f32_16x16x32_bf16 v[134:137], v[150:153], v[166:169], v[134:137]
	v_mfma_f32_16x16x32_bf16 v[130:133], v[158:161], v[166:169], v[130:133]
	v_mfma_f32_16x16x32_bf16 v[102:105], v[150:153], v[198:201], v[102:105]
	v_mfma_f32_16x16x32_bf16 v[94:97], v[158:161], v[198:201], v[94:97]
	v_mfma_f32_16x16x32_bf16 v[86:89], v[150:153], v[210:213], v[86:89]
	v_mfma_f32_16x16x32_bf16 v[78:81], v[158:161], v[210:213], v[78:81]
	v_mfma_f32_16x16x32_bf16 v[70:73], v[150:153], v[218:221], v[70:73]
	v_mfma_f32_16x16x32_bf16 v[66:69], v[158:161], v[218:221], v[66:69]
	s_setprio 0
	s_barrier
	s_add_i32 s63, s63, s86
	v_lshl_add_u64 v[186:187], v[186:187], 0, s[22:23]
	s_mov_b32 m0, s63
	ds_read_b128 v[162:165], v192 offset:49152
	ds_read_b128 v[166:169], v192 offset:50176
	ds_read_b128 v[194:197], v192 offset:51200
	ds_read_b128 v[198:201], v192 offset:52224
	ds_read_b128 v[206:209], v192 offset:53248
	ds_read_b128 v[210:213], v192 offset:54272
	ds_read_b128 v[214:217], v192 offset:55296
	ds_read_b128 v[218:221], v192 offset:56320
	global_load_lds_dwordx4 v[186:187], off
	s_add_i32 m0, s63, 0x2000
	s_add_u32 s78, s78, 0x100080
	v_lshl_add_u64 v[186:187], v[202:203], 0, s[22:23]
	s_addc_u32 s79, s79, 0
	s_add_i32 s63, s83, s86
	global_load_lds_dwordx4 v[186:187], off
	v_lshl_add_u64 v[186:187], s[78:79], 0, v[172:173]
	s_mov_b32 m0, s63
	s_nop 0
	global_load_lds_dwordx4 v[186:187], off
	v_lshl_add_u64 v[186:187], s[78:79], 0, v[176:177]
	s_add_i32 m0, s63, 0x2000
	s_nop 0
	global_load_lds_dwordx4 v[186:187], off
	v_lshl_add_u64 v[186:187], v[222:223], 0, s[22:23]
	s_mov_b32 m0, s95
	s_nop 0
	global_load_lds_dwordx4 v[186:187], off
	v_lshl_add_u64 v[186:187], v[224:225], 0, s[22:23]
	s_waitcnt vmcnt(7)
	s_waitcnt lgkmcnt(0)
	s_barrier
	s_setprio 1
	s_waitcnt lgkmcnt(0)
	v_mfma_f32_16x16x32_bf16 v[62:65], v[114:117], v[162:165], v[62:65]
	v_mfma_f32_16x16x32_bf16 v[58:61], v[122:125], v[162:165], v[58:61]
	v_mfma_f32_16x16x32_bf16 v[50:53], v[114:117], v[194:197], v[50:53]
	v_mfma_f32_16x16x32_bf16 v[42:45], v[122:125], v[194:197], v[42:45]
	v_mfma_f32_16x16x32_bf16 v[34:37], v[114:117], v[206:209], v[34:37]
	v_mfma_f32_16x16x32_bf16 v[26:29], v[122:125], v[206:209], v[26:29]
	v_mfma_f32_16x16x32_bf16 v[18:21], v[114:117], v[214:217], v[18:21]
	v_mfma_f32_16x16x32_bf16 v[10:13], v[122:125], v[214:217], v[10:13]
	s_mov_b32 m0, s96
	s_nop 0
	global_load_lds_dwordx4 v[186:187], off
	v_mfma_f32_16x16x32_bf16 v[62:65], v[118:121], v[166:169], v[62:65]
	v_mfma_f32_16x16x32_bf16 v[58:61], v[126:129], v[166:169], v[58:61]
	v_mfma_f32_16x16x32_bf16 v[50:53], v[118:121], v[198:201], v[50:53]
	v_mfma_f32_16x16x32_bf16 v[42:45], v[126:129], v[198:201], v[42:45]
	v_mfma_f32_16x16x32_bf16 v[34:37], v[118:121], v[210:213], v[34:37]
	v_mfma_f32_16x16x32_bf16 v[26:29], v[126:129], v[210:213], v[26:29]
	v_mfma_f32_16x16x32_bf16 v[18:21], v[118:121], v[218:221], v[18:21]
	v_mfma_f32_16x16x32_bf16 v[10:13], v[126:129], v[218:221], v[10:13]
	s_setprio 0
	s_setprio 1
	v_mfma_f32_16x16x32_bf16 v[54:57], v[146:149], v[162:165], v[54:57]
	v_mfma_f32_16x16x32_bf16 v[46:49], v[154:157], v[162:165], v[46:49]
	v_mfma_f32_16x16x32_bf16 v[38:41], v[146:149], v[194:197], v[38:41]
	v_mfma_f32_16x16x32_bf16 v[30:33], v[154:157], v[194:197], v[30:33]
	v_mfma_f32_16x16x32_bf16 v[22:25], v[146:149], v[206:209], v[22:25]
	v_mfma_f32_16x16x32_bf16 v[14:17], v[154:157], v[206:209], v[14:17]
	v_mfma_f32_16x16x32_bf16 v[6:9], v[146:149], v[214:217], v[6:9]
	v_mfma_f32_16x16x32_bf16 v[2:5], v[154:157], v[214:217], v[2:5]
	v_mfma_f32_16x16x32_bf16 v[54:57], v[150:153], v[166:169], v[54:57]
	v_mfma_f32_16x16x32_bf16 v[46:49], v[158:161], v[166:169], v[46:49]
	v_mfma_f32_16x16x32_bf16 v[38:41], v[150:153], v[198:201], v[38:41]
	v_mfma_f32_16x16x32_bf16 v[30:33], v[158:161], v[198:201], v[30:33]
	v_mfma_f32_16x16x32_bf16 v[22:25], v[150:153], v[210:213], v[22:25]
	v_mfma_f32_16x16x32_bf16 v[14:17], v[158:161], v[210:213], v[14:17]
	v_mfma_f32_16x16x32_bf16 v[6:9], v[150:153], v[218:221], v[6:9]
	v_mfma_f32_16x16x32_bf16 v[2:5], v[158:161], v[218:221], v[2:5]
	s_setprio 0
	s_barrier
	s_add_u32 s76, s76, 0x100
	s_addc_u32 s77, s77, 0
	s_add_u32 s47, s47, 0x100
	s_addc_u32 s62, s62, 0
	s_cmp_ge_i32 s82, s7
	s_mov_b32 s63, s82
	s_cbranch_scc0 .LBB0_834
	s_and_b64 vcc, exec, s[26:27]
	s_cbranch_vccz .LBB0_837
	s_barrier

.LBB0_1012:
	s_add_u32 s48, s96, s44
	s_addc_u32 s49, s97, s45
	s_and_b64 s[14:15], s[4:5], exec
	s_cselect_b32 s6, s49, s65
	s_cselect_b32 s14, s48, s64
	s_add_u32 s50, s3, s46
	s_addc_u32 s51, s35, s47
	s_and_b64 s[18:19], s[4:5], exec
	s_cselect_b32 s15, s51, s67
	s_cselect_b32 s17, s50, s66
	s_add_u32 s64, s64, 0x40080
	s_addc_u32 s65, s65, 0
	s_add_u32 s18, s66, 0x100
	s_addc_u32 s19, s67, 0
	s_mov_b32 s24, -2
	s_waitcnt vmcnt(0)
	ds_read_b128 v[130:133], v172
	ds_read_b128 v[134:137], v172 offset:1024
	ds_read_b128 v[138:141], v172 offset:2048
	ds_read_b128 v[142:145], v172 offset:3072
	ds_read_b128 v[164:167], v173
	ds_read_b128 v[176:179], v173 offset:1024
	ds_read_b128 v[180:183], v173 offset:2048
	ds_read_b128 v[184:187], v173 offset:3072
	s_add_u32 s25, s64, 0xfffc0080
	s_addc_u32 s28, s65, -1
	s_cmp_eq_u32 s24, 12
	s_cselect_b32 s69, s6, s28
	s_cselect_b32 s68, s14, s25
	s_cselect_b32 s67, s15, s19
	s_cselect_b32 s66, s17, s18
	v_lshl_add_u64 v[168:169], s[64:65], 0, v[156:157]
	s_add_i32 m0, s73, 0xc000
	ds_read_b128 v[188:191], v174
	ds_read_b128 v[192:195], v174 offset:1024
	ds_read_b128 v[196:199], v174 offset:2048
	ds_read_b128 v[200:203], v174 offset:3072
	ds_read_b128 v[206:209], v174 offset:4096
	ds_read_b128 v[210:213], v174 offset:5120
	ds_read_b128 v[214:217], v174 offset:6144
	ds_read_b128 v[218:221], v174 offset:7168
	global_load_lds_dwordx4 v[168:169], off
	v_lshl_add_u64 v[168:169], s[64:65], 0, v[158:159]
	s_add_i32 m0, s73, 0xe000
	s_nop 0
	global_load_lds_dwordx4 v[168:169], off
	s_waitcnt vmcnt(8)
	s_waitcnt lgkmcnt(0)
	s_barrier
	s_setprio 1
	s_waitcnt lgkmcnt(0)
	v_mfma_f32_16x16x32_bf16 v[126:129], v[130:133], v[188:191], 0
	v_mfma_f32_16x16x32_bf16 v[122:125], v[138:141], v[188:191], 0
	v_mfma_f32_16x16x32_bf16 v[110:113], v[130:133], v[196:199], 0
	v_mfma_f32_16x16x32_bf16 v[106:109], v[138:141], v[196:199], 0
	v_mfma_f32_16x16x32_bf16 v[94:97], v[130:133], v[206:209], 0
	v_mfma_f32_16x16x32_bf16 v[90:93], v[138:141], v[206:209], 0
	v_mfma_f32_16x16x32_bf16 v[78:81], v[130:133], v[214:217], 0
	v_mfma_f32_16x16x32_bf16 v[74:77], v[138:141], v[214:217], 0
	v_mfma_f32_16x16x32_bf16 v[126:129], v[134:137], v[192:195], v[126:129]
	v_mfma_f32_16x16x32_bf16 v[122:125], v[142:145], v[192:195], v[122:125]
	v_mfma_f32_16x16x32_bf16 v[110:113], v[134:137], v[200:203], v[110:113]
	v_mfma_f32_16x16x32_bf16 v[106:109], v[142:145], v[200:203], v[106:109]
	v_mfma_f32_16x16x32_bf16 v[94:97], v[134:137], v[210:213], v[94:97]
	v_mfma_f32_16x16x32_bf16 v[90:93], v[142:145], v[210:213], v[90:93]
	v_mfma_f32_16x16x32_bf16 v[78:81], v[134:137], v[218:221], v[78:81]
	v_mfma_f32_16x16x32_bf16 v[74:77], v[142:145], v[218:221], v[74:77]
	s_setprio 0
	s_setprio 1
	v_mfma_f32_16x16x32_bf16 v[118:121], v[164:167], v[188:191], 0
	v_mfma_f32_16x16x32_bf16 v[114:117], v[180:183], v[188:191], 0
	v_mfma_f32_16x16x32_bf16 v[102:105], v[164:167], v[196:199], 0
	v_mfma_f32_16x16x32_bf16 v[98:101], v[180:183], v[196:199], 0
	v_mfma_f32_16x16x32_bf16 v[86:89], v[164:167], v[206:209], 0
	v_mfma_f32_16x16x32_bf16 v[82:85], v[180:183], v[206:209], 0
	v_mfma_f32_16x16x32_bf16 v[70:73], v[164:167], v[214:217], 0
	v_mfma_f32_16x16x32_bf16 v[66:69], v[180:183], v[214:217], 0
	v_mfma_f32_16x16x32_bf16 v[118:121], v[176:179], v[192:195], v[118:121]
	v_mfma_f32_16x16x32_bf16 v[114:117], v[184:187], v[192:195], v[114:117]
	v_mfma_f32_16x16x32_bf16 v[102:105], v[176:179], v[200:203], v[102:105]
	v_mfma_f32_16x16x32_bf16 v[98:101], v[184:187], v[200:203], v[98:101]
	v_mfma_f32_16x16x32_bf16 v[86:89], v[176:179], v[210:213], v[86:89]
	v_mfma_f32_16x16x32_bf16 v[82:85], v[184:187], v[210:213], v[82:85]
	v_mfma_f32_16x16x32_bf16 v[70:73], v[176:179], v[218:221], v[70:73]
	v_mfma_f32_16x16x32_bf16 v[66:69], v[184:187], v[218:221], v[66:69]
	s_setprio 0
	s_barrier
	s_add_i32 s25, s82, s70
	v_lshl_add_u64 v[168:169], s[66:67], 0, v[150:151]
	s_mov_b32 m0, s25
	ds_read_b128 v[188:191], v174 offset:16384
	ds_read_b128 v[192:195], v174 offset:17408
	ds_read_b128 v[196:199], v174 offset:18432
	ds_read_b128 v[200:203], v174 offset:19456
	ds_read_b128 v[206:209], v174 offset:20480
	ds_read_b128 v[210:213], v174 offset:21504
	ds_read_b128 v[214:217], v174 offset:22528
	ds_read_b128 v[218:221], v174 offset:23552
	global_load_lds_dwordx4 v[168:169], off
	s_add_i32 m0, s25, 0x2000
	s_add_u32 s28, s66, 0x40000
	v_lshl_add_u64 v[222:223], s[66:67], 0, v[146:147]
	s_addc_u32 s29, s67, 0
	s_add_i32 s25, s83, s70
	global_load_lds_dwordx4 v[222:223], off
	v_lshl_add_u64 v[224:225], s[28:29], 0, v[150:151]
	s_mov_b32 m0, s25
	v_lshl_add_u64 v[226:227], s[68:69], 0, v[148:149]
	global_load_lds_dwordx4 v[224:225], off
	v_lshl_add_u64 v[224:225], s[28:29], 0, v[146:147]
	s_add_i32 m0, s25, 0x2000
	s_nop 0
	global_load_lds_dwordx4 v[224:225], off
	v_lshl_add_u64 v[224:225], s[68:69], 0, v[152:153]
	s_mov_b32 m0, s73
	s_nop 0
	global_load_lds_dwordx4 v[224:225], off
	s_waitcnt vmcnt(7)
	s_waitcnt lgkmcnt(0)
	s_barrier
	s_setprio 1
	s_waitcnt lgkmcnt(0)
	v_mfma_f32_16x16x32_bf16 v[62:65], v[130:133], v[188:191], 0
	v_mfma_f32_16x16x32_bf16 v[58:61], v[138:141], v[188:191], 0
	v_mfma_f32_16x16x32_bf16 v[46:49], v[130:133], v[196:199], 0
	v_mfma_f32_16x16x32_bf16 v[42:45], v[138:141], v[196:199], 0
	v_mfma_f32_16x16x32_bf16 v[30:33], v[130:133], v[206:209], 0
	v_mfma_f32_16x16x32_bf16 v[26:29], v[138:141], v[206:209], 0
	v_mfma_f32_16x16x32_bf16 v[14:17], v[130:133], v[214:217], 0
	v_mfma_f32_16x16x32_bf16 v[10:13], v[138:141], v[214:217], 0
	s_mov_b32 m0, s74
	s_nop 0
	global_load_lds_dwordx4 v[226:227], off
	v_mfma_f32_16x16x32_bf16 v[62:65], v[134:137], v[192:195], v[62:65]
	v_mfma_f32_16x16x32_bf16 v[58:61], v[142:145], v[192:195], v[58:61]
	v_mfma_f32_16x16x32_bf16 v[46:49], v[134:137], v[200:203], v[46:49]
	v_mfma_f32_16x16x32_bf16 v[42:45], v[142:145], v[200:203], v[42:45]
	v_mfma_f32_16x16x32_bf16 v[30:33], v[134:137], v[210:213], v[30:33]
	v_mfma_f32_16x16x32_bf16 v[26:29], v[142:145], v[210:213], v[26:29]
	v_mfma_f32_16x16x32_bf16 v[14:17], v[134:137], v[218:221], v[14:17]
	v_mfma_f32_16x16x32_bf16 v[10:13], v[142:145], v[218:221], v[10:13]
	s_setprio 0
	s_setprio 1
	v_mfma_f32_16x16x32_bf16 v[54:57], v[164:167], v[188:191], 0
	v_mfma_f32_16x16x32_bf16 v[50:53], v[180:183], v[188:191], 0
	v_mfma_f32_16x16x32_bf16 v[38:41], v[164:167], v[196:199], 0
	v_mfma_f32_16x16x32_bf16 v[34:37], v[180:183], v[196:199], 0
	v_mfma_f32_16x16x32_bf16 v[22:25], v[164:167], v[206:209], 0
	v_mfma_f32_16x16x32_bf16 v[18:21], v[180:183], v[206:209], 0
	v_mfma_f32_16x16x32_bf16 v[6:9], v[164:167], v[214:217], 0
	v_mfma_f32_16x16x32_bf16 v[2:5], v[180:183], v[214:217], 0
	v_mfma_f32_16x16x32_bf16 v[54:57], v[176:179], v[192:195], v[54:57]
	v_mfma_f32_16x16x32_bf16 v[50:53], v[184:187], v[192:195], v[50:53]
	v_mfma_f32_16x16x32_bf16 v[38:41], v[176:179], v[200:203], v[38:41]
	v_mfma_f32_16x16x32_bf16 v[34:37], v[184:187], v[200:203], v[34:37]
	v_mfma_f32_16x16x32_bf16 v[22:25], v[176:179], v[210:213], v[22:25]
	v_mfma_f32_16x16x32_bf16 v[18:21], v[184:187], v[210:213], v[18:21]
	v_mfma_f32_16x16x32_bf16 v[6:9], v[176:179], v[218:221], v[6:9]
	v_mfma_f32_16x16x32_bf16 v[2:5], v[184:187], v[218:221], v[2:5]
	s_setprio 0
	s_barrier
	s_add_i32 s25, 0, 0x18000
	s_add_i32 s30, 0, 0x1c000
	v_add_u32_e32 v142, s25, v171
	v_add_u32_e32 v175, s30, v171
	ds_read_b128 v[130:133], v142
	ds_read_b128 v[134:137], v142 offset:1024
	ds_read_b128 v[138:141], v142 offset:2048
	ds_read_b128 v[142:145], v142 offset:3072
	ds_read_b128 v[164:167], v175
	ds_read_b128 v[176:179], v175 offset:1024
	ds_read_b128 v[180:183], v175 offset:2048
	ds_read_b128 v[184:187], v175 offset:3072
	s_add_u32 s28, s68, 0x40000
	s_addc_u32 s29, s69, 0
	s_mov_b32 m0, s75
	v_lshl_add_u64 v[228:229], s[28:29], 0, v[152:153]
	ds_read_b128 v[188:191], v174 offset:32768
	ds_read_b128 v[192:195], v174 offset:33792
	ds_read_b128 v[196:199], v174 offset:34816
	ds_read_b128 v[200:203], v174 offset:35840
	ds_read_b128 v[206:209], v174 offset:36864
	ds_read_b128 v[210:213], v174 offset:37888
	ds_read_b128 v[214:217], v174 offset:38912
	ds_read_b128 v[218:221], v174 offset:39936
	global_load_lds_dwordx4 v[228:229], off
	v_lshl_add_u64 v[228:229], s[28:29], 0, v[148:149]
	s_mov_b32 m0, s76
	s_nop 0
	global_load_lds_dwordx4 v[228:229], off
	s_waitcnt vmcnt(8)
	s_waitcnt lgkmcnt(0)
	s_barrier
	s_setprio 1
	s_waitcnt lgkmcnt(0)
	v_mfma_f32_16x16x32_bf16 v[126:129], v[130:133], v[188:191], v[126:129]
	v_mfma_f32_16x16x32_bf16 v[122:125], v[138:141], v[188:191], v[122:125]
	v_mfma_f32_16x16x32_bf16 v[110:113], v[130:133], v[196:199], v[110:113]
	v_mfma_f32_16x16x32_bf16 v[106:109], v[138:141], v[196:199], v[106:109]
	v_mfma_f32_16x16x32_bf16 v[94:97], v[130:133], v[206:209], v[94:97]
	v_mfma_f32_16x16x32_bf16 v[90:93], v[138:141], v[206:209], v[90:93]
	v_mfma_f32_16x16x32_bf16 v[78:81], v[130:133], v[214:217], v[78:81]
	v_mfma_f32_16x16x32_bf16 v[74:77], v[138:141], v[214:217], v[74:77]
	v_mfma_f32_16x16x32_bf16 v[126:129], v[134:137], v[192:195], v[126:129]
	v_mfma_f32_16x16x32_bf16 v[122:125], v[142:145], v[192:195], v[122:125]
	v_mfma_f32_16x16x32_bf16 v[110:113], v[134:137], v[200:203], v[110:113]
	v_mfma_f32_16x16x32_bf16 v[106:109], v[142:145], v[200:203], v[106:109]
	v_mfma_f32_16x16x32_bf16 v[94:97], v[134:137], v[210:213], v[94:97]
	v_mfma_f32_16x16x32_bf16 v[90:93], v[142:145], v[210:213], v[90:93]
	v_mfma_f32_16x16x32_bf16 v[78:81], v[134:137], v[218:221], v[78:81]
	v_mfma_f32_16x16x32_bf16 v[74:77], v[142:145], v[218:221], v[74:77]
	s_setprio 0
	s_setprio 1
	v_mfma_f32_16x16x32_bf16 v[118:121], v[164:167], v[188:191], v[118:121]
	v_mfma_f32_16x16x32_bf16 v[114:117], v[180:183], v[188:191], v[114:117]
	v_mfma_f32_16x16x32_bf16 v[102:105], v[164:167], v[196:199], v[102:105]
	v_mfma_f32_16x16x32_bf16 v[98:101], v[180:183], v[196:199], v[98:101]
	v_mfma_f32_16x16x32_bf16 v[86:89], v[164:167], v[206:209], v[86:89]
	v_mfma_f32_16x16x32_bf16 v[82:85], v[180:183], v[206:209], v[82:85]
	v_mfma_f32_16x16x32_bf16 v[70:73], v[164:167], v[214:217], v[70:73]
	v_mfma_f32_16x16x32_bf16 v[66:69], v[180:183], v[214:217], v[66:69]
	v_mfma_f32_16x16x32_bf16 v[118:121], v[176:179], v[192:195], v[118:121]
	v_mfma_f32_16x16x32_bf16 v[114:117], v[184:187], v[192:195], v[114:117]
	v_mfma_f32_16x16x32_bf16 v[102:105], v[176:179], v[200:203], v[102:105]
	v_mfma_f32_16x16x32_bf16 v[98:101], v[184:187], v[200:203], v[98:101]
	v_mfma_f32_16x16x32_bf16 v[86:89], v[176:179], v[210:213], v[86:89]
	v_mfma_f32_16x16x32_bf16 v[82:85], v[184:187], v[210:213], v[82:85]
	v_mfma_f32_16x16x32_bf16 v[70:73], v[176:179], v[218:221], v[70:73]
	v_mfma_f32_16x16x32_bf16 v[66:69], v[184:187], v[218:221], v[66:69]
	s_setprio 0
	s_barrier
	s_add_i32 s25, s25, s70
	v_lshl_add_u64 v[168:169], v[168:169], 0, s[36:37]
	s_mov_b32 m0, s25
	ds_read_b128 v[188:191], v174 offset:49152
	ds_read_b128 v[192:195], v174 offset:50176
	ds_read_b128 v[196:199], v174 offset:51200
	ds_read_b128 v[200:203], v174 offset:52224
	ds_read_b128 v[206:209], v174 offset:53248
	ds_read_b128 v[210:213], v174 offset:54272
	ds_read_b128 v[214:217], v174 offset:55296
	ds_read_b128 v[218:221], v174 offset:56320
	global_load_lds_dwordx4 v[168:169], off
	s_add_i32 m0, s25, 0x2000
	s_add_u32 s28, s66, 0x40080
	v_lshl_add_u64 v[168:169], v[222:223], 0, s[36:37]
	s_addc_u32 s29, s67, 0
	s_add_i32 s25, s30, s70
	global_load_lds_dwordx4 v[168:169], off
	v_lshl_add_u64 v[168:169], s[28:29], 0, v[150:151]
	s_mov_b32 m0, s25
	s_nop 0
	global_load_lds_dwordx4 v[168:169], off
	v_lshl_add_u64 v[168:169], s[28:29], 0, v[146:147]
	s_add_i32 m0, s25, 0x2000
	s_nop 0
	global_load_lds_dwordx4 v[168:169], off
	v_lshl_add_u64 v[168:169], v[224:225], 0, s[36:37]
	s_mov_b32 m0, s79
	s_nop 0
	global_load_lds_dwordx4 v[168:169], off
	v_lshl_add_u64 v[168:169], v[226:227], 0, s[36:37]
	s_waitcnt vmcnt(7)
	s_waitcnt lgkmcnt(0)
	s_barrier
	s_setprio 1
	s_waitcnt lgkmcnt(0)
	v_mfma_f32_16x16x32_bf16 v[62:65], v[130:133], v[188:191], v[62:65]
	v_mfma_f32_16x16x32_bf16 v[58:61], v[138:141], v[188:191], v[58:61]
	v_mfma_f32_16x16x32_bf16 v[46:49], v[130:133], v[196:199], v[46:49]
	v_mfma_f32_16x16x32_bf16 v[42:45], v[138:141], v[196:199], v[42:45]
	v_mfma_f32_16x16x32_bf16 v[30:33], v[130:133], v[206:209], v[30:33]
	v_mfma_f32_16x16x32_bf16 v[26:29], v[138:141], v[206:209], v[26:29]
	v_mfma_f32_16x16x32_bf16 v[14:17], v[130:133], v[214:217], v[14:17]
	v_mfma_f32_16x16x32_bf16 v[10:13], v[138:141], v[214:217], v[10:13]
	s_mov_b32 m0, s80
	s_nop 0
	global_load_lds_dwordx4 v[168:169], off
	v_mfma_f32_16x16x32_bf16 v[62:65], v[134:137], v[192:195], v[62:65]
	v_mfma_f32_16x16x32_bf16 v[58:61], v[142:145], v[192:195], v[58:61]
	v_mfma_f32_16x16x32_bf16 v[46:49], v[134:137], v[200:203], v[46:49]
	v_mfma_f32_16x16x32_bf16 v[42:45], v[142:145], v[200:203], v[42:45]
	v_mfma_f32_16x16x32_bf16 v[30:33], v[134:137], v[210:213], v[30:33]
	v_mfma_f32_16x16x32_bf16 v[26:29], v[142:145], v[210:213], v[26:29]
	v_mfma_f32_16x16x32_bf16 v[14:17], v[134:137], v[218:221], v[14:17]
	v_mfma_f32_16x16x32_bf16 v[10:13], v[142:145], v[218:221], v[10:13]
	s_setprio 0
	s_setprio 1
	v_mfma_f32_16x16x32_bf16 v[54:57], v[164:167], v[188:191], v[54:57]
	v_mfma_f32_16x16x32_bf16 v[50:53], v[180:183], v[188:191], v[50:53]
	v_mfma_f32_16x16x32_bf16 v[38:41], v[164:167], v[196:199], v[38:41]
	v_mfma_f32_16x16x32_bf16 v[34:37], v[180:183], v[196:199], v[34:37]
	v_mfma_f32_16x16x32_bf16 v[22:25], v[164:167], v[206:209], v[22:25]
	v_mfma_f32_16x16x32_bf16 v[18:21], v[180:183], v[206:209], v[18:21]
	v_mfma_f32_16x16x32_bf16 v[6:9], v[164:167], v[214:217], v[6:9]
	v_mfma_f32_16x16x32_bf16 v[2:5], v[180:183], v[214:217], v[2:5]
	v_mfma_f32_16x16x32_bf16 v[54:57], v[176:179], v[192:195], v[54:57]
	v_mfma_f32_16x16x32_bf16 v[50:53], v[184:187], v[192:195], v[50:53]
	v_mfma_f32_16x16x32_bf16 v[38:41], v[176:179], v[200:203], v[38:41]
	v_mfma_f32_16x16x32_bf16 v[34:37], v[184:187], v[200:203], v[34:37]
	v_mfma_f32_16x16x32_bf16 v[22:25], v[176:179], v[210:213], v[22:25]
	v_mfma_f32_16x16x32_bf16 v[18:21], v[184:187], v[210:213], v[18:21]
	v_mfma_f32_16x16x32_bf16 v[6:9], v[176:179], v[218:221], v[6:9]
	v_mfma_f32_16x16x32_bf16 v[2:5], v[184:187], v[218:221], v[2:5]
	s_setprio 0
	s_barrier
	s_add_i32 s24, s24, 2
	s_add_u32 s64, s64, 0x100
	s_addc_u32 s65, s65, 0
	s_add_u32 s18, s18, 0x100
	s_addc_u32 s19, s19, 0
	s_cmp_gt_u32 s24, 13
.LBB0_1013:
	ds_read_b128 v[130:133], v172
	ds_read_b128 v[134:137], v172 offset:1024
	ds_read_b128 v[138:141], v172 offset:2048
	ds_read_b128 v[142:145], v172 offset:3072
	ds_read_b128 v[164:167], v173
	ds_read_b128 v[176:179], v173 offset:1024
	ds_read_b128 v[180:183], v173 offset:2048
	ds_read_b128 v[184:187], v173 offset:3072
	s_add_u32 s25, s64, 0xfffc0080
	s_addc_u32 s28, s65, -1
	s_cmp_eq_u32 s24, 12
	s_cselect_b32 s69, s6, s28
	s_cselect_b32 s68, s14, s25
	s_cselect_b32 s67, s15, s19
	s_cselect_b32 s66, s17, s18
	v_lshl_add_u64 v[168:169], s[64:65], 0, v[156:157]
	s_add_i32 m0, s73, 0xc000
	ds_read_b128 v[188:191], v174
	ds_read_b128 v[192:195], v174 offset:1024
	ds_read_b128 v[196:199], v174 offset:2048
	ds_read_b128 v[200:203], v174 offset:3072
	ds_read_b128 v[206:209], v174 offset:4096
	ds_read_b128 v[210:213], v174 offset:5120
	ds_read_b128 v[214:217], v174 offset:6144
	ds_read_b128 v[218:221], v174 offset:7168
	global_load_lds_dwordx4 v[168:169], off
	v_lshl_add_u64 v[168:169], s[64:65], 0, v[158:159]
	s_add_i32 m0, s73, 0xe000
	s_nop 0
	global_load_lds_dwordx4 v[168:169], off
	s_waitcnt vmcnt(8)
	s_waitcnt lgkmcnt(0)
	s_barrier
	s_setprio 1
	s_waitcnt lgkmcnt(0)
	v_mfma_f32_16x16x32_bf16 v[126:129], v[130:133], v[188:191], v[126:129]
	v_mfma_f32_16x16x32_bf16 v[122:125], v[138:141], v[188:191], v[122:125]
	v_mfma_f32_16x16x32_bf16 v[110:113], v[130:133], v[196:199], v[110:113]
	v_mfma_f32_16x16x32_bf16 v[106:109], v[138:141], v[196:199], v[106:109]
	v_mfma_f32_16x16x32_bf16 v[94:97], v[130:133], v[206:209], v[94:97]
	v_mfma_f32_16x16x32_bf16 v[90:93], v[138:141], v[206:209], v[90:93]
	v_mfma_f32_16x16x32_bf16 v[78:81], v[130:133], v[214:217], v[78:81]
	v_mfma_f32_16x16x32_bf16 v[74:77], v[138:141], v[214:217], v[74:77]
	v_mfma_f32_16x16x32_bf16 v[126:129], v[134:137], v[192:195], v[126:129]
	v_mfma_f32_16x16x32_bf16 v[122:125], v[142:145], v[192:195], v[122:125]
	v_mfma_f32_16x16x32_bf16 v[110:113], v[134:137], v[200:203], v[110:113]
	v_mfma_f32_16x16x32_bf16 v[106:109], v[142:145], v[200:203], v[106:109]
	v_mfma_f32_16x16x32_bf16 v[94:97], v[134:137], v[210:213], v[94:97]
	v_mfma_f32_16x16x32_bf16 v[90:93], v[142:145], v[210:213], v[90:93]
	v_mfma_f32_16x16x32_bf16 v[78:81], v[134:137], v[218:221], v[78:81]
	v_mfma_f32_16x16x32_bf16 v[74:77], v[142:145], v[218:221], v[74:77]
	s_setprio 0
	s_setprio 1
	v_mfma_f32_16x16x32_bf16 v[118:121], v[164:167], v[188:191], v[118:121]
	v_mfma_f32_16x16x32_bf16 v[114:117], v[180:183], v[188:191], v[114:117]
	v_mfma_f32_16x16x32_bf16 v[102:105], v[164:167], v[196:199], v[102:105]
	v_mfma_f32_16x16x32_bf16 v[98:101], v[180:183], v[196:199], v[98:101]
	v_mfma_f32_16x16x32_bf16 v[86:89], v[164:167], v[206:209], v[86:89]
	v_mfma_f32_16x16x32_bf16 v[82:85], v[180:183], v[206:209], v[82:85]
	v_mfma_f32_16x16x32_bf16 v[70:73], v[164:167], v[214:217], v[70:73]
	v_mfma_f32_16x16x32_bf16 v[66:69], v[180:183], v[214:217], v[66:69]
	v_mfma_f32_16x16x32_bf16 v[118:121], v[176:179], v[192:195], v[118:121]
	v_mfma_f32_16x16x32_bf16 v[114:117], v[184:187], v[192:195], v[114:117]
	v_mfma_f32_16x16x32_bf16 v[102:105], v[176:179], v[200:203], v[102:105]
	v_mfma_f32_16x16x32_bf16 v[98:101], v[184:187], v[200:203], v[98:101]
	v_mfma_f32_16x16x32_bf16 v[86:89], v[176:179], v[210:213], v[86:89]
	v_mfma_f32_16x16x32_bf16 v[82:85], v[184:187], v[210:213], v[82:85]
	v_mfma_f32_16x16x32_bf16 v[70:73], v[176:179], v[218:221], v[70:73]
	v_mfma_f32_16x16x32_bf16 v[66:69], v[184:187], v[218:221], v[66:69]
	s_setprio 0
	s_barrier
	s_add_i32 s25, s82, s70
	v_lshl_add_u64 v[168:169], s[66:67], 0, v[150:151]
	s_mov_b32 m0, s25
	ds_read_b128 v[188:191], v174 offset:16384
	ds_read_b128 v[192:195], v174 offset:17408
	ds_read_b128 v[196:199], v174 offset:18432
	ds_read_b128 v[200:203], v174 offset:19456
	ds_read_b128 v[206:209], v174 offset:20480
	ds_read_b128 v[210:213], v174 offset:21504
	ds_read_b128 v[214:217], v174 offset:22528
	ds_read_b128 v[218:221], v174 offset:23552
	global_load_lds_dwordx4 v[168:169], off
	s_add_i32 m0, s25, 0x2000
	s_add_u32 s28, s66, 0x40000
	v_lshl_add_u64 v[222:223], s[66:67], 0, v[146:147]
	s_addc_u32 s29, s67, 0
	s_add_i32 s25, s83, s70
	global_load_lds_dwordx4 v[222:223], off
	v_lshl_add_u64 v[224:225], s[28:29], 0, v[150:151]
	s_mov_b32 m0, s25
	v_lshl_add_u64 v[226:227], s[68:69], 0, v[148:149]
	global_load_lds_dwordx4 v[224:225], off
	v_lshl_add_u64 v[224:225], s[28:29], 0, v[146:147]
	s_add_i32 m0, s25, 0x2000
	s_nop 0
	global_load_lds_dwordx4 v[224:225], off
	v_lshl_add_u64 v[224:225], s[68:69], 0, v[152:153]
	s_mov_b32 m0, s73
	s_nop 0
	global_load_lds_dwordx4 v[224:225], off
	s_waitcnt vmcnt(7)
	s_waitcnt lgkmcnt(0)
	s_barrier
	s_setprio 1
	s_waitcnt lgkmcnt(0)
	v_mfma_f32_16x16x32_bf16 v[62:65], v[130:133], v[188:191], v[62:65]
	v_mfma_f32_16x16x32_bf16 v[58:61], v[138:141], v[188:191], v[58:61]
	v_mfma_f32_16x16x32_bf16 v[46:49], v[130:133], v[196:199], v[46:49]
	v_mfma_f32_16x16x32_bf16 v[42:45], v[138:141], v[196:199], v[42:45]
	v_mfma_f32_16x16x32_bf16 v[30:33], v[130:133], v[206:209], v[30:33]
	v_mfma_f32_16x16x32_bf16 v[26:29], v[138:141], v[206:209], v[26:29]
	v_mfma_f32_16x16x32_bf16 v[14:17], v[130:133], v[214:217], v[14:17]
	v_mfma_f32_16x16x32_bf16 v[10:13], v[138:141], v[214:217], v[10:13]
	s_mov_b32 m0, s74
	s_nop 0
	global_load_lds_dwordx4 v[226:227], off
	v_mfma_f32_16x16x32_bf16 v[62:65], v[134:137], v[192:195], v[62:65]
	v_mfma_f32_16x16x32_bf16 v[58:61], v[142:145], v[192:195], v[58:61]
	v_mfma_f32_16x16x32_bf16 v[46:49], v[134:137], v[200:203], v[46:49]
	v_mfma_f32_16x16x32_bf16 v[42:45], v[142:145], v[200:203], v[42:45]
	v_mfma_f32_16x16x32_bf16 v[30:33], v[134:137], v[210:213], v[30:33]
	v_mfma_f32_16x16x32_bf16 v[26:29], v[142:145], v[210:213], v[26:29]
	v_mfma_f32_16x16x32_bf16 v[14:17], v[134:137], v[218:221], v[14:17]
	v_mfma_f32_16x16x32_bf16 v[10:13], v[142:145], v[218:221], v[10:13]
	s_setprio 0
	s_setprio 1
	v_mfma_f32_16x16x32_bf16 v[54:57], v[164:167], v[188:191], v[54:57]
	v_mfma_f32_16x16x32_bf16 v[50:53], v[180:183], v[188:191], v[50:53]
	v_mfma_f32_16x16x32_bf16 v[38:41], v[164:167], v[196:199], v[38:41]
	v_mfma_f32_16x16x32_bf16 v[34:37], v[180:183], v[196:199], v[34:37]
	v_mfma_f32_16x16x32_bf16 v[22:25], v[164:167], v[206:209], v[22:25]
	v_mfma_f32_16x16x32_bf16 v[18:21], v[180:183], v[206:209], v[18:21]
	v_mfma_f32_16x16x32_bf16 v[6:9], v[164:167], v[214:217], v[6:9]
	v_mfma_f32_16x16x32_bf16 v[2:5], v[180:183], v[214:217], v[2:5]
	v_mfma_f32_16x16x32_bf16 v[54:57], v[176:179], v[192:195], v[54:57]
	v_mfma_f32_16x16x32_bf16 v[50:53], v[184:187], v[192:195], v[50:53]
	v_mfma_f32_16x16x32_bf16 v[38:41], v[176:179], v[200:203], v[38:41]
	v_mfma_f32_16x16x32_bf16 v[34:37], v[184:187], v[200:203], v[34:37]
	v_mfma_f32_16x16x32_bf16 v[22:25], v[176:179], v[210:213], v[22:25]
	v_mfma_f32_16x16x32_bf16 v[18:21], v[184:187], v[210:213], v[18:21]
	v_mfma_f32_16x16x32_bf16 v[6:9], v[176:179], v[218:221], v[6:9]
	v_mfma_f32_16x16x32_bf16 v[2:5], v[184:187], v[218:221], v[2:5]
	s_setprio 0
	s_barrier
	s_add_i32 s25, 0, 0x18000
	s_add_i32 s30, 0, 0x1c000
	v_add_u32_e32 v142, s25, v171
	v_add_u32_e32 v175, s30, v171
	ds_read_b128 v[130:133], v142
	ds_read_b128 v[134:137], v142 offset:1024
	ds_read_b128 v[138:141], v142 offset:2048
	ds_read_b128 v[142:145], v142 offset:3072
	ds_read_b128 v[164:167], v175
	ds_read_b128 v[176:179], v175 offset:1024
	ds_read_b128 v[180:183], v175 offset:2048
	ds_read_b128 v[184:187], v175 offset:3072
	s_add_u32 s28, s68, 0x40000
	s_addc_u32 s29, s69, 0
	s_mov_b32 m0, s75
	v_lshl_add_u64 v[228:229], s[28:29], 0, v[152:153]
	ds_read_b128 v[188:191], v174 offset:32768
	ds_read_b128 v[192:195], v174 offset:33792
	ds_read_b128 v[196:199], v174 offset:34816
	ds_read_b128 v[200:203], v174 offset:35840
	ds_read_b128 v[206:209], v174 offset:36864
	ds_read_b128 v[210:213], v174 offset:37888
	ds_read_b128 v[214:217], v174 offset:38912
	ds_read_b128 v[218:221], v174 offset:39936
	global_load_lds_dwordx4 v[228:229], off
	v_lshl_add_u64 v[228:229], s[28:29], 0, v[148:149]
	s_mov_b32 m0, s76
	s_nop 0
	global_load_lds_dwordx4 v[228:229], off
	s_waitcnt vmcnt(8)
	s_waitcnt lgkmcnt(0)
	s_barrier
	s_setprio 1
	s_waitcnt lgkmcnt(0)
	v_mfma_f32_16x16x32_bf16 v[126:129], v[130:133], v[188:191], v[126:129]
	v_mfma_f32_16x16x32_bf16 v[122:125], v[138:141], v[188:191], v[122:125]
	v_mfma_f32_16x16x32_bf16 v[110:113], v[130:133], v[196:199], v[110:113]
	v_mfma_f32_16x16x32_bf16 v[106:109], v[138:141], v[196:199], v[106:109]
	v_mfma_f32_16x16x32_bf16 v[94:97], v[130:133], v[206:209], v[94:97]
	v_mfma_f32_16x16x32_bf16 v[90:93], v[138:141], v[206:209], v[90:93]
	v_mfma_f32_16x16x32_bf16 v[78:81], v[130:133], v[214:217], v[78:81]
	v_mfma_f32_16x16x32_bf16 v[74:77], v[138:141], v[214:217], v[74:77]
	v_mfma_f32_16x16x32_bf16 v[126:129], v[134:137], v[192:195], v[126:129]
	v_mfma_f32_16x16x32_bf16 v[122:125], v[142:145], v[192:195], v[122:125]
	v_mfma_f32_16x16x32_bf16 v[110:113], v[134:137], v[200:203], v[110:113]
	v_mfma_f32_16x16x32_bf16 v[106:109], v[142:145], v[200:203], v[106:109]
	v_mfma_f32_16x16x32_bf16 v[94:97], v[134:137], v[210:213], v[94:97]
	v_mfma_f32_16x16x32_bf16 v[90:93], v[142:145], v[210:213], v[90:93]
	v_mfma_f32_16x16x32_bf16 v[78:81], v[134:137], v[218:221], v[78:81]
	v_mfma_f32_16x16x32_bf16 v[74:77], v[142:145], v[218:221], v[74:77]
	s_setprio 0
	s_setprio 1
	v_mfma_f32_16x16x32_bf16 v[118:121], v[164:167], v[188:191], v[118:121]
	v_mfma_f32_16x16x32_bf16 v[114:117], v[180:183], v[188:191], v[114:117]
	v_mfma_f32_16x16x32_bf16 v[102:105], v[164:167], v[196:199], v[102:105]
	v_mfma_f32_16x16x32_bf16 v[98:101], v[180:183], v[196:199], v[98:101]
	v_mfma_f32_16x16x32_bf16 v[86:89], v[164:167], v[206:209], v[86:89]
	v_mfma_f32_16x16x32_bf16 v[82:85], v[180:183], v[206:209], v[82:85]
	v_mfma_f32_16x16x32_bf16 v[70:73], v[164:167], v[214:217], v[70:73]
	v_mfma_f32_16x16x32_bf16 v[66:69], v[180:183], v[214:217], v[66:69]
	v_mfma_f32_16x16x32_bf16 v[118:121], v[176:179], v[192:195], v[118:121]
	v_mfma_f32_16x16x32_bf16 v[114:117], v[184:187], v[192:195], v[114:117]
	v_mfma_f32_16x16x32_bf16 v[102:105], v[176:179], v[200:203], v[102:105]
	v_mfma_f32_16x16x32_bf16 v[98:101], v[184:187], v[200:203], v[98:101]
	v_mfma_f32_16x16x32_bf16 v[86:89], v[176:179], v[210:213], v[86:89]
	v_mfma_f32_16x16x32_bf16 v[82:85], v[184:187], v[210:213], v[82:85]
	v_mfma_f32_16x16x32_bf16 v[70:73], v[176:179], v[218:221], v[70:73]
	v_mfma_f32_16x16x32_bf16 v[66:69], v[184:187], v[218:221], v[66:69]
	s_setprio 0
	s_barrier
	s_add_i32 s25, s25, s70
	v_lshl_add_u64 v[168:169], v[168:169], 0, s[36:37]
	s_mov_b32 m0, s25
	ds_read_b128 v[188:191], v174 offset:49152
	ds_read_b128 v[192:195], v174 offset:50176
	ds_read_b128 v[196:199], v174 offset:51200
	ds_read_b128 v[200:203], v174 offset:52224
	ds_read_b128 v[206:209], v174 offset:53248
	ds_read_b128 v[210:213], v174 offset:54272
	ds_read_b128 v[214:217], v174 offset:55296
	ds_read_b128 v[218:221], v174 offset:56320
	global_load_lds_dwordx4 v[168:169], off
	s_add_i32 m0, s25, 0x2000
	s_add_u32 s28, s66, 0x40080
	v_lshl_add_u64 v[168:169], v[222:223], 0, s[36:37]
	s_addc_u32 s29, s67, 0
	s_add_i32 s25, s30, s70
	global_load_lds_dwordx4 v[168:169], off
	v_lshl_add_u64 v[168:169], s[28:29], 0, v[150:151]
	s_mov_b32 m0, s25
	s_nop 0
	global_load_lds_dwordx4 v[168:169], off
	v_lshl_add_u64 v[168:169], s[28:29], 0, v[146:147]
	s_add_i32 m0, s25, 0x2000
	s_nop 0
	global_load_lds_dwordx4 v[168:169], off
	v_lshl_add_u64 v[168:169], v[224:225], 0, s[36:37]
	s_mov_b32 m0, s79
	s_nop 0
	global_load_lds_dwordx4 v[168:169], off
	v_lshl_add_u64 v[168:169], v[226:227], 0, s[36:37]
	s_waitcnt vmcnt(7)
	s_waitcnt lgkmcnt(0)
	s_barrier
	s_setprio 1
	s_waitcnt lgkmcnt(0)
	v_mfma_f32_16x16x32_bf16 v[62:65], v[130:133], v[188:191], v[62:65]
	v_mfma_f32_16x16x32_bf16 v[58:61], v[138:141], v[188:191], v[58:61]
	v_mfma_f32_16x16x32_bf16 v[46:49], v[130:133], v[196:199], v[46:49]
	v_mfma_f32_16x16x32_bf16 v[42:45], v[138:141], v[196:199], v[42:45]
	v_mfma_f32_16x16x32_bf16 v[30:33], v[130:133], v[206:209], v[30:33]
	v_mfma_f32_16x16x32_bf16 v[26:29], v[138:141], v[206:209], v[26:29]
	v_mfma_f32_16x16x32_bf16 v[14:17], v[130:133], v[214:217], v[14:17]
	v_mfma_f32_16x16x32_bf16 v[10:13], v[138:141], v[214:217], v[10:13]
	s_mov_b32 m0, s80
	s_nop 0
	global_load_lds_dwordx4 v[168:169], off
	v_mfma_f32_16x16x32_bf16 v[62:65], v[134:137], v[192:195], v[62:65]
	v_mfma_f32_16x16x32_bf16 v[58:61], v[142:145], v[192:195], v[58:61]
	v_mfma_f32_16x16x32_bf16 v[46:49], v[134:137], v[200:203], v[46:49]
	v_mfma_f32_16x16x32_bf16 v[42:45], v[142:145], v[200:203], v[42:45]
	v_mfma_f32_16x16x32_bf16 v[30:33], v[134:137], v[210:213], v[30:33]
	v_mfma_f32_16x16x32_bf16 v[26:29], v[142:145], v[210:213], v[26:29]
	v_mfma_f32_16x16x32_bf16 v[14:17], v[134:137], v[218:221], v[14:17]
	v_mfma_f32_16x16x32_bf16 v[10:13], v[142:145], v[218:221], v[10:13]
	s_setprio 0
	s_setprio 1
	v_mfma_f32_16x16x32_bf16 v[54:57], v[164:167], v[188:191], v[54:57]
	v_mfma_f32_16x16x32_bf16 v[50:53], v[180:183], v[188:191], v[50:53]
	v_mfma_f32_16x16x32_bf16 v[38:41], v[164:167], v[196:199], v[38:41]
	v_mfma_f32_16x16x32_bf16 v[34:37], v[180:183], v[196:199], v[34:37]
	v_mfma_f32_16x16x32_bf16 v[22:25], v[164:167], v[206:209], v[22:25]
	v_mfma_f32_16x16x32_bf16 v[18:21], v[180:183], v[206:209], v[18:21]
	v_mfma_f32_16x16x32_bf16 v[6:9], v[164:167], v[214:217], v[6:9]
	v_mfma_f32_16x16x32_bf16 v[2:5], v[180:183], v[214:217], v[2:5]
	v_mfma_f32_16x16x32_bf16 v[54:57], v[176:179], v[192:195], v[54:57]
	v_mfma_f32_16x16x32_bf16 v[50:53], v[184:187], v[192:195], v[50:53]
	v_mfma_f32_16x16x32_bf16 v[38:41], v[176:179], v[200:203], v[38:41]
	v_mfma_f32_16x16x32_bf16 v[34:37], v[184:187], v[200:203], v[34:37]
	v_mfma_f32_16x16x32_bf16 v[22:25], v[176:179], v[210:213], v[22:25]
	v_mfma_f32_16x16x32_bf16 v[18:21], v[184:187], v[210:213], v[18:21]
	v_mfma_f32_16x16x32_bf16 v[6:9], v[176:179], v[218:221], v[6:9]
	v_mfma_f32_16x16x32_bf16 v[2:5], v[184:187], v[218:221], v[2:5]
	s_setprio 0
	s_barrier
	s_add_i32 s24, s24, 2
	s_add_u32 s64, s64, 0x100
	s_addc_u32 s65, s65, 0
	s_add_u32 s18, s18, 0x100
	s_addc_u32 s19, s19, 0
	s_cmp_gt_u32 s24, 13
	s_cbranch_scc0 .LBB0_1013
	s_and_b64 vcc, exec, s[38:39]
	s_cbranch_vccz .LBB0_1016
	s_barrier

.LBB0_1427:
	s_add_u32 s90, s35, s86
	s_addc_u32 s91, s64, s87
	s_and_b64 s[14:15], s[88:89], exec
	s_cselect_b32 s14, s91, s11
	s_cselect_b32 s15, s90, s10
	s_add_u32 s92, s65, s74
	s_addc_u32 s93, s68, s75
	s_and_b64 s[66:67], s[88:89], exec
	s_cselect_b32 s51, s93, s95
	s_cselect_b32 s84, s92, s94
	s_add_i32 s85, s18, -2
	s_add_u32 s10, s10, 0x40080
	s_addc_u32 s11, s11, 0
	s_add_u32 vcc_lo, s94, 0x100
	s_addc_u32 vcc_hi, s95, 0
	s_mov_b32 s94, 0
	s_waitcnt vmcnt(0)
	s_add_i32 s66, s94, 2
	s_add_u32 s67, s10, 0xfffc0080
	s_addc_u32 s72, s11, -1
	s_cmp_eq_u32 s85, s94
	s_cselect_b32 s97, s14, s72
	s_cselect_b32 s96, s15, s67
	s_cselect_b32 s95, s51, vcc_hi
	s_cselect_b32 s94, s84, vcc_lo
	s_add_i32 s67, 0, 0x10000
	s_add_i32 s62, 0, 0x14000
	v_add_u32_e32 v126, s67, v199
	v_add_u32_e32 v158, s62, v199
	ds_read_b128 v[114:117], v126
	ds_read_b128 v[118:121], v126 offset:1024
	ds_read_b128 v[122:125], v126 offset:2048
	ds_read_b128 v[126:129], v126 offset:3072
	ds_read_b128 v[146:149], v158
	ds_read_b128 v[150:153], v158 offset:1024
	ds_read_b128 v[154:157], v158 offset:2048
	ds_read_b128 v[158:161], v158 offset:3072
	v_lshl_add_u64 v[202:203], s[10:11], 0, v[196:197]
	s_add_i32 m0, s28, 0xc000
	ds_read_b128 v[162:165], v214
	ds_read_b128 v[166:169], v214 offset:1024
	ds_read_b128 v[216:219], v214 offset:2048
	ds_read_b128 v[220:223], v214 offset:3072
	ds_read_b128 v[224:227], v214 offset:4096
	ds_read_b128 v[228:231], v214 offset:5120
	ds_read_b128 v[232:235], v214 offset:6144
	ds_read_b128 v[236:239], v214 offset:7168
	global_load_lds_dwordx4 v[202:203], off
	v_lshl_add_u64 v[202:203], s[10:11], 0, v[176:177]
	s_add_i32 m0, s28, 0xe000
	s_nop 0
	global_load_lds_dwordx4 v[202:203], off
	s_waitcnt vmcnt(8)
	s_waitcnt lgkmcnt(0)
	s_barrier
	s_setprio 1
	s_waitcnt lgkmcnt(0)
	v_mfma_f32_16x16x32_bf16 v[142:145], v[114:117], v[162:165], 0
	v_mfma_f32_16x16x32_bf16 v[138:141], v[122:125], v[162:165], 0
	v_mfma_f32_16x16x32_bf16 v[110:113], v[114:117], v[216:219], 0
	v_mfma_f32_16x16x32_bf16 v[106:109], v[122:125], v[216:219], 0
	v_mfma_f32_16x16x32_bf16 v[98:101], v[114:117], v[224:227], 0
	v_mfma_f32_16x16x32_bf16 v[90:93], v[122:125], v[224:227], 0
	v_mfma_f32_16x16x32_bf16 v[82:85], v[114:117], v[232:235], 0
	v_mfma_f32_16x16x32_bf16 v[74:77], v[122:125], v[232:235], 0
	v_mfma_f32_16x16x32_bf16 v[142:145], v[118:121], v[166:169], v[142:145]
	v_mfma_f32_16x16x32_bf16 v[138:141], v[126:129], v[166:169], v[138:141]
	v_mfma_f32_16x16x32_bf16 v[110:113], v[118:121], v[220:223], v[110:113]
	v_mfma_f32_16x16x32_bf16 v[106:109], v[126:129], v[220:223], v[106:109]
	v_mfma_f32_16x16x32_bf16 v[98:101], v[118:121], v[228:231], v[98:101]
	v_mfma_f32_16x16x32_bf16 v[90:93], v[126:129], v[228:231], v[90:93]
	v_mfma_f32_16x16x32_bf16 v[82:85], v[118:121], v[236:239], v[82:85]
	v_mfma_f32_16x16x32_bf16 v[74:77], v[126:129], v[236:239], v[74:77]
	s_setprio 0
	s_setprio 1
	v_mfma_f32_16x16x32_bf16 v[134:137], v[146:149], v[162:165], 0
	v_mfma_f32_16x16x32_bf16 v[130:133], v[154:157], v[162:165], 0
	v_mfma_f32_16x16x32_bf16 v[102:105], v[146:149], v[216:219], 0
	v_mfma_f32_16x16x32_bf16 v[94:97], v[154:157], v[216:219], 0
	v_mfma_f32_16x16x32_bf16 v[86:89], v[146:149], v[224:227], 0
	v_mfma_f32_16x16x32_bf16 v[78:81], v[154:157], v[224:227], 0
	v_mfma_f32_16x16x32_bf16 v[70:73], v[146:149], v[232:235], 0
	v_mfma_f32_16x16x32_bf16 v[66:69], v[154:157], v[232:235], 0
	v_mfma_f32_16x16x32_bf16 v[134:137], v[150:153], v[166:169], v[134:137]
	v_mfma_f32_16x16x32_bf16 v[130:133], v[158:161], v[166:169], v[130:133]
	v_mfma_f32_16x16x32_bf16 v[102:105], v[150:153], v[220:223], v[102:105]
	v_mfma_f32_16x16x32_bf16 v[94:97], v[158:161], v[220:223], v[94:97]
	v_mfma_f32_16x16x32_bf16 v[86:89], v[150:153], v[228:231], v[86:89]
	v_mfma_f32_16x16x32_bf16 v[78:81], v[158:161], v[228:231], v[78:81]
	v_mfma_f32_16x16x32_bf16 v[70:73], v[150:153], v[236:239], v[70:73]
	v_mfma_f32_16x16x32_bf16 v[66:69], v[158:161], v[236:239], v[66:69]
	s_setprio 0
	s_barrier
	s_add_i32 s63, s67, s17
	v_lshl_add_u64 v[202:203], s[94:95], 0, v[174:175]
	s_mov_b32 m0, s63
	ds_read_b128 v[162:165], v214 offset:16384
	ds_read_b128 v[166:169], v214 offset:17408
	ds_read_b128 v[216:219], v214 offset:18432
	ds_read_b128 v[220:223], v214 offset:19456
	ds_read_b128 v[224:227], v214 offset:20480
	ds_read_b128 v[228:231], v214 offset:21504
	ds_read_b128 v[232:235], v214 offset:22528
	ds_read_b128 v[236:239], v214 offset:23552
	global_load_lds_dwordx4 v[202:203], off
	s_add_i32 m0, s63, 0x2000
	s_add_u32 s72, s94, 0x40000
	v_lshl_add_u64 v[240:241], s[94:95], 0, v[178:179]
	s_addc_u32 s73, s95, 0
	s_add_i32 s62, s62, s17
	global_load_lds_dwordx4 v[240:241], off
	v_lshl_add_u64 v[242:243], s[72:73], 0, v[174:175]
	s_mov_b32 m0, s62
	v_lshl_add_u64 v[244:245], s[96:97], 0, v[176:177]
	global_load_lds_dwordx4 v[242:243], off
	v_lshl_add_u64 v[242:243], s[72:73], 0, v[178:179]
	s_add_i32 m0, s62, 0x2000
	s_nop 0
	global_load_lds_dwordx4 v[242:243], off
	v_lshl_add_u64 v[242:243], s[96:97], 0, v[172:173]
	s_mov_b32 m0, s28
	s_nop 0
	global_load_lds_dwordx4 v[242:243], off
	s_waitcnt vmcnt(7)
	s_waitcnt lgkmcnt(0)
	s_barrier
	s_setprio 1
	s_waitcnt lgkmcnt(0)
	v_mfma_f32_16x16x32_bf16 v[62:65], v[114:117], v[162:165], 0
	v_mfma_f32_16x16x32_bf16 v[58:61], v[122:125], v[162:165], 0
	v_mfma_f32_16x16x32_bf16 v[50:53], v[114:117], v[216:219], 0
	v_mfma_f32_16x16x32_bf16 v[42:45], v[122:125], v[216:219], 0
	v_mfma_f32_16x16x32_bf16 v[34:37], v[114:117], v[224:227], 0
	v_mfma_f32_16x16x32_bf16 v[26:29], v[122:125], v[224:227], 0
	v_mfma_f32_16x16x32_bf16 v[18:21], v[114:117], v[232:235], 0
	v_mfma_f32_16x16x32_bf16 v[10:13], v[122:125], v[232:235], 0
	s_mov_b32 m0, s29
	s_nop 0
	global_load_lds_dwordx4 v[244:245], off
	v_mfma_f32_16x16x32_bf16 v[62:65], v[118:121], v[166:169], v[62:65]
	v_mfma_f32_16x16x32_bf16 v[58:61], v[126:129], v[166:169], v[58:61]
	v_mfma_f32_16x16x32_bf16 v[50:53], v[118:121], v[220:223], v[50:53]
	v_mfma_f32_16x16x32_bf16 v[42:45], v[126:129], v[220:223], v[42:45]
	v_mfma_f32_16x16x32_bf16 v[34:37], v[118:121], v[228:231], v[34:37]
	v_mfma_f32_16x16x32_bf16 v[26:29], v[126:129], v[228:231], v[26:29]
	v_mfma_f32_16x16x32_bf16 v[18:21], v[118:121], v[236:239], v[18:21]
	v_mfma_f32_16x16x32_bf16 v[10:13], v[126:129], v[236:239], v[10:13]
	s_setprio 0
	s_setprio 1
	v_mfma_f32_16x16x32_bf16 v[54:57], v[146:149], v[162:165], 0
	v_mfma_f32_16x16x32_bf16 v[46:49], v[154:157], v[162:165], 0
	v_mfma_f32_16x16x32_bf16 v[38:41], v[146:149], v[216:219], 0
	v_mfma_f32_16x16x32_bf16 v[30:33], v[154:157], v[216:219], 0
	v_mfma_f32_16x16x32_bf16 v[22:25], v[146:149], v[224:227], 0
	v_mfma_f32_16x16x32_bf16 v[14:17], v[154:157], v[224:227], 0
	v_mfma_f32_16x16x32_bf16 v[6:9], v[146:149], v[232:235], 0
	v_mfma_f32_16x16x32_bf16 v[2:5], v[154:157], v[232:235], 0
	v_mfma_f32_16x16x32_bf16 v[54:57], v[150:153], v[166:169], v[54:57]
	v_mfma_f32_16x16x32_bf16 v[46:49], v[158:161], v[166:169], v[46:49]
	v_mfma_f32_16x16x32_bf16 v[38:41], v[150:153], v[220:223], v[38:41]
	v_mfma_f32_16x16x32_bf16 v[30:33], v[158:161], v[220:223], v[30:33]
	v_mfma_f32_16x16x32_bf16 v[22:25], v[150:153], v[228:231], v[22:25]
	v_mfma_f32_16x16x32_bf16 v[14:17], v[158:161], v[228:231], v[14:17]
	v_mfma_f32_16x16x32_bf16 v[6:9], v[150:153], v[236:239], v[6:9]
	v_mfma_f32_16x16x32_bf16 v[2:5], v[158:161], v[236:239], v[2:5]
	s_setprio 0
	s_barrier
	s_add_i32 s62, 0, 0x18000
	s_add_i32 s63, 0, 0x1c000
	v_add_u32_e32 v126, s62, v199
	v_add_u32_e32 v158, s63, v199
	ds_read_b128 v[114:117], v126
	ds_read_b128 v[118:121], v126 offset:1024
	ds_read_b128 v[122:125], v126 offset:2048
	ds_read_b128 v[126:129], v126 offset:3072
	ds_read_b128 v[146:149], v158
	ds_read_b128 v[150:153], v158 offset:1024
	ds_read_b128 v[154:157], v158 offset:2048
	ds_read_b128 v[158:161], v158 offset:3072
	s_add_u32 s72, s96, 0x40000
	s_addc_u32 s73, s97, 0
	s_mov_b32 m0, s30
	v_lshl_add_u64 v[246:247], s[72:73], 0, v[172:173]
	ds_read_b128 v[162:165], v214 offset:32768
	ds_read_b128 v[166:169], v214 offset:33792
	ds_read_b128 v[216:219], v214 offset:34816
	ds_read_b128 v[220:223], v214 offset:35840
	ds_read_b128 v[224:227], v214 offset:36864
	ds_read_b128 v[228:231], v214 offset:37888
	ds_read_b128 v[232:235], v214 offset:38912
	ds_read_b128 v[236:239], v214 offset:39936
	global_load_lds_dwordx4 v[246:247], off
	v_lshl_add_u64 v[246:247], s[72:73], 0, v[176:177]
	s_mov_b32 m0, s31
	s_nop 0
	global_load_lds_dwordx4 v[246:247], off
	s_waitcnt vmcnt(8)
	s_waitcnt lgkmcnt(0)
	s_barrier
	s_setprio 1
	s_waitcnt lgkmcnt(0)
	v_mfma_f32_16x16x32_bf16 v[142:145], v[114:117], v[162:165], v[142:145]
	v_mfma_f32_16x16x32_bf16 v[138:141], v[122:125], v[162:165], v[138:141]
	v_mfma_f32_16x16x32_bf16 v[110:113], v[114:117], v[216:219], v[110:113]
	v_mfma_f32_16x16x32_bf16 v[106:109], v[122:125], v[216:219], v[106:109]
	v_mfma_f32_16x16x32_bf16 v[98:101], v[114:117], v[224:227], v[98:101]
	v_mfma_f32_16x16x32_bf16 v[90:93], v[122:125], v[224:227], v[90:93]
	v_mfma_f32_16x16x32_bf16 v[82:85], v[114:117], v[232:235], v[82:85]
	v_mfma_f32_16x16x32_bf16 v[74:77], v[122:125], v[232:235], v[74:77]
	v_mfma_f32_16x16x32_bf16 v[142:145], v[118:121], v[166:169], v[142:145]
	v_mfma_f32_16x16x32_bf16 v[138:141], v[126:129], v[166:169], v[138:141]
	v_mfma_f32_16x16x32_bf16 v[110:113], v[118:121], v[220:223], v[110:113]
	v_mfma_f32_16x16x32_bf16 v[106:109], v[126:129], v[220:223], v[106:109]
	v_mfma_f32_16x16x32_bf16 v[98:101], v[118:121], v[228:231], v[98:101]
	v_mfma_f32_16x16x32_bf16 v[90:93], v[126:129], v[228:231], v[90:93]
	v_mfma_f32_16x16x32_bf16 v[82:85], v[118:121], v[236:239], v[82:85]
	v_mfma_f32_16x16x32_bf16 v[74:77], v[126:129], v[236:239], v[74:77]
	s_setprio 0
	s_setprio 1
	v_mfma_f32_16x16x32_bf16 v[134:137], v[146:149], v[162:165], v[134:137]
	v_mfma_f32_16x16x32_bf16 v[130:133], v[154:157], v[162:165], v[130:133]
	v_mfma_f32_16x16x32_bf16 v[102:105], v[146:149], v[216:219], v[102:105]
	v_mfma_f32_16x16x32_bf16 v[94:97], v[154:157], v[216:219], v[94:97]
	v_mfma_f32_16x16x32_bf16 v[86:89], v[146:149], v[224:227], v[86:89]
	v_mfma_f32_16x16x32_bf16 v[78:81], v[154:157], v[224:227], v[78:81]
	v_mfma_f32_16x16x32_bf16 v[70:73], v[146:149], v[232:235], v[70:73]
	v_mfma_f32_16x16x32_bf16 v[66:69], v[154:157], v[232:235], v[66:69]
	v_mfma_f32_16x16x32_bf16 v[134:137], v[150:153], v[166:169], v[134:137]
	v_mfma_f32_16x16x32_bf16 v[130:133], v[158:161], v[166:169], v[130:133]
	v_mfma_f32_16x16x32_bf16 v[102:105], v[150:153], v[220:223], v[102:105]
	v_mfma_f32_16x16x32_bf16 v[94:97], v[158:161], v[220:223], v[94:97]
	v_mfma_f32_16x16x32_bf16 v[86:89], v[150:153], v[228:231], v[86:89]
	v_mfma_f32_16x16x32_bf16 v[78:81], v[158:161], v[228:231], v[78:81]
	v_mfma_f32_16x16x32_bf16 v[70:73], v[150:153], v[236:239], v[70:73]
	v_mfma_f32_16x16x32_bf16 v[66:69], v[158:161], v[236:239], v[66:69]
	s_setprio 0
	s_barrier
	s_add_i32 s62, s62, s17
	v_lshl_add_u64 v[202:203], v[202:203], 0, s[76:77]
	s_mov_b32 m0, s62
	ds_read_b128 v[162:165], v214 offset:49152
	ds_read_b128 v[166:169], v214 offset:50176
	ds_read_b128 v[216:219], v214 offset:51200
	ds_read_b128 v[220:223], v214 offset:52224
	ds_read_b128 v[224:227], v214 offset:53248
	ds_read_b128 v[228:231], v214 offset:54272
	ds_read_b128 v[232:235], v214 offset:55296
	ds_read_b128 v[236:239], v214 offset:56320
	global_load_lds_dwordx4 v[202:203], off
	s_add_i32 m0, s62, 0x2000
	s_add_u32 s72, s94, 0x40080
	v_lshl_add_u64 v[202:203], v[240:241], 0, s[76:77]
	s_addc_u32 s73, s95, 0
	s_add_i32 s62, s63, s17
	global_load_lds_dwordx4 v[202:203], off
	v_lshl_add_u64 v[202:203], s[72:73], 0, v[174:175]
	s_mov_b32 m0, s62
	s_nop 0
	global_load_lds_dwordx4 v[202:203], off
	v_lshl_add_u64 v[202:203], s[72:73], 0, v[178:179]
	s_add_i32 m0, s62, 0x2000
	s_nop 0
	global_load_lds_dwordx4 v[202:203], off
	v_lshl_add_u64 v[202:203], v[242:243], 0, s[76:77]
	s_mov_b32 m0, s44
	s_nop 0
	global_load_lds_dwordx4 v[202:203], off
	v_lshl_add_u64 v[202:203], v[244:245], 0, s[76:77]
	s_waitcnt vmcnt(7)
	s_waitcnt lgkmcnt(0)
	s_barrier
	s_setprio 1
	s_waitcnt lgkmcnt(0)
	v_mfma_f32_16x16x32_bf16 v[62:65], v[114:117], v[162:165], v[62:65]
	v_mfma_f32_16x16x32_bf16 v[58:61], v[122:125], v[162:165], v[58:61]
	v_mfma_f32_16x16x32_bf16 v[50:53], v[114:117], v[216:219], v[50:53]
	v_mfma_f32_16x16x32_bf16 v[42:45], v[122:125], v[216:219], v[42:45]
	v_mfma_f32_16x16x32_bf16 v[34:37], v[114:117], v[224:227], v[34:37]
	v_mfma_f32_16x16x32_bf16 v[26:29], v[122:125], v[224:227], v[26:29]
	v_mfma_f32_16x16x32_bf16 v[18:21], v[114:117], v[232:235], v[18:21]
	v_mfma_f32_16x16x32_bf16 v[10:13], v[122:125], v[232:235], v[10:13]
	s_mov_b32 m0, s36
	s_nop 0
	global_load_lds_dwordx4 v[202:203], off
	v_mfma_f32_16x16x32_bf16 v[62:65], v[118:121], v[166:169], v[62:65]
	v_mfma_f32_16x16x32_bf16 v[58:61], v[126:129], v[166:169], v[58:61]
	v_mfma_f32_16x16x32_bf16 v[50:53], v[118:121], v[220:223], v[50:53]
	v_mfma_f32_16x16x32_bf16 v[42:45], v[126:129], v[220:223], v[42:45]
	v_mfma_f32_16x16x32_bf16 v[34:37], v[118:121], v[228:231], v[34:37]
	v_mfma_f32_16x16x32_bf16 v[26:29], v[126:129], v[228:231], v[26:29]
	v_mfma_f32_16x16x32_bf16 v[18:21], v[118:121], v[236:239], v[18:21]
	v_mfma_f32_16x16x32_bf16 v[10:13], v[126:129], v[236:239], v[10:13]
	s_setprio 0
	s_setprio 1
	v_mfma_f32_16x16x32_bf16 v[54:57], v[146:149], v[162:165], v[54:57]
	v_mfma_f32_16x16x32_bf16 v[46:49], v[154:157], v[162:165], v[46:49]
	v_mfma_f32_16x16x32_bf16 v[38:41], v[146:149], v[216:219], v[38:41]
	v_mfma_f32_16x16x32_bf16 v[30:33], v[154:157], v[216:219], v[30:33]
	v_mfma_f32_16x16x32_bf16 v[22:25], v[146:149], v[224:227], v[22:25]
	v_mfma_f32_16x16x32_bf16 v[14:17], v[154:157], v[224:227], v[14:17]
	v_mfma_f32_16x16x32_bf16 v[6:9], v[146:149], v[232:235], v[6:9]
	v_mfma_f32_16x16x32_bf16 v[2:5], v[154:157], v[232:235], v[2:5]
	v_mfma_f32_16x16x32_bf16 v[54:57], v[150:153], v[166:169], v[54:57]
	v_mfma_f32_16x16x32_bf16 v[46:49], v[158:161], v[166:169], v[46:49]
	v_mfma_f32_16x16x32_bf16 v[38:41], v[150:153], v[220:223], v[38:41]
	v_mfma_f32_16x16x32_bf16 v[30:33], v[158:161], v[220:223], v[30:33]
	v_mfma_f32_16x16x32_bf16 v[22:25], v[150:153], v[228:231], v[22:25]
	v_mfma_f32_16x16x32_bf16 v[14:17], v[158:161], v[228:231], v[14:17]
	v_mfma_f32_16x16x32_bf16 v[6:9], v[150:153], v[236:239], v[6:9]
	v_mfma_f32_16x16x32_bf16 v[2:5], v[158:161], v[236:239], v[2:5]
	s_setprio 0
	s_barrier
	s_add_u32 s10, s10, 0x100
	s_addc_u32 s11, s11, 0
	s_add_u32 vcc_lo, vcc_lo, 0x100
	s_addc_u32 vcc_hi, vcc_hi, 0
	s_cmp_ge_i32 s66, s18
	s_mov_b32 s94, s66
.LBB0_1428:
	s_add_i32 s66, s94, 2
	s_add_u32 s67, s10, 0xfffc0080
	s_addc_u32 s72, s11, -1
	s_cmp_eq_u32 s85, s94
	s_cselect_b32 s97, s14, s72
	s_cselect_b32 s96, s15, s67
	s_cselect_b32 s95, s51, vcc_hi
	s_cselect_b32 s94, s84, vcc_lo
	s_add_i32 s67, 0, 0x10000
	s_add_i32 s62, 0, 0x14000
	v_add_u32_e32 v126, s67, v199
	v_add_u32_e32 v158, s62, v199
	ds_read_b128 v[114:117], v126
	ds_read_b128 v[118:121], v126 offset:1024
	ds_read_b128 v[122:125], v126 offset:2048
	ds_read_b128 v[126:129], v126 offset:3072
	ds_read_b128 v[146:149], v158
	ds_read_b128 v[150:153], v158 offset:1024
	ds_read_b128 v[154:157], v158 offset:2048
	ds_read_b128 v[158:161], v158 offset:3072
	v_lshl_add_u64 v[202:203], s[10:11], 0, v[196:197]
	s_add_i32 m0, s28, 0xc000
	ds_read_b128 v[162:165], v214
	ds_read_b128 v[166:169], v214 offset:1024
	ds_read_b128 v[216:219], v214 offset:2048
	ds_read_b128 v[220:223], v214 offset:3072
	ds_read_b128 v[224:227], v214 offset:4096
	ds_read_b128 v[228:231], v214 offset:5120
	ds_read_b128 v[232:235], v214 offset:6144
	ds_read_b128 v[236:239], v214 offset:7168
	global_load_lds_dwordx4 v[202:203], off
	v_lshl_add_u64 v[202:203], s[10:11], 0, v[176:177]
	s_add_i32 m0, s28, 0xe000
	s_nop 0
	global_load_lds_dwordx4 v[202:203], off
	s_waitcnt vmcnt(8)
	s_waitcnt lgkmcnt(0)
	s_barrier
	s_setprio 1
	s_waitcnt lgkmcnt(0)
	v_mfma_f32_16x16x32_bf16 v[142:145], v[114:117], v[162:165], v[142:145]
	v_mfma_f32_16x16x32_bf16 v[138:141], v[122:125], v[162:165], v[138:141]
	v_mfma_f32_16x16x32_bf16 v[110:113], v[114:117], v[216:219], v[110:113]
	v_mfma_f32_16x16x32_bf16 v[106:109], v[122:125], v[216:219], v[106:109]
	v_mfma_f32_16x16x32_bf16 v[98:101], v[114:117], v[224:227], v[98:101]
	v_mfma_f32_16x16x32_bf16 v[90:93], v[122:125], v[224:227], v[90:93]
	v_mfma_f32_16x16x32_bf16 v[82:85], v[114:117], v[232:235], v[82:85]
	v_mfma_f32_16x16x32_bf16 v[74:77], v[122:125], v[232:235], v[74:77]
	v_mfma_f32_16x16x32_bf16 v[142:145], v[118:121], v[166:169], v[142:145]
	v_mfma_f32_16x16x32_bf16 v[138:141], v[126:129], v[166:169], v[138:141]
	v_mfma_f32_16x16x32_bf16 v[110:113], v[118:121], v[220:223], v[110:113]
	v_mfma_f32_16x16x32_bf16 v[106:109], v[126:129], v[220:223], v[106:109]
	v_mfma_f32_16x16x32_bf16 v[98:101], v[118:121], v[228:231], v[98:101]
	v_mfma_f32_16x16x32_bf16 v[90:93], v[126:129], v[228:231], v[90:93]
	v_mfma_f32_16x16x32_bf16 v[82:85], v[118:121], v[236:239], v[82:85]
	v_mfma_f32_16x16x32_bf16 v[74:77], v[126:129], v[236:239], v[74:77]
	s_setprio 0
	s_setprio 1
	v_mfma_f32_16x16x32_bf16 v[134:137], v[146:149], v[162:165], v[134:137]
	v_mfma_f32_16x16x32_bf16 v[130:133], v[154:157], v[162:165], v[130:133]
	v_mfma_f32_16x16x32_bf16 v[102:105], v[146:149], v[216:219], v[102:105]
	v_mfma_f32_16x16x32_bf16 v[94:97], v[154:157], v[216:219], v[94:97]
	v_mfma_f32_16x16x32_bf16 v[86:89], v[146:149], v[224:227], v[86:89]
	v_mfma_f32_16x16x32_bf16 v[78:81], v[154:157], v[224:227], v[78:81]
	v_mfma_f32_16x16x32_bf16 v[70:73], v[146:149], v[232:235], v[70:73]
	v_mfma_f32_16x16x32_bf16 v[66:69], v[154:157], v[232:235], v[66:69]
	v_mfma_f32_16x16x32_bf16 v[134:137], v[150:153], v[166:169], v[134:137]
	v_mfma_f32_16x16x32_bf16 v[130:133], v[158:161], v[166:169], v[130:133]
	v_mfma_f32_16x16x32_bf16 v[102:105], v[150:153], v[220:223], v[102:105]
	v_mfma_f32_16x16x32_bf16 v[94:97], v[158:161], v[220:223], v[94:97]
	v_mfma_f32_16x16x32_bf16 v[86:89], v[150:153], v[228:231], v[86:89]
	v_mfma_f32_16x16x32_bf16 v[78:81], v[158:161], v[228:231], v[78:81]
	v_mfma_f32_16x16x32_bf16 v[70:73], v[150:153], v[236:239], v[70:73]
	v_mfma_f32_16x16x32_bf16 v[66:69], v[158:161], v[236:239], v[66:69]
	s_setprio 0
	s_barrier
	s_add_i32 s63, s67, s17
	v_lshl_add_u64 v[202:203], s[94:95], 0, v[174:175]
	s_mov_b32 m0, s63
	ds_read_b128 v[162:165], v214 offset:16384
	ds_read_b128 v[166:169], v214 offset:17408
	ds_read_b128 v[216:219], v214 offset:18432
	ds_read_b128 v[220:223], v214 offset:19456
	ds_read_b128 v[224:227], v214 offset:20480
	ds_read_b128 v[228:231], v214 offset:21504
	ds_read_b128 v[232:235], v214 offset:22528
	ds_read_b128 v[236:239], v214 offset:23552
	global_load_lds_dwordx4 v[202:203], off
	s_add_i32 m0, s63, 0x2000
	s_add_u32 s72, s94, 0x40000
	v_lshl_add_u64 v[240:241], s[94:95], 0, v[178:179]
	s_addc_u32 s73, s95, 0
	s_add_i32 s62, s62, s17
	global_load_lds_dwordx4 v[240:241], off
	v_lshl_add_u64 v[242:243], s[72:73], 0, v[174:175]
	s_mov_b32 m0, s62
	v_lshl_add_u64 v[244:245], s[96:97], 0, v[176:177]
	global_load_lds_dwordx4 v[242:243], off
	v_lshl_add_u64 v[242:243], s[72:73], 0, v[178:179]
	s_add_i32 m0, s62, 0x2000
	s_nop 0
	global_load_lds_dwordx4 v[242:243], off
	v_lshl_add_u64 v[242:243], s[96:97], 0, v[172:173]
	s_mov_b32 m0, s28
	s_nop 0
	global_load_lds_dwordx4 v[242:243], off
	s_waitcnt vmcnt(7)
	s_waitcnt lgkmcnt(0)
	s_barrier
	s_setprio 1
	s_waitcnt lgkmcnt(0)
	v_mfma_f32_16x16x32_bf16 v[62:65], v[114:117], v[162:165], v[62:65]
	v_mfma_f32_16x16x32_bf16 v[58:61], v[122:125], v[162:165], v[58:61]
	v_mfma_f32_16x16x32_bf16 v[50:53], v[114:117], v[216:219], v[50:53]
	v_mfma_f32_16x16x32_bf16 v[42:45], v[122:125], v[216:219], v[42:45]
	v_mfma_f32_16x16x32_bf16 v[34:37], v[114:117], v[224:227], v[34:37]
	v_mfma_f32_16x16x32_bf16 v[26:29], v[122:125], v[224:227], v[26:29]
	v_mfma_f32_16x16x32_bf16 v[18:21], v[114:117], v[232:235], v[18:21]
	v_mfma_f32_16x16x32_bf16 v[10:13], v[122:125], v[232:235], v[10:13]
	s_mov_b32 m0, s29
	s_nop 0
	global_load_lds_dwordx4 v[244:245], off
	v_mfma_f32_16x16x32_bf16 v[62:65], v[118:121], v[166:169], v[62:65]
	v_mfma_f32_16x16x32_bf16 v[58:61], v[126:129], v[166:169], v[58:61]
	v_mfma_f32_16x16x32_bf16 v[50:53], v[118:121], v[220:223], v[50:53]
	v_mfma_f32_16x16x32_bf16 v[42:45], v[126:129], v[220:223], v[42:45]
	v_mfma_f32_16x16x32_bf16 v[34:37], v[118:121], v[228:231], v[34:37]
	v_mfma_f32_16x16x32_bf16 v[26:29], v[126:129], v[228:231], v[26:29]
	v_mfma_f32_16x16x32_bf16 v[18:21], v[118:121], v[236:239], v[18:21]
	v_mfma_f32_16x16x32_bf16 v[10:13], v[126:129], v[236:239], v[10:13]
	s_setprio 0
	s_setprio 1
	v_mfma_f32_16x16x32_bf16 v[54:57], v[146:149], v[162:165], v[54:57]
	v_mfma_f32_16x16x32_bf16 v[46:49], v[154:157], v[162:165], v[46:49]
	v_mfma_f32_16x16x32_bf16 v[38:41], v[146:149], v[216:219], v[38:41]
	v_mfma_f32_16x16x32_bf16 v[30:33], v[154:157], v[216:219], v[30:33]
	v_mfma_f32_16x16x32_bf16 v[22:25], v[146:149], v[224:227], v[22:25]
	v_mfma_f32_16x16x32_bf16 v[14:17], v[154:157], v[224:227], v[14:17]
	v_mfma_f32_16x16x32_bf16 v[6:9], v[146:149], v[232:235], v[6:9]
	v_mfma_f32_16x16x32_bf16 v[2:5], v[154:157], v[232:235], v[2:5]
	v_mfma_f32_16x16x32_bf16 v[54:57], v[150:153], v[166:169], v[54:57]
	v_mfma_f32_16x16x32_bf16 v[46:49], v[158:161], v[166:169], v[46:49]
	v_mfma_f32_16x16x32_bf16 v[38:41], v[150:153], v[220:223], v[38:41]
	v_mfma_f32_16x16x32_bf16 v[30:33], v[158:161], v[220:223], v[30:33]
	v_mfma_f32_16x16x32_bf16 v[22:25], v[150:153], v[228:231], v[22:25]
	v_mfma_f32_16x16x32_bf16 v[14:17], v[158:161], v[228:231], v[14:17]
	v_mfma_f32_16x16x32_bf16 v[6:9], v[150:153], v[236:239], v[6:9]
	v_mfma_f32_16x16x32_bf16 v[2:5], v[158:161], v[236:239], v[2:5]
	s_setprio 0
	s_barrier
	s_add_i32 s62, 0, 0x18000
	s_add_i32 s63, 0, 0x1c000
	v_add_u32_e32 v126, s62, v199
	v_add_u32_e32 v158, s63, v199
	ds_read_b128 v[114:117], v126
	ds_read_b128 v[118:121], v126 offset:1024
	ds_read_b128 v[122:125], v126 offset:2048
	ds_read_b128 v[126:129], v126 offset:3072
	ds_read_b128 v[146:149], v158
	ds_read_b128 v[150:153], v158 offset:1024
	ds_read_b128 v[154:157], v158 offset:2048
	ds_read_b128 v[158:161], v158 offset:3072
	s_add_u32 s72, s96, 0x40000
	s_addc_u32 s73, s97, 0
	s_mov_b32 m0, s30
	v_lshl_add_u64 v[246:247], s[72:73], 0, v[172:173]
	ds_read_b128 v[162:165], v214 offset:32768
	ds_read_b128 v[166:169], v214 offset:33792
	ds_read_b128 v[216:219], v214 offset:34816
	ds_read_b128 v[220:223], v214 offset:35840
	ds_read_b128 v[224:227], v214 offset:36864
	ds_read_b128 v[228:231], v214 offset:37888
	ds_read_b128 v[232:235], v214 offset:38912
	ds_read_b128 v[236:239], v214 offset:39936
	global_load_lds_dwordx4 v[246:247], off
	v_lshl_add_u64 v[246:247], s[72:73], 0, v[176:177]
	s_mov_b32 m0, s31
	s_nop 0
	global_load_lds_dwordx4 v[246:247], off
	s_waitcnt vmcnt(8)
	s_waitcnt lgkmcnt(0)
	s_barrier
	s_setprio 1
	s_waitcnt lgkmcnt(0)
	v_mfma_f32_16x16x32_bf16 v[142:145], v[114:117], v[162:165], v[142:145]
	v_mfma_f32_16x16x32_bf16 v[138:141], v[122:125], v[162:165], v[138:141]
	v_mfma_f32_16x16x32_bf16 v[110:113], v[114:117], v[216:219], v[110:113]
	v_mfma_f32_16x16x32_bf16 v[106:109], v[122:125], v[216:219], v[106:109]
	v_mfma_f32_16x16x32_bf16 v[98:101], v[114:117], v[224:227], v[98:101]
	v_mfma_f32_16x16x32_bf16 v[90:93], v[122:125], v[224:227], v[90:93]
	v_mfma_f32_16x16x32_bf16 v[82:85], v[114:117], v[232:235], v[82:85]
	v_mfma_f32_16x16x32_bf16 v[74:77], v[122:125], v[232:235], v[74:77]
	v_mfma_f32_16x16x32_bf16 v[142:145], v[118:121], v[166:169], v[142:145]
	v_mfma_f32_16x16x32_bf16 v[138:141], v[126:129], v[166:169], v[138:141]
	v_mfma_f32_16x16x32_bf16 v[110:113], v[118:121], v[220:223], v[110:113]
	v_mfma_f32_16x16x32_bf16 v[106:109], v[126:129], v[220:223], v[106:109]
	v_mfma_f32_16x16x32_bf16 v[98:101], v[118:121], v[228:231], v[98:101]
	v_mfma_f32_16x16x32_bf16 v[90:93], v[126:129], v[228:231], v[90:93]
	v_mfma_f32_16x16x32_bf16 v[82:85], v[118:121], v[236:239], v[82:85]
	v_mfma_f32_16x16x32_bf16 v[74:77], v[126:129], v[236:239], v[74:77]
	s_setprio 0
	s_setprio 1
	v_mfma_f32_16x16x32_bf16 v[134:137], v[146:149], v[162:165], v[134:137]
	v_mfma_f32_16x16x32_bf16 v[130:133], v[154:157], v[162:165], v[130:133]
	v_mfma_f32_16x16x32_bf16 v[102:105], v[146:149], v[216:219], v[102:105]
	v_mfma_f32_16x16x32_bf16 v[94:97], v[154:157], v[216:219], v[94:97]
	v_mfma_f32_16x16x32_bf16 v[86:89], v[146:149], v[224:227], v[86:89]
	v_mfma_f32_16x16x32_bf16 v[78:81], v[154:157], v[224:227], v[78:81]
	v_mfma_f32_16x16x32_bf16 v[70:73], v[146:149], v[232:235], v[70:73]
	v_mfma_f32_16x16x32_bf16 v[66:69], v[154:157], v[232:235], v[66:69]
	v_mfma_f32_16x16x32_bf16 v[134:137], v[150:153], v[166:169], v[134:137]
	v_mfma_f32_16x16x32_bf16 v[130:133], v[158:161], v[166:169], v[130:133]
	v_mfma_f32_16x16x32_bf16 v[102:105], v[150:153], v[220:223], v[102:105]
	v_mfma_f32_16x16x32_bf16 v[94:97], v[158:161], v[220:223], v[94:97]
	v_mfma_f32_16x16x32_bf16 v[86:89], v[150:153], v[228:231], v[86:89]
	v_mfma_f32_16x16x32_bf16 v[78:81], v[158:161], v[228:231], v[78:81]
	v_mfma_f32_16x16x32_bf16 v[70:73], v[150:153], v[236:239], v[70:73]
	v_mfma_f32_16x16x32_bf16 v[66:69], v[158:161], v[236:239], v[66:69]
	s_setprio 0
	s_barrier
	s_add_i32 s62, s62, s17
	v_lshl_add_u64 v[202:203], v[202:203], 0, s[76:77]
	s_mov_b32 m0, s62
	ds_read_b128 v[162:165], v214 offset:49152
	ds_read_b128 v[166:169], v214 offset:50176
	ds_read_b128 v[216:219], v214 offset:51200
	ds_read_b128 v[220:223], v214 offset:52224
	ds_read_b128 v[224:227], v214 offset:53248
	ds_read_b128 v[228:231], v214 offset:54272
	ds_read_b128 v[232:235], v214 offset:55296
	ds_read_b128 v[236:239], v214 offset:56320
	global_load_lds_dwordx4 v[202:203], off
	s_add_i32 m0, s62, 0x2000
	s_add_u32 s72, s94, 0x40080
	v_lshl_add_u64 v[202:203], v[240:241], 0, s[76:77]
	s_addc_u32 s73, s95, 0
	s_add_i32 s62, s63, s17
	global_load_lds_dwordx4 v[202:203], off
	v_lshl_add_u64 v[202:203], s[72:73], 0, v[174:175]
	s_mov_b32 m0, s62
	s_nop 0
	global_load_lds_dwordx4 v[202:203], off
	v_lshl_add_u64 v[202:203], s[72:73], 0, v[178:179]
	s_add_i32 m0, s62, 0x2000
	s_nop 0
	global_load_lds_dwordx4 v[202:203], off
	v_lshl_add_u64 v[202:203], v[242:243], 0, s[76:77]
	s_mov_b32 m0, s44
	s_nop 0
	global_load_lds_dwordx4 v[202:203], off
	v_lshl_add_u64 v[202:203], v[244:245], 0, s[76:77]
	s_waitcnt vmcnt(7)
	s_waitcnt lgkmcnt(0)
	s_barrier
	s_setprio 1
	s_waitcnt lgkmcnt(0)
	v_mfma_f32_16x16x32_bf16 v[62:65], v[114:117], v[162:165], v[62:65]
	v_mfma_f32_16x16x32_bf16 v[58:61], v[122:125], v[162:165], v[58:61]
	v_mfma_f32_16x16x32_bf16 v[50:53], v[114:117], v[216:219], v[50:53]
	v_mfma_f32_16x16x32_bf16 v[42:45], v[122:125], v[216:219], v[42:45]
	v_mfma_f32_16x16x32_bf16 v[34:37], v[114:117], v[224:227], v[34:37]
	v_mfma_f32_16x16x32_bf16 v[26:29], v[122:125], v[224:227], v[26:29]
	v_mfma_f32_16x16x32_bf16 v[18:21], v[114:117], v[232:235], v[18:21]
	v_mfma_f32_16x16x32_bf16 v[10:13], v[122:125], v[232:235], v[10:13]
	s_mov_b32 m0, s36
	s_nop 0
	global_load_lds_dwordx4 v[202:203], off
	v_mfma_f32_16x16x32_bf16 v[62:65], v[118:121], v[166:169], v[62:65]
	v_mfma_f32_16x16x32_bf16 v[58:61], v[126:129], v[166:169], v[58:61]
	v_mfma_f32_16x16x32_bf16 v[50:53], v[118:121], v[220:223], v[50:53]
	v_mfma_f32_16x16x32_bf16 v[42:45], v[126:129], v[220:223], v[42:45]
	v_mfma_f32_16x16x32_bf16 v[34:37], v[118:121], v[228:231], v[34:37]
	v_mfma_f32_16x16x32_bf16 v[26:29], v[126:129], v[228:231], v[26:29]
	v_mfma_f32_16x16x32_bf16 v[18:21], v[118:121], v[236:239], v[18:21]
	v_mfma_f32_16x16x32_bf16 v[10:13], v[126:129], v[236:239], v[10:13]
	s_setprio 0
	s_setprio 1
	v_mfma_f32_16x16x32_bf16 v[54:57], v[146:149], v[162:165], v[54:57]
	v_mfma_f32_16x16x32_bf16 v[46:49], v[154:157], v[162:165], v[46:49]
	v_mfma_f32_16x16x32_bf16 v[38:41], v[146:149], v[216:219], v[38:41]
	v_mfma_f32_16x16x32_bf16 v[30:33], v[154:157], v[216:219], v[30:33]
	v_mfma_f32_16x16x32_bf16 v[22:25], v[146:149], v[224:227], v[22:25]
	v_mfma_f32_16x16x32_bf16 v[14:17], v[154:157], v[224:227], v[14:17]
	v_mfma_f32_16x16x32_bf16 v[6:9], v[146:149], v[232:235], v[6:9]
	v_mfma_f32_16x16x32_bf16 v[2:5], v[154:157], v[232:235], v[2:5]
	v_mfma_f32_16x16x32_bf16 v[54:57], v[150:153], v[166:169], v[54:57]
	v_mfma_f32_16x16x32_bf16 v[46:49], v[158:161], v[166:169], v[46:49]
	v_mfma_f32_16x16x32_bf16 v[38:41], v[150:153], v[220:223], v[38:41]
	v_mfma_f32_16x16x32_bf16 v[30:33], v[158:161], v[220:223], v[30:33]
	v_mfma_f32_16x16x32_bf16 v[22:25], v[150:153], v[228:231], v[22:25]
	v_mfma_f32_16x16x32_bf16 v[14:17], v[158:161], v[228:231], v[14:17]
	v_mfma_f32_16x16x32_bf16 v[6:9], v[150:153], v[236:239], v[6:9]
	v_mfma_f32_16x16x32_bf16 v[2:5], v[158:161], v[236:239], v[2:5]
	s_setprio 0
	s_barrier
	s_add_u32 s10, s10, 0x100
	s_addc_u32 s11, s11, 0
	s_add_u32 vcc_lo, vcc_lo, 0x100
	s_addc_u32 vcc_hi, vcc_hi, 0
	s_cmp_ge_i32 s66, s18
	s_mov_b32 s94, s66
	s_cbranch_scc0 .LBB0_1428
	s_and_b64 vcc, exec, s[82:83]
	s_cbranch_vccz .LBB0_1431
	s_barrier

.LBB0_1618:
	s_add_u32 s24, s96, s20
	s_addc_u32 s25, s97, s21
	s_and_b64 s[14:15], s[4:5], exec
	s_cselect_b32 s14, s25, s29
	s_cselect_b32 s15, s24, s28
	s_add_u32 s26, s2, s22
	s_addc_u32 s27, s3, s23
	s_and_b64 s[36:37], s[4:5], exec
	s_cselect_b32 s17, s27, s31
	s_cselect_b32 s49, s26, s30
	s_add_u32 s28, s28, 0x40080
	s_addc_u32 s29, s29, 0
	s_add_u32 s50, s30, 0x100
	s_addc_u32 s51, s31, 0
	s_mov_b32 s62, -2
	ds_read_b128 v[154:157], v150
	ds_read_b128 v[158:161], v150 offset:1024
	ds_read_b128 v[162:165], v150 offset:2048
	ds_read_b128 v[166:169], v150 offset:3072
	ds_read_b128 v[170:173], v151
	ds_read_b128 v[174:177], v151 offset:1024
	ds_read_b128 v[178:181], v151 offset:2048
	ds_read_b128 v[182:185], v151 offset:3072
	s_add_u32 s30, s28, 0xfffc0080
	s_addc_u32 s31, s29, -1
	s_cmp_eq_u32 s62, 12
	s_cselect_b32 s37, s14, s31
	s_cselect_b32 s36, s15, s30
	s_cselect_b32 s31, s17, s51
	s_cselect_b32 s30, s49, s50
	v_lshl_add_u64 v[146:147], s[28:29], 0, v[138:139]
	s_add_i32 m0, s19, 0xc000
	ds_read_b128 v[186:189], v152
	ds_read_b128 v[190:193], v152 offset:1024
	ds_read_b128 v[194:197], v152 offset:2048
	ds_read_b128 v[198:201], v152 offset:3072
	ds_read_b128 v[206:209], v152 offset:4096
	ds_read_b128 v[210:213], v152 offset:5120
	ds_read_b128 v[214:217], v152 offset:6144
	ds_read_b128 v[218:221], v152 offset:7168
	global_load_lds_dwordx4 v[146:147], off
	v_lshl_add_u64 v[146:147], s[28:29], 0, v[140:141]
	s_add_i32 m0, s19, 0xe000
	s_nop 0
	global_load_lds_dwordx4 v[146:147], off
	s_waitcnt vmcnt(8)
	s_waitcnt lgkmcnt(0)
	s_barrier
	s_setprio 1
	s_waitcnt lgkmcnt(0)
	v_mfma_f32_16x16x32_bf16 v[126:129], v[154:157], v[186:189], 0
	v_mfma_f32_16x16x32_bf16 v[122:125], v[162:165], v[186:189], 0
	v_mfma_f32_16x16x32_bf16 v[110:113], v[154:157], v[194:197], 0
	v_mfma_f32_16x16x32_bf16 v[106:109], v[162:165], v[194:197], 0
	v_mfma_f32_16x16x32_bf16 v[94:97], v[154:157], v[206:209], 0
	v_mfma_f32_16x16x32_bf16 v[90:93], v[162:165], v[206:209], 0
	v_mfma_f32_16x16x32_bf16 v[78:81], v[154:157], v[214:217], 0
	v_mfma_f32_16x16x32_bf16 v[74:77], v[162:165], v[214:217], 0
	v_mfma_f32_16x16x32_bf16 v[126:129], v[158:161], v[190:193], v[126:129]
	v_mfma_f32_16x16x32_bf16 v[122:125], v[166:169], v[190:193], v[122:125]
	v_mfma_f32_16x16x32_bf16 v[110:113], v[158:161], v[198:201], v[110:113]
	v_mfma_f32_16x16x32_bf16 v[106:109], v[166:169], v[198:201], v[106:109]
	v_mfma_f32_16x16x32_bf16 v[94:97], v[158:161], v[210:213], v[94:97]
	v_mfma_f32_16x16x32_bf16 v[90:93], v[166:169], v[210:213], v[90:93]
	v_mfma_f32_16x16x32_bf16 v[78:81], v[158:161], v[218:221], v[78:81]
	v_mfma_f32_16x16x32_bf16 v[74:77], v[166:169], v[218:221], v[74:77]
	s_setprio 0
	s_setprio 1
	v_mfma_f32_16x16x32_bf16 v[118:121], v[170:173], v[186:189], 0
	v_mfma_f32_16x16x32_bf16 v[114:117], v[178:181], v[186:189], 0
	v_mfma_f32_16x16x32_bf16 v[102:105], v[170:173], v[194:197], 0
	v_mfma_f32_16x16x32_bf16 v[98:101], v[178:181], v[194:197], 0
	v_mfma_f32_16x16x32_bf16 v[86:89], v[170:173], v[206:209], 0
	v_mfma_f32_16x16x32_bf16 v[82:85], v[178:181], v[206:209], 0
	v_mfma_f32_16x16x32_bf16 v[70:73], v[170:173], v[214:217], 0
	v_mfma_f32_16x16x32_bf16 v[66:69], v[178:181], v[214:217], 0
	v_mfma_f32_16x16x32_bf16 v[118:121], v[174:177], v[190:193], v[118:121]
	v_mfma_f32_16x16x32_bf16 v[114:117], v[182:185], v[190:193], v[114:117]
	v_mfma_f32_16x16x32_bf16 v[102:105], v[174:177], v[198:201], v[102:105]
	v_mfma_f32_16x16x32_bf16 v[98:101], v[182:185], v[198:201], v[98:101]
	v_mfma_f32_16x16x32_bf16 v[86:89], v[174:177], v[210:213], v[86:89]
	v_mfma_f32_16x16x32_bf16 v[82:85], v[182:185], v[210:213], v[82:85]
	v_mfma_f32_16x16x32_bf16 v[70:73], v[174:177], v[218:221], v[70:73]
	v_mfma_f32_16x16x32_bf16 v[66:69], v[182:185], v[218:221], v[66:69]
	s_setprio 0
	s_barrier
	s_add_i32 s63, s45, s12
	v_lshl_add_u64 v[146:147], s[30:31], 0, v[134:135]
	s_mov_b32 m0, s63
	ds_read_b128 v[186:189], v152 offset:16384
	ds_read_b128 v[190:193], v152 offset:17408
	ds_read_b128 v[194:197], v152 offset:18432
	ds_read_b128 v[198:201], v152 offset:19456
	ds_read_b128 v[206:209], v152 offset:20480
	ds_read_b128 v[210:213], v152 offset:21504
	ds_read_b128 v[214:217], v152 offset:22528
	ds_read_b128 v[218:221], v152 offset:23552
	global_load_lds_dwordx4 v[146:147], off
	s_add_i32 m0, s63, 0x2000
	s_add_u32 s64, s30, 0x40000
	v_lshl_add_u64 v[202:203], s[30:31], 0, v[130:131]
	s_addc_u32 s65, s31, 0
	s_add_i32 s63, s46, s12
	global_load_lds_dwordx4 v[202:203], off
	v_lshl_add_u64 v[222:223], s[64:65], 0, v[134:135]
	s_mov_b32 m0, s63
	v_lshl_add_u64 v[224:225], s[36:37], 0, v[132:133]
	global_load_lds_dwordx4 v[222:223], off
	v_lshl_add_u64 v[222:223], s[64:65], 0, v[130:131]
	s_add_i32 m0, s63, 0x2000
	s_nop 0
	global_load_lds_dwordx4 v[222:223], off
	v_lshl_add_u64 v[222:223], s[36:37], 0, v[136:137]
	s_mov_b32 m0, s19
	s_nop 0
	global_load_lds_dwordx4 v[222:223], off
	s_waitcnt vmcnt(7)
	s_waitcnt lgkmcnt(0)
	s_barrier
	s_setprio 1
	s_waitcnt lgkmcnt(0)
	v_mfma_f32_16x16x32_bf16 v[62:65], v[154:157], v[186:189], 0
	v_mfma_f32_16x16x32_bf16 v[58:61], v[162:165], v[186:189], 0
	v_mfma_f32_16x16x32_bf16 v[46:49], v[154:157], v[194:197], 0
	v_mfma_f32_16x16x32_bf16 v[42:45], v[162:165], v[194:197], 0
	v_mfma_f32_16x16x32_bf16 v[30:33], v[154:157], v[206:209], 0
	v_mfma_f32_16x16x32_bf16 v[26:29], v[162:165], v[206:209], 0
	v_mfma_f32_16x16x32_bf16 v[14:17], v[154:157], v[214:217], 0
	v_mfma_f32_16x16x32_bf16 v[10:13], v[162:165], v[214:217], 0
	s_mov_b32 m0, s33
	s_nop 0
	global_load_lds_dwordx4 v[224:225], off
	v_mfma_f32_16x16x32_bf16 v[62:65], v[158:161], v[190:193], v[62:65]
	v_mfma_f32_16x16x32_bf16 v[58:61], v[166:169], v[190:193], v[58:61]
	v_mfma_f32_16x16x32_bf16 v[46:49], v[158:161], v[198:201], v[46:49]
	v_mfma_f32_16x16x32_bf16 v[42:45], v[166:169], v[198:201], v[42:45]
	v_mfma_f32_16x16x32_bf16 v[30:33], v[158:161], v[210:213], v[30:33]
	v_mfma_f32_16x16x32_bf16 v[26:29], v[166:169], v[210:213], v[26:29]
	v_mfma_f32_16x16x32_bf16 v[14:17], v[158:161], v[218:221], v[14:17]
	v_mfma_f32_16x16x32_bf16 v[10:13], v[166:169], v[218:221], v[10:13]
	s_setprio 0
	s_setprio 1
	v_mfma_f32_16x16x32_bf16 v[54:57], v[170:173], v[186:189], 0
	v_mfma_f32_16x16x32_bf16 v[50:53], v[178:181], v[186:189], 0
	v_mfma_f32_16x16x32_bf16 v[38:41], v[170:173], v[194:197], 0
	v_mfma_f32_16x16x32_bf16 v[34:37], v[178:181], v[194:197], 0
	v_mfma_f32_16x16x32_bf16 v[22:25], v[170:173], v[206:209], 0
	v_mfma_f32_16x16x32_bf16 v[18:21], v[178:181], v[206:209], 0
	v_mfma_f32_16x16x32_bf16 v[6:9], v[170:173], v[214:217], 0
	v_mfma_f32_16x16x32_bf16 v[2:5], v[178:181], v[214:217], 0
	v_mfma_f32_16x16x32_bf16 v[54:57], v[174:177], v[190:193], v[54:57]
	v_mfma_f32_16x16x32_bf16 v[50:53], v[182:185], v[190:193], v[50:53]
	v_mfma_f32_16x16x32_bf16 v[38:41], v[174:177], v[198:201], v[38:41]
	v_mfma_f32_16x16x32_bf16 v[34:37], v[182:185], v[198:201], v[34:37]
	v_mfma_f32_16x16x32_bf16 v[22:25], v[174:177], v[210:213], v[22:25]
	v_mfma_f32_16x16x32_bf16 v[18:21], v[182:185], v[210:213], v[18:21]
	v_mfma_f32_16x16x32_bf16 v[6:9], v[174:177], v[218:221], v[6:9]
	v_mfma_f32_16x16x32_bf16 v[2:5], v[182:185], v[218:221], v[2:5]
	s_setprio 0
	s_barrier
	s_add_i32 s63, 0, 0x18000
	v_add_u32_e32 v153, s63, v149
	s_add_i32 s64, 0, 0x1c000
	ds_read_b128 v[154:157], v153
	ds_read_b128 v[158:161], v153 offset:1024
	ds_read_b128 v[162:165], v153 offset:2048
	ds_read_b128 v[166:169], v153 offset:3072
	v_add_u32_e32 v153, s64, v149
	ds_read_b128 v[170:173], v153
	ds_read_b128 v[174:177], v153 offset:1024
	ds_read_b128 v[178:181], v153 offset:2048
	ds_read_b128 v[182:185], v153 offset:3072
	s_add_u32 s36, s36, 0x40000
	s_addc_u32 s37, s37, 0
	s_mov_b32 m0, s35
	v_lshl_add_u64 v[226:227], s[36:37], 0, v[136:137]
	ds_read_b128 v[186:189], v152 offset:32768
	ds_read_b128 v[190:193], v152 offset:33792
	ds_read_b128 v[194:197], v152 offset:34816
	ds_read_b128 v[198:201], v152 offset:35840
	ds_read_b128 v[206:209], v152 offset:36864
	ds_read_b128 v[210:213], v152 offset:37888
	ds_read_b128 v[214:217], v152 offset:38912
	ds_read_b128 v[218:221], v152 offset:39936
	global_load_lds_dwordx4 v[226:227], off
	v_lshl_add_u64 v[226:227], s[36:37], 0, v[132:133]
	s_mov_b32 m0, s38
	s_nop 0
	global_load_lds_dwordx4 v[226:227], off
	s_waitcnt vmcnt(8)
	s_waitcnt lgkmcnt(0)
	s_barrier
	s_setprio 1
	s_waitcnt lgkmcnt(0)
	v_mfma_f32_16x16x32_bf16 v[126:129], v[154:157], v[186:189], v[126:129]
	v_mfma_f32_16x16x32_bf16 v[122:125], v[162:165], v[186:189], v[122:125]
	v_mfma_f32_16x16x32_bf16 v[110:113], v[154:157], v[194:197], v[110:113]
	v_mfma_f32_16x16x32_bf16 v[106:109], v[162:165], v[194:197], v[106:109]
	v_mfma_f32_16x16x32_bf16 v[94:97], v[154:157], v[206:209], v[94:97]
	v_mfma_f32_16x16x32_bf16 v[90:93], v[162:165], v[206:209], v[90:93]
	v_mfma_f32_16x16x32_bf16 v[78:81], v[154:157], v[214:217], v[78:81]
	v_mfma_f32_16x16x32_bf16 v[74:77], v[162:165], v[214:217], v[74:77]
	v_mfma_f32_16x16x32_bf16 v[126:129], v[158:161], v[190:193], v[126:129]
	v_mfma_f32_16x16x32_bf16 v[122:125], v[166:169], v[190:193], v[122:125]
	v_mfma_f32_16x16x32_bf16 v[110:113], v[158:161], v[198:201], v[110:113]
	v_mfma_f32_16x16x32_bf16 v[106:109], v[166:169], v[198:201], v[106:109]
	v_mfma_f32_16x16x32_bf16 v[94:97], v[158:161], v[210:213], v[94:97]
	v_mfma_f32_16x16x32_bf16 v[90:93], v[166:169], v[210:213], v[90:93]
	v_mfma_f32_16x16x32_bf16 v[78:81], v[158:161], v[218:221], v[78:81]
	v_mfma_f32_16x16x32_bf16 v[74:77], v[166:169], v[218:221], v[74:77]
	s_setprio 0
	s_setprio 1
	v_mfma_f32_16x16x32_bf16 v[118:121], v[170:173], v[186:189], v[118:121]
	v_mfma_f32_16x16x32_bf16 v[114:117], v[178:181], v[186:189], v[114:117]
	v_mfma_f32_16x16x32_bf16 v[102:105], v[170:173], v[194:197], v[102:105]
	v_mfma_f32_16x16x32_bf16 v[98:101], v[178:181], v[194:197], v[98:101]
	v_mfma_f32_16x16x32_bf16 v[86:89], v[170:173], v[206:209], v[86:89]
	v_mfma_f32_16x16x32_bf16 v[82:85], v[178:181], v[206:209], v[82:85]
	v_mfma_f32_16x16x32_bf16 v[70:73], v[170:173], v[214:217], v[70:73]
	v_mfma_f32_16x16x32_bf16 v[66:69], v[178:181], v[214:217], v[66:69]
	v_mfma_f32_16x16x32_bf16 v[118:121], v[174:177], v[190:193], v[118:121]
	v_mfma_f32_16x16x32_bf16 v[114:117], v[182:185], v[190:193], v[114:117]
	v_mfma_f32_16x16x32_bf16 v[102:105], v[174:177], v[198:201], v[102:105]
	v_mfma_f32_16x16x32_bf16 v[98:101], v[182:185], v[198:201], v[98:101]
	v_mfma_f32_16x16x32_bf16 v[86:89], v[174:177], v[210:213], v[86:89]
	v_mfma_f32_16x16x32_bf16 v[82:85], v[182:185], v[210:213], v[82:85]
	v_mfma_f32_16x16x32_bf16 v[70:73], v[174:177], v[218:221], v[70:73]
	v_mfma_f32_16x16x32_bf16 v[66:69], v[182:185], v[218:221], v[66:69]
	s_setprio 0
	s_barrier
	s_add_i32 s36, s63, s12
	v_lshl_add_u64 v[146:147], v[146:147], 0, s[8:9]
	s_mov_b32 m0, s36
	ds_read_b128 v[186:189], v152 offset:49152
	ds_read_b128 v[190:193], v152 offset:50176
	ds_read_b128 v[194:197], v152 offset:51200
	ds_read_b128 v[198:201], v152 offset:52224
	ds_read_b128 v[206:209], v152 offset:53248
	ds_read_b128 v[210:213], v152 offset:54272
	ds_read_b128 v[214:217], v152 offset:55296
	ds_read_b128 v[218:221], v152 offset:56320
	global_load_lds_dwordx4 v[146:147], off
	s_add_i32 m0, s36, 0x2000
	s_add_u32 s30, s30, 0x40080
	v_lshl_add_u64 v[146:147], v[202:203], 0, s[8:9]
	s_addc_u32 s31, s31, 0
	s_add_i32 s36, s64, s12
	global_load_lds_dwordx4 v[146:147], off
	v_lshl_add_u64 v[146:147], s[30:31], 0, v[134:135]
	s_mov_b32 m0, s36
	s_nop 0
	global_load_lds_dwordx4 v[146:147], off
	v_lshl_add_u64 v[146:147], s[30:31], 0, v[130:131]
	s_add_i32 m0, s36, 0x2000
	s_nop 0
	global_load_lds_dwordx4 v[146:147], off
	v_lshl_add_u64 v[146:147], v[222:223], 0, s[8:9]
	s_mov_b32 m0, s42
	s_nop 0
	global_load_lds_dwordx4 v[146:147], off
	v_lshl_add_u64 v[146:147], v[224:225], 0, s[8:9]
	s_waitcnt vmcnt(7)
	s_waitcnt lgkmcnt(0)
	s_barrier
	s_setprio 1
	s_waitcnt lgkmcnt(0)
	v_mfma_f32_16x16x32_bf16 v[62:65], v[154:157], v[186:189], v[62:65]
	v_mfma_f32_16x16x32_bf16 v[58:61], v[162:165], v[186:189], v[58:61]
	v_mfma_f32_16x16x32_bf16 v[46:49], v[154:157], v[194:197], v[46:49]
	v_mfma_f32_16x16x32_bf16 v[42:45], v[162:165], v[194:197], v[42:45]
	v_mfma_f32_16x16x32_bf16 v[30:33], v[154:157], v[206:209], v[30:33]
	v_mfma_f32_16x16x32_bf16 v[26:29], v[162:165], v[206:209], v[26:29]
	v_mfma_f32_16x16x32_bf16 v[14:17], v[154:157], v[214:217], v[14:17]
	v_mfma_f32_16x16x32_bf16 v[10:13], v[162:165], v[214:217], v[10:13]
	s_mov_b32 m0, s43
	s_nop 0
	global_load_lds_dwordx4 v[146:147], off
	v_mfma_f32_16x16x32_bf16 v[62:65], v[158:161], v[190:193], v[62:65]
	v_mfma_f32_16x16x32_bf16 v[58:61], v[166:169], v[190:193], v[58:61]
	v_mfma_f32_16x16x32_bf16 v[46:49], v[158:161], v[198:201], v[46:49]
	v_mfma_f32_16x16x32_bf16 v[42:45], v[166:169], v[198:201], v[42:45]
	v_mfma_f32_16x16x32_bf16 v[30:33], v[158:161], v[210:213], v[30:33]
	v_mfma_f32_16x16x32_bf16 v[26:29], v[166:169], v[210:213], v[26:29]
	v_mfma_f32_16x16x32_bf16 v[14:17], v[158:161], v[218:221], v[14:17]
	v_mfma_f32_16x16x32_bf16 v[10:13], v[166:169], v[218:221], v[10:13]
	s_setprio 0
	s_setprio 1
	v_mfma_f32_16x16x32_bf16 v[54:57], v[170:173], v[186:189], v[54:57]
	v_mfma_f32_16x16x32_bf16 v[50:53], v[178:181], v[186:189], v[50:53]
	v_mfma_f32_16x16x32_bf16 v[38:41], v[170:173], v[194:197], v[38:41]
	v_mfma_f32_16x16x32_bf16 v[34:37], v[178:181], v[194:197], v[34:37]
	v_mfma_f32_16x16x32_bf16 v[22:25], v[170:173], v[206:209], v[22:25]
	v_mfma_f32_16x16x32_bf16 v[18:21], v[178:181], v[206:209], v[18:21]
	v_mfma_f32_16x16x32_bf16 v[6:9], v[170:173], v[214:217], v[6:9]
	v_mfma_f32_16x16x32_bf16 v[2:5], v[178:181], v[214:217], v[2:5]
	v_mfma_f32_16x16x32_bf16 v[54:57], v[174:177], v[190:193], v[54:57]
	v_mfma_f32_16x16x32_bf16 v[50:53], v[182:185], v[190:193], v[50:53]
	v_mfma_f32_16x16x32_bf16 v[38:41], v[174:177], v[198:201], v[38:41]
	v_mfma_f32_16x16x32_bf16 v[34:37], v[182:185], v[198:201], v[34:37]
	v_mfma_f32_16x16x32_bf16 v[22:25], v[174:177], v[210:213], v[22:25]
	v_mfma_f32_16x16x32_bf16 v[18:21], v[182:185], v[210:213], v[18:21]
	v_mfma_f32_16x16x32_bf16 v[6:9], v[174:177], v[218:221], v[6:9]
	v_mfma_f32_16x16x32_bf16 v[2:5], v[182:185], v[218:221], v[2:5]
	s_setprio 0
	s_barrier
	s_add_i32 s62, s62, 2
	s_add_u32 s28, s28, 0x100
	s_addc_u32 s29, s29, 0
	s_add_u32 s50, s50, 0x100
	s_addc_u32 s51, s51, 0
	s_cmp_gt_u32 s62, 13
.LBB0_1619:
	ds_read_b128 v[154:157], v150
	ds_read_b128 v[158:161], v150 offset:1024
	ds_read_b128 v[162:165], v150 offset:2048
	ds_read_b128 v[166:169], v150 offset:3072
	ds_read_b128 v[170:173], v151
	ds_read_b128 v[174:177], v151 offset:1024
	ds_read_b128 v[178:181], v151 offset:2048
	ds_read_b128 v[182:185], v151 offset:3072
	s_add_u32 s30, s28, 0xfffc0080
	s_addc_u32 s31, s29, -1
	s_cmp_eq_u32 s62, 12
	s_cselect_b32 s37, s14, s31
	s_cselect_b32 s36, s15, s30
	s_cselect_b32 s31, s17, s51
	s_cselect_b32 s30, s49, s50
	v_lshl_add_u64 v[146:147], s[28:29], 0, v[138:139]
	s_add_i32 m0, s19, 0xc000
	ds_read_b128 v[186:189], v152
	ds_read_b128 v[190:193], v152 offset:1024
	ds_read_b128 v[194:197], v152 offset:2048
	ds_read_b128 v[198:201], v152 offset:3072
	ds_read_b128 v[206:209], v152 offset:4096
	ds_read_b128 v[210:213], v152 offset:5120
	ds_read_b128 v[214:217], v152 offset:6144
	ds_read_b128 v[218:221], v152 offset:7168
	global_load_lds_dwordx4 v[146:147], off
	v_lshl_add_u64 v[146:147], s[28:29], 0, v[140:141]
	s_add_i32 m0, s19, 0xe000
	s_nop 0
	global_load_lds_dwordx4 v[146:147], off
	s_waitcnt vmcnt(8)
	s_waitcnt lgkmcnt(0)
	s_barrier
	s_setprio 1
	s_waitcnt lgkmcnt(0)
	v_mfma_f32_16x16x32_bf16 v[126:129], v[154:157], v[186:189], v[126:129]
	v_mfma_f32_16x16x32_bf16 v[122:125], v[162:165], v[186:189], v[122:125]
	v_mfma_f32_16x16x32_bf16 v[110:113], v[154:157], v[194:197], v[110:113]
	v_mfma_f32_16x16x32_bf16 v[106:109], v[162:165], v[194:197], v[106:109]
	v_mfma_f32_16x16x32_bf16 v[94:97], v[154:157], v[206:209], v[94:97]
	v_mfma_f32_16x16x32_bf16 v[90:93], v[162:165], v[206:209], v[90:93]
	v_mfma_f32_16x16x32_bf16 v[78:81], v[154:157], v[214:217], v[78:81]
	v_mfma_f32_16x16x32_bf16 v[74:77], v[162:165], v[214:217], v[74:77]
	v_mfma_f32_16x16x32_bf16 v[126:129], v[158:161], v[190:193], v[126:129]
	v_mfma_f32_16x16x32_bf16 v[122:125], v[166:169], v[190:193], v[122:125]
	v_mfma_f32_16x16x32_bf16 v[110:113], v[158:161], v[198:201], v[110:113]
	v_mfma_f32_16x16x32_bf16 v[106:109], v[166:169], v[198:201], v[106:109]
	v_mfma_f32_16x16x32_bf16 v[94:97], v[158:161], v[210:213], v[94:97]
	v_mfma_f32_16x16x32_bf16 v[90:93], v[166:169], v[210:213], v[90:93]
	v_mfma_f32_16x16x32_bf16 v[78:81], v[158:161], v[218:221], v[78:81]
	v_mfma_f32_16x16x32_bf16 v[74:77], v[166:169], v[218:221], v[74:77]
	s_setprio 0
	s_setprio 1
	v_mfma_f32_16x16x32_bf16 v[118:121], v[170:173], v[186:189], v[118:121]
	v_mfma_f32_16x16x32_bf16 v[114:117], v[178:181], v[186:189], v[114:117]
	v_mfma_f32_16x16x32_bf16 v[102:105], v[170:173], v[194:197], v[102:105]
	v_mfma_f32_16x16x32_bf16 v[98:101], v[178:181], v[194:197], v[98:101]
	v_mfma_f32_16x16x32_bf16 v[86:89], v[170:173], v[206:209], v[86:89]
	v_mfma_f32_16x16x32_bf16 v[82:85], v[178:181], v[206:209], v[82:85]
	v_mfma_f32_16x16x32_bf16 v[70:73], v[170:173], v[214:217], v[70:73]
	v_mfma_f32_16x16x32_bf16 v[66:69], v[178:181], v[214:217], v[66:69]
	v_mfma_f32_16x16x32_bf16 v[118:121], v[174:177], v[190:193], v[118:121]
	v_mfma_f32_16x16x32_bf16 v[114:117], v[182:185], v[190:193], v[114:117]
	v_mfma_f32_16x16x32_bf16 v[102:105], v[174:177], v[198:201], v[102:105]
	v_mfma_f32_16x16x32_bf16 v[98:101], v[182:185], v[198:201], v[98:101]
	v_mfma_f32_16x16x32_bf16 v[86:89], v[174:177], v[210:213], v[86:89]
	v_mfma_f32_16x16x32_bf16 v[82:85], v[182:185], v[210:213], v[82:85]
	v_mfma_f32_16x16x32_bf16 v[70:73], v[174:177], v[218:221], v[70:73]
	v_mfma_f32_16x16x32_bf16 v[66:69], v[182:185], v[218:221], v[66:69]
	s_setprio 0
	s_barrier
	s_add_i32 s63, s45, s12
	v_lshl_add_u64 v[146:147], s[30:31], 0, v[134:135]
	s_mov_b32 m0, s63
	ds_read_b128 v[186:189], v152 offset:16384
	ds_read_b128 v[190:193], v152 offset:17408
	ds_read_b128 v[194:197], v152 offset:18432
	ds_read_b128 v[198:201], v152 offset:19456
	ds_read_b128 v[206:209], v152 offset:20480
	ds_read_b128 v[210:213], v152 offset:21504
	ds_read_b128 v[214:217], v152 offset:22528
	ds_read_b128 v[218:221], v152 offset:23552
	global_load_lds_dwordx4 v[146:147], off
	s_add_i32 m0, s63, 0x2000
	s_add_u32 s64, s30, 0x40000
	v_lshl_add_u64 v[202:203], s[30:31], 0, v[130:131]
	s_addc_u32 s65, s31, 0
	s_add_i32 s63, s46, s12
	global_load_lds_dwordx4 v[202:203], off
	v_lshl_add_u64 v[222:223], s[64:65], 0, v[134:135]
	s_mov_b32 m0, s63
	v_lshl_add_u64 v[224:225], s[36:37], 0, v[132:133]
	global_load_lds_dwordx4 v[222:223], off
	v_lshl_add_u64 v[222:223], s[64:65], 0, v[130:131]
	s_add_i32 m0, s63, 0x2000
	s_nop 0
	global_load_lds_dwordx4 v[222:223], off
	v_lshl_add_u64 v[222:223], s[36:37], 0, v[136:137]
	s_mov_b32 m0, s19
	s_nop 0
	global_load_lds_dwordx4 v[222:223], off
	s_waitcnt vmcnt(7)
	s_waitcnt lgkmcnt(0)
	s_barrier
	s_setprio 1
	s_waitcnt lgkmcnt(0)
	v_mfma_f32_16x16x32_bf16 v[62:65], v[154:157], v[186:189], v[62:65]
	v_mfma_f32_16x16x32_bf16 v[58:61], v[162:165], v[186:189], v[58:61]
	v_mfma_f32_16x16x32_bf16 v[46:49], v[154:157], v[194:197], v[46:49]
	v_mfma_f32_16x16x32_bf16 v[42:45], v[162:165], v[194:197], v[42:45]
	v_mfma_f32_16x16x32_bf16 v[30:33], v[154:157], v[206:209], v[30:33]
	v_mfma_f32_16x16x32_bf16 v[26:29], v[162:165], v[206:209], v[26:29]
	v_mfma_f32_16x16x32_bf16 v[14:17], v[154:157], v[214:217], v[14:17]
	v_mfma_f32_16x16x32_bf16 v[10:13], v[162:165], v[214:217], v[10:13]
	s_mov_b32 m0, s33
	s_nop 0
	global_load_lds_dwordx4 v[224:225], off
	v_mfma_f32_16x16x32_bf16 v[62:65], v[158:161], v[190:193], v[62:65]
	v_mfma_f32_16x16x32_bf16 v[58:61], v[166:169], v[190:193], v[58:61]
	v_mfma_f32_16x16x32_bf16 v[46:49], v[158:161], v[198:201], v[46:49]
	v_mfma_f32_16x16x32_bf16 v[42:45], v[166:169], v[198:201], v[42:45]
	v_mfma_f32_16x16x32_bf16 v[30:33], v[158:161], v[210:213], v[30:33]
	v_mfma_f32_16x16x32_bf16 v[26:29], v[166:169], v[210:213], v[26:29]
	v_mfma_f32_16x16x32_bf16 v[14:17], v[158:161], v[218:221], v[14:17]
	v_mfma_f32_16x16x32_bf16 v[10:13], v[166:169], v[218:221], v[10:13]
	s_setprio 0
	s_setprio 1
	v_mfma_f32_16x16x32_bf16 v[54:57], v[170:173], v[186:189], v[54:57]
	v_mfma_f32_16x16x32_bf16 v[50:53], v[178:181], v[186:189], v[50:53]
	v_mfma_f32_16x16x32_bf16 v[38:41], v[170:173], v[194:197], v[38:41]
	v_mfma_f32_16x16x32_bf16 v[34:37], v[178:181], v[194:197], v[34:37]
	v_mfma_f32_16x16x32_bf16 v[22:25], v[170:173], v[206:209], v[22:25]
	v_mfma_f32_16x16x32_bf16 v[18:21], v[178:181], v[206:209], v[18:21]
	v_mfma_f32_16x16x32_bf16 v[6:9], v[170:173], v[214:217], v[6:9]
	v_mfma_f32_16x16x32_bf16 v[2:5], v[178:181], v[214:217], v[2:5]
	v_mfma_f32_16x16x32_bf16 v[54:57], v[174:177], v[190:193], v[54:57]
	v_mfma_f32_16x16x32_bf16 v[50:53], v[182:185], v[190:193], v[50:53]
	v_mfma_f32_16x16x32_bf16 v[38:41], v[174:177], v[198:201], v[38:41]
	v_mfma_f32_16x16x32_bf16 v[34:37], v[182:185], v[198:201], v[34:37]
	v_mfma_f32_16x16x32_bf16 v[22:25], v[174:177], v[210:213], v[22:25]
	v_mfma_f32_16x16x32_bf16 v[18:21], v[182:185], v[210:213], v[18:21]
	v_mfma_f32_16x16x32_bf16 v[6:9], v[174:177], v[218:221], v[6:9]
	v_mfma_f32_16x16x32_bf16 v[2:5], v[182:185], v[218:221], v[2:5]
	s_setprio 0
	s_barrier
	s_add_i32 s63, 0, 0x18000
	v_add_u32_e32 v153, s63, v149
	s_add_i32 s64, 0, 0x1c000
	ds_read_b128 v[154:157], v153
	ds_read_b128 v[158:161], v153 offset:1024
	ds_read_b128 v[162:165], v153 offset:2048
	ds_read_b128 v[166:169], v153 offset:3072
	v_add_u32_e32 v153, s64, v149
	ds_read_b128 v[170:173], v153
	ds_read_b128 v[174:177], v153 offset:1024
	ds_read_b128 v[178:181], v153 offset:2048
	ds_read_b128 v[182:185], v153 offset:3072
	s_add_u32 s36, s36, 0x40000
	s_addc_u32 s37, s37, 0
	s_mov_b32 m0, s35
	v_lshl_add_u64 v[226:227], s[36:37], 0, v[136:137]
	ds_read_b128 v[186:189], v152 offset:32768
	ds_read_b128 v[190:193], v152 offset:33792
	ds_read_b128 v[194:197], v152 offset:34816
	ds_read_b128 v[198:201], v152 offset:35840
	ds_read_b128 v[206:209], v152 offset:36864
	ds_read_b128 v[210:213], v152 offset:37888
	ds_read_b128 v[214:217], v152 offset:38912
	ds_read_b128 v[218:221], v152 offset:39936
	global_load_lds_dwordx4 v[226:227], off
	v_lshl_add_u64 v[226:227], s[36:37], 0, v[132:133]
	s_mov_b32 m0, s38
	s_nop 0
	global_load_lds_dwordx4 v[226:227], off
	s_waitcnt vmcnt(8)
	s_waitcnt lgkmcnt(0)
	s_barrier
	s_setprio 1
	s_waitcnt lgkmcnt(0)
	v_mfma_f32_16x16x32_bf16 v[126:129], v[154:157], v[186:189], v[126:129]
	v_mfma_f32_16x16x32_bf16 v[122:125], v[162:165], v[186:189], v[122:125]
	v_mfma_f32_16x16x32_bf16 v[110:113], v[154:157], v[194:197], v[110:113]
	v_mfma_f32_16x16x32_bf16 v[106:109], v[162:165], v[194:197], v[106:109]
	v_mfma_f32_16x16x32_bf16 v[94:97], v[154:157], v[206:209], v[94:97]
	v_mfma_f32_16x16x32_bf16 v[90:93], v[162:165], v[206:209], v[90:93]
	v_mfma_f32_16x16x32_bf16 v[78:81], v[154:157], v[214:217], v[78:81]
	v_mfma_f32_16x16x32_bf16 v[74:77], v[162:165], v[214:217], v[74:77]
	v_mfma_f32_16x16x32_bf16 v[126:129], v[158:161], v[190:193], v[126:129]
	v_mfma_f32_16x16x32_bf16 v[122:125], v[166:169], v[190:193], v[122:125]
	v_mfma_f32_16x16x32_bf16 v[110:113], v[158:161], v[198:201], v[110:113]
	v_mfma_f32_16x16x32_bf16 v[106:109], v[166:169], v[198:201], v[106:109]
	v_mfma_f32_16x16x32_bf16 v[94:97], v[158:161], v[210:213], v[94:97]
	v_mfma_f32_16x16x32_bf16 v[90:93], v[166:169], v[210:213], v[90:93]
	v_mfma_f32_16x16x32_bf16 v[78:81], v[158:161], v[218:221], v[78:81]
	v_mfma_f32_16x16x32_bf16 v[74:77], v[166:169], v[218:221], v[74:77]
	s_setprio 0
	s_setprio 1
	v_mfma_f32_16x16x32_bf16 v[118:121], v[170:173], v[186:189], v[118:121]
	v_mfma_f32_16x16x32_bf16 v[114:117], v[178:181], v[186:189], v[114:117]
	v_mfma_f32_16x16x32_bf16 v[102:105], v[170:173], v[194:197], v[102:105]
	v_mfma_f32_16x16x32_bf16 v[98:101], v[178:181], v[194:197], v[98:101]
	v_mfma_f32_16x16x32_bf16 v[86:89], v[170:173], v[206:209], v[86:89]
	v_mfma_f32_16x16x32_bf16 v[82:85], v[178:181], v[206:209], v[82:85]
	v_mfma_f32_16x16x32_bf16 v[70:73], v[170:173], v[214:217], v[70:73]
	v_mfma_f32_16x16x32_bf16 v[66:69], v[178:181], v[214:217], v[66:69]
	v_mfma_f32_16x16x32_bf16 v[118:121], v[174:177], v[190:193], v[118:121]
	v_mfma_f32_16x16x32_bf16 v[114:117], v[182:185], v[190:193], v[114:117]
	v_mfma_f32_16x16x32_bf16 v[102:105], v[174:177], v[198:201], v[102:105]
	v_mfma_f32_16x16x32_bf16 v[98:101], v[182:185], v[198:201], v[98:101]
	v_mfma_f32_16x16x32_bf16 v[86:89], v[174:177], v[210:213], v[86:89]
	v_mfma_f32_16x16x32_bf16 v[82:85], v[182:185], v[210:213], v[82:85]
	v_mfma_f32_16x16x32_bf16 v[70:73], v[174:177], v[218:221], v[70:73]
	v_mfma_f32_16x16x32_bf16 v[66:69], v[182:185], v[218:221], v[66:69]
	s_setprio 0
	s_barrier
	s_add_i32 s36, s63, s12
	v_lshl_add_u64 v[146:147], v[146:147], 0, s[8:9]
	s_mov_b32 m0, s36
	ds_read_b128 v[186:189], v152 offset:49152
	ds_read_b128 v[190:193], v152 offset:50176
	ds_read_b128 v[194:197], v152 offset:51200
	ds_read_b128 v[198:201], v152 offset:52224
	ds_read_b128 v[206:209], v152 offset:53248
	ds_read_b128 v[210:213], v152 offset:54272
	ds_read_b128 v[214:217], v152 offset:55296
	ds_read_b128 v[218:221], v152 offset:56320
	global_load_lds_dwordx4 v[146:147], off
	s_add_i32 m0, s36, 0x2000
	s_add_u32 s30, s30, 0x40080
	v_lshl_add_u64 v[146:147], v[202:203], 0, s[8:9]
	s_addc_u32 s31, s31, 0
	s_add_i32 s36, s64, s12
	global_load_lds_dwordx4 v[146:147], off
	v_lshl_add_u64 v[146:147], s[30:31], 0, v[134:135]
	s_mov_b32 m0, s36
	s_nop 0
	global_load_lds_dwordx4 v[146:147], off
	v_lshl_add_u64 v[146:147], s[30:31], 0, v[130:131]
	s_add_i32 m0, s36, 0x2000
	s_nop 0
	global_load_lds_dwordx4 v[146:147], off
	v_lshl_add_u64 v[146:147], v[222:223], 0, s[8:9]
	s_mov_b32 m0, s42
	s_nop 0
	global_load_lds_dwordx4 v[146:147], off
	v_lshl_add_u64 v[146:147], v[224:225], 0, s[8:9]
	s_waitcnt vmcnt(7)
	s_waitcnt lgkmcnt(0)
	s_barrier
	s_setprio 1
	s_waitcnt lgkmcnt(0)
	v_mfma_f32_16x16x32_bf16 v[62:65], v[154:157], v[186:189], v[62:65]
	v_mfma_f32_16x16x32_bf16 v[58:61], v[162:165], v[186:189], v[58:61]
	v_mfma_f32_16x16x32_bf16 v[46:49], v[154:157], v[194:197], v[46:49]
	v_mfma_f32_16x16x32_bf16 v[42:45], v[162:165], v[194:197], v[42:45]
	v_mfma_f32_16x16x32_bf16 v[30:33], v[154:157], v[206:209], v[30:33]
	v_mfma_f32_16x16x32_bf16 v[26:29], v[162:165], v[206:209], v[26:29]
	v_mfma_f32_16x16x32_bf16 v[14:17], v[154:157], v[214:217], v[14:17]
	v_mfma_f32_16x16x32_bf16 v[10:13], v[162:165], v[214:217], v[10:13]
	s_mov_b32 m0, s43
	s_nop 0
	global_load_lds_dwordx4 v[146:147], off
	v_mfma_f32_16x16x32_bf16 v[62:65], v[158:161], v[190:193], v[62:65]
	v_mfma_f32_16x16x32_bf16 v[58:61], v[166:169], v[190:193], v[58:61]
	v_mfma_f32_16x16x32_bf16 v[46:49], v[158:161], v[198:201], v[46:49]
	v_mfma_f32_16x16x32_bf16 v[42:45], v[166:169], v[198:201], v[42:45]
	v_mfma_f32_16x16x32_bf16 v[30:33], v[158:161], v[210:213], v[30:33]
	v_mfma_f32_16x16x32_bf16 v[26:29], v[166:169], v[210:213], v[26:29]
	v_mfma_f32_16x16x32_bf16 v[14:17], v[158:161], v[218:221], v[14:17]
	v_mfma_f32_16x16x32_bf16 v[10:13], v[166:169], v[218:221], v[10:13]
	s_setprio 0
	s_setprio 1
	v_mfma_f32_16x16x32_bf16 v[54:57], v[170:173], v[186:189], v[54:57]
	v_mfma_f32_16x16x32_bf16 v[50:53], v[178:181], v[186:189], v[50:53]
	v_mfma_f32_16x16x32_bf16 v[38:41], v[170:173], v[194:197], v[38:41]
	v_mfma_f32_16x16x32_bf16 v[34:37], v[178:181], v[194:197], v[34:37]
	v_mfma_f32_16x16x32_bf16 v[22:25], v[170:173], v[206:209], v[22:25]
	v_mfma_f32_16x16x32_bf16 v[18:21], v[178:181], v[206:209], v[18:21]
	v_mfma_f32_16x16x32_bf16 v[6:9], v[170:173], v[214:217], v[6:9]
	v_mfma_f32_16x16x32_bf16 v[2:5], v[178:181], v[214:217], v[2:5]
	v_mfma_f32_16x16x32_bf16 v[54:57], v[174:177], v[190:193], v[54:57]
	v_mfma_f32_16x16x32_bf16 v[50:53], v[182:185], v[190:193], v[50:53]
	v_mfma_f32_16x16x32_bf16 v[38:41], v[174:177], v[198:201], v[38:41]
	v_mfma_f32_16x16x32_bf16 v[34:37], v[182:185], v[198:201], v[34:37]
	v_mfma_f32_16x16x32_bf16 v[22:25], v[174:177], v[210:213], v[22:25]
	v_mfma_f32_16x16x32_bf16 v[18:21], v[182:185], v[210:213], v[18:21]
	v_mfma_f32_16x16x32_bf16 v[6:9], v[174:177], v[218:221], v[6:9]
	v_mfma_f32_16x16x32_bf16 v[2:5], v[182:185], v[218:221], v[2:5]
	s_setprio 0
	s_barrier
	s_add_i32 s62, s62, 2
	s_add_u32 s28, s28, 0x100
	s_addc_u32 s29, s29, 0
	s_add_u32 s50, s50, 0x100
	s_addc_u32 s51, s51, 0
	s_cmp_gt_u32 s62, 13
	s_cbranch_scc0 .LBB0_1619
	s_and_b64 vcc, exec, s[10:11]
	s_cbranch_vccz .LBB0_1622
	s_barrier

.LBB0_1707:
	v_readlane_b32 s46, v249, 32
	v_readlane_b32 s47, v249, 33
	s_add_u32 s46, s46, s42
	s_addc_u32 s47, s47, s43
	s_and_b64 s[48:49], s[44:45], exec
	s_cselect_b32 s34, s47, s51
	s_cselect_b32 s66, s46, s50
	s_add_u32 s48, s35, s40
	s_addc_u32 s49, s70, s41
	s_and_b64 s[64:65], s[44:45], exec
	s_cselect_b32 s67, s49, s63
	s_cselect_b32 s68, s48, s62
	s_add_i32 s69, s7, -2
	s_add_u32 s50, s50, 0x100080
	s_addc_u32 s51, s51, 0
	s_add_u32 s91, s62, 0x100
	s_addc_u32 s92, s63, 0
	s_mov_b32 s62, 0
	s_waitcnt vmcnt(0)
	ds_read_b128 v[130:133], v168
	ds_read_b128 v[134:137], v168 offset:1024
	ds_read_b128 v[138:141], v168 offset:2048
	ds_read_b128 v[142:145], v168 offset:3072
	ds_read_b128 v[162:165], v169
	ds_read_b128 v[172:175], v169 offset:1024
	ds_read_b128 v[176:179], v169 offset:2048
	ds_read_b128 v[180:183], v169 offset:3072
	s_add_i32 s93, s62, 2
	s_add_u32 s63, s50, 0xfff00080
	s_addc_u32 s64, s51, -1
	s_cmp_eq_u32 s69, s62
	s_cselect_b32 s62, s68, s91
	s_cselect_b32 s65, s34, s64
	s_cselect_b32 s64, s66, s63
	s_cselect_b32 s63, s67, s92
	v_lshl_add_u64 v[218:219], s[50:51], 0, v[156:157]
	s_add_i32 m0, s12, 0xc000
	ds_read_b128 v[184:187], v170
	ds_read_b128 v[188:191], v170 offset:1024
	ds_read_b128 v[192:195], v170 offset:2048
	ds_read_b128 v[196:199], v170 offset:3072
	ds_read_b128 v[200:203], v170 offset:4096
	ds_read_b128 v[206:209], v170 offset:5120
	ds_read_b128 v[210:213], v170 offset:6144
	ds_read_b128 v[214:217], v170 offset:7168
	global_load_lds_dwordx4 v[218:219], off
	v_lshl_add_u64 v[218:219], s[50:51], 0, v[158:159]
	s_add_i32 m0, s12, 0xe000
	s_nop 0
	global_load_lds_dwordx4 v[218:219], off
	s_waitcnt vmcnt(8)
	s_waitcnt lgkmcnt(0)
	s_barrier
	s_setprio 1
	s_waitcnt lgkmcnt(0)
	v_mfma_f32_16x16x32_bf16 v[126:129], v[130:133], v[184:187], 0
	v_mfma_f32_16x16x32_bf16 v[122:125], v[138:141], v[184:187], 0
	v_mfma_f32_16x16x32_bf16 v[110:113], v[130:133], v[192:195], 0
	v_mfma_f32_16x16x32_bf16 v[106:109], v[138:141], v[192:195], 0
	v_mfma_f32_16x16x32_bf16 v[98:101], v[130:133], v[200:203], 0
	v_mfma_f32_16x16x32_bf16 v[90:93], v[138:141], v[200:203], 0
	v_mfma_f32_16x16x32_bf16 v[82:85], v[130:133], v[210:213], 0
	v_mfma_f32_16x16x32_bf16 v[74:77], v[138:141], v[210:213], 0
	v_mfma_f32_16x16x32_bf16 v[126:129], v[134:137], v[188:191], v[126:129]
	v_mfma_f32_16x16x32_bf16 v[122:125], v[142:145], v[188:191], v[122:125]
	v_mfma_f32_16x16x32_bf16 v[110:113], v[134:137], v[196:199], v[110:113]
	v_mfma_f32_16x16x32_bf16 v[106:109], v[142:145], v[196:199], v[106:109]
	v_mfma_f32_16x16x32_bf16 v[98:101], v[134:137], v[206:209], v[98:101]
	v_mfma_f32_16x16x32_bf16 v[90:93], v[142:145], v[206:209], v[90:93]
	v_mfma_f32_16x16x32_bf16 v[82:85], v[134:137], v[214:217], v[82:85]
	v_mfma_f32_16x16x32_bf16 v[74:77], v[142:145], v[214:217], v[74:77]
	s_setprio 0
	s_setprio 1
	v_mfma_f32_16x16x32_bf16 v[118:121], v[162:165], v[184:187], 0
	v_mfma_f32_16x16x32_bf16 v[114:117], v[176:179], v[184:187], 0
	v_mfma_f32_16x16x32_bf16 v[102:105], v[162:165], v[192:195], 0
	v_mfma_f32_16x16x32_bf16 v[94:97], v[176:179], v[192:195], 0
	v_mfma_f32_16x16x32_bf16 v[86:89], v[162:165], v[200:203], 0
	v_mfma_f32_16x16x32_bf16 v[78:81], v[176:179], v[200:203], 0
	v_mfma_f32_16x16x32_bf16 v[70:73], v[162:165], v[210:213], 0
	v_mfma_f32_16x16x32_bf16 v[66:69], v[176:179], v[210:213], 0
	v_mfma_f32_16x16x32_bf16 v[118:121], v[172:175], v[188:191], v[118:121]
	v_mfma_f32_16x16x32_bf16 v[114:117], v[180:183], v[188:191], v[114:117]
	v_mfma_f32_16x16x32_bf16 v[102:105], v[172:175], v[196:199], v[102:105]
	v_mfma_f32_16x16x32_bf16 v[94:97], v[180:183], v[196:199], v[94:97]
	v_mfma_f32_16x16x32_bf16 v[86:89], v[172:175], v[206:209], v[86:89]
	v_mfma_f32_16x16x32_bf16 v[78:81], v[180:183], v[206:209], v[78:81]
	v_mfma_f32_16x16x32_bf16 v[70:73], v[172:175], v[214:217], v[70:73]
	v_mfma_f32_16x16x32_bf16 v[66:69], v[180:183], v[214:217], v[66:69]
	s_setprio 0
	s_barrier
	s_add_i32 s94, s31, s2
	v_lshl_add_u64 v[218:219], s[62:63], 0, v[148:149]
	s_mov_b32 m0, s94
	ds_read_b128 v[184:187], v170 offset:16384
	ds_read_b128 v[188:191], v170 offset:17408
	ds_read_b128 v[192:195], v170 offset:18432
	ds_read_b128 v[196:199], v170 offset:19456
	ds_read_b128 v[200:203], v170 offset:20480
	ds_read_b128 v[206:209], v170 offset:21504
	ds_read_b128 v[210:213], v170 offset:22528
	ds_read_b128 v[214:217], v170 offset:23552
	global_load_lds_dwordx4 v[218:219], off
	s_add_i32 m0, s94, 0x2000
	s_add_u32 s94, s62, 0x100000
	v_lshl_add_u64 v[220:221], s[62:63], 0, v[152:153]
	s_addc_u32 s95, s63, 0
	s_add_i32 s96, s82, s2
	global_load_lds_dwordx4 v[220:221], off
	v_lshl_add_u64 v[222:223], s[94:95], 0, v[148:149]
	s_mov_b32 m0, s96
	v_lshl_add_u64 v[224:225], s[64:65], 0, v[150:151]
	global_load_lds_dwordx4 v[222:223], off
	v_lshl_add_u64 v[222:223], s[94:95], 0, v[152:153]
	s_add_i32 m0, s96, 0x2000
	s_nop 0
	global_load_lds_dwordx4 v[222:223], off
	v_lshl_add_u64 v[222:223], s[64:65], 0, v[146:147]
	s_mov_b32 m0, s12
	s_nop 0
	global_load_lds_dwordx4 v[222:223], off
	s_waitcnt vmcnt(7)
	s_waitcnt lgkmcnt(0)
	s_barrier
	s_setprio 1
	s_waitcnt lgkmcnt(0)
	v_mfma_f32_16x16x32_bf16 v[62:65], v[130:133], v[184:187], 0
	v_mfma_f32_16x16x32_bf16 v[58:61], v[138:141], v[184:187], 0
	v_mfma_f32_16x16x32_bf16 v[50:53], v[130:133], v[192:195], 0
	v_mfma_f32_16x16x32_bf16 v[42:45], v[138:141], v[192:195], 0
	v_mfma_f32_16x16x32_bf16 v[34:37], v[130:133], v[200:203], 0
	v_mfma_f32_16x16x32_bf16 v[26:29], v[138:141], v[200:203], 0
	v_mfma_f32_16x16x32_bf16 v[18:21], v[130:133], v[210:213], 0
	v_mfma_f32_16x16x32_bf16 v[10:13], v[138:141], v[210:213], 0
	s_mov_b32 m0, s13
	s_nop 0
	global_load_lds_dwordx4 v[224:225], off
	v_mfma_f32_16x16x32_bf16 v[62:65], v[134:137], v[188:191], v[62:65]
	v_mfma_f32_16x16x32_bf16 v[58:61], v[142:145], v[188:191], v[58:61]
	v_mfma_f32_16x16x32_bf16 v[50:53], v[134:137], v[196:199], v[50:53]
	v_mfma_f32_16x16x32_bf16 v[42:45], v[142:145], v[196:199], v[42:45]
	v_mfma_f32_16x16x32_bf16 v[34:37], v[134:137], v[206:209], v[34:37]
	v_mfma_f32_16x16x32_bf16 v[26:29], v[142:145], v[206:209], v[26:29]
	v_mfma_f32_16x16x32_bf16 v[18:21], v[134:137], v[214:217], v[18:21]
	v_mfma_f32_16x16x32_bf16 v[10:13], v[142:145], v[214:217], v[10:13]
	s_setprio 0
	s_setprio 1
	v_mfma_f32_16x16x32_bf16 v[54:57], v[162:165], v[184:187], 0
	v_mfma_f32_16x16x32_bf16 v[46:49], v[176:179], v[184:187], 0
	v_mfma_f32_16x16x32_bf16 v[38:41], v[162:165], v[192:195], 0
	v_mfma_f32_16x16x32_bf16 v[30:33], v[176:179], v[192:195], 0
	v_mfma_f32_16x16x32_bf16 v[22:25], v[162:165], v[200:203], 0
	v_mfma_f32_16x16x32_bf16 v[14:17], v[176:179], v[200:203], 0
	v_mfma_f32_16x16x32_bf16 v[6:9], v[162:165], v[210:213], 0
	v_mfma_f32_16x16x32_bf16 v[2:5], v[176:179], v[210:213], 0
	v_mfma_f32_16x16x32_bf16 v[54:57], v[172:175], v[188:191], v[54:57]
	v_mfma_f32_16x16x32_bf16 v[46:49], v[180:183], v[188:191], v[46:49]
	v_mfma_f32_16x16x32_bf16 v[38:41], v[172:175], v[196:199], v[38:41]
	v_mfma_f32_16x16x32_bf16 v[30:33], v[180:183], v[196:199], v[30:33]
	v_mfma_f32_16x16x32_bf16 v[22:25], v[172:175], v[206:209], v[22:25]
	v_mfma_f32_16x16x32_bf16 v[14:17], v[180:183], v[206:209], v[14:17]
	v_mfma_f32_16x16x32_bf16 v[6:9], v[172:175], v[214:217], v[6:9]
	v_mfma_f32_16x16x32_bf16 v[2:5], v[180:183], v[214:217], v[2:5]
	s_setprio 0
	s_barrier
	s_add_i32 s94, 0, 0x18000
	s_add_i32 s95, 0, 0x1c000
	v_add_u32_e32 v142, s94, v167
	v_add_u32_e32 v154, s95, v167
	ds_read_b128 v[130:133], v142
	ds_read_b128 v[134:137], v142 offset:1024
	ds_read_b128 v[138:141], v142 offset:2048
	ds_read_b128 v[142:145], v142 offset:3072
	ds_read_b128 v[162:165], v154
	ds_read_b128 v[172:175], v154 offset:1024
	ds_read_b128 v[176:179], v154 offset:2048
	ds_read_b128 v[180:183], v154 offset:3072
	s_add_u32 s64, s64, 0x100000
	s_addc_u32 s65, s65, 0
	s_mov_b32 m0, s18
	v_lshl_add_u64 v[226:227], s[64:65], 0, v[146:147]
	ds_read_b128 v[184:187], v170 offset:32768
	ds_read_b128 v[188:191], v170 offset:33792
	ds_read_b128 v[192:195], v170 offset:34816
	ds_read_b128 v[196:199], v170 offset:35840
	ds_read_b128 v[200:203], v170 offset:36864
	ds_read_b128 v[206:209], v170 offset:37888
	ds_read_b128 v[210:213], v170 offset:38912
	ds_read_b128 v[214:217], v170 offset:39936
	global_load_lds_dwordx4 v[226:227], off
	v_lshl_add_u64 v[226:227], s[64:65], 0, v[150:151]
	s_mov_b32 m0, s19
	s_nop 0
	global_load_lds_dwordx4 v[226:227], off
	s_waitcnt vmcnt(8)
	s_waitcnt lgkmcnt(0)
	s_barrier
	s_setprio 1
	s_waitcnt lgkmcnt(0)
	v_mfma_f32_16x16x32_bf16 v[126:129], v[130:133], v[184:187], v[126:129]
	v_mfma_f32_16x16x32_bf16 v[122:125], v[138:141], v[184:187], v[122:125]
	v_mfma_f32_16x16x32_bf16 v[110:113], v[130:133], v[192:195], v[110:113]
	v_mfma_f32_16x16x32_bf16 v[106:109], v[138:141], v[192:195], v[106:109]
	v_mfma_f32_16x16x32_bf16 v[98:101], v[130:133], v[200:203], v[98:101]
	v_mfma_f32_16x16x32_bf16 v[90:93], v[138:141], v[200:203], v[90:93]
	v_mfma_f32_16x16x32_bf16 v[82:85], v[130:133], v[210:213], v[82:85]
	v_mfma_f32_16x16x32_bf16 v[74:77], v[138:141], v[210:213], v[74:77]
	v_mfma_f32_16x16x32_bf16 v[126:129], v[134:137], v[188:191], v[126:129]
	v_mfma_f32_16x16x32_bf16 v[122:125], v[142:145], v[188:191], v[122:125]
	v_mfma_f32_16x16x32_bf16 v[110:113], v[134:137], v[196:199], v[110:113]
	v_mfma_f32_16x16x32_bf16 v[106:109], v[142:145], v[196:199], v[106:109]
	v_mfma_f32_16x16x32_bf16 v[98:101], v[134:137], v[206:209], v[98:101]
	v_mfma_f32_16x16x32_bf16 v[90:93], v[142:145], v[206:209], v[90:93]
	v_mfma_f32_16x16x32_bf16 v[82:85], v[134:137], v[214:217], v[82:85]
	v_mfma_f32_16x16x32_bf16 v[74:77], v[142:145], v[214:217], v[74:77]
	s_setprio 0
	s_setprio 1
	v_mfma_f32_16x16x32_bf16 v[118:121], v[162:165], v[184:187], v[118:121]
	v_mfma_f32_16x16x32_bf16 v[114:117], v[176:179], v[184:187], v[114:117]
	v_mfma_f32_16x16x32_bf16 v[102:105], v[162:165], v[192:195], v[102:105]
	v_mfma_f32_16x16x32_bf16 v[94:97], v[176:179], v[192:195], v[94:97]
	v_mfma_f32_16x16x32_bf16 v[86:89], v[162:165], v[200:203], v[86:89]
	v_mfma_f32_16x16x32_bf16 v[78:81], v[176:179], v[200:203], v[78:81]
	v_mfma_f32_16x16x32_bf16 v[70:73], v[162:165], v[210:213], v[70:73]
	v_mfma_f32_16x16x32_bf16 v[66:69], v[176:179], v[210:213], v[66:69]
	v_mfma_f32_16x16x32_bf16 v[118:121], v[172:175], v[188:191], v[118:121]
	v_mfma_f32_16x16x32_bf16 v[114:117], v[180:183], v[188:191], v[114:117]
	v_mfma_f32_16x16x32_bf16 v[102:105], v[172:175], v[196:199], v[102:105]
	v_mfma_f32_16x16x32_bf16 v[94:97], v[180:183], v[196:199], v[94:97]
	v_mfma_f32_16x16x32_bf16 v[86:89], v[172:175], v[206:209], v[86:89]
	v_mfma_f32_16x16x32_bf16 v[78:81], v[180:183], v[206:209], v[78:81]
	v_mfma_f32_16x16x32_bf16 v[70:73], v[172:175], v[214:217], v[70:73]
	v_mfma_f32_16x16x32_bf16 v[66:69], v[180:183], v[214:217], v[66:69]
	s_setprio 0
	s_barrier
	s_add_i32 s64, s94, s2
	v_lshl_add_u64 v[218:219], v[218:219], 0, s[16:17]
	s_mov_b32 m0, s64
	ds_read_b128 v[184:187], v170 offset:49152
	ds_read_b128 v[188:191], v170 offset:50176
	ds_read_b128 v[192:195], v170 offset:51200
	ds_read_b128 v[196:199], v170 offset:52224
	ds_read_b128 v[200:203], v170 offset:53248
	ds_read_b128 v[206:209], v170 offset:54272
	ds_read_b128 v[210:213], v170 offset:55296
	ds_read_b128 v[214:217], v170 offset:56320
	global_load_lds_dwordx4 v[218:219], off
	s_add_i32 m0, s64, 0x2000
	s_add_u32 s62, s62, 0x100080
	v_lshl_add_u64 v[218:219], v[220:221], 0, s[16:17]
	s_addc_u32 s63, s63, 0
	s_add_i32 s64, s95, s2
	global_load_lds_dwordx4 v[218:219], off
	v_lshl_add_u64 v[218:219], s[62:63], 0, v[148:149]
	s_mov_b32 m0, s64
	s_nop 0
	global_load_lds_dwordx4 v[218:219], off
	v_lshl_add_u64 v[218:219], s[62:63], 0, v[152:153]
	s_add_i32 m0, s64, 0x2000
	s_nop 0
	global_load_lds_dwordx4 v[218:219], off
	v_lshl_add_u64 v[218:219], v[222:223], 0, s[16:17]
	s_mov_b32 m0, s74
	s_nop 0
	global_load_lds_dwordx4 v[218:219], off
	v_lshl_add_u64 v[218:219], v[224:225], 0, s[16:17]
	s_waitcnt vmcnt(7)
	s_waitcnt lgkmcnt(0)
	s_barrier
	s_setprio 1
	s_waitcnt lgkmcnt(0)
	v_mfma_f32_16x16x32_bf16 v[62:65], v[130:133], v[184:187], v[62:65]
	v_mfma_f32_16x16x32_bf16 v[58:61], v[138:141], v[184:187], v[58:61]
	v_mfma_f32_16x16x32_bf16 v[50:53], v[130:133], v[192:195], v[50:53]
	v_mfma_f32_16x16x32_bf16 v[42:45], v[138:141], v[192:195], v[42:45]
	v_mfma_f32_16x16x32_bf16 v[34:37], v[130:133], v[200:203], v[34:37]
	v_mfma_f32_16x16x32_bf16 v[26:29], v[138:141], v[200:203], v[26:29]
	v_mfma_f32_16x16x32_bf16 v[18:21], v[130:133], v[210:213], v[18:21]
	v_mfma_f32_16x16x32_bf16 v[10:13], v[138:141], v[210:213], v[10:13]
	s_mov_b32 m0, s75
	s_nop 0
	global_load_lds_dwordx4 v[218:219], off
	v_mfma_f32_16x16x32_bf16 v[62:65], v[134:137], v[188:191], v[62:65]
	v_mfma_f32_16x16x32_bf16 v[58:61], v[142:145], v[188:191], v[58:61]
	v_mfma_f32_16x16x32_bf16 v[50:53], v[134:137], v[196:199], v[50:53]
	v_mfma_f32_16x16x32_bf16 v[42:45], v[142:145], v[196:199], v[42:45]
	v_mfma_f32_16x16x32_bf16 v[34:37], v[134:137], v[206:209], v[34:37]
	v_mfma_f32_16x16x32_bf16 v[26:29], v[142:145], v[206:209], v[26:29]
	v_mfma_f32_16x16x32_bf16 v[18:21], v[134:137], v[214:217], v[18:21]
	v_mfma_f32_16x16x32_bf16 v[10:13], v[142:145], v[214:217], v[10:13]
	s_setprio 0
	s_setprio 1
	v_mfma_f32_16x16x32_bf16 v[54:57], v[162:165], v[184:187], v[54:57]
	v_mfma_f32_16x16x32_bf16 v[46:49], v[176:179], v[184:187], v[46:49]
	v_mfma_f32_16x16x32_bf16 v[38:41], v[162:165], v[192:195], v[38:41]
	v_mfma_f32_16x16x32_bf16 v[30:33], v[176:179], v[192:195], v[30:33]
	v_mfma_f32_16x16x32_bf16 v[22:25], v[162:165], v[200:203], v[22:25]
	v_mfma_f32_16x16x32_bf16 v[14:17], v[176:179], v[200:203], v[14:17]
	v_mfma_f32_16x16x32_bf16 v[6:9], v[162:165], v[210:213], v[6:9]
	v_mfma_f32_16x16x32_bf16 v[2:5], v[176:179], v[210:213], v[2:5]
	v_mfma_f32_16x16x32_bf16 v[54:57], v[172:175], v[188:191], v[54:57]
	v_mfma_f32_16x16x32_bf16 v[46:49], v[180:183], v[188:191], v[46:49]
	v_mfma_f32_16x16x32_bf16 v[38:41], v[172:175], v[196:199], v[38:41]
	v_mfma_f32_16x16x32_bf16 v[30:33], v[180:183], v[196:199], v[30:33]
	v_mfma_f32_16x16x32_bf16 v[22:25], v[172:175], v[206:209], v[22:25]
	v_mfma_f32_16x16x32_bf16 v[14:17], v[180:183], v[206:209], v[14:17]
	v_mfma_f32_16x16x32_bf16 v[6:9], v[172:175], v[214:217], v[6:9]
	v_mfma_f32_16x16x32_bf16 v[2:5], v[180:183], v[214:217], v[2:5]
	s_setprio 0
	s_barrier
	s_add_u32 s50, s50, 0x100
	s_addc_u32 s51, s51, 0
	s_add_u32 s91, s91, 0x100
	s_addc_u32 s92, s92, 0
	s_cmp_ge_i32 s93, s7
	s_mov_b32 s62, s93
.LBB0_1708:
	ds_read_b128 v[130:133], v168
	ds_read_b128 v[134:137], v168 offset:1024
	ds_read_b128 v[138:141], v168 offset:2048
	ds_read_b128 v[142:145], v168 offset:3072
	ds_read_b128 v[162:165], v169
	ds_read_b128 v[172:175], v169 offset:1024
	ds_read_b128 v[176:179], v169 offset:2048
	ds_read_b128 v[180:183], v169 offset:3072
	s_add_i32 s93, s62, 2
	s_add_u32 s63, s50, 0xfff00080
	s_addc_u32 s64, s51, -1
	s_cmp_eq_u32 s69, s62
	s_cselect_b32 s62, s68, s91
	s_cselect_b32 s65, s34, s64
	s_cselect_b32 s64, s66, s63
	s_cselect_b32 s63, s67, s92
	v_lshl_add_u64 v[218:219], s[50:51], 0, v[156:157]
	s_add_i32 m0, s12, 0xc000
	ds_read_b128 v[184:187], v170
	ds_read_b128 v[188:191], v170 offset:1024
	ds_read_b128 v[192:195], v170 offset:2048
	ds_read_b128 v[196:199], v170 offset:3072
	ds_read_b128 v[200:203], v170 offset:4096
	ds_read_b128 v[206:209], v170 offset:5120
	ds_read_b128 v[210:213], v170 offset:6144
	ds_read_b128 v[214:217], v170 offset:7168
	global_load_lds_dwordx4 v[218:219], off
	v_lshl_add_u64 v[218:219], s[50:51], 0, v[158:159]
	s_add_i32 m0, s12, 0xe000
	s_nop 0
	global_load_lds_dwordx4 v[218:219], off
	s_waitcnt vmcnt(8)
	s_waitcnt lgkmcnt(0)
	s_barrier
	s_setprio 1
	s_waitcnt lgkmcnt(0)
	v_mfma_f32_16x16x32_bf16 v[126:129], v[130:133], v[184:187], v[126:129]
	v_mfma_f32_16x16x32_bf16 v[122:125], v[138:141], v[184:187], v[122:125]
	v_mfma_f32_16x16x32_bf16 v[110:113], v[130:133], v[192:195], v[110:113]
	v_mfma_f32_16x16x32_bf16 v[106:109], v[138:141], v[192:195], v[106:109]
	v_mfma_f32_16x16x32_bf16 v[98:101], v[130:133], v[200:203], v[98:101]
	v_mfma_f32_16x16x32_bf16 v[90:93], v[138:141], v[200:203], v[90:93]
	v_mfma_f32_16x16x32_bf16 v[82:85], v[130:133], v[210:213], v[82:85]
	v_mfma_f32_16x16x32_bf16 v[74:77], v[138:141], v[210:213], v[74:77]
	v_mfma_f32_16x16x32_bf16 v[126:129], v[134:137], v[188:191], v[126:129]
	v_mfma_f32_16x16x32_bf16 v[122:125], v[142:145], v[188:191], v[122:125]
	v_mfma_f32_16x16x32_bf16 v[110:113], v[134:137], v[196:199], v[110:113]
	v_mfma_f32_16x16x32_bf16 v[106:109], v[142:145], v[196:199], v[106:109]
	v_mfma_f32_16x16x32_bf16 v[98:101], v[134:137], v[206:209], v[98:101]
	v_mfma_f32_16x16x32_bf16 v[90:93], v[142:145], v[206:209], v[90:93]
	v_mfma_f32_16x16x32_bf16 v[82:85], v[134:137], v[214:217], v[82:85]
	v_mfma_f32_16x16x32_bf16 v[74:77], v[142:145], v[214:217], v[74:77]
	s_setprio 0
	s_setprio 1
	v_mfma_f32_16x16x32_bf16 v[118:121], v[162:165], v[184:187], v[118:121]
	v_mfma_f32_16x16x32_bf16 v[114:117], v[176:179], v[184:187], v[114:117]
	v_mfma_f32_16x16x32_bf16 v[102:105], v[162:165], v[192:195], v[102:105]
	v_mfma_f32_16x16x32_bf16 v[94:97], v[176:179], v[192:195], v[94:97]
	v_mfma_f32_16x16x32_bf16 v[86:89], v[162:165], v[200:203], v[86:89]
	v_mfma_f32_16x16x32_bf16 v[78:81], v[176:179], v[200:203], v[78:81]
	v_mfma_f32_16x16x32_bf16 v[70:73], v[162:165], v[210:213], v[70:73]
	v_mfma_f32_16x16x32_bf16 v[66:69], v[176:179], v[210:213], v[66:69]
	v_mfma_f32_16x16x32_bf16 v[118:121], v[172:175], v[188:191], v[118:121]
	v_mfma_f32_16x16x32_bf16 v[114:117], v[180:183], v[188:191], v[114:117]
	v_mfma_f32_16x16x32_bf16 v[102:105], v[172:175], v[196:199], v[102:105]
	v_mfma_f32_16x16x32_bf16 v[94:97], v[180:183], v[196:199], v[94:97]
	v_mfma_f32_16x16x32_bf16 v[86:89], v[172:175], v[206:209], v[86:89]
	v_mfma_f32_16x16x32_bf16 v[78:81], v[180:183], v[206:209], v[78:81]
	v_mfma_f32_16x16x32_bf16 v[70:73], v[172:175], v[214:217], v[70:73]
	v_mfma_f32_16x16x32_bf16 v[66:69], v[180:183], v[214:217], v[66:69]
	s_setprio 0
	s_barrier
	s_add_i32 s94, s31, s2
	v_lshl_add_u64 v[218:219], s[62:63], 0, v[148:149]
	s_mov_b32 m0, s94
	ds_read_b128 v[184:187], v170 offset:16384
	ds_read_b128 v[188:191], v170 offset:17408
	ds_read_b128 v[192:195], v170 offset:18432
	ds_read_b128 v[196:199], v170 offset:19456
	ds_read_b128 v[200:203], v170 offset:20480
	ds_read_b128 v[206:209], v170 offset:21504
	ds_read_b128 v[210:213], v170 offset:22528
	ds_read_b128 v[214:217], v170 offset:23552
	global_load_lds_dwordx4 v[218:219], off
	s_add_i32 m0, s94, 0x2000
	s_add_u32 s94, s62, 0x100000
	v_lshl_add_u64 v[220:221], s[62:63], 0, v[152:153]
	s_addc_u32 s95, s63, 0
	s_add_i32 s96, s82, s2
	global_load_lds_dwordx4 v[220:221], off
	v_lshl_add_u64 v[222:223], s[94:95], 0, v[148:149]
	s_mov_b32 m0, s96
	v_lshl_add_u64 v[224:225], s[64:65], 0, v[150:151]
	global_load_lds_dwordx4 v[222:223], off
	v_lshl_add_u64 v[222:223], s[94:95], 0, v[152:153]
	s_add_i32 m0, s96, 0x2000
	s_nop 0
	global_load_lds_dwordx4 v[222:223], off
	v_lshl_add_u64 v[222:223], s[64:65], 0, v[146:147]
	s_mov_b32 m0, s12
	s_nop 0
	global_load_lds_dwordx4 v[222:223], off
	s_waitcnt vmcnt(7)
	s_waitcnt lgkmcnt(0)
	s_barrier
	s_setprio 1
	s_waitcnt lgkmcnt(0)
	v_mfma_f32_16x16x32_bf16 v[62:65], v[130:133], v[184:187], v[62:65]
	v_mfma_f32_16x16x32_bf16 v[58:61], v[138:141], v[184:187], v[58:61]
	v_mfma_f32_16x16x32_bf16 v[50:53], v[130:133], v[192:195], v[50:53]
	v_mfma_f32_16x16x32_bf16 v[42:45], v[138:141], v[192:195], v[42:45]
	v_mfma_f32_16x16x32_bf16 v[34:37], v[130:133], v[200:203], v[34:37]
	v_mfma_f32_16x16x32_bf16 v[26:29], v[138:141], v[200:203], v[26:29]
	v_mfma_f32_16x16x32_bf16 v[18:21], v[130:133], v[210:213], v[18:21]
	v_mfma_f32_16x16x32_bf16 v[10:13], v[138:141], v[210:213], v[10:13]
	s_mov_b32 m0, s13
	s_nop 0
	global_load_lds_dwordx4 v[224:225], off
	v_mfma_f32_16x16x32_bf16 v[62:65], v[134:137], v[188:191], v[62:65]
	v_mfma_f32_16x16x32_bf16 v[58:61], v[142:145], v[188:191], v[58:61]
	v_mfma_f32_16x16x32_bf16 v[50:53], v[134:137], v[196:199], v[50:53]
	v_mfma_f32_16x16x32_bf16 v[42:45], v[142:145], v[196:199], v[42:45]
	v_mfma_f32_16x16x32_bf16 v[34:37], v[134:137], v[206:209], v[34:37]
	v_mfma_f32_16x16x32_bf16 v[26:29], v[142:145], v[206:209], v[26:29]
	v_mfma_f32_16x16x32_bf16 v[18:21], v[134:137], v[214:217], v[18:21]
	v_mfma_f32_16x16x32_bf16 v[10:13], v[142:145], v[214:217], v[10:13]
	s_setprio 0
	s_setprio 1
	v_mfma_f32_16x16x32_bf16 v[54:57], v[162:165], v[184:187], v[54:57]
	v_mfma_f32_16x16x32_bf16 v[46:49], v[176:179], v[184:187], v[46:49]
	v_mfma_f32_16x16x32_bf16 v[38:41], v[162:165], v[192:195], v[38:41]
	v_mfma_f32_16x16x32_bf16 v[30:33], v[176:179], v[192:195], v[30:33]
	v_mfma_f32_16x16x32_bf16 v[22:25], v[162:165], v[200:203], v[22:25]
	v_mfma_f32_16x16x32_bf16 v[14:17], v[176:179], v[200:203], v[14:17]
	v_mfma_f32_16x16x32_bf16 v[6:9], v[162:165], v[210:213], v[6:9]
	v_mfma_f32_16x16x32_bf16 v[2:5], v[176:179], v[210:213], v[2:5]
	v_mfma_f32_16x16x32_bf16 v[54:57], v[172:175], v[188:191], v[54:57]
	v_mfma_f32_16x16x32_bf16 v[46:49], v[180:183], v[188:191], v[46:49]
	v_mfma_f32_16x16x32_bf16 v[38:41], v[172:175], v[196:199], v[38:41]
	v_mfma_f32_16x16x32_bf16 v[30:33], v[180:183], v[196:199], v[30:33]
	v_mfma_f32_16x16x32_bf16 v[22:25], v[172:175], v[206:209], v[22:25]
	v_mfma_f32_16x16x32_bf16 v[14:17], v[180:183], v[206:209], v[14:17]
	v_mfma_f32_16x16x32_bf16 v[6:9], v[172:175], v[214:217], v[6:9]
	v_mfma_f32_16x16x32_bf16 v[2:5], v[180:183], v[214:217], v[2:5]
	s_setprio 0
	s_barrier
	s_add_i32 s94, 0, 0x18000
	s_add_i32 s95, 0, 0x1c000
	v_add_u32_e32 v142, s94, v167
	v_add_u32_e32 v154, s95, v167
	ds_read_b128 v[130:133], v142
	ds_read_b128 v[134:137], v142 offset:1024
	ds_read_b128 v[138:141], v142 offset:2048
	ds_read_b128 v[142:145], v142 offset:3072
	ds_read_b128 v[162:165], v154
	ds_read_b128 v[172:175], v154 offset:1024
	ds_read_b128 v[176:179], v154 offset:2048
	ds_read_b128 v[180:183], v154 offset:3072
	s_add_u32 s64, s64, 0x100000
	s_addc_u32 s65, s65, 0
	s_mov_b32 m0, s18
	v_lshl_add_u64 v[226:227], s[64:65], 0, v[146:147]
	ds_read_b128 v[184:187], v170 offset:32768
	ds_read_b128 v[188:191], v170 offset:33792
	ds_read_b128 v[192:195], v170 offset:34816
	ds_read_b128 v[196:199], v170 offset:35840
	ds_read_b128 v[200:203], v170 offset:36864
	ds_read_b128 v[206:209], v170 offset:37888
	ds_read_b128 v[210:213], v170 offset:38912
	ds_read_b128 v[214:217], v170 offset:39936
	global_load_lds_dwordx4 v[226:227], off
	v_lshl_add_u64 v[226:227], s[64:65], 0, v[150:151]
	s_mov_b32 m0, s19
	s_nop 0
	global_load_lds_dwordx4 v[226:227], off
	s_waitcnt vmcnt(8)
	s_waitcnt lgkmcnt(0)
	s_barrier
	s_setprio 1
	s_waitcnt lgkmcnt(0)
	v_mfma_f32_16x16x32_bf16 v[126:129], v[130:133], v[184:187], v[126:129]
	v_mfma_f32_16x16x32_bf16 v[122:125], v[138:141], v[184:187], v[122:125]
	v_mfma_f32_16x16x32_bf16 v[110:113], v[130:133], v[192:195], v[110:113]
	v_mfma_f32_16x16x32_bf16 v[106:109], v[138:141], v[192:195], v[106:109]
	v_mfma_f32_16x16x32_bf16 v[98:101], v[130:133], v[200:203], v[98:101]
	v_mfma_f32_16x16x32_bf16 v[90:93], v[138:141], v[200:203], v[90:93]
	v_mfma_f32_16x16x32_bf16 v[82:85], v[130:133], v[210:213], v[82:85]
	v_mfma_f32_16x16x32_bf16 v[74:77], v[138:141], v[210:213], v[74:77]
	v_mfma_f32_16x16x32_bf16 v[126:129], v[134:137], v[188:191], v[126:129]
	v_mfma_f32_16x16x32_bf16 v[122:125], v[142:145], v[188:191], v[122:125]
	v_mfma_f32_16x16x32_bf16 v[110:113], v[134:137], v[196:199], v[110:113]
	v_mfma_f32_16x16x32_bf16 v[106:109], v[142:145], v[196:199], v[106:109]
	v_mfma_f32_16x16x32_bf16 v[98:101], v[134:137], v[206:209], v[98:101]
	v_mfma_f32_16x16x32_bf16 v[90:93], v[142:145], v[206:209], v[90:93]
	v_mfma_f32_16x16x32_bf16 v[82:85], v[134:137], v[214:217], v[82:85]
	v_mfma_f32_16x16x32_bf16 v[74:77], v[142:145], v[214:217], v[74:77]
	s_setprio 0
	s_setprio 1
	v_mfma_f32_16x16x32_bf16 v[118:121], v[162:165], v[184:187], v[118:121]
	v_mfma_f32_16x16x32_bf16 v[114:117], v[176:179], v[184:187], v[114:117]
	v_mfma_f32_16x16x32_bf16 v[102:105], v[162:165], v[192:195], v[102:105]
	v_mfma_f32_16x16x32_bf16 v[94:97], v[176:179], v[192:195], v[94:97]
	v_mfma_f32_16x16x32_bf16 v[86:89], v[162:165], v[200:203], v[86:89]
	v_mfma_f32_16x16x32_bf16 v[78:81], v[176:179], v[200:203], v[78:81]
	v_mfma_f32_16x16x32_bf16 v[70:73], v[162:165], v[210:213], v[70:73]
	v_mfma_f32_16x16x32_bf16 v[66:69], v[176:179], v[210:213], v[66:69]
	v_mfma_f32_16x16x32_bf16 v[118:121], v[172:175], v[188:191], v[118:121]
	v_mfma_f32_16x16x32_bf16 v[114:117], v[180:183], v[188:191], v[114:117]
	v_mfma_f32_16x16x32_bf16 v[102:105], v[172:175], v[196:199], v[102:105]
	v_mfma_f32_16x16x32_bf16 v[94:97], v[180:183], v[196:199], v[94:97]
	v_mfma_f32_16x16x32_bf16 v[86:89], v[172:175], v[206:209], v[86:89]
	v_mfma_f32_16x16x32_bf16 v[78:81], v[180:183], v[206:209], v[78:81]
	v_mfma_f32_16x16x32_bf16 v[70:73], v[172:175], v[214:217], v[70:73]
	v_mfma_f32_16x16x32_bf16 v[66:69], v[180:183], v[214:217], v[66:69]
	s_setprio 0
	s_barrier
	s_add_i32 s64, s94, s2
	v_lshl_add_u64 v[218:219], v[218:219], 0, s[16:17]
	s_mov_b32 m0, s64
	ds_read_b128 v[184:187], v170 offset:49152
	ds_read_b128 v[188:191], v170 offset:50176
	ds_read_b128 v[192:195], v170 offset:51200
	ds_read_b128 v[196:199], v170 offset:52224
	ds_read_b128 v[200:203], v170 offset:53248
	ds_read_b128 v[206:209], v170 offset:54272
	ds_read_b128 v[210:213], v170 offset:55296
	ds_read_b128 v[214:217], v170 offset:56320
	global_load_lds_dwordx4 v[218:219], off
	s_add_i32 m0, s64, 0x2000
	s_add_u32 s62, s62, 0x100080
	v_lshl_add_u64 v[218:219], v[220:221], 0, s[16:17]
	s_addc_u32 s63, s63, 0
	s_add_i32 s64, s95, s2
	global_load_lds_dwordx4 v[218:219], off
	v_lshl_add_u64 v[218:219], s[62:63], 0, v[148:149]
	s_mov_b32 m0, s64
	s_nop 0
	global_load_lds_dwordx4 v[218:219], off
	v_lshl_add_u64 v[218:219], s[62:63], 0, v[152:153]
	s_add_i32 m0, s64, 0x2000
	s_nop 0
	global_load_lds_dwordx4 v[218:219], off
	v_lshl_add_u64 v[218:219], v[222:223], 0, s[16:17]
	s_mov_b32 m0, s74
	s_nop 0
	global_load_lds_dwordx4 v[218:219], off
	v_lshl_add_u64 v[218:219], v[224:225], 0, s[16:17]
	s_waitcnt vmcnt(7)
	s_waitcnt lgkmcnt(0)
	s_barrier
	s_setprio 1
	s_waitcnt lgkmcnt(0)
	v_mfma_f32_16x16x32_bf16 v[62:65], v[130:133], v[184:187], v[62:65]
	v_mfma_f32_16x16x32_bf16 v[58:61], v[138:141], v[184:187], v[58:61]
	v_mfma_f32_16x16x32_bf16 v[50:53], v[130:133], v[192:195], v[50:53]
	v_mfma_f32_16x16x32_bf16 v[42:45], v[138:141], v[192:195], v[42:45]
	v_mfma_f32_16x16x32_bf16 v[34:37], v[130:133], v[200:203], v[34:37]
	v_mfma_f32_16x16x32_bf16 v[26:29], v[138:141], v[200:203], v[26:29]
	v_mfma_f32_16x16x32_bf16 v[18:21], v[130:133], v[210:213], v[18:21]
	v_mfma_f32_16x16x32_bf16 v[10:13], v[138:141], v[210:213], v[10:13]
	s_mov_b32 m0, s75
	s_nop 0
	global_load_lds_dwordx4 v[218:219], off
	v_mfma_f32_16x16x32_bf16 v[62:65], v[134:137], v[188:191], v[62:65]
	v_mfma_f32_16x16x32_bf16 v[58:61], v[142:145], v[188:191], v[58:61]
	v_mfma_f32_16x16x32_bf16 v[50:53], v[134:137], v[196:199], v[50:53]
	v_mfma_f32_16x16x32_bf16 v[42:45], v[142:145], v[196:199], v[42:45]
	v_mfma_f32_16x16x32_bf16 v[34:37], v[134:137], v[206:209], v[34:37]
	v_mfma_f32_16x16x32_bf16 v[26:29], v[142:145], v[206:209], v[26:29]
	v_mfma_f32_16x16x32_bf16 v[18:21], v[134:137], v[214:217], v[18:21]
	v_mfma_f32_16x16x32_bf16 v[10:13], v[142:145], v[214:217], v[10:13]
	s_setprio 0
	s_setprio 1
	v_mfma_f32_16x16x32_bf16 v[54:57], v[162:165], v[184:187], v[54:57]
	v_mfma_f32_16x16x32_bf16 v[46:49], v[176:179], v[184:187], v[46:49]
	v_mfma_f32_16x16x32_bf16 v[38:41], v[162:165], v[192:195], v[38:41]
	v_mfma_f32_16x16x32_bf16 v[30:33], v[176:179], v[192:195], v[30:33]
	v_mfma_f32_16x16x32_bf16 v[22:25], v[162:165], v[200:203], v[22:25]
	v_mfma_f32_16x16x32_bf16 v[14:17], v[176:179], v[200:203], v[14:17]
	v_mfma_f32_16x16x32_bf16 v[6:9], v[162:165], v[210:213], v[6:9]
	v_mfma_f32_16x16x32_bf16 v[2:5], v[176:179], v[210:213], v[2:5]
	v_mfma_f32_16x16x32_bf16 v[54:57], v[172:175], v[188:191], v[54:57]
	v_mfma_f32_16x16x32_bf16 v[46:49], v[180:183], v[188:191], v[46:49]
	v_mfma_f32_16x16x32_bf16 v[38:41], v[172:175], v[196:199], v[38:41]
	v_mfma_f32_16x16x32_bf16 v[30:33], v[180:183], v[196:199], v[30:33]
	v_mfma_f32_16x16x32_bf16 v[22:25], v[172:175], v[206:209], v[22:25]
	v_mfma_f32_16x16x32_bf16 v[14:17], v[180:183], v[206:209], v[14:17]
	v_mfma_f32_16x16x32_bf16 v[6:9], v[172:175], v[214:217], v[6:9]
	v_mfma_f32_16x16x32_bf16 v[2:5], v[180:183], v[214:217], v[2:5]
	s_setprio 0
	s_barrier
	s_add_u32 s50, s50, 0x100
	s_addc_u32 s51, s51, 0
	s_add_u32 s91, s91, 0x100
	s_addc_u32 s92, s92, 0
	s_cmp_ge_i32 s93, s7
	s_mov_b32 s62, s93
	s_cbranch_scc0 .LBB0_1708
	s_and_b64 vcc, exec, s[20:21]
	s_cbranch_vccz .LBB0_1711
	s_barrier
